# xor-16/32 reduction steps via v_permlane16/32_swap instead of ds_bpermute where the partial sum is dead after the add
# speedup vs baseline: 1.0221x; 1.0075x over previous
.LBB0_209:
	s_or_b64 exec, exec, s[6:7]
	v_ashrrev_i32_e32 v1, 12, v2
	v_mad_i32_i24 v1, v1, s35, s35
	v_cndmask_b32_e64 v34, v1, 0, s[4:5]
	v_ashrrev_i32_e32 v35, 31, v34
	v_lshl_add_u64 v[42:43], v[34:35], 2, s[14:15]
	v_lshl_add_u64 v[54:55], v[42:43], 0, s[28:29]
	v_lshl_add_u64 v[46:47], v[24:25], 0, v[12:13]
	v_lshl_add_u64 v[24:25], v[54:55], 0, v[12:13]
	s_waitcnt lgkmcnt(0)
	v_readfirstlane_b32 s4, v4
	v_readfirstlane_b32 s5, v5
	global_load_dwordx4 v[34:37], v[46:47], off
	s_nop 3
	global_load_dwordx4 v[38:41], v12, s[4:5]
	global_load_dwordx4 v[42:45], v[24:25], off
	v_lshlrev_b64 v[24:25], 12, v[22:23]
	v_lshlrev_b64 v[22:23], 11, v[22:23]
	v_lshl_add_u64 v[58:59], v[6:7], 0, v[24:25]
	v_lshl_add_u64 v[62:63], v[8:9], 0, v[22:23]
	v_lshl_add_u64 v[50:51], v[54:55], 0, v[16:17]
	s_waitcnt vmcnt(2)
	global_store_dwordx4 v[58:59], v[34:37], off sc1
	s_waitcnt vmcnt(2)
	v_pk_mul_f32 v[22:23], v[36:37], v[40:41]
	v_pk_mul_f32 v[24:25], v[34:35], v[38:39]
	s_waitcnt vmcnt(1)
	v_pk_add_f32 v[38:39], v[42:43], 1.0 op_sel_hi:[1,0]
	v_pk_add_f32 v[40:41], v[44:45], 1.0 op_sel_hi:[1,0]
	v_pk_mul_f32 v[24:25], v[38:39], v[24:25]
	v_pk_mul_f32 v[22:23], v[40:41], v[22:23]
	v_cvt_pk_bf16_f32 v24, v24, v25
	v_cvt_pk_bf16_f32 v25, v22, v23
	global_store_dwordx2 v[62:63], v[24:25], off sc1
	v_lshl_add_u64 v[42:43], v[54:55], 0, v[14:15]
	global_load_dwordx4 v[22:25], v[46:47], off offset:1024
	global_load_dwordx4 v[38:41], v12, s[4:5] offset:1024
	v_mul_f32_e32 v1, v35, v35
	global_load_dwordx4 v[42:45], v[42:43], off
	v_fmac_f32_e32 v1, v34, v34
	v_fmac_f32_e32 v1, v36, v36
	v_fmac_f32_e32 v1, v37, v37
	s_waitcnt vmcnt(2)
	global_store_dwordx4 v[58:59], v[22:25], off offset:1024 sc1
	s_waitcnt vmcnt(2)
	v_pk_mul_f32 v[40:41], v[24:25], v[40:41]
	v_pk_mul_f32 v[38:39], v[22:23], v[38:39]
	s_waitcnt vmcnt(1)
	v_pk_add_f32 v[42:43], v[42:43], 1.0 op_sel_hi:[1,0]
	v_pk_add_f32 v[44:45], v[44:45], 1.0 op_sel_hi:[1,0]
	v_pk_mul_f32 v[38:39], v[42:43], v[38:39]
	v_pk_mul_f32 v[40:41], v[44:45], v[40:41]
	v_cvt_pk_bf16_f32 v38, v38, v39
	v_cvt_pk_bf16_f32 v39, v40, v41
	global_store_dwordx2 v[62:63], v[38:39], off offset:512 sc1
	global_load_dwordx4 v[38:41], v[46:47], off offset:2048
	s_nop 0
	global_load_dwordx4 v[42:45], v12, s[4:5] offset:2048
	v_mul_f32_e32 v2, v23, v23
	global_load_dwordx4 v[50:53], v[50:51], off
	v_fmac_f32_e32 v2, v22, v22
	v_fmac_f32_e32 v2, v24, v24
	v_fmac_f32_e32 v2, v25, v25
	v_add_f32_e32 v1, v1, v2
	s_waitcnt vmcnt(2)
	global_store_dwordx4 v[58:59], v[38:41], off offset:2048 sc1
	s_waitcnt vmcnt(2)
	v_pk_mul_f32 v[44:45], v[40:41], v[44:45]
	v_pk_mul_f32 v[42:43], v[38:39], v[42:43]
	s_waitcnt vmcnt(1)
	v_pk_add_f32 v[50:51], v[50:51], 1.0 op_sel_hi:[1,0]
	v_pk_add_f32 v[52:53], v[52:53], 1.0 op_sel_hi:[1,0]
	v_pk_mul_f32 v[42:43], v[50:51], v[42:43]
	v_pk_mul_f32 v[44:45], v[52:53], v[44:45]
	v_cvt_pk_bf16_f32 v42, v42, v43
	v_cvt_pk_bf16_f32 v43, v44, v45
	global_store_dwordx2 v[62:63], v[42:43], off offset:1024 sc1
	global_load_dwordx4 v[42:45], v[46:47], off offset:3072
	s_nop 0
	global_load_dwordx4 v[50:53], v12, s[4:5] offset:3072
	v_lshl_add_u64 v[46:47], v[54:55], 0, v[18:19]
	global_load_dwordx4 v[54:57], v[46:47], off
	v_mul_f32_e32 v2, v39, v39
	v_fmac_f32_e32 v2, v38, v38
	v_fmac_f32_e32 v2, v40, v40
	v_fmac_f32_e32 v2, v41, v41
	v_add_f32_e32 v1, v1, v2
	s_waitcnt vmcnt(2)
	v_mul_f32_e32 v2, v43, v43
	v_fmac_f32_e32 v2, v42, v42
	v_fmac_f32_e32 v2, v44, v44
	v_fmac_f32_e32 v2, v45, v45
	v_add_f32_e32 v1, v1, v2
	s_nop 1
	v_mov_b32_dpp v2, v1 quad_perm:[1,0,3,2] row_mask:0xf bank_mask:0xf
	s_waitcnt vmcnt(1)
	v_pk_mul_f32 v[24:25], v[42:43], v[50:51]
	s_waitcnt vmcnt(0)
	v_pk_add_f32 v[34:35], v[54:55], 1.0 op_sel_hi:[1,0]
	v_pk_mul_f32 v[22:23], v[44:45], v[52:53]
	v_pk_mul_f32 v[24:25], v[34:35], v[24:25]
	s_waitcnt lgkmcnt(0)
	v_add_f32_e32 v1, v1, v2
	s_nop 1
	v_mov_b32_dpp v2, v1 quad_perm:[2,3,0,1] row_mask:0xf bank_mask:0xf
	v_pk_add_f32 v[34:35], v[56:57], 1.0 op_sel_hi:[1,0]
	v_cvt_pk_bf16_f32 v24, v24, v25
	v_pk_mul_f32 v[22:23], v[34:35], v[22:23]
	global_store_dwordx4 v[58:59], v[42:45], off offset:3072 sc1
	s_waitcnt lgkmcnt(0)
	v_add_f32_e32 v1, v1, v2
	s_nop 1
	v_mov_b32_dpp v2, v1 row_half_mirror row_mask:0xf bank_mask:0xf
	v_cvt_pk_bf16_f32 v25, v22, v23
	global_store_dwordx2 v[62:63], v[24:25], off offset:1536 sc1
	s_waitcnt lgkmcnt(0)
	v_add_f32_e32 v1, v1, v2
	s_nop 1
	v_mov_b32_dpp v2, v1 row_mirror row_mask:0xf bank_mask:0xf
	s_waitcnt lgkmcnt(0)
	v_add_f32_e32 v1, v1, v2
	v_mov_b32_e32 v2, v1
	s_nop 1
	v_permlane16_swap_b32_e32 v1, v2
	s_nop 0
	s_waitcnt lgkmcnt(0)
	v_add_f32_e32 v1, v1, v2
	ds_bpermute_b32 v2, v31, v1
	s_and_saveexec_b64 s[4:5], vcc
	s_cbranch_execz .LBB0_204
	v_add_u32_e32 v22, v32, v20
	v_ashrrev_i32_e32 v23, 31, v22
	s_waitcnt lgkmcnt(0)
	v_add_f32_e32 v1, v1, v2
	v_lshl_add_u64 v[22:23], v[22:23], 2, s[22:23]
	v_cndmask_b32_e64 v1, 0, v1, s[0:1]
	global_store_dword v[22:23], v1, off sc1
	s_branch .LBB0_204

.LBB0_214:
	v_lshl_add_u64 v[72:73], s[14:15], 0, v[54:55]
	s_waitcnt lgkmcnt(1)
	global_load_dwordx4 v[64:67], v[72:73], off
	s_waitcnt lgkmcnt(0)
	global_load_dwordx4 v[68:71], v[72:73], off offset:16
	s_waitcnt vmcnt(1)
	v_lshlrev_b32_e32 v63, 16, v64
	v_and_b32_e32 v64, 0xffff0000, v64
	v_lshlrev_b32_e32 v72, 16, v65
	v_and_b32_e32 v65, 0xffff0000, v65
	v_mul_f32_e32 v79, v9, v64
	v_mul_f32_e32 v80, v25, v64
	v_mul_f32_e32 v64, v41, v64
	v_lshlrev_b32_e32 v73, 16, v66
	v_and_b32_e32 v66, 0xffff0000, v66
	v_mul_f32_e32 v81, v11, v65
	v_mul_f32_e32 v82, v27, v65
	v_mul_f32_e32 v65, v43, v65
	v_fmac_f32_e32 v79, v8, v63
	v_fmac_f32_e32 v80, v24, v63
	v_fmac_f32_e32 v64, v40, v63
	v_lshlrev_b32_e32 v74, 16, v67
	v_and_b32_e32 v67, 0xffff0000, v67
	v_mul_f32_e32 v83, v1, v66
	v_mul_f32_e32 v84, v17, v66
	v_mul_f32_e32 v66, v33, v66
	v_fmac_f32_e32 v81, v10, v72
	v_fmac_f32_e32 v82, v26, v72
	v_fmac_f32_e32 v65, v42, v72
	v_add_f32_e32 v63, 0, v79
	v_add_f32_e32 v72, 0, v80
	v_add_f32_e32 v64, 0, v64
	s_waitcnt vmcnt(0)
	v_lshlrev_b32_e32 v75, 16, v68
	v_and_b32_e32 v68, 0xffff0000, v68
	v_mul_f32_e32 v85, v3, v67
	v_mul_f32_e32 v86, v19, v67
	v_mul_f32_e32 v67, v35, v67
	v_fmac_f32_e32 v83, v0, v73
	v_fmac_f32_e32 v84, v16, v73
	v_fmac_f32_e32 v66, v32, v73
	v_add_f32_e32 v63, v63, v81
	v_add_f32_e32 v72, v72, v82
	v_add_f32_e32 v64, v64, v65
	v_lshlrev_b32_e32 v76, 16, v69
	v_and_b32_e32 v69, 0xffff0000, v69
	v_mul_f32_e32 v87, v5, v68
	v_mul_f32_e32 v88, v21, v68
	v_mul_f32_e32 v68, v37, v68
	v_fmac_f32_e32 v85, v2, v74
	v_fmac_f32_e32 v86, v18, v74
	v_fmac_f32_e32 v67, v34, v74
	v_add_f32_e32 v63, v63, v83
	v_add_f32_e32 v65, v72, v84
	v_add_f32_e32 v64, v64, v66
	v_lshlrev_b32_e32 v77, 16, v70
	v_and_b32_e32 v70, 0xffff0000, v70
	v_mul_f32_e32 v89, v7, v69
	v_mul_f32_e32 v90, v23, v69
	v_mul_f32_e32 v69, v39, v69
	v_fmac_f32_e32 v87, v4, v75
	v_fmac_f32_e32 v88, v20, v75
	v_fmac_f32_e32 v68, v36, v75
	v_add_f32_e32 v63, v63, v85
	v_add_f32_e32 v65, v65, v86
	v_add_f32_e32 v64, v64, v67
	v_lshlrev_b32_e32 v78, 16, v71
	v_and_b32_e32 v71, 0xffff0000, v71
	v_mul_f32_e32 v91, v13, v70
	v_mul_f32_e32 v92, v29, v70
	v_mul_f32_e32 v70, v45, v70
	v_fmac_f32_e32 v89, v6, v76
	v_fmac_f32_e32 v90, v22, v76
	v_fmac_f32_e32 v69, v38, v76
	v_add_f32_e32 v63, v63, v87
	v_add_f32_e32 v65, v65, v88
	v_add_f32_e32 v64, v64, v68
	v_mul_f32_e32 v93, v15, v71
	v_mul_f32_e32 v94, v31, v71
	v_mul_f32_e32 v71, v47, v71
	v_fmac_f32_e32 v91, v12, v77
	v_fmac_f32_e32 v92, v28, v77
	v_fmac_f32_e32 v70, v44, v77
	v_add_f32_e32 v63, v63, v89
	v_add_f32_e32 v65, v65, v90
	v_add_f32_e32 v64, v64, v69
	v_fmac_f32_e32 v93, v14, v78
	v_fmac_f32_e32 v94, v30, v78
	v_fmac_f32_e32 v71, v46, v78
	v_add_f32_e32 v63, v63, v91
	v_add_f32_e32 v65, v65, v92
	v_add_f32_e32 v64, v64, v70
	v_add_f32_e32 v63, v63, v93
	v_add_f32_e32 v65, v65, v94
	v_add_f32_e32 v64, v64, v71
	s_nop 1
	v_mov_b32_dpp v66, v63 quad_perm:[1,0,3,2] row_mask:0xf bank_mask:0xf
	s_nop 1
	v_mov_b32_dpp v67, v65 quad_perm:[1,0,3,2] row_mask:0xf bank_mask:0xf
	s_nop 1
	v_mov_b32_dpp v68, v64 quad_perm:[1,0,3,2] row_mask:0xf bank_mask:0xf
	s_waitcnt lgkmcnt(0)
	v_add_f32_e32 v63, v63, v66
	s_waitcnt lgkmcnt(0)
	v_add_f32_e32 v65, v65, v67
	s_waitcnt lgkmcnt(0)
	v_add_f32_e32 v64, v64, v68
	s_nop 1
	v_mov_b32_dpp v66, v63 quad_perm:[2,3,0,1] row_mask:0xf bank_mask:0xf
	s_nop 1
	v_mov_b32_dpp v67, v65 quad_perm:[2,3,0,1] row_mask:0xf bank_mask:0xf
	s_nop 1
	v_mov_b32_dpp v68, v64 quad_perm:[2,3,0,1] row_mask:0xf bank_mask:0xf
	s_waitcnt lgkmcnt(0)
	v_add_f32_e32 v63, v63, v66
	s_waitcnt lgkmcnt(0)
	v_add_f32_e32 v65, v65, v67
	s_waitcnt lgkmcnt(0)
	v_add_f32_e32 v64, v64, v68
	s_nop 1
	v_mov_b32_dpp v66, v63 row_half_mirror row_mask:0xf bank_mask:0xf
	s_nop 1
	v_mov_b32_dpp v67, v65 row_half_mirror row_mask:0xf bank_mask:0xf
	s_nop 1
	v_mov_b32_dpp v68, v64 row_half_mirror row_mask:0xf bank_mask:0xf
	s_waitcnt lgkmcnt(0)
	v_add_f32_e32 v63, v63, v66
	s_waitcnt lgkmcnt(0)
	v_add_f32_e32 v65, v65, v67
	s_waitcnt lgkmcnt(0)
	v_add_f32_e32 v64, v64, v68
	s_nop 1
	v_mov_b32_dpp v66, v63 row_mirror row_mask:0xf bank_mask:0xf
	s_nop 1
	v_mov_b32_dpp v67, v65 row_mirror row_mask:0xf bank_mask:0xf
	s_nop 1
	v_mov_b32_dpp v68, v64 row_mirror row_mask:0xf bank_mask:0xf
	s_waitcnt lgkmcnt(0)
	v_add_f32_e32 v63, v63, v66
	s_waitcnt lgkmcnt(0)
	v_add_f32_e32 v65, v65, v67
	s_waitcnt lgkmcnt(0)
	v_add_f32_e32 v66, v64, v68
	v_mov_b32_e32 v64, v63
	s_nop 1
	v_permlane16_swap_b32_e32 v63, v64
	s_nop 0
	v_mov_b32_e32 v67, v65
	s_nop 1
	v_permlane16_swap_b32_e32 v65, v67
	s_nop 0
	v_mov_b32_e32 v68, v66
	s_nop 1
	v_permlane16_swap_b32_e32 v66, v68
	s_nop 0
	s_waitcnt lgkmcnt(0)
	v_add_f32_e32 v63, v63, v64
	s_waitcnt lgkmcnt(0)
	v_add_f32_e32 v64, v65, v67
	s_waitcnt lgkmcnt(0)
	v_add_f32_e32 v66, v66, v68
	ds_bpermute_b32 v65, v61, v63
	ds_bpermute_b32 v67, v61, v64
	ds_bpermute_b32 v68, v61, v66
	s_and_saveexec_b64 s[24:25], s[0:1]
	s_cbranch_execz .LBB0_213
	s_waitcnt lgkmcnt(1)
	v_add_f32_e32 v69, v64, v67
	v_add_f32_e32 v63, v63, v65
	v_lshl_add_u64 v[64:65], s[14:15], 0, v[52:53]
	s_waitcnt lgkmcnt(0)
	v_add_f32_e32 v68, v66, v68
	v_add_co_u32_e32 v66, vcc, 0x5be8000, v64
	s_nop 1
	v_addc_co_u32_e32 v67, vcc, 0, v65, vcc
	global_store_dword v[66:67], v63, off sc1
	v_add_co_u32_e32 v66, vcc, 0x5beb000, v64
	s_nop 1
	v_addc_co_u32_e32 v67, vcc, 0, v65, vcc
	v_add_co_u32_e32 v64, vcc, 0x5bee000, v64
	global_store_dword v[66:67], v69, off sc1
	s_nop 0
	v_addc_co_u32_e32 v65, vcc, 0, v65, vcc
	global_store_dword v[64:65], v68, off sc1
	s_branch .LBB0_213

.LBB0_219:
	s_waitcnt lgkmcnt(0)
	v_lshl_add_u64 v[68:69], s[14:15], 0, v[54:55]
	v_add_co_u32_e32 v64, vcc, 0x5a0000, v68
	s_nop 1
	v_addc_co_u32_e32 v65, vcc, 0, v69, vcc
	global_load_dwordx4 v[64:67], v[64:65], off
	v_lshl_add_u64 v[68:69], v[68:69], 0, s[24:25]
	global_load_dwordx4 v[68:71], v[68:69], off offset:16
	s_waitcnt vmcnt(1)
	v_lshlrev_b32_e32 v63, 16, v64
	v_and_b32_e32 v64, 0xffff0000, v64
	v_lshlrev_b32_e32 v72, 16, v65
	v_and_b32_e32 v65, 0xffff0000, v65
	v_mul_f32_e32 v79, v9, v64
	v_mul_f32_e32 v80, v25, v64
	v_mul_f32_e32 v64, v41, v64
	v_lshlrev_b32_e32 v73, 16, v66
	v_and_b32_e32 v66, 0xffff0000, v66
	v_mul_f32_e32 v81, v11, v65
	v_mul_f32_e32 v82, v27, v65
	v_mul_f32_e32 v65, v43, v65
	v_fmac_f32_e32 v79, v8, v63
	v_fmac_f32_e32 v80, v24, v63
	v_fmac_f32_e32 v64, v40, v63
	v_lshlrev_b32_e32 v74, 16, v67
	v_and_b32_e32 v67, 0xffff0000, v67
	v_mul_f32_e32 v83, v1, v66
	v_mul_f32_e32 v84, v17, v66
	v_mul_f32_e32 v66, v33, v66
	v_fmac_f32_e32 v81, v10, v72
	v_fmac_f32_e32 v82, v26, v72
	v_fmac_f32_e32 v65, v42, v72
	v_add_f32_e32 v63, 0, v79
	v_add_f32_e32 v72, 0, v80
	v_add_f32_e32 v64, 0, v64
	s_waitcnt vmcnt(0)
	v_lshlrev_b32_e32 v75, 16, v68
	v_and_b32_e32 v68, 0xffff0000, v68
	v_mul_f32_e32 v85, v3, v67
	v_mul_f32_e32 v86, v19, v67
	v_mul_f32_e32 v67, v35, v67
	v_fmac_f32_e32 v83, v0, v73
	v_fmac_f32_e32 v84, v16, v73
	v_fmac_f32_e32 v66, v32, v73
	v_add_f32_e32 v63, v63, v81
	v_add_f32_e32 v72, v72, v82
	v_add_f32_e32 v64, v64, v65
	v_lshlrev_b32_e32 v76, 16, v69
	v_and_b32_e32 v69, 0xffff0000, v69
	v_mul_f32_e32 v87, v5, v68
	v_mul_f32_e32 v88, v21, v68
	v_mul_f32_e32 v68, v37, v68
	v_fmac_f32_e32 v85, v2, v74
	v_fmac_f32_e32 v86, v18, v74
	v_fmac_f32_e32 v67, v34, v74
	v_add_f32_e32 v63, v63, v83
	v_add_f32_e32 v65, v72, v84
	v_add_f32_e32 v64, v64, v66
	v_lshlrev_b32_e32 v77, 16, v70
	v_and_b32_e32 v70, 0xffff0000, v70
	v_mul_f32_e32 v89, v7, v69
	v_mul_f32_e32 v90, v23, v69
	v_mul_f32_e32 v69, v39, v69
	v_fmac_f32_e32 v87, v4, v75
	v_fmac_f32_e32 v88, v20, v75
	v_fmac_f32_e32 v68, v36, v75
	v_add_f32_e32 v63, v63, v85
	v_add_f32_e32 v65, v65, v86
	v_add_f32_e32 v64, v64, v67
	v_lshlrev_b32_e32 v78, 16, v71
	v_and_b32_e32 v71, 0xffff0000, v71
	v_mul_f32_e32 v91, v13, v70
	v_mul_f32_e32 v92, v29, v70
	v_mul_f32_e32 v70, v45, v70
	v_fmac_f32_e32 v89, v6, v76
	v_fmac_f32_e32 v90, v22, v76
	v_fmac_f32_e32 v69, v38, v76
	v_add_f32_e32 v63, v63, v87
	v_add_f32_e32 v65, v65, v88
	v_add_f32_e32 v64, v64, v68
	v_mul_f32_e32 v93, v15, v71
	v_mul_f32_e32 v94, v31, v71
	v_fmac_f32_e32 v91, v12, v77
	v_fmac_f32_e32 v92, v28, v77
	v_fmac_f32_e32 v70, v44, v77
	v_add_f32_e32 v63, v63, v89
	v_add_f32_e32 v65, v65, v90
	v_add_f32_e32 v64, v64, v69
	v_mul_f32_e32 v66, v47, v71
	v_fmac_f32_e32 v93, v14, v78
	v_fmac_f32_e32 v94, v30, v78
	v_add_f32_e32 v63, v63, v91
	v_add_f32_e32 v65, v65, v92
	v_add_f32_e32 v64, v64, v70
	v_fmac_f32_e32 v66, v46, v78
	v_add_f32_e32 v63, v63, v93
	v_add_f32_e32 v65, v65, v94
	v_add_f32_e32 v64, v64, v66
	s_nop 1
	v_mov_b32_dpp v67, v63 quad_perm:[1,0,3,2] row_mask:0xf bank_mask:0xf
	s_nop 1
	v_mov_b32_dpp v68, v65 quad_perm:[1,0,3,2] row_mask:0xf bank_mask:0xf
	s_nop 1
	v_mov_b32_dpp v66, v64 quad_perm:[1,0,3,2] row_mask:0xf bank_mask:0xf
	s_waitcnt lgkmcnt(0)
	v_add_f32_e32 v63, v63, v67
	s_waitcnt lgkmcnt(0)
	v_add_f32_e32 v65, v65, v68
	s_waitcnt lgkmcnt(0)
	v_add_f32_e32 v64, v64, v66
	s_nop 1
	v_mov_b32_dpp v67, v63 quad_perm:[2,3,0,1] row_mask:0xf bank_mask:0xf
	s_nop 1
	v_mov_b32_dpp v68, v65 quad_perm:[2,3,0,1] row_mask:0xf bank_mask:0xf
	s_nop 1
	v_mov_b32_dpp v66, v64 quad_perm:[2,3,0,1] row_mask:0xf bank_mask:0xf
	s_waitcnt lgkmcnt(0)
	v_add_f32_e32 v63, v63, v67
	s_waitcnt lgkmcnt(0)
	v_add_f32_e32 v65, v65, v68
	s_waitcnt lgkmcnt(0)
	v_add_f32_e32 v64, v64, v66
	s_nop 1
	v_mov_b32_dpp v67, v63 row_half_mirror row_mask:0xf bank_mask:0xf
	s_nop 1
	v_mov_b32_dpp v68, v65 row_half_mirror row_mask:0xf bank_mask:0xf
	s_nop 1
	v_mov_b32_dpp v66, v64 row_half_mirror row_mask:0xf bank_mask:0xf
	s_waitcnt lgkmcnt(0)
	v_add_f32_e32 v63, v63, v67
	s_waitcnt lgkmcnt(0)
	v_add_f32_e32 v65, v65, v68
	s_waitcnt lgkmcnt(0)
	v_add_f32_e32 v64, v64, v66
	s_nop 1
	v_mov_b32_dpp v67, v63 row_mirror row_mask:0xf bank_mask:0xf
	s_nop 1
	v_mov_b32_dpp v68, v65 row_mirror row_mask:0xf bank_mask:0xf
	s_nop 1
	v_mov_b32_dpp v66, v64 row_mirror row_mask:0xf bank_mask:0xf
	s_waitcnt lgkmcnt(0)
	v_add_f32_e32 v63, v63, v67
	s_waitcnt lgkmcnt(0)
	v_add_f32_e32 v65, v65, v68
	s_waitcnt lgkmcnt(0)
	v_add_f32_e32 v69, v64, v66
	v_mov_b32_e32 v67, v63
	s_nop 1
	v_permlane16_swap_b32_e32 v63, v67
	s_nop 0
	v_mov_b32_e32 v68, v65
	s_nop 1
	v_permlane16_swap_b32_e32 v65, v68
	s_nop 0
	ds_bpermute_b32 v70, v59, v69
	s_waitcnt lgkmcnt(1)
	v_add_f32_e32 v63, v63, v67
	s_waitcnt lgkmcnt(1)
	v_add_f32_e32 v65, v65, v68
	s_waitcnt lgkmcnt(0)
	v_add_f32_e32 v67, v69, v70
	ds_bpermute_b32 v64, v61, v63
	ds_bpermute_b32 v66, v61, v65
	ds_bpermute_b32 v68, v61, v67
	s_and_saveexec_b64 s[26:27], s[0:1]
	s_cbranch_execz .LBB0_218
	s_waitcnt lgkmcnt(1)
	v_add_f32_e32 v69, v65, v66
	v_add_f32_e32 v63, v63, v64
	v_lshl_add_u64 v[64:65], s[14:15], 0, v[52:53]
	v_add_co_u32_e32 v66, vcc, 0x5bf1000, v64
	s_waitcnt lgkmcnt(0)
	v_add_f32_e32 v68, v67, v68
	v_addc_co_u32_e32 v67, vcc, 0, v65, vcc
	global_store_dword v[66:67], v63, off sc1
	v_add_co_u32_e32 v66, vcc, 0x5bf4000, v64
	s_nop 1
	v_addc_co_u32_e32 v67, vcc, 0, v65, vcc
	v_add_co_u32_e32 v64, vcc, 0x5bf7000, v64
	global_store_dword v[66:67], v69, off sc1
	s_nop 0
	v_addc_co_u32_e32 v65, vcc, 0, v65, vcc
	global_store_dword v[64:65], v68, off sc1
	s_branch .LBB0_218

.LBB0_224:
	s_waitcnt lgkmcnt(0)
	v_lshl_add_u64 v[68:69], s[14:15], 0, v[54:55]
	v_add_co_u32_e32 v64, vcc, 0xda0000, v68
	s_nop 1
	v_addc_co_u32_e32 v65, vcc, 0, v69, vcc
	global_load_dwordx4 v[64:67], v[64:65], off
	v_lshl_add_u64 v[68:69], v[68:69], 0, s[24:25]
	global_load_dwordx4 v[68:71], v[68:69], off offset:16
	s_waitcnt vmcnt(1)
	v_lshlrev_b32_e32 v63, 16, v64
	v_and_b32_e32 v64, 0xffff0000, v64
	v_lshlrev_b32_e32 v72, 16, v65
	v_and_b32_e32 v65, 0xffff0000, v65
	v_mul_f32_e32 v79, v9, v64
	v_mul_f32_e32 v80, v25, v64
	v_mul_f32_e32 v64, v41, v64
	v_lshlrev_b32_e32 v73, 16, v66
	v_and_b32_e32 v66, 0xffff0000, v66
	v_mul_f32_e32 v81, v11, v65
	v_mul_f32_e32 v82, v27, v65
	v_mul_f32_e32 v65, v43, v65
	v_fmac_f32_e32 v79, v8, v63
	v_fmac_f32_e32 v80, v24, v63
	v_fmac_f32_e32 v64, v40, v63
	v_lshlrev_b32_e32 v74, 16, v67
	v_and_b32_e32 v67, 0xffff0000, v67
	v_mul_f32_e32 v83, v1, v66
	v_mul_f32_e32 v84, v17, v66
	v_mul_f32_e32 v66, v33, v66
	v_fmac_f32_e32 v81, v10, v72
	v_fmac_f32_e32 v82, v26, v72
	v_fmac_f32_e32 v65, v42, v72
	v_add_f32_e32 v63, 0, v79
	v_add_f32_e32 v72, 0, v80
	v_add_f32_e32 v64, 0, v64
	s_waitcnt vmcnt(0)
	v_lshlrev_b32_e32 v75, 16, v68
	v_and_b32_e32 v68, 0xffff0000, v68
	v_mul_f32_e32 v85, v3, v67
	v_mul_f32_e32 v86, v19, v67
	v_mul_f32_e32 v67, v35, v67
	v_fmac_f32_e32 v83, v0, v73
	v_fmac_f32_e32 v84, v16, v73
	v_fmac_f32_e32 v66, v32, v73
	v_add_f32_e32 v63, v63, v81
	v_add_f32_e32 v72, v72, v82
	v_add_f32_e32 v64, v64, v65
	v_lshlrev_b32_e32 v76, 16, v69
	v_and_b32_e32 v69, 0xffff0000, v69
	v_mul_f32_e32 v87, v5, v68
	v_mul_f32_e32 v88, v21, v68
	v_mul_f32_e32 v68, v37, v68
	v_fmac_f32_e32 v85, v2, v74
	v_fmac_f32_e32 v86, v18, v74
	v_fmac_f32_e32 v67, v34, v74
	v_add_f32_e32 v63, v63, v83
	v_add_f32_e32 v65, v72, v84
	v_add_f32_e32 v64, v64, v66
	v_lshlrev_b32_e32 v77, 16, v70
	v_and_b32_e32 v70, 0xffff0000, v70
	v_mul_f32_e32 v89, v7, v69
	v_mul_f32_e32 v90, v23, v69
	v_mul_f32_e32 v69, v39, v69
	v_fmac_f32_e32 v87, v4, v75
	v_fmac_f32_e32 v88, v20, v75
	v_fmac_f32_e32 v68, v36, v75
	v_add_f32_e32 v63, v63, v85
	v_add_f32_e32 v65, v65, v86
	v_add_f32_e32 v64, v64, v67
	v_lshlrev_b32_e32 v78, 16, v71
	v_and_b32_e32 v71, 0xffff0000, v71
	v_mul_f32_e32 v91, v13, v70
	v_mul_f32_e32 v92, v29, v70
	v_mul_f32_e32 v70, v45, v70
	v_fmac_f32_e32 v89, v6, v76
	v_fmac_f32_e32 v90, v22, v76
	v_fmac_f32_e32 v69, v38, v76
	v_add_f32_e32 v63, v63, v87
	v_add_f32_e32 v65, v65, v88
	v_add_f32_e32 v64, v64, v68
	v_mul_f32_e32 v93, v15, v71
	v_mul_f32_e32 v94, v31, v71
	v_fmac_f32_e32 v91, v12, v77
	v_fmac_f32_e32 v92, v28, v77
	v_fmac_f32_e32 v70, v44, v77
	v_add_f32_e32 v63, v63, v89
	v_add_f32_e32 v65, v65, v90
	v_add_f32_e32 v64, v64, v69
	v_mul_f32_e32 v66, v47, v71
	v_fmac_f32_e32 v93, v14, v78
	v_fmac_f32_e32 v94, v30, v78
	v_add_f32_e32 v63, v63, v91
	v_add_f32_e32 v65, v65, v92
	v_add_f32_e32 v64, v64, v70
	v_fmac_f32_e32 v66, v46, v78
	v_add_f32_e32 v63, v63, v93
	v_add_f32_e32 v65, v65, v94
	v_add_f32_e32 v64, v64, v66
	s_nop 1
	v_mov_b32_dpp v67, v63 quad_perm:[1,0,3,2] row_mask:0xf bank_mask:0xf
	s_nop 1
	v_mov_b32_dpp v68, v65 quad_perm:[1,0,3,2] row_mask:0xf bank_mask:0xf
	s_nop 1
	v_mov_b32_dpp v66, v64 quad_perm:[1,0,3,2] row_mask:0xf bank_mask:0xf
	s_waitcnt lgkmcnt(0)
	v_add_f32_e32 v63, v63, v67
	s_waitcnt lgkmcnt(0)
	v_add_f32_e32 v65, v65, v68
	s_waitcnt lgkmcnt(0)
	v_add_f32_e32 v64, v64, v66
	s_nop 1
	v_mov_b32_dpp v67, v63 quad_perm:[2,3,0,1] row_mask:0xf bank_mask:0xf
	s_nop 1
	v_mov_b32_dpp v68, v65 quad_perm:[2,3,0,1] row_mask:0xf bank_mask:0xf
	s_nop 1
	v_mov_b32_dpp v66, v64 quad_perm:[2,3,0,1] row_mask:0xf bank_mask:0xf
	s_waitcnt lgkmcnt(0)
	v_add_f32_e32 v63, v63, v67
	s_waitcnt lgkmcnt(0)
	v_add_f32_e32 v65, v65, v68
	s_waitcnt lgkmcnt(0)
	v_add_f32_e32 v64, v64, v66
	s_nop 1
	v_mov_b32_dpp v67, v63 row_half_mirror row_mask:0xf bank_mask:0xf
	s_nop 1
	v_mov_b32_dpp v68, v65 row_half_mirror row_mask:0xf bank_mask:0xf
	s_nop 1
	v_mov_b32_dpp v66, v64 row_half_mirror row_mask:0xf bank_mask:0xf
	s_waitcnt lgkmcnt(0)
	v_add_f32_e32 v63, v63, v67
	s_waitcnt lgkmcnt(0)
	v_add_f32_e32 v65, v65, v68
	s_waitcnt lgkmcnt(0)
	v_add_f32_e32 v64, v64, v66
	s_nop 1
	v_mov_b32_dpp v67, v63 row_mirror row_mask:0xf bank_mask:0xf
	s_nop 1
	v_mov_b32_dpp v68, v65 row_mirror row_mask:0xf bank_mask:0xf
	s_nop 1
	v_mov_b32_dpp v66, v64 row_mirror row_mask:0xf bank_mask:0xf
	s_waitcnt lgkmcnt(0)
	v_add_f32_e32 v63, v63, v67
	s_waitcnt lgkmcnt(0)
	v_add_f32_e32 v65, v65, v68
	s_waitcnt lgkmcnt(0)
	v_add_f32_e32 v69, v64, v66
	v_mov_b32_e32 v67, v63
	s_nop 1
	v_permlane16_swap_b32_e32 v63, v67
	s_nop 0
	v_mov_b32_e32 v68, v65
	s_nop 1
	v_permlane16_swap_b32_e32 v65, v68
	s_nop 0
	ds_bpermute_b32 v70, v59, v69
	s_waitcnt lgkmcnt(1)
	v_add_f32_e32 v63, v63, v67
	s_waitcnt lgkmcnt(1)
	v_add_f32_e32 v65, v65, v68
	s_waitcnt lgkmcnt(0)
	v_add_f32_e32 v67, v69, v70
	ds_bpermute_b32 v64, v61, v63
	ds_bpermute_b32 v66, v61, v65
	ds_bpermute_b32 v68, v61, v67
	s_and_saveexec_b64 s[26:27], s[0:1]
	s_cbranch_execz .LBB0_223
	s_waitcnt lgkmcnt(1)
	v_add_f32_e32 v69, v65, v66
	v_add_f32_e32 v63, v63, v64
	v_lshl_add_u64 v[64:65], s[14:15], 0, v[52:53]
	v_add_co_u32_e32 v66, vcc, 0x5bfa000, v64
	s_waitcnt lgkmcnt(0)
	v_add_f32_e32 v68, v67, v68
	v_addc_co_u32_e32 v67, vcc, 0, v65, vcc
	global_store_dword v[66:67], v63, off sc1
	v_add_co_u32_e32 v66, vcc, 0x5bfd000, v64
	s_nop 1
	v_addc_co_u32_e32 v67, vcc, 0, v65, vcc
	v_add_co_u32_e32 v64, vcc, 0x5c00000, v64
	global_store_dword v[66:67], v69, off sc1
	s_nop 0
	v_addc_co_u32_e32 v65, vcc, 0, v65, vcc
	global_store_dword v[64:65], v68, off sc1
	s_branch .LBB0_223

.LBB0_231:
	s_waitcnt lgkmcnt(0)
	v_lshl_add_u64 v[70:71], s[14:15], 0, v[52:53]
	v_add_co_u32_e32 v66, vcc, 0x12a0000, v70
	s_nop 1
	v_addc_co_u32_e32 v67, vcc, 0, v71, vcc
	global_load_dwordx4 v[66:69], v[66:67], off
	v_lshl_add_u64 v[70:71], v[70:71], 0, s[24:25]
	global_load_dwordx4 v[70:73], v[70:71], off offset:16
	s_waitcnt vmcnt(1)
	v_lshlrev_b32_e32 v74, 16, v66
	v_and_b32_e32 v66, 0xffff0000, v66
	v_lshlrev_b32_e32 v75, 16, v67
	v_and_b32_e32 v67, 0xffff0000, v67
	v_mul_f32_e32 v82, v9, v66
	v_mul_f32_e32 v83, v25, v66
	v_mul_f32_e32 v66, v41, v66
	v_lshlrev_b32_e32 v76, 16, v68
	v_and_b32_e32 v68, 0xffff0000, v68
	v_mul_f32_e32 v84, v11, v67
	v_mul_f32_e32 v85, v27, v67
	v_mul_f32_e32 v67, v43, v67
	v_fmac_f32_e32 v82, v8, v74
	v_fmac_f32_e32 v83, v24, v74
	v_fmac_f32_e32 v66, v40, v74
	v_lshlrev_b32_e32 v77, 16, v69
	v_and_b32_e32 v69, 0xffff0000, v69
	v_mul_f32_e32 v86, v1, v68
	v_mul_f32_e32 v87, v17, v68
	v_mul_f32_e32 v68, v33, v68
	v_fmac_f32_e32 v84, v10, v75
	v_fmac_f32_e32 v85, v26, v75
	v_fmac_f32_e32 v67, v42, v75
	v_add_f32_e32 v74, 0, v82
	v_add_f32_e32 v75, 0, v83
	v_add_f32_e32 v66, 0, v66
	s_waitcnt vmcnt(0)
	v_lshlrev_b32_e32 v78, 16, v70
	v_and_b32_e32 v70, 0xffff0000, v70
	v_mul_f32_e32 v88, v3, v69
	v_mul_f32_e32 v89, v19, v69
	v_mul_f32_e32 v69, v35, v69
	v_fmac_f32_e32 v86, v0, v76
	v_fmac_f32_e32 v87, v16, v76
	v_fmac_f32_e32 v68, v32, v76
	v_add_f32_e32 v74, v74, v84
	v_add_f32_e32 v75, v75, v85
	v_add_f32_e32 v66, v66, v67
	v_lshlrev_b32_e32 v79, 16, v71
	v_and_b32_e32 v71, 0xffff0000, v71
	v_mul_f32_e32 v90, v5, v70
	v_mul_f32_e32 v91, v21, v70
	v_mul_f32_e32 v70, v37, v70
	v_fmac_f32_e32 v88, v2, v77
	v_fmac_f32_e32 v89, v18, v77
	v_fmac_f32_e32 v69, v34, v77
	v_add_f32_e32 v67, v74, v86
	v_add_f32_e32 v74, v75, v87
	v_add_f32_e32 v66, v66, v68
	v_lshlrev_b32_e32 v80, 16, v72
	v_and_b32_e32 v72, 0xffff0000, v72
	v_mul_f32_e32 v92, v7, v71
	v_mul_f32_e32 v93, v23, v71
	v_mul_f32_e32 v71, v39, v71
	v_fmac_f32_e32 v90, v4, v78
	v_fmac_f32_e32 v91, v20, v78
	v_fmac_f32_e32 v70, v36, v78
	v_add_f32_e32 v67, v67, v88
	v_add_f32_e32 v68, v74, v89
	v_add_f32_e32 v66, v66, v69
	v_lshlrev_b32_e32 v81, 16, v73
	v_and_b32_e32 v73, 0xffff0000, v73
	v_mul_f32_e32 v94, v13, v72
	v_mul_f32_e32 v95, v29, v72
	v_mul_f32_e32 v72, v45, v72
	v_fmac_f32_e32 v92, v6, v79
	v_fmac_f32_e32 v93, v22, v79
	v_fmac_f32_e32 v71, v38, v79
	v_add_f32_e32 v67, v67, v90
	v_add_f32_e32 v68, v68, v91
	v_add_f32_e32 v66, v66, v70
	v_mul_f32_e32 v96, v15, v73
	v_mul_f32_e32 v97, v31, v73
	v_fmac_f32_e32 v94, v12, v80
	v_fmac_f32_e32 v95, v28, v80
	v_fmac_f32_e32 v72, v44, v80
	v_add_f32_e32 v67, v67, v92
	v_add_f32_e32 v68, v68, v93
	v_add_f32_e32 v66, v66, v71
	v_mul_f32_e32 v69, v47, v73
	v_fmac_f32_e32 v96, v14, v81
	v_fmac_f32_e32 v97, v30, v81
	v_add_f32_e32 v67, v67, v94
	v_add_f32_e32 v68, v68, v95
	v_add_f32_e32 v66, v66, v72
	v_fmac_f32_e32 v69, v46, v81
	v_add_f32_e32 v67, v67, v96
	v_add_f32_e32 v68, v68, v97
	v_add_f32_e32 v66, v66, v69
	s_nop 1
	v_mov_b32_dpp v70, v67 quad_perm:[1,0,3,2] row_mask:0xf bank_mask:0xf
	s_nop 1
	v_mov_b32_dpp v71, v68 quad_perm:[1,0,3,2] row_mask:0xf bank_mask:0xf
	s_nop 1
	v_mov_b32_dpp v69, v66 quad_perm:[1,0,3,2] row_mask:0xf bank_mask:0xf
	s_waitcnt lgkmcnt(0)
	v_add_f32_e32 v67, v67, v70
	s_waitcnt lgkmcnt(0)
	v_add_f32_e32 v68, v68, v71
	s_waitcnt lgkmcnt(0)
	v_add_f32_e32 v66, v66, v69
	s_nop 1
	v_mov_b32_dpp v70, v67 quad_perm:[2,3,0,1] row_mask:0xf bank_mask:0xf
	s_nop 1
	v_mov_b32_dpp v71, v68 quad_perm:[2,3,0,1] row_mask:0xf bank_mask:0xf
	s_nop 1
	v_mov_b32_dpp v69, v66 quad_perm:[2,3,0,1] row_mask:0xf bank_mask:0xf
	s_waitcnt lgkmcnt(0)
	v_add_f32_e32 v67, v67, v70
	s_waitcnt lgkmcnt(0)
	v_add_f32_e32 v68, v68, v71
	s_waitcnt lgkmcnt(0)
	v_add_f32_e32 v66, v66, v69
	s_nop 1
	v_mov_b32_dpp v70, v67 row_half_mirror row_mask:0xf bank_mask:0xf
	s_nop 1
	v_mov_b32_dpp v71, v68 row_half_mirror row_mask:0xf bank_mask:0xf
	s_nop 1
	v_mov_b32_dpp v69, v66 row_half_mirror row_mask:0xf bank_mask:0xf
	s_waitcnt lgkmcnt(0)
	v_add_f32_e32 v67, v67, v70
	s_waitcnt lgkmcnt(0)
	v_add_f32_e32 v68, v68, v71
	s_waitcnt lgkmcnt(0)
	v_add_f32_e32 v66, v66, v69
	s_nop 1
	v_mov_b32_dpp v70, v67 row_mirror row_mask:0xf bank_mask:0xf
	s_nop 1
	v_mov_b32_dpp v71, v68 row_mirror row_mask:0xf bank_mask:0xf
	s_nop 1
	v_mov_b32_dpp v69, v66 row_mirror row_mask:0xf bank_mask:0xf
	s_waitcnt lgkmcnt(0)
	v_add_f32_e32 v67, v67, v70
	s_waitcnt lgkmcnt(0)
	v_add_f32_e32 v68, v68, v71
	s_waitcnt lgkmcnt(0)
	v_add_f32_e32 v72, v66, v69
	v_mov_b32_e32 v70, v67
	s_nop 1
	v_permlane16_swap_b32_e32 v67, v70
	s_nop 0
	v_mov_b32_e32 v71, v68
	s_nop 1
	v_permlane16_swap_b32_e32 v68, v71
	s_nop 0
	ds_bpermute_b32 v73, v64, v72
	s_waitcnt lgkmcnt(1)
	v_add_f32_e32 v66, v67, v70
	s_waitcnt lgkmcnt(1)
	v_add_f32_e32 v68, v68, v71
	s_waitcnt lgkmcnt(0)
	v_add_f32_e32 v70, v72, v73
	ds_bpermute_b32 v67, v65, v66
	ds_bpermute_b32 v69, v65, v68
	ds_bpermute_b32 v71, v65, v70
	s_and_saveexec_b64 s[26:27], s[0:1]
	s_cbranch_execz .LBB0_230
	s_waitcnt lgkmcnt(2)
	v_add_f32_e32 v72, v66, v67
	v_lshl_add_u64 v[66:67], s[14:15], 0, v[54:55]
	s_waitcnt lgkmcnt(0)
	v_add_f32_e32 v70, v70, v71
	v_add_f32_e32 v71, v68, v69
	v_add_co_u32_e32 v68, vcc, 0x5c03000, v66
	s_nop 1
	v_addc_co_u32_e32 v69, vcc, 0, v67, vcc
	global_store_dword v[68:69], v72, off sc1
	v_add_co_u32_e32 v68, vcc, 0x5c06000, v66
	s_nop 1
	v_addc_co_u32_e32 v69, vcc, 0, v67, vcc
	v_add_co_u32_e32 v66, vcc, 0x5c09000, v66
	global_store_dword v[68:69], v71, off sc1
	s_nop 0
	v_addc_co_u32_e32 v67, vcc, 0, v67, vcc
	global_store_dword v[66:67], v70, off sc1
	s_branch .LBB0_230

.LBB0_239:
	s_waitcnt lgkmcnt(2)
	global_load_dwordx4 v[78:81], v[60:61], off offset:-16
	s_waitcnt lgkmcnt(0)
	global_load_dwordx4 v[82:85], v[60:61], off
	s_waitcnt vmcnt(1)
	v_lshlrev_b32_e32 v86, 16, v78
	v_and_b32_e32 v78, 0xffff0000, v78
	v_lshlrev_b32_e32 v87, 16, v79
	v_and_b32_e32 v79, 0xffff0000, v79
	v_mul_f32_e32 v94, v9, v78
	v_mul_f32_e32 v95, v25, v78
	v_mul_f32_e32 v78, v41, v78
	v_lshlrev_b32_e32 v88, 16, v80
	v_and_b32_e32 v80, 0xffff0000, v80
	v_mul_f32_e32 v96, v11, v79
	v_mul_f32_e32 v97, v27, v79
	v_mul_f32_e32 v79, v43, v79
	v_fmac_f32_e32 v94, v8, v86
	v_fmac_f32_e32 v95, v24, v86
	v_fmac_f32_e32 v78, v40, v86
	v_lshlrev_b32_e32 v89, 16, v81
	v_and_b32_e32 v81, 0xffff0000, v81
	v_mul_f32_e32 v98, v1, v80
	v_mul_f32_e32 v99, v17, v80
	v_mul_f32_e32 v80, v33, v80
	v_fmac_f32_e32 v96, v10, v87
	v_fmac_f32_e32 v97, v26, v87
	v_fmac_f32_e32 v79, v42, v87
	v_add_f32_e32 v86, 0, v94
	v_add_f32_e32 v87, 0, v95
	v_add_f32_e32 v78, 0, v78
	s_waitcnt vmcnt(0)
	v_lshlrev_b32_e32 v90, 16, v82
	v_and_b32_e32 v82, 0xffff0000, v82
	v_mul_f32_e32 v100, v3, v81
	v_mul_f32_e32 v101, v19, v81
	v_mul_f32_e32 v81, v35, v81
	v_fmac_f32_e32 v98, v0, v88
	v_fmac_f32_e32 v99, v16, v88
	v_fmac_f32_e32 v80, v32, v88
	v_add_f32_e32 v86, v86, v96
	v_add_f32_e32 v87, v87, v97
	v_add_f32_e32 v78, v78, v79
	v_lshlrev_b32_e32 v91, 16, v83
	v_and_b32_e32 v83, 0xffff0000, v83
	v_mul_f32_e32 v102, v5, v82
	v_mul_f32_e32 v103, v21, v82
	v_mul_f32_e32 v82, v37, v82
	v_fmac_f32_e32 v100, v2, v89
	v_fmac_f32_e32 v101, v18, v89
	v_fmac_f32_e32 v81, v34, v89
	v_add_f32_e32 v79, v86, v98
	v_add_f32_e32 v86, v87, v99
	v_add_f32_e32 v78, v78, v80
	v_lshlrev_b32_e32 v92, 16, v84
	v_and_b32_e32 v84, 0xffff0000, v84
	v_mul_f32_e32 v104, v7, v83
	v_mul_f32_e32 v105, v23, v83
	v_mul_f32_e32 v83, v39, v83
	v_fmac_f32_e32 v102, v4, v90
	v_fmac_f32_e32 v103, v20, v90
	v_fmac_f32_e32 v82, v36, v90
	v_add_f32_e32 v79, v79, v100
	v_add_f32_e32 v80, v86, v101
	v_add_f32_e32 v78, v78, v81
	v_lshlrev_b32_e32 v93, 16, v85
	v_and_b32_e32 v85, 0xffff0000, v85
	v_mul_f32_e32 v106, v13, v84
	v_mul_f32_e32 v107, v29, v84
	v_mul_f32_e32 v84, v45, v84
	v_fmac_f32_e32 v104, v6, v91
	v_fmac_f32_e32 v105, v22, v91
	v_fmac_f32_e32 v83, v38, v91
	v_add_f32_e32 v79, v79, v102
	v_add_f32_e32 v80, v80, v103
	v_add_f32_e32 v78, v78, v82
	v_mul_f32_e32 v108, v15, v85
	v_mul_f32_e32 v109, v31, v85
	v_mul_f32_e32 v85, v47, v85
	v_fmac_f32_e32 v106, v12, v92
	v_fmac_f32_e32 v107, v28, v92
	v_fmac_f32_e32 v84, v44, v92
	v_add_f32_e32 v79, v79, v104
	v_add_f32_e32 v80, v80, v105
	v_add_f32_e32 v78, v78, v83
	v_fmac_f32_e32 v108, v14, v93
	v_fmac_f32_e32 v109, v30, v93
	v_fmac_f32_e32 v85, v46, v93
	v_add_f32_e32 v79, v79, v106
	v_add_f32_e32 v80, v80, v107
	v_add_f32_e32 v78, v78, v84
	v_add_f32_e32 v79, v79, v108
	v_add_f32_e32 v80, v80, v109
	v_add_f32_e32 v78, v78, v85
	s_nop 1
	v_mov_b32_dpp v81, v79 quad_perm:[1,0,3,2] row_mask:0xf bank_mask:0xf
	s_nop 1
	v_mov_b32_dpp v82, v80 quad_perm:[1,0,3,2] row_mask:0xf bank_mask:0xf
	s_nop 1
	v_mov_b32_dpp v83, v78 quad_perm:[1,0,3,2] row_mask:0xf bank_mask:0xf
	s_waitcnt lgkmcnt(0)
	v_add_f32_e32 v79, v79, v81
	s_waitcnt lgkmcnt(0)
	v_add_f32_e32 v80, v80, v82
	s_waitcnt lgkmcnt(0)
	v_add_f32_e32 v78, v78, v83
	s_nop 1
	v_mov_b32_dpp v81, v79 quad_perm:[2,3,0,1] row_mask:0xf bank_mask:0xf
	s_nop 1
	v_mov_b32_dpp v82, v80 quad_perm:[2,3,0,1] row_mask:0xf bank_mask:0xf
	s_nop 1
	v_mov_b32_dpp v83, v78 quad_perm:[2,3,0,1] row_mask:0xf bank_mask:0xf
	s_waitcnt lgkmcnt(0)
	v_add_f32_e32 v79, v79, v81
	s_waitcnt lgkmcnt(0)
	v_add_f32_e32 v80, v80, v82
	s_waitcnt lgkmcnt(0)
	v_add_f32_e32 v78, v78, v83
	s_nop 1
	v_mov_b32_dpp v81, v79 row_half_mirror row_mask:0xf bank_mask:0xf
	s_nop 1
	v_mov_b32_dpp v82, v80 row_half_mirror row_mask:0xf bank_mask:0xf
	s_nop 1
	v_mov_b32_dpp v83, v78 row_half_mirror row_mask:0xf bank_mask:0xf
	s_waitcnt lgkmcnt(0)
	v_add_f32_e32 v79, v79, v81
	s_waitcnt lgkmcnt(0)
	v_add_f32_e32 v80, v80, v82
	s_waitcnt lgkmcnt(0)
	v_add_f32_e32 v78, v78, v83
	s_nop 1
	v_mov_b32_dpp v81, v79 row_mirror row_mask:0xf bank_mask:0xf
	s_nop 1
	v_mov_b32_dpp v82, v80 row_mirror row_mask:0xf bank_mask:0xf
	s_nop 1
	v_mov_b32_dpp v83, v78 row_mirror row_mask:0xf bank_mask:0xf
	s_waitcnt lgkmcnt(0)
	v_add_f32_e32 v79, v79, v81
	s_waitcnt lgkmcnt(0)
	v_add_f32_e32 v80, v80, v82
	s_waitcnt lgkmcnt(0)
	v_add_f32_e32 v81, v78, v83
	v_mov_b32_e32 v78, v79
	s_nop 1
	v_permlane16_swap_b32_e32 v79, v78
	s_nop 0
	v_mov_b32_e32 v82, v80
	s_nop 1
	v_permlane16_swap_b32_e32 v80, v82
	s_nop 0
	v_mov_b32_e32 v83, v81
	s_nop 1
	v_permlane16_swap_b32_e32 v81, v83
	s_nop 0
	s_waitcnt lgkmcnt(0)
	v_add_f32_e32 v78, v79, v78
	s_waitcnt lgkmcnt(0)
	v_add_f32_e32 v79, v80, v82
	s_waitcnt lgkmcnt(0)
	v_add_f32_e32 v81, v81, v83
	ds_bpermute_b32 v80, v76, v78
	ds_bpermute_b32 v82, v76, v79
	ds_bpermute_b32 v83, v76, v81
	s_and_saveexec_b64 s[36:37], s[4:5]
	s_cbranch_execz .LBB0_238
	s_waitcnt lgkmcnt(2)
	v_add_f32_e32 v78, v78, v80
	global_store_dword v[62:63], v78, off sc1
	v_add_co_u32_e32 v78, vcc, 0x5000, v62
	s_waitcnt lgkmcnt(1)
	v_add_f32_e32 v82, v79, v82
	v_addc_co_u32_e32 v79, vcc, 0, v63, vcc
	global_store_dword v[78:79], v82, off offset:2048 sc1
	v_add_co_u32_e32 v78, vcc, 0xb000, v62
	s_waitcnt lgkmcnt(0)
	v_add_f32_e32 v81, v81, v83
	v_addc_co_u32_e32 v79, vcc, 0, v63, vcc
	global_store_dword v[78:79], v81, off sc1
	s_branch .LBB0_238

.LBB0_266:
	v_add_u32_e32 v164, s76, v173
	v_and_b32_e32 v222, 31, v199
	v_bfe_u32 v223, v199, 5, 1
	v_lshlrev_b32_e32 v224, 2, v223
	v_sub_u32_e32 v222, v222, v224
	v_add_u32_e32 v224, s76, v173
	v_add_lshl_u32 v222, v222, v224, 2
	v_lshlrev_b32_e32 v223, 4, v223
	global_load_dword v194, v222, s[18:19]
	v_add_u32_e32 v224, 0x10000, v222
	global_load_dword v195, v224, s[18:19]
	v_add_u32_e32 v224, 0x20000, v222
	global_load_dword v196, v224, s[18:19]
	v_add_u32_e32 v224, 0x30000, v222
	global_load_dword v197, v224, s[18:19]
	v_add_u32_e32 v224, 0x40000, v222
	global_load_dword v202, v224, s[18:19]
	v_add_u32_e32 v224, 0x50000, v222
	global_load_dword v203, v224, s[18:19]
	v_add_u32_e32 v224, 0x60000, v222
	global_load_dword v204, v224, s[18:19]
	v_add_u32_e32 v224, 0x70000, v222
	global_load_dword v205, v224, s[18:19]
	s_waitcnt vmcnt(0)
	v_add_f32_e32 v194, v194, v195
	v_add_f32_e32 v196, v196, v197
	v_add_f32_e32 v202, v202, v203
	v_add_f32_e32 v204, v204, v205
	v_add_f32_e32 v194, v194, v196
	v_add_f32_e32 v202, v202, v204
	v_add_f32_e32 v194, v194, v202
	v_fmamk_f32 v194, v194, 0x3a800000, v209
	v_rsq_f32_e32 v194, v194
	s_nop 1
	ds_bpermute_b32 v225, v223, v194
	ds_bpermute_b32 v230, v223, v194 offset:4
	ds_bpermute_b32 v231, v223, v194 offset:8
	ds_bpermute_b32 v232, v223, v194 offset:12
	ds_bpermute_b32 v233, v223, v194 offset:32
	ds_bpermute_b32 v234, v223, v194 offset:36
	ds_bpermute_b32 v235, v223, v194 offset:40
	ds_bpermute_b32 v236, v223, v194 offset:44
	ds_bpermute_b32 v237, v223, v194 offset:64
	ds_bpermute_b32 v238, v223, v194 offset:68
	ds_bpermute_b32 v239, v223, v194 offset:72
	ds_bpermute_b32 v240, v223, v194 offset:76
	ds_bpermute_b32 v241, v223, v194 offset:96
	ds_bpermute_b32 v242, v223, v194 offset:100
	ds_bpermute_b32 v243, v223, v194 offset:104
	ds_bpermute_b32 v244, v223, v194 offset:108
	s_waitcnt lgkmcnt(0)
	s_lshl_b64 s[80:81], s[80:81], 2
	s_add_u32 s80, s84, s80
	s_addc_u32 s81, s85, s81
	s_cmp_gt_i32 s95, 23
	v_or_b32_e32 v92, 16, v164
	v_ashrrev_i32_e32 v93, 31, v92
	v_lshl_add_u64 v[92:93], v[92:93], 2, s[18:19]
	v_or_b32_e32 v68, 24, v164
	v_add_co_u32_e32 v94, vcc, s91, v92
	v_ashrrev_i32_e32 v69, 31, v68
	s_nop 0
	v_addc_co_u32_e32 v95, vcc, 0, v93, vcc
	v_lshl_add_u64 v[80:81], v[68:69], 2, s[18:19]
	v_add_co_u32_e32 v88, vcc, s90, v80
	s_nop 1
	v_addc_co_u32_e32 v89, vcc, 0, v81, vcc
	v_add_co_u32_e32 v84, vcc, s91, v80
	s_nop 1
	v_addc_co_u32_e32 v85, vcc, 0, v81, vcc
	v_add_co_u32_e32 v80, vcc, s92, v80
	s_nop 1
	v_addc_co_u32_e32 v81, vcc, 0, v81, vcc
	v_or_b32_e32 v76, s78, v156
	v_ashrrev_i32_e32 v77, 31, v76
	v_lshl_add_u64 v[64:65], v[76:77], 2, s[80:81]
	global_load_dword v81, v[64:65], off
	global_load_dword v80, v[64:65], off offset:128
	global_load_dword v82, v[64:65], off offset:256
	global_load_dword v83, v[64:65], off offset:384
	v_mov_b32_e32 v65, v48
	v_mov_b32_e32 v48, v33
	v_mov_b32_e32 v33, v50
	v_mov_b32_e32 v50, v35
	s_mov_b64 s[80:81], -1
	v_mov_b32_e32 v94, v234
	v_mov_b32_e32 v96, v235
	v_mov_b32_e32 v98, v236
	v_mov_b32_e32 v100, v237
	v_mov_b32_e32 v84, v225
	v_mov_b32_e32 v102, v238
	v_mov_b32_e32 v86, v230
	v_mov_b32_e32 v104, v239
	v_mov_b32_e32 v88, v231
	v_mov_b32_e32 v106, v240
	v_mov_b32_e32 v90, v232
	v_mov_b32_e32 v108, v241
	v_mov_b32_e32 v92, v233
	v_mov_b32_e32 v110, v242
	v_mov_b32_e32 v112, v243
	v_mov_b32_e32 v114, v244
	v_mov_b32_e32 v64, v32
	v_mov_b32_e32 v32, v34
	s_waitcnt vmcnt(2)
	v_pk_fma_f32 v[72:73], v[32:33], v[88:89], v[80:81] op_sel_hi:[1,0,1]
	v_mov_b32_e32 v32, v36
	v_mov_b32_e32 v33, v52
	v_pk_fma_f32 v[68:69], v[32:33], v[92:93], v[80:81] op_sel_hi:[1,0,1]
	v_mov_b32_e32 v32, v38
	v_mov_b32_e32 v33, v54
	v_pk_fma_f32 v[78:79], v[64:65], v[84:85], v[80:81] op_sel_hi:[1,0,1]
	v_mov_b32_e32 v52, v37
	v_pk_fma_f32 v[64:65], v[32:33], v[96:97], v[80:81] op_sel_hi:[1,0,1]
	v_mov_b32_e32 v32, v40
	v_mov_b32_e32 v33, v56
	v_pk_fma_f32 v[66:67], v[52:53], v[94:95], v[80:81] op_sel_hi:[1,0,1]
	v_pk_fma_f32 v[52:53], v[32:33], v[100:101], v[80:81] op_sel_hi:[1,0,1]
	v_mov_b32_e32 v32, v42
	v_mov_b32_e32 v33, v58
	v_pk_fma_f32 v[74:75], v[48:49], v[86:87], v[80:81] op_sel_hi:[1,0,1]
	v_pk_fma_f32 v[48:49], v[32:33], v[104:105], v[80:81] op_sel_hi:[1,0,1]
	v_mov_b32_e32 v32, v44
	v_mov_b32_e32 v33, v60
	v_mov_b32_e32 v54, v39
	v_mov_b32_e32 v56, v41
	v_mov_b32_e32 v58, v43
	v_pk_fma_f32 v[38:39], v[32:33], v[108:109], v[80:81] op_sel_hi:[1,0,1]
	v_mov_b32_e32 v60, v45
	v_mov_b32_e32 v32, v46
	v_mov_b32_e32 v33, v62
	v_mov_b32_e32 v62, v47
	v_pk_fma_f32 v[70:71], v[50:51], v[90:91], v[80:81] op_sel_hi:[1,0,1]
	v_pk_fma_f32 v[54:55], v[54:55], v[98:99], v[80:81] op_sel_hi:[1,0,1]
	v_pk_fma_f32 v[50:51], v[56:57], v[102:103], v[80:81] op_sel_hi:[1,0,1]
	v_pk_fma_f32 v[40:41], v[58:59], v[106:107], v[80:81] op_sel_hi:[1,0,1]
	v_pk_fma_f32 v[36:37], v[60:61], v[110:111], v[80:81] op_sel_hi:[1,0,1]
	v_pk_fma_f32 v[34:35], v[32:33], v[112:113], v[80:81] op_sel_hi:[1,0,1]
	v_pk_fma_f32 v[32:33], v[62:63], v[114:115], v[80:81] op_sel_hi:[1,0,1]
	s_waitcnt vmcnt(1)
	v_fma_f32 v57, v16, v84, v82
	v_fma_f32 v47, v17, v86, v82
	v_fma_f32 v46, v18, v88, v82
	v_fma_f32 v45, v19, v90, v82
	v_fma_f32 v44, v20, v92, v82
	v_fma_f32 v43, v21, v94, v82
	v_fma_f32 v42, v22, v96, v82
	v_fma_f32 v23, v23, v98, v82
	v_fma_f32 v22, v24, v100, v82
	v_fma_f32 v21, v25, v102, v82
	v_fma_f32 v20, v26, v104, v82
	v_fma_f32 v19, v27, v106, v82
	v_fma_f32 v18, v28, v108, v82
	v_fma_f32 v17, v29, v110, v82
	v_fma_f32 v16, v30, v112, v82
	v_fmac_f32_e32 v82, v31, v114
	s_waitcnt vmcnt(0)
	v_fma_f32 v56, v0, v84, v83
	v_fma_f32 v31, v1, v86, v83
	v_fma_f32 v30, v2, v88, v83
	v_fma_f32 v29, v3, v90, v83
	v_fma_f32 v28, v4, v92, v83
	v_fma_f32 v27, v5, v94, v83
	v_fma_f32 v26, v6, v96, v83
	v_fma_f32 v25, v7, v98, v83
	v_fma_f32 v24, v8, v100, v83
	v_fma_f32 v9, v9, v102, v83
	v_fma_f32 v8, v10, v104, v83
	v_fma_f32 v7, v11, v106, v83
	v_fma_f32 v6, v12, v108, v83
	v_fma_f32 v5, v13, v110, v83
	v_fma_f32 v4, v14, v112, v83
	v_fmac_f32_e32 v83, v15, v114
	s_cbranch_scc0 .LBB0_496
	v_cndmask_b32_e64 v0, 0, 1, s[4:5]
	s_cmp_gt_u32 s10, 4
	v_cmp_ne_u32_e64 s[4:5], 1, v0
	s_cbranch_scc0 .LBB0_333
	v_mov_b32_e32 v0, s93
	ds_read_b64 v[0:1], v0
	v_and_b32_e32 v11, 64, v214
	v_xor_b32_e32 v10, 1, v214
	v_add_u32_e32 v13, 64, v11
	v_pk_mul_f32 v[2:3], v[78:79], v[78:79]
	s_waitcnt lgkmcnt(0)
	v_readfirstlane_b32 s80, v0
	v_readfirstlane_b32 s81, v1
	s_nop 4
	global_load_dword v1, v210, s[80:81] offset:1280
	global_load_dword v0, v210, s[80:81] offset:1408
	v_cmp_lt_i32_e32 vcc, v10, v13
	v_add_f32_e32 v2, v3, v2
	v_xor_b32_e32 v11, 4, v214
	v_cndmask_b32_e32 v3, v214, v10, vcc
	v_lshlrev_b32_e32 v14, 2, v3
	s_nop 1
	v_mov_b32_dpp v3, v2 quad_perm:[1,0,3,2] row_mask:0xf bank_mask:0xf
	v_xor_b32_e32 v10, 2, v214
	v_cmp_lt_i32_e32 vcc, v10, v13
	v_xor_b32_e32 v12, 8, v214
	v_xor_b32_e32 v15, 16, v214
	v_cndmask_b32_e32 v10, v214, v10, vcc
	v_lshlrev_b32_e32 v10, 2, v10
	s_waitcnt lgkmcnt(0)
	v_add_f32_e32 v2, v2, v3
	s_nop 1
	v_mov_b32_dpp v3, v2 quad_perm:[2,3,0,1] row_mask:0xf bank_mask:0xf
	v_cmp_lt_i32_e32 vcc, v11, v13
	s_mov_b64 s[80:81], -1
	s_waitcnt lgkmcnt(0)
	v_add_f32_e32 v2, v2, v3
	v_cndmask_b32_e32 v11, v214, v11, vcc
	v_lshlrev_b32_e32 v11, 2, v11
	s_nop 1
	v_mov_b32_dpp v3, v2 row_half_mirror row_mask:0xf bank_mask:0xf
	v_cmp_lt_i32_e32 vcc, v12, v13
	s_waitcnt lgkmcnt(0)
	v_add_f32_e32 v2, v2, v3
	v_cndmask_b32_e32 v12, v214, v12, vcc
	v_lshlrev_b32_e32 v12, 2, v12
	s_nop 1
	v_mov_b32_dpp v3, v2 row_mirror row_mask:0xf bank_mask:0xf
	v_cmp_lt_i32_e32 vcc, v15, v13
	s_waitcnt lgkmcnt(0)
	v_add_f32_e32 v2, v2, v3
	v_cndmask_b32_e32 v13, v214, v15, vcc
	v_lshlrev_b32_e32 v13, 2, v13
	v_mov_b32_e32 v3, v2
	s_nop 1
	v_permlane16_swap_b32_e32 v2, v3
	s_nop 0
	s_and_b64 vcc, exec, s[4:5]
	s_waitcnt lgkmcnt(0)
	v_add_f32_e32 v2, v2, v3
	v_fmamk_f32 v2, v2, 0x3c800000, v209
	v_rsq_f32_e32 v2, v2
	s_waitcnt vmcnt(0)
	v_pk_mul_f32 v[2:3], v[0:1], v[2:3] op_sel_hi:[1,0]
	s_nop 0
	v_pk_mul_f32 v[2:3], v[78:79], v[2:3]
	s_cbranch_vccnz .LBB0_270
	v_lshl_or_b32 v58, v164, 6, v156
	v_ashrrev_i32_e32 v59, 31, v58
	v_lshl_add_u64 v[58:59], v[58:59], 2, s[24:25]
	s_mov_b64 s[80:81], 0
	global_store_dword v[58:59], v3, off sc1
	global_store_dword v[58:59], v2, off offset:128 sc1

.LBB0_272:
	v_cvt_pk_bf16_f32 v60, v2, s0
	v_add_u32_e32 v2, s11, v173
	v_mul_lo_u32 v61, v2, s94
	v_or_b32_e32 v2, v61, v174
	v_cvt_pk_bf16_f32 v15, v3, s0
	v_ashrrev_i32_e32 v3, 31, v2
	v_lshl_add_u64 v[2:3], v[2:3], 1, s[22:23]
	global_store_short v[2:3], v15, off sc1
	v_or_b32_e32 v2, v61, v175
	v_ashrrev_i32_e32 v3, 31, v2
	v_lshl_add_u64 v[2:3], v[2:3], 1, s[22:23]
	v_or_b32_e32 v58, 0xc0, v61
	global_store_short v[2:3], v60, off sc1
	v_add_u32_e32 v2, v58, v174
	v_ashrrev_i32_e32 v3, 31, v2
	v_lshl_add_u64 v[2:3], v[2:3], 1, s[22:23]
	global_store_short v[2:3], v15, off sc1
	v_add_u32_e32 v2, v58, v175
	v_ashrrev_i32_e32 v3, 31, v2
	v_lshl_add_u64 v[2:3], v[2:3], 1, s[22:23]
	v_or_b32_e32 v58, 0x180, v61
	global_store_short v[2:3], v60, off sc1
	v_add_u32_e32 v2, v58, v174
	v_ashrrev_i32_e32 v3, 31, v2
	v_lshl_add_u64 v[2:3], v[2:3], 1, s[22:23]
	global_store_short v[2:3], v15, off sc1
	v_add_u32_e32 v2, v58, v175
	v_ashrrev_i32_e32 v3, 31, v2
	v_lshl_add_u64 v[2:3], v[2:3], 1, s[22:23]
	v_add_u32_e32 v58, 0x240, v61
	global_store_short v[2:3], v60, off sc1
	v_or_b32_e32 v2, v58, v174
	v_ashrrev_i32_e32 v3, 31, v2
	v_lshl_add_u64 v[2:3], v[2:3], 1, s[22:23]
	global_store_short v[2:3], v15, off sc1
	v_or_b32_e32 v2, v58, v175
	v_ashrrev_i32_e32 v3, 31, v2
	v_lshl_add_u64 v[2:3], v[2:3], 1, s[22:23]
	v_add_u32_e32 v58, 0x300, v61
	global_store_short v[2:3], v60, off sc1
	v_or_b32_e32 v2, v58, v174
	v_ashrrev_i32_e32 v3, 31, v2
	v_lshl_add_u64 v[2:3], v[2:3], 1, s[22:23]
	global_store_short v[2:3], v15, off sc1
	v_or_b32_e32 v2, v58, v175
	v_pk_mul_f32 v[58:59], v[74:75], v[74:75]
	v_ashrrev_i32_e32 v3, 31, v2
	v_add_f32_e32 v58, v59, v58
	s_nop 1
	v_mov_b32_dpp v59, v58 quad_perm:[1,0,3,2] row_mask:0xf bank_mask:0xf
	v_lshl_add_u64 v[2:3], v[2:3], 1, s[22:23]
	v_add_u32_e32 v62, 0x3c0, v61
	global_store_short v[2:3], v60, off sc1
	v_add_u32_e32 v2, v62, v174
	s_waitcnt lgkmcnt(0)
	v_add_f32_e32 v58, v58, v59
	s_nop 1
	v_mov_b32_dpp v59, v58 quad_perm:[2,3,0,1] row_mask:0xf bank_mask:0xf
	v_ashrrev_i32_e32 v3, 31, v2
	v_lshl_add_u64 v[2:3], v[2:3], 1, s[22:23]
	global_store_short v[2:3], v15, off sc1
	v_add_u32_e32 v2, v62, v175
	s_waitcnt lgkmcnt(0)
	v_add_f32_e32 v58, v58, v59
	s_nop 1
	v_mov_b32_dpp v59, v58 row_half_mirror row_mask:0xf bank_mask:0xf
	v_ashrrev_i32_e32 v3, 31, v2
	v_lshl_add_u64 v[2:3], v[2:3], 1, s[22:23]
	v_add_u32_e32 v62, 0x480, v61
	global_store_short v[2:3], v60, off sc1
	s_waitcnt lgkmcnt(0)
	v_add_f32_e32 v58, v58, v59
	s_nop 1
	v_mov_b32_dpp v59, v58 row_mirror row_mask:0xf bank_mask:0xf
	v_add_u32_e32 v2, v62, v174
	v_ashrrev_i32_e32 v3, 31, v2
	v_lshl_add_u64 v[2:3], v[2:3], 1, s[22:23]
	global_store_short v[2:3], v15, off sc1
	v_add_u32_e32 v2, v62, v175
	s_waitcnt lgkmcnt(0)
	v_add_f32_e32 v58, v58, v59
	v_ashrrev_i32_e32 v3, 31, v2
	v_mov_b32_e32 v59, v58
	s_nop 1
	v_permlane16_swap_b32_e32 v58, v59
	s_nop 0
	v_lshl_add_u64 v[2:3], v[2:3], 1, s[22:23]
	v_add_u32_e32 v61, 0x540, v61
	global_store_short v[2:3], v60, off sc1
	v_or_b32_e32 v2, v61, v174
	v_ashrrev_i32_e32 v3, 31, v2
	v_lshl_add_u64 v[2:3], v[2:3], 1, s[22:23]
	global_store_short v[2:3], v15, off sc1
	s_waitcnt lgkmcnt(0)
	v_add_f32_e32 v3, v58, v59
	v_fmamk_f32 v3, v3, 0x3c800000, v209
	v_rsq_f32_e32 v58, v3
	v_or_b32_e32 v2, v61, v175
	v_ashrrev_i32_e32 v3, 31, v2
	v_lshl_add_u64 v[2:3], v[2:3], 1, s[22:23]
	global_store_short v[2:3], v60, off sc1
	v_pk_mul_f32 v[2:3], v[0:1], v[58:59] op_sel_hi:[1,0]
	s_and_b64 vcc, exec, s[4:5]
	v_pk_mul_f32 v[2:3], v[74:75], v[2:3]
	s_mov_b64 s[80:81], -1
	s_cbranch_vccnz .LBB0_274
	v_add_u32_e32 v15, s76, v176
	v_lshl_or_b32 v58, v15, 6, v156
	v_ashrrev_i32_e32 v59, 31, v58
	v_lshl_add_u64 v[58:59], v[58:59], 2, s[24:25]
	s_mov_b64 s[80:81], 0
	global_store_dword v[58:59], v3, off sc1
	global_store_dword v[58:59], v2, off offset:128 sc1

.LBB0_276:
	v_cvt_pk_bf16_f32 v60, v2, s0
	v_add_u32_e32 v2, s11, v176
	v_mul_lo_u32 v61, v2, s94
	v_or_b32_e32 v2, v61, v174
	v_cvt_pk_bf16_f32 v15, v3, s0
	v_ashrrev_i32_e32 v3, 31, v2
	v_lshl_add_u64 v[2:3], v[2:3], 1, s[22:23]
	global_store_short v[2:3], v15, off sc1
	v_or_b32_e32 v2, v61, v175
	v_ashrrev_i32_e32 v3, 31, v2
	v_lshl_add_u64 v[2:3], v[2:3], 1, s[22:23]
	v_or_b32_e32 v58, 0xc0, v61
	global_store_short v[2:3], v60, off sc1
	v_add_u32_e32 v2, v58, v174
	v_ashrrev_i32_e32 v3, 31, v2
	v_lshl_add_u64 v[2:3], v[2:3], 1, s[22:23]
	global_store_short v[2:3], v15, off sc1
	v_add_u32_e32 v2, v58, v175
	v_ashrrev_i32_e32 v3, 31, v2
	v_lshl_add_u64 v[2:3], v[2:3], 1, s[22:23]
	v_or_b32_e32 v58, 0x180, v61
	global_store_short v[2:3], v60, off sc1
	v_add_u32_e32 v2, v58, v174
	v_ashrrev_i32_e32 v3, 31, v2
	v_lshl_add_u64 v[2:3], v[2:3], 1, s[22:23]
	global_store_short v[2:3], v15, off sc1
	v_add_u32_e32 v2, v58, v175
	v_ashrrev_i32_e32 v3, 31, v2
	v_lshl_add_u64 v[2:3], v[2:3], 1, s[22:23]
	v_add_u32_e32 v58, 0x240, v61
	global_store_short v[2:3], v60, off sc1
	v_or_b32_e32 v2, v58, v174
	v_ashrrev_i32_e32 v3, 31, v2
	v_lshl_add_u64 v[2:3], v[2:3], 1, s[22:23]
	global_store_short v[2:3], v15, off sc1
	v_or_b32_e32 v2, v58, v175
	v_ashrrev_i32_e32 v3, 31, v2
	v_lshl_add_u64 v[2:3], v[2:3], 1, s[22:23]
	v_add_u32_e32 v58, 0x300, v61
	global_store_short v[2:3], v60, off sc1
	v_or_b32_e32 v2, v58, v174
	v_ashrrev_i32_e32 v3, 31, v2
	v_lshl_add_u64 v[2:3], v[2:3], 1, s[22:23]
	global_store_short v[2:3], v15, off sc1
	v_or_b32_e32 v2, v58, v175
	v_pk_mul_f32 v[58:59], v[72:73], v[72:73]
	v_ashrrev_i32_e32 v3, 31, v2
	v_add_f32_e32 v58, v59, v58
	s_nop 1
	v_mov_b32_dpp v59, v58 quad_perm:[1,0,3,2] row_mask:0xf bank_mask:0xf
	v_lshl_add_u64 v[2:3], v[2:3], 1, s[22:23]
	v_add_u32_e32 v62, 0x3c0, v61
	global_store_short v[2:3], v60, off sc1
	v_add_u32_e32 v2, v62, v174
	s_waitcnt lgkmcnt(0)
	v_add_f32_e32 v58, v58, v59
	s_nop 1
	v_mov_b32_dpp v59, v58 quad_perm:[2,3,0,1] row_mask:0xf bank_mask:0xf
	v_ashrrev_i32_e32 v3, 31, v2
	v_lshl_add_u64 v[2:3], v[2:3], 1, s[22:23]
	global_store_short v[2:3], v15, off sc1
	v_add_u32_e32 v2, v62, v175
	s_waitcnt lgkmcnt(0)
	v_add_f32_e32 v58, v58, v59
	s_nop 1
	v_mov_b32_dpp v59, v58 row_half_mirror row_mask:0xf bank_mask:0xf
	v_ashrrev_i32_e32 v3, 31, v2
	v_lshl_add_u64 v[2:3], v[2:3], 1, s[22:23]
	v_add_u32_e32 v62, 0x480, v61
	global_store_short v[2:3], v60, off sc1
	s_waitcnt lgkmcnt(0)
	v_add_f32_e32 v58, v58, v59
	s_nop 1
	v_mov_b32_dpp v59, v58 row_mirror row_mask:0xf bank_mask:0xf
	v_add_u32_e32 v2, v62, v174
	v_ashrrev_i32_e32 v3, 31, v2
	v_lshl_add_u64 v[2:3], v[2:3], 1, s[22:23]
	global_store_short v[2:3], v15, off sc1
	v_add_u32_e32 v2, v62, v175
	s_waitcnt lgkmcnt(0)
	v_add_f32_e32 v58, v58, v59
	v_ashrrev_i32_e32 v3, 31, v2
	v_mov_b32_e32 v59, v58
	s_nop 1
	v_permlane16_swap_b32_e32 v58, v59
	s_nop 0
	v_lshl_add_u64 v[2:3], v[2:3], 1, s[22:23]
	v_add_u32_e32 v61, 0x540, v61
	global_store_short v[2:3], v60, off sc1
	v_or_b32_e32 v2, v61, v174
	v_ashrrev_i32_e32 v3, 31, v2
	v_lshl_add_u64 v[2:3], v[2:3], 1, s[22:23]
	global_store_short v[2:3], v15, off sc1
	s_waitcnt lgkmcnt(0)
	v_add_f32_e32 v3, v58, v59
	v_fmamk_f32 v3, v3, 0x3c800000, v209
	v_rsq_f32_e32 v58, v3
	v_or_b32_e32 v2, v61, v175
	v_ashrrev_i32_e32 v3, 31, v2
	v_lshl_add_u64 v[2:3], v[2:3], 1, s[22:23]
	global_store_short v[2:3], v60, off sc1
	v_pk_mul_f32 v[2:3], v[0:1], v[58:59] op_sel_hi:[1,0]
	s_and_b64 vcc, exec, s[4:5]
	v_pk_mul_f32 v[2:3], v[72:73], v[2:3]
	s_mov_b64 s[80:81], -1
	s_cbranch_vccnz .LBB0_278
	v_add_u32_e32 v15, s76, v177
	v_lshl_or_b32 v58, v15, 6, v156
	v_ashrrev_i32_e32 v59, 31, v58
	v_lshl_add_u64 v[58:59], v[58:59], 2, s[24:25]
	s_mov_b64 s[80:81], 0
	global_store_dword v[58:59], v3, off sc1
	global_store_dword v[58:59], v2, off offset:128 sc1

.LBB0_280:
	v_cvt_pk_bf16_f32 v60, v2, s0
	v_add_u32_e32 v2, s11, v177
	v_mul_lo_u32 v61, v2, s94
	v_or_b32_e32 v2, v61, v174
	v_cvt_pk_bf16_f32 v15, v3, s0
	v_ashrrev_i32_e32 v3, 31, v2
	v_lshl_add_u64 v[2:3], v[2:3], 1, s[22:23]
	global_store_short v[2:3], v15, off sc1
	v_or_b32_e32 v2, v61, v175
	v_ashrrev_i32_e32 v3, 31, v2
	v_lshl_add_u64 v[2:3], v[2:3], 1, s[22:23]
	v_or_b32_e32 v58, 0xc0, v61
	global_store_short v[2:3], v60, off sc1
	v_add_u32_e32 v2, v58, v174
	v_ashrrev_i32_e32 v3, 31, v2
	v_lshl_add_u64 v[2:3], v[2:3], 1, s[22:23]
	global_store_short v[2:3], v15, off sc1
	v_add_u32_e32 v2, v58, v175
	v_ashrrev_i32_e32 v3, 31, v2
	v_lshl_add_u64 v[2:3], v[2:3], 1, s[22:23]
	v_or_b32_e32 v58, 0x180, v61
	global_store_short v[2:3], v60, off sc1
	v_add_u32_e32 v2, v58, v174
	v_ashrrev_i32_e32 v3, 31, v2
	v_lshl_add_u64 v[2:3], v[2:3], 1, s[22:23]
	global_store_short v[2:3], v15, off sc1
	v_add_u32_e32 v2, v58, v175
	v_ashrrev_i32_e32 v3, 31, v2
	v_lshl_add_u64 v[2:3], v[2:3], 1, s[22:23]
	v_add_u32_e32 v58, 0x240, v61
	global_store_short v[2:3], v60, off sc1
	v_or_b32_e32 v2, v58, v174
	v_ashrrev_i32_e32 v3, 31, v2
	v_lshl_add_u64 v[2:3], v[2:3], 1, s[22:23]
	global_store_short v[2:3], v15, off sc1
	v_or_b32_e32 v2, v58, v175
	v_ashrrev_i32_e32 v3, 31, v2
	v_lshl_add_u64 v[2:3], v[2:3], 1, s[22:23]
	v_add_u32_e32 v58, 0x300, v61
	global_store_short v[2:3], v60, off sc1
	v_or_b32_e32 v2, v58, v174
	v_ashrrev_i32_e32 v3, 31, v2
	v_lshl_add_u64 v[2:3], v[2:3], 1, s[22:23]
	global_store_short v[2:3], v15, off sc1
	v_or_b32_e32 v2, v58, v175
	v_pk_mul_f32 v[58:59], v[70:71], v[70:71]
	v_ashrrev_i32_e32 v3, 31, v2
	v_add_f32_e32 v58, v59, v58
	s_nop 1
	v_mov_b32_dpp v59, v58 quad_perm:[1,0,3,2] row_mask:0xf bank_mask:0xf
	v_lshl_add_u64 v[2:3], v[2:3], 1, s[22:23]
	v_add_u32_e32 v62, 0x3c0, v61
	global_store_short v[2:3], v60, off sc1
	v_add_u32_e32 v2, v62, v174
	s_waitcnt lgkmcnt(0)
	v_add_f32_e32 v58, v58, v59
	s_nop 1
	v_mov_b32_dpp v59, v58 quad_perm:[2,3,0,1] row_mask:0xf bank_mask:0xf
	v_ashrrev_i32_e32 v3, 31, v2
	v_lshl_add_u64 v[2:3], v[2:3], 1, s[22:23]
	global_store_short v[2:3], v15, off sc1
	v_add_u32_e32 v2, v62, v175
	s_waitcnt lgkmcnt(0)
	v_add_f32_e32 v58, v58, v59
	s_nop 1
	v_mov_b32_dpp v59, v58 row_half_mirror row_mask:0xf bank_mask:0xf
	v_ashrrev_i32_e32 v3, 31, v2
	v_lshl_add_u64 v[2:3], v[2:3], 1, s[22:23]
	v_add_u32_e32 v62, 0x480, v61
	global_store_short v[2:3], v60, off sc1
	s_waitcnt lgkmcnt(0)
	v_add_f32_e32 v58, v58, v59
	s_nop 1
	v_mov_b32_dpp v59, v58 row_mirror row_mask:0xf bank_mask:0xf
	v_add_u32_e32 v2, v62, v174
	v_ashrrev_i32_e32 v3, 31, v2
	v_lshl_add_u64 v[2:3], v[2:3], 1, s[22:23]
	global_store_short v[2:3], v15, off sc1
	v_add_u32_e32 v2, v62, v175
	s_waitcnt lgkmcnt(0)
	v_add_f32_e32 v58, v58, v59
	v_ashrrev_i32_e32 v3, 31, v2
	v_mov_b32_e32 v59, v58
	s_nop 1
	v_permlane16_swap_b32_e32 v58, v59
	s_nop 0
	v_lshl_add_u64 v[2:3], v[2:3], 1, s[22:23]
	v_add_u32_e32 v61, 0x540, v61
	global_store_short v[2:3], v60, off sc1
	v_or_b32_e32 v2, v61, v174
	v_ashrrev_i32_e32 v3, 31, v2
	v_lshl_add_u64 v[2:3], v[2:3], 1, s[22:23]
	global_store_short v[2:3], v15, off sc1
	s_waitcnt lgkmcnt(0)
	v_add_f32_e32 v3, v58, v59
	v_fmamk_f32 v3, v3, 0x3c800000, v209
	v_rsq_f32_e32 v58, v3
	v_or_b32_e32 v2, v61, v175
	v_ashrrev_i32_e32 v3, 31, v2
	v_lshl_add_u64 v[2:3], v[2:3], 1, s[22:23]
	global_store_short v[2:3], v60, off sc1
	v_pk_mul_f32 v[2:3], v[0:1], v[58:59] op_sel_hi:[1,0]
	s_and_b64 vcc, exec, s[4:5]
	v_pk_mul_f32 v[2:3], v[70:71], v[2:3]
	s_mov_b64 s[80:81], -1
	s_cbranch_vccnz .LBB0_282
	v_add_u32_e32 v15, s76, v178
	v_lshl_or_b32 v58, v15, 6, v156
	v_ashrrev_i32_e32 v59, 31, v58
	v_lshl_add_u64 v[58:59], v[58:59], 2, s[24:25]
	s_mov_b64 s[80:81], 0
	global_store_dword v[58:59], v3, off sc1
	global_store_dword v[58:59], v2, off offset:128 sc1

.LBB0_284:
	v_cvt_pk_bf16_f32 v60, v2, s0
	v_add_u32_e32 v2, s11, v178
	v_mul_lo_u32 v61, v2, s94
	v_or_b32_e32 v2, v61, v174
	v_cvt_pk_bf16_f32 v15, v3, s0
	v_ashrrev_i32_e32 v3, 31, v2
	v_lshl_add_u64 v[2:3], v[2:3], 1, s[22:23]
	global_store_short v[2:3], v15, off sc1
	v_or_b32_e32 v2, v61, v175
	v_ashrrev_i32_e32 v3, 31, v2
	v_lshl_add_u64 v[2:3], v[2:3], 1, s[22:23]
	v_or_b32_e32 v58, 0xc0, v61
	global_store_short v[2:3], v60, off sc1
	v_add_u32_e32 v2, v58, v174
	v_ashrrev_i32_e32 v3, 31, v2
	v_lshl_add_u64 v[2:3], v[2:3], 1, s[22:23]
	global_store_short v[2:3], v15, off sc1
	v_add_u32_e32 v2, v58, v175
	v_ashrrev_i32_e32 v3, 31, v2
	v_lshl_add_u64 v[2:3], v[2:3], 1, s[22:23]
	v_or_b32_e32 v58, 0x180, v61
	global_store_short v[2:3], v60, off sc1
	v_add_u32_e32 v2, v58, v174
	v_ashrrev_i32_e32 v3, 31, v2
	v_lshl_add_u64 v[2:3], v[2:3], 1, s[22:23]
	global_store_short v[2:3], v15, off sc1
	v_add_u32_e32 v2, v58, v175
	v_ashrrev_i32_e32 v3, 31, v2
	v_lshl_add_u64 v[2:3], v[2:3], 1, s[22:23]
	v_add_u32_e32 v58, 0x240, v61
	global_store_short v[2:3], v60, off sc1
	v_or_b32_e32 v2, v58, v174
	v_ashrrev_i32_e32 v3, 31, v2
	v_lshl_add_u64 v[2:3], v[2:3], 1, s[22:23]
	global_store_short v[2:3], v15, off sc1
	v_or_b32_e32 v2, v58, v175
	v_ashrrev_i32_e32 v3, 31, v2
	v_lshl_add_u64 v[2:3], v[2:3], 1, s[22:23]
	v_add_u32_e32 v58, 0x300, v61
	global_store_short v[2:3], v60, off sc1
	v_or_b32_e32 v2, v58, v174
	v_ashrrev_i32_e32 v3, 31, v2
	v_lshl_add_u64 v[2:3], v[2:3], 1, s[22:23]
	global_store_short v[2:3], v15, off sc1
	v_or_b32_e32 v2, v58, v175
	v_pk_mul_f32 v[58:59], v[68:69], v[68:69]
	v_ashrrev_i32_e32 v3, 31, v2
	v_add_f32_e32 v58, v59, v58
	s_nop 1
	v_mov_b32_dpp v59, v58 quad_perm:[1,0,3,2] row_mask:0xf bank_mask:0xf
	v_lshl_add_u64 v[2:3], v[2:3], 1, s[22:23]
	v_add_u32_e32 v62, 0x3c0, v61
	global_store_short v[2:3], v60, off sc1
	v_add_u32_e32 v2, v62, v174
	s_waitcnt lgkmcnt(0)
	v_add_f32_e32 v58, v58, v59
	s_nop 1
	v_mov_b32_dpp v59, v58 quad_perm:[2,3,0,1] row_mask:0xf bank_mask:0xf
	v_ashrrev_i32_e32 v3, 31, v2
	v_lshl_add_u64 v[2:3], v[2:3], 1, s[22:23]
	global_store_short v[2:3], v15, off sc1
	v_add_u32_e32 v2, v62, v175
	s_waitcnt lgkmcnt(0)
	v_add_f32_e32 v58, v58, v59
	s_nop 1
	v_mov_b32_dpp v59, v58 row_half_mirror row_mask:0xf bank_mask:0xf
	v_ashrrev_i32_e32 v3, 31, v2
	v_lshl_add_u64 v[2:3], v[2:3], 1, s[22:23]
	v_add_u32_e32 v62, 0x480, v61
	global_store_short v[2:3], v60, off sc1
	s_waitcnt lgkmcnt(0)
	v_add_f32_e32 v58, v58, v59
	s_nop 1
	v_mov_b32_dpp v59, v58 row_mirror row_mask:0xf bank_mask:0xf
	v_add_u32_e32 v2, v62, v174
	v_ashrrev_i32_e32 v3, 31, v2
	v_lshl_add_u64 v[2:3], v[2:3], 1, s[22:23]
	global_store_short v[2:3], v15, off sc1
	v_add_u32_e32 v2, v62, v175
	s_waitcnt lgkmcnt(0)
	v_add_f32_e32 v58, v58, v59
	v_ashrrev_i32_e32 v3, 31, v2
	v_mov_b32_e32 v59, v58
	s_nop 1
	v_permlane16_swap_b32_e32 v58, v59
	s_nop 0
	v_lshl_add_u64 v[2:3], v[2:3], 1, s[22:23]
	v_add_u32_e32 v61, 0x540, v61
	global_store_short v[2:3], v60, off sc1
	v_or_b32_e32 v2, v61, v174
	v_ashrrev_i32_e32 v3, 31, v2
	v_lshl_add_u64 v[2:3], v[2:3], 1, s[22:23]
	global_store_short v[2:3], v15, off sc1
	s_waitcnt lgkmcnt(0)
	v_add_f32_e32 v3, v58, v59
	v_fmamk_f32 v3, v3, 0x3c800000, v209
	v_rsq_f32_e32 v58, v3
	v_or_b32_e32 v2, v61, v175
	v_ashrrev_i32_e32 v3, 31, v2
	v_lshl_add_u64 v[2:3], v[2:3], 1, s[22:23]
	global_store_short v[2:3], v60, off sc1
	v_pk_mul_f32 v[2:3], v[0:1], v[58:59] op_sel_hi:[1,0]
	s_and_b64 vcc, exec, s[4:5]
	v_pk_mul_f32 v[2:3], v[68:69], v[2:3]
	s_mov_b64 s[80:81], -1
	s_cbranch_vccnz .LBB0_286
	v_add_u32_e32 v15, s76, v179
	v_lshl_or_b32 v58, v15, 6, v156
	v_ashrrev_i32_e32 v59, 31, v58
	v_lshl_add_u64 v[58:59], v[58:59], 2, s[24:25]
	s_mov_b64 s[80:81], 0
	global_store_dword v[58:59], v3, off sc1
	global_store_dword v[58:59], v2, off offset:128 sc1

.LBB0_288:
	v_cvt_pk_bf16_f32 v60, v2, s0
	v_add_u32_e32 v2, s11, v179
	v_mul_lo_u32 v61, v2, s94
	v_or_b32_e32 v2, v61, v174
	v_cvt_pk_bf16_f32 v15, v3, s0
	v_ashrrev_i32_e32 v3, 31, v2
	v_lshl_add_u64 v[2:3], v[2:3], 1, s[22:23]
	global_store_short v[2:3], v15, off sc1
	v_or_b32_e32 v2, v61, v175
	v_ashrrev_i32_e32 v3, 31, v2
	v_lshl_add_u64 v[2:3], v[2:3], 1, s[22:23]
	v_or_b32_e32 v58, 0xc0, v61
	global_store_short v[2:3], v60, off sc1
	v_add_u32_e32 v2, v58, v174
	v_ashrrev_i32_e32 v3, 31, v2
	v_lshl_add_u64 v[2:3], v[2:3], 1, s[22:23]
	global_store_short v[2:3], v15, off sc1
	v_add_u32_e32 v2, v58, v175
	v_ashrrev_i32_e32 v3, 31, v2
	v_lshl_add_u64 v[2:3], v[2:3], 1, s[22:23]
	v_or_b32_e32 v58, 0x180, v61
	global_store_short v[2:3], v60, off sc1
	v_add_u32_e32 v2, v58, v174
	v_ashrrev_i32_e32 v3, 31, v2
	v_lshl_add_u64 v[2:3], v[2:3], 1, s[22:23]
	global_store_short v[2:3], v15, off sc1
	v_add_u32_e32 v2, v58, v175
	v_ashrrev_i32_e32 v3, 31, v2
	v_lshl_add_u64 v[2:3], v[2:3], 1, s[22:23]
	v_add_u32_e32 v58, 0x240, v61
	global_store_short v[2:3], v60, off sc1
	v_or_b32_e32 v2, v58, v174
	v_ashrrev_i32_e32 v3, 31, v2
	v_lshl_add_u64 v[2:3], v[2:3], 1, s[22:23]
	global_store_short v[2:3], v15, off sc1
	v_or_b32_e32 v2, v58, v175
	v_ashrrev_i32_e32 v3, 31, v2
	v_lshl_add_u64 v[2:3], v[2:3], 1, s[22:23]
	v_add_u32_e32 v58, 0x300, v61
	global_store_short v[2:3], v60, off sc1
	v_or_b32_e32 v2, v58, v174
	v_ashrrev_i32_e32 v3, 31, v2
	v_lshl_add_u64 v[2:3], v[2:3], 1, s[22:23]
	global_store_short v[2:3], v15, off sc1
	v_or_b32_e32 v2, v58, v175
	v_pk_mul_f32 v[58:59], v[66:67], v[66:67]
	v_ashrrev_i32_e32 v3, 31, v2
	v_add_f32_e32 v58, v59, v58
	s_nop 1
	v_mov_b32_dpp v59, v58 quad_perm:[1,0,3,2] row_mask:0xf bank_mask:0xf
	v_lshl_add_u64 v[2:3], v[2:3], 1, s[22:23]
	v_add_u32_e32 v62, 0x3c0, v61
	global_store_short v[2:3], v60, off sc1
	v_add_u32_e32 v2, v62, v174
	s_waitcnt lgkmcnt(0)
	v_add_f32_e32 v58, v58, v59
	s_nop 1
	v_mov_b32_dpp v59, v58 quad_perm:[2,3,0,1] row_mask:0xf bank_mask:0xf
	v_ashrrev_i32_e32 v3, 31, v2
	v_lshl_add_u64 v[2:3], v[2:3], 1, s[22:23]
	global_store_short v[2:3], v15, off sc1
	v_add_u32_e32 v2, v62, v175
	s_waitcnt lgkmcnt(0)
	v_add_f32_e32 v58, v58, v59
	s_nop 1
	v_mov_b32_dpp v59, v58 row_half_mirror row_mask:0xf bank_mask:0xf
	v_ashrrev_i32_e32 v3, 31, v2
	v_lshl_add_u64 v[2:3], v[2:3], 1, s[22:23]
	v_add_u32_e32 v62, 0x480, v61
	global_store_short v[2:3], v60, off sc1
	s_waitcnt lgkmcnt(0)
	v_add_f32_e32 v58, v58, v59
	s_nop 1
	v_mov_b32_dpp v59, v58 row_mirror row_mask:0xf bank_mask:0xf
	v_add_u32_e32 v2, v62, v174
	v_ashrrev_i32_e32 v3, 31, v2
	v_lshl_add_u64 v[2:3], v[2:3], 1, s[22:23]
	global_store_short v[2:3], v15, off sc1
	v_add_u32_e32 v2, v62, v175
	s_waitcnt lgkmcnt(0)
	v_add_f32_e32 v58, v58, v59
	v_ashrrev_i32_e32 v3, 31, v2
	v_mov_b32_e32 v59, v58
	s_nop 1
	v_permlane16_swap_b32_e32 v58, v59
	s_nop 0
	v_lshl_add_u64 v[2:3], v[2:3], 1, s[22:23]
	v_add_u32_e32 v61, 0x540, v61
	global_store_short v[2:3], v60, off sc1
	v_or_b32_e32 v2, v61, v174
	v_ashrrev_i32_e32 v3, 31, v2
	v_lshl_add_u64 v[2:3], v[2:3], 1, s[22:23]
	global_store_short v[2:3], v15, off sc1
	s_waitcnt lgkmcnt(0)
	v_add_f32_e32 v3, v58, v59
	v_fmamk_f32 v3, v3, 0x3c800000, v209
	v_rsq_f32_e32 v58, v3
	v_or_b32_e32 v2, v61, v175
	v_ashrrev_i32_e32 v3, 31, v2
	v_lshl_add_u64 v[2:3], v[2:3], 1, s[22:23]
	global_store_short v[2:3], v60, off sc1
	v_pk_mul_f32 v[2:3], v[0:1], v[58:59] op_sel_hi:[1,0]
	s_and_b64 vcc, exec, s[4:5]
	v_pk_mul_f32 v[2:3], v[66:67], v[2:3]
	s_mov_b64 s[80:81], -1
	s_cbranch_vccnz .LBB0_290
	v_add_u32_e32 v15, s76, v180
	v_lshl_or_b32 v58, v15, 6, v156
	v_ashrrev_i32_e32 v59, 31, v58
	v_lshl_add_u64 v[58:59], v[58:59], 2, s[24:25]
	s_mov_b64 s[80:81], 0
	global_store_dword v[58:59], v3, off sc1
	global_store_dword v[58:59], v2, off offset:128 sc1

.LBB0_292:
	v_cvt_pk_bf16_f32 v60, v2, s0
	v_add_u32_e32 v2, s11, v180
	v_mul_lo_u32 v61, v2, s94
	v_or_b32_e32 v2, v61, v174
	v_cvt_pk_bf16_f32 v15, v3, s0
	v_ashrrev_i32_e32 v3, 31, v2
	v_lshl_add_u64 v[2:3], v[2:3], 1, s[22:23]
	global_store_short v[2:3], v15, off sc1
	v_or_b32_e32 v2, v61, v175
	v_ashrrev_i32_e32 v3, 31, v2
	v_lshl_add_u64 v[2:3], v[2:3], 1, s[22:23]
	v_or_b32_e32 v58, 0xc0, v61
	global_store_short v[2:3], v60, off sc1
	v_add_u32_e32 v2, v58, v174
	v_ashrrev_i32_e32 v3, 31, v2
	v_lshl_add_u64 v[2:3], v[2:3], 1, s[22:23]
	global_store_short v[2:3], v15, off sc1
	v_add_u32_e32 v2, v58, v175
	v_ashrrev_i32_e32 v3, 31, v2
	v_lshl_add_u64 v[2:3], v[2:3], 1, s[22:23]
	v_or_b32_e32 v58, 0x180, v61
	global_store_short v[2:3], v60, off sc1
	v_add_u32_e32 v2, v58, v174
	v_ashrrev_i32_e32 v3, 31, v2
	v_lshl_add_u64 v[2:3], v[2:3], 1, s[22:23]
	global_store_short v[2:3], v15, off sc1
	v_add_u32_e32 v2, v58, v175
	v_ashrrev_i32_e32 v3, 31, v2
	v_lshl_add_u64 v[2:3], v[2:3], 1, s[22:23]
	v_add_u32_e32 v58, 0x240, v61
	global_store_short v[2:3], v60, off sc1
	v_or_b32_e32 v2, v58, v174
	v_ashrrev_i32_e32 v3, 31, v2
	v_lshl_add_u64 v[2:3], v[2:3], 1, s[22:23]
	global_store_short v[2:3], v15, off sc1
	v_or_b32_e32 v2, v58, v175
	v_ashrrev_i32_e32 v3, 31, v2
	v_lshl_add_u64 v[2:3], v[2:3], 1, s[22:23]
	v_add_u32_e32 v58, 0x300, v61
	global_store_short v[2:3], v60, off sc1
	v_or_b32_e32 v2, v58, v174
	v_ashrrev_i32_e32 v3, 31, v2
	v_lshl_add_u64 v[2:3], v[2:3], 1, s[22:23]
	global_store_short v[2:3], v15, off sc1
	v_or_b32_e32 v2, v58, v175
	v_pk_mul_f32 v[58:59], v[64:65], v[64:65]
	v_ashrrev_i32_e32 v3, 31, v2
	v_add_f32_e32 v58, v59, v58
	s_nop 1
	v_mov_b32_dpp v59, v58 quad_perm:[1,0,3,2] row_mask:0xf bank_mask:0xf
	v_lshl_add_u64 v[2:3], v[2:3], 1, s[22:23]
	v_add_u32_e32 v62, 0x3c0, v61
	global_store_short v[2:3], v60, off sc1
	v_add_u32_e32 v2, v62, v174
	s_waitcnt lgkmcnt(0)
	v_add_f32_e32 v58, v58, v59
	s_nop 1
	v_mov_b32_dpp v59, v58 quad_perm:[2,3,0,1] row_mask:0xf bank_mask:0xf
	v_ashrrev_i32_e32 v3, 31, v2
	v_lshl_add_u64 v[2:3], v[2:3], 1, s[22:23]
	global_store_short v[2:3], v15, off sc1
	v_add_u32_e32 v2, v62, v175
	s_waitcnt lgkmcnt(0)
	v_add_f32_e32 v58, v58, v59
	s_nop 1
	v_mov_b32_dpp v59, v58 row_half_mirror row_mask:0xf bank_mask:0xf
	v_ashrrev_i32_e32 v3, 31, v2
	v_lshl_add_u64 v[2:3], v[2:3], 1, s[22:23]
	v_add_u32_e32 v62, 0x480, v61
	global_store_short v[2:3], v60, off sc1
	s_waitcnt lgkmcnt(0)
	v_add_f32_e32 v58, v58, v59
	s_nop 1
	v_mov_b32_dpp v59, v58 row_mirror row_mask:0xf bank_mask:0xf
	v_add_u32_e32 v2, v62, v174
	v_ashrrev_i32_e32 v3, 31, v2
	v_lshl_add_u64 v[2:3], v[2:3], 1, s[22:23]
	global_store_short v[2:3], v15, off sc1
	v_add_u32_e32 v2, v62, v175
	s_waitcnt lgkmcnt(0)
	v_add_f32_e32 v58, v58, v59
	v_ashrrev_i32_e32 v3, 31, v2
	v_mov_b32_e32 v59, v58
	s_nop 1
	v_permlane16_swap_b32_e32 v58, v59
	s_nop 0
	v_lshl_add_u64 v[2:3], v[2:3], 1, s[22:23]
	v_add_u32_e32 v61, 0x540, v61
	global_store_short v[2:3], v60, off sc1
	v_or_b32_e32 v2, v61, v174
	v_ashrrev_i32_e32 v3, 31, v2
	v_lshl_add_u64 v[2:3], v[2:3], 1, s[22:23]
	global_store_short v[2:3], v15, off sc1
	s_waitcnt lgkmcnt(0)
	v_add_f32_e32 v3, v58, v59
	v_fmamk_f32 v3, v3, 0x3c800000, v209
	v_rsq_f32_e32 v58, v3
	v_or_b32_e32 v2, v61, v175
	v_ashrrev_i32_e32 v3, 31, v2
	v_lshl_add_u64 v[2:3], v[2:3], 1, s[22:23]
	global_store_short v[2:3], v60, off sc1
	v_pk_mul_f32 v[2:3], v[0:1], v[58:59] op_sel_hi:[1,0]
	s_and_b64 vcc, exec, s[4:5]
	v_pk_mul_f32 v[2:3], v[64:65], v[2:3]
	s_mov_b64 s[80:81], -1
	s_cbranch_vccnz .LBB0_294
	v_add_u32_e32 v15, s76, v181
	v_lshl_or_b32 v58, v15, 6, v156
	v_ashrrev_i32_e32 v59, 31, v58
	v_lshl_add_u64 v[58:59], v[58:59], 2, s[24:25]
	s_mov_b64 s[80:81], 0
	global_store_dword v[58:59], v3, off sc1
	global_store_dword v[58:59], v2, off offset:128 sc1

.LBB0_296:
	v_cvt_pk_bf16_f32 v60, v2, s0
	v_add_u32_e32 v2, s11, v181
	v_mul_lo_u32 v61, v2, s94
	v_or_b32_e32 v2, v61, v174
	v_cvt_pk_bf16_f32 v15, v3, s0
	v_ashrrev_i32_e32 v3, 31, v2
	v_lshl_add_u64 v[2:3], v[2:3], 1, s[22:23]
	global_store_short v[2:3], v15, off sc1
	v_or_b32_e32 v2, v61, v175
	v_ashrrev_i32_e32 v3, 31, v2
	v_lshl_add_u64 v[2:3], v[2:3], 1, s[22:23]
	v_or_b32_e32 v58, 0xc0, v61
	global_store_short v[2:3], v60, off sc1
	v_add_u32_e32 v2, v58, v174
	v_ashrrev_i32_e32 v3, 31, v2
	v_lshl_add_u64 v[2:3], v[2:3], 1, s[22:23]
	global_store_short v[2:3], v15, off sc1
	v_add_u32_e32 v2, v58, v175
	v_ashrrev_i32_e32 v3, 31, v2
	v_lshl_add_u64 v[2:3], v[2:3], 1, s[22:23]
	v_or_b32_e32 v58, 0x180, v61
	global_store_short v[2:3], v60, off sc1
	v_add_u32_e32 v2, v58, v174
	v_ashrrev_i32_e32 v3, 31, v2
	v_lshl_add_u64 v[2:3], v[2:3], 1, s[22:23]
	global_store_short v[2:3], v15, off sc1
	v_add_u32_e32 v2, v58, v175
	v_ashrrev_i32_e32 v3, 31, v2
	v_lshl_add_u64 v[2:3], v[2:3], 1, s[22:23]
	v_add_u32_e32 v58, 0x240, v61
	global_store_short v[2:3], v60, off sc1
	v_or_b32_e32 v2, v58, v174
	v_ashrrev_i32_e32 v3, 31, v2
	v_lshl_add_u64 v[2:3], v[2:3], 1, s[22:23]
	global_store_short v[2:3], v15, off sc1
	v_or_b32_e32 v2, v58, v175
	v_ashrrev_i32_e32 v3, 31, v2
	v_lshl_add_u64 v[2:3], v[2:3], 1, s[22:23]
	v_add_u32_e32 v58, 0x300, v61
	global_store_short v[2:3], v60, off sc1
	v_or_b32_e32 v2, v58, v174
	v_ashrrev_i32_e32 v3, 31, v2
	v_lshl_add_u64 v[2:3], v[2:3], 1, s[22:23]
	global_store_short v[2:3], v15, off sc1
	v_or_b32_e32 v2, v58, v175
	v_pk_mul_f32 v[58:59], v[54:55], v[54:55]
	v_ashrrev_i32_e32 v3, 31, v2
	v_add_f32_e32 v58, v59, v58
	s_nop 1
	v_mov_b32_dpp v59, v58 quad_perm:[1,0,3,2] row_mask:0xf bank_mask:0xf
	v_lshl_add_u64 v[2:3], v[2:3], 1, s[22:23]
	v_add_u32_e32 v62, 0x3c0, v61
	global_store_short v[2:3], v60, off sc1
	v_add_u32_e32 v2, v62, v174
	s_waitcnt lgkmcnt(0)
	v_add_f32_e32 v58, v58, v59
	s_nop 1
	v_mov_b32_dpp v59, v58 quad_perm:[2,3,0,1] row_mask:0xf bank_mask:0xf
	v_ashrrev_i32_e32 v3, 31, v2
	v_lshl_add_u64 v[2:3], v[2:3], 1, s[22:23]
	global_store_short v[2:3], v15, off sc1
	v_add_u32_e32 v2, v62, v175
	s_waitcnt lgkmcnt(0)
	v_add_f32_e32 v58, v58, v59
	s_nop 1
	v_mov_b32_dpp v59, v58 row_half_mirror row_mask:0xf bank_mask:0xf
	v_ashrrev_i32_e32 v3, 31, v2
	v_lshl_add_u64 v[2:3], v[2:3], 1, s[22:23]
	v_add_u32_e32 v62, 0x480, v61
	global_store_short v[2:3], v60, off sc1
	s_waitcnt lgkmcnt(0)
	v_add_f32_e32 v58, v58, v59
	s_nop 1
	v_mov_b32_dpp v59, v58 row_mirror row_mask:0xf bank_mask:0xf
	v_add_u32_e32 v2, v62, v174
	v_ashrrev_i32_e32 v3, 31, v2
	v_lshl_add_u64 v[2:3], v[2:3], 1, s[22:23]
	global_store_short v[2:3], v15, off sc1
	v_add_u32_e32 v2, v62, v175
	s_waitcnt lgkmcnt(0)
	v_add_f32_e32 v58, v58, v59
	v_ashrrev_i32_e32 v3, 31, v2
	v_mov_b32_e32 v59, v58
	s_nop 1
	v_permlane16_swap_b32_e32 v58, v59
	s_nop 0
	v_lshl_add_u64 v[2:3], v[2:3], 1, s[22:23]
	v_add_u32_e32 v61, 0x540, v61
	global_store_short v[2:3], v60, off sc1
	v_or_b32_e32 v2, v61, v174
	v_ashrrev_i32_e32 v3, 31, v2
	v_lshl_add_u64 v[2:3], v[2:3], 1, s[22:23]
	global_store_short v[2:3], v15, off sc1
	s_waitcnt lgkmcnt(0)
	v_add_f32_e32 v3, v58, v59
	v_fmamk_f32 v3, v3, 0x3c800000, v209
	v_rsq_f32_e32 v58, v3
	v_or_b32_e32 v2, v61, v175
	v_ashrrev_i32_e32 v3, 31, v2
	v_lshl_add_u64 v[2:3], v[2:3], 1, s[22:23]
	global_store_short v[2:3], v60, off sc1
	v_pk_mul_f32 v[2:3], v[0:1], v[58:59] op_sel_hi:[1,0]
	s_and_b64 vcc, exec, s[4:5]
	v_pk_mul_f32 v[2:3], v[54:55], v[2:3]
	s_mov_b64 s[80:81], -1
	s_cbranch_vccnz .LBB0_298
	v_add_u32_e32 v15, s76, v182
	v_lshl_or_b32 v58, v15, 6, v156
	v_ashrrev_i32_e32 v59, 31, v58
	v_lshl_add_u64 v[58:59], v[58:59], 2, s[24:25]
	s_mov_b64 s[80:81], 0
	global_store_dword v[58:59], v3, off sc1
	global_store_dword v[58:59], v2, off offset:128 sc1

.LBB0_300:
	v_cvt_pk_bf16_f32 v60, v2, s0
	v_add_u32_e32 v2, s11, v182
	v_mul_lo_u32 v61, v2, s94
	v_or_b32_e32 v2, v61, v174
	v_cvt_pk_bf16_f32 v15, v3, s0
	v_ashrrev_i32_e32 v3, 31, v2
	v_lshl_add_u64 v[2:3], v[2:3], 1, s[22:23]
	global_store_short v[2:3], v15, off sc1
	v_or_b32_e32 v2, v61, v175
	v_ashrrev_i32_e32 v3, 31, v2
	v_lshl_add_u64 v[2:3], v[2:3], 1, s[22:23]
	v_or_b32_e32 v58, 0xc0, v61
	global_store_short v[2:3], v60, off sc1
	v_add_u32_e32 v2, v58, v174
	v_ashrrev_i32_e32 v3, 31, v2
	v_lshl_add_u64 v[2:3], v[2:3], 1, s[22:23]
	global_store_short v[2:3], v15, off sc1
	v_add_u32_e32 v2, v58, v175
	v_ashrrev_i32_e32 v3, 31, v2
	v_lshl_add_u64 v[2:3], v[2:3], 1, s[22:23]
	v_or_b32_e32 v58, 0x180, v61
	global_store_short v[2:3], v60, off sc1
	v_add_u32_e32 v2, v58, v174
	v_ashrrev_i32_e32 v3, 31, v2
	v_lshl_add_u64 v[2:3], v[2:3], 1, s[22:23]
	global_store_short v[2:3], v15, off sc1
	v_add_u32_e32 v2, v58, v175
	v_ashrrev_i32_e32 v3, 31, v2
	v_lshl_add_u64 v[2:3], v[2:3], 1, s[22:23]
	v_add_u32_e32 v58, 0x240, v61
	global_store_short v[2:3], v60, off sc1
	v_or_b32_e32 v2, v58, v174
	v_ashrrev_i32_e32 v3, 31, v2
	v_lshl_add_u64 v[2:3], v[2:3], 1, s[22:23]
	global_store_short v[2:3], v15, off sc1
	v_or_b32_e32 v2, v58, v175
	v_ashrrev_i32_e32 v3, 31, v2
	v_lshl_add_u64 v[2:3], v[2:3], 1, s[22:23]
	v_add_u32_e32 v58, 0x300, v61
	global_store_short v[2:3], v60, off sc1
	v_or_b32_e32 v2, v58, v174
	v_ashrrev_i32_e32 v3, 31, v2
	v_lshl_add_u64 v[2:3], v[2:3], 1, s[22:23]
	global_store_short v[2:3], v15, off sc1
	v_or_b32_e32 v2, v58, v175
	v_pk_mul_f32 v[58:59], v[52:53], v[52:53]
	v_ashrrev_i32_e32 v3, 31, v2
	v_add_f32_e32 v58, v59, v58
	s_nop 1
	v_mov_b32_dpp v59, v58 quad_perm:[1,0,3,2] row_mask:0xf bank_mask:0xf
	v_lshl_add_u64 v[2:3], v[2:3], 1, s[22:23]
	v_add_u32_e32 v62, 0x3c0, v61
	global_store_short v[2:3], v60, off sc1
	v_add_u32_e32 v2, v62, v174
	s_waitcnt lgkmcnt(0)
	v_add_f32_e32 v58, v58, v59
	s_nop 1
	v_mov_b32_dpp v59, v58 quad_perm:[2,3,0,1] row_mask:0xf bank_mask:0xf
	v_ashrrev_i32_e32 v3, 31, v2
	v_lshl_add_u64 v[2:3], v[2:3], 1, s[22:23]
	global_store_short v[2:3], v15, off sc1
	v_add_u32_e32 v2, v62, v175
	s_waitcnt lgkmcnt(0)
	v_add_f32_e32 v58, v58, v59
	s_nop 1
	v_mov_b32_dpp v59, v58 row_half_mirror row_mask:0xf bank_mask:0xf
	v_ashrrev_i32_e32 v3, 31, v2
	v_lshl_add_u64 v[2:3], v[2:3], 1, s[22:23]
	v_add_u32_e32 v62, 0x480, v61
	global_store_short v[2:3], v60, off sc1
	s_waitcnt lgkmcnt(0)
	v_add_f32_e32 v58, v58, v59
	s_nop 1
	v_mov_b32_dpp v59, v58 row_mirror row_mask:0xf bank_mask:0xf
	v_add_u32_e32 v2, v62, v174
	v_ashrrev_i32_e32 v3, 31, v2
	v_lshl_add_u64 v[2:3], v[2:3], 1, s[22:23]
	global_store_short v[2:3], v15, off sc1
	v_add_u32_e32 v2, v62, v175
	s_waitcnt lgkmcnt(0)
	v_add_f32_e32 v58, v58, v59
	v_ashrrev_i32_e32 v3, 31, v2
	v_mov_b32_e32 v59, v58
	s_nop 1
	v_permlane16_swap_b32_e32 v58, v59
	s_nop 0
	v_lshl_add_u64 v[2:3], v[2:3], 1, s[22:23]
	v_add_u32_e32 v61, 0x540, v61
	global_store_short v[2:3], v60, off sc1
	v_or_b32_e32 v2, v61, v174
	v_ashrrev_i32_e32 v3, 31, v2
	v_lshl_add_u64 v[2:3], v[2:3], 1, s[22:23]
	global_store_short v[2:3], v15, off sc1
	s_waitcnt lgkmcnt(0)
	v_add_f32_e32 v3, v58, v59
	v_fmamk_f32 v3, v3, 0x3c800000, v209
	v_rsq_f32_e32 v58, v3
	v_or_b32_e32 v2, v61, v175
	v_ashrrev_i32_e32 v3, 31, v2
	v_lshl_add_u64 v[2:3], v[2:3], 1, s[22:23]
	global_store_short v[2:3], v60, off sc1
	v_pk_mul_f32 v[2:3], v[0:1], v[58:59] op_sel_hi:[1,0]
	s_and_b64 vcc, exec, s[4:5]
	v_pk_mul_f32 v[2:3], v[52:53], v[2:3]
	s_mov_b64 s[80:81], -1
	s_cbranch_vccnz .LBB0_302
	v_add_u32_e32 v15, s76, v183
	v_lshl_or_b32 v58, v15, 6, v156
	v_ashrrev_i32_e32 v59, 31, v58
	v_lshl_add_u64 v[58:59], v[58:59], 2, s[24:25]
	s_mov_b64 s[80:81], 0
	global_store_dword v[58:59], v3, off sc1
	global_store_dword v[58:59], v2, off offset:128 sc1

.LBB0_304:
	v_cvt_pk_bf16_f32 v60, v2, s0
	v_add_u32_e32 v2, s11, v183
	v_mul_lo_u32 v61, v2, s94
	v_or_b32_e32 v2, v61, v174
	v_cvt_pk_bf16_f32 v15, v3, s0
	v_ashrrev_i32_e32 v3, 31, v2
	v_lshl_add_u64 v[2:3], v[2:3], 1, s[22:23]
	global_store_short v[2:3], v15, off sc1
	v_or_b32_e32 v2, v61, v175
	v_ashrrev_i32_e32 v3, 31, v2
	v_lshl_add_u64 v[2:3], v[2:3], 1, s[22:23]
	v_or_b32_e32 v58, 0xc0, v61
	global_store_short v[2:3], v60, off sc1
	v_add_u32_e32 v2, v58, v174
	v_ashrrev_i32_e32 v3, 31, v2
	v_lshl_add_u64 v[2:3], v[2:3], 1, s[22:23]
	global_store_short v[2:3], v15, off sc1
	v_add_u32_e32 v2, v58, v175
	v_ashrrev_i32_e32 v3, 31, v2
	v_lshl_add_u64 v[2:3], v[2:3], 1, s[22:23]
	v_or_b32_e32 v58, 0x180, v61
	global_store_short v[2:3], v60, off sc1
	v_add_u32_e32 v2, v58, v174
	v_ashrrev_i32_e32 v3, 31, v2
	v_lshl_add_u64 v[2:3], v[2:3], 1, s[22:23]
	global_store_short v[2:3], v15, off sc1
	v_add_u32_e32 v2, v58, v175
	v_ashrrev_i32_e32 v3, 31, v2
	v_lshl_add_u64 v[2:3], v[2:3], 1, s[22:23]
	v_add_u32_e32 v58, 0x240, v61
	global_store_short v[2:3], v60, off sc1
	v_or_b32_e32 v2, v58, v174
	v_ashrrev_i32_e32 v3, 31, v2
	v_lshl_add_u64 v[2:3], v[2:3], 1, s[22:23]
	global_store_short v[2:3], v15, off sc1
	v_or_b32_e32 v2, v58, v175
	v_ashrrev_i32_e32 v3, 31, v2
	v_lshl_add_u64 v[2:3], v[2:3], 1, s[22:23]
	v_add_u32_e32 v58, 0x300, v61
	global_store_short v[2:3], v60, off sc1
	v_or_b32_e32 v2, v58, v174
	v_ashrrev_i32_e32 v3, 31, v2
	v_lshl_add_u64 v[2:3], v[2:3], 1, s[22:23]
	global_store_short v[2:3], v15, off sc1
	v_or_b32_e32 v2, v58, v175
	v_pk_mul_f32 v[58:59], v[50:51], v[50:51]
	v_ashrrev_i32_e32 v3, 31, v2
	v_add_f32_e32 v58, v59, v58
	s_nop 1
	v_mov_b32_dpp v59, v58 quad_perm:[1,0,3,2] row_mask:0xf bank_mask:0xf
	v_lshl_add_u64 v[2:3], v[2:3], 1, s[22:23]
	v_add_u32_e32 v62, 0x3c0, v61
	global_store_short v[2:3], v60, off sc1
	v_add_u32_e32 v2, v62, v174
	s_waitcnt lgkmcnt(0)
	v_add_f32_e32 v58, v58, v59
	s_nop 1
	v_mov_b32_dpp v59, v58 quad_perm:[2,3,0,1] row_mask:0xf bank_mask:0xf
	v_ashrrev_i32_e32 v3, 31, v2
	v_lshl_add_u64 v[2:3], v[2:3], 1, s[22:23]
	global_store_short v[2:3], v15, off sc1
	v_add_u32_e32 v2, v62, v175
	s_waitcnt lgkmcnt(0)
	v_add_f32_e32 v58, v58, v59
	s_nop 1
	v_mov_b32_dpp v59, v58 row_half_mirror row_mask:0xf bank_mask:0xf
	v_ashrrev_i32_e32 v3, 31, v2
	v_lshl_add_u64 v[2:3], v[2:3], 1, s[22:23]
	v_add_u32_e32 v62, 0x480, v61
	global_store_short v[2:3], v60, off sc1
	s_waitcnt lgkmcnt(0)
	v_add_f32_e32 v58, v58, v59
	s_nop 1
	v_mov_b32_dpp v59, v58 row_mirror row_mask:0xf bank_mask:0xf
	v_add_u32_e32 v2, v62, v174
	v_ashrrev_i32_e32 v3, 31, v2
	v_lshl_add_u64 v[2:3], v[2:3], 1, s[22:23]
	global_store_short v[2:3], v15, off sc1
	v_add_u32_e32 v2, v62, v175
	s_waitcnt lgkmcnt(0)
	v_add_f32_e32 v58, v58, v59
	v_ashrrev_i32_e32 v3, 31, v2
	v_mov_b32_e32 v59, v58
	s_nop 1
	v_permlane16_swap_b32_e32 v58, v59
	s_nop 0
	v_lshl_add_u64 v[2:3], v[2:3], 1, s[22:23]
	v_add_u32_e32 v61, 0x540, v61
	global_store_short v[2:3], v60, off sc1
	v_or_b32_e32 v2, v61, v174
	v_ashrrev_i32_e32 v3, 31, v2
	v_lshl_add_u64 v[2:3], v[2:3], 1, s[22:23]
	global_store_short v[2:3], v15, off sc1
	s_waitcnt lgkmcnt(0)
	v_add_f32_e32 v3, v58, v59
	v_fmamk_f32 v3, v3, 0x3c800000, v209
	v_rsq_f32_e32 v58, v3
	v_or_b32_e32 v2, v61, v175
	v_ashrrev_i32_e32 v3, 31, v2
	v_lshl_add_u64 v[2:3], v[2:3], 1, s[22:23]
	global_store_short v[2:3], v60, off sc1
	v_pk_mul_f32 v[2:3], v[0:1], v[58:59] op_sel_hi:[1,0]
	s_and_b64 vcc, exec, s[4:5]
	v_pk_mul_f32 v[2:3], v[50:51], v[2:3]
	s_mov_b64 s[80:81], -1
	s_cbranch_vccnz .LBB0_306
	v_add_u32_e32 v15, s76, v184
	v_lshl_or_b32 v58, v15, 6, v156
	v_ashrrev_i32_e32 v59, 31, v58
	v_lshl_add_u64 v[58:59], v[58:59], 2, s[24:25]
	s_mov_b64 s[80:81], 0
	global_store_dword v[58:59], v3, off sc1
	global_store_dword v[58:59], v2, off offset:128 sc1

.LBB0_308:
	v_cvt_pk_bf16_f32 v60, v2, s0
	v_add_u32_e32 v2, s11, v184
	v_mul_lo_u32 v61, v2, s94
	v_or_b32_e32 v2, v61, v174
	v_cvt_pk_bf16_f32 v15, v3, s0
	v_ashrrev_i32_e32 v3, 31, v2
	v_lshl_add_u64 v[2:3], v[2:3], 1, s[22:23]
	global_store_short v[2:3], v15, off sc1
	v_or_b32_e32 v2, v61, v175
	v_ashrrev_i32_e32 v3, 31, v2
	v_lshl_add_u64 v[2:3], v[2:3], 1, s[22:23]
	v_or_b32_e32 v58, 0xc0, v61
	global_store_short v[2:3], v60, off sc1
	v_add_u32_e32 v2, v58, v174
	v_ashrrev_i32_e32 v3, 31, v2
	v_lshl_add_u64 v[2:3], v[2:3], 1, s[22:23]
	global_store_short v[2:3], v15, off sc1
	v_add_u32_e32 v2, v58, v175
	v_ashrrev_i32_e32 v3, 31, v2
	v_lshl_add_u64 v[2:3], v[2:3], 1, s[22:23]
	v_or_b32_e32 v58, 0x180, v61
	global_store_short v[2:3], v60, off sc1
	v_add_u32_e32 v2, v58, v174
	v_ashrrev_i32_e32 v3, 31, v2
	v_lshl_add_u64 v[2:3], v[2:3], 1, s[22:23]
	global_store_short v[2:3], v15, off sc1
	v_add_u32_e32 v2, v58, v175
	v_ashrrev_i32_e32 v3, 31, v2
	v_lshl_add_u64 v[2:3], v[2:3], 1, s[22:23]
	v_add_u32_e32 v58, 0x240, v61
	global_store_short v[2:3], v60, off sc1
	v_or_b32_e32 v2, v58, v174
	v_ashrrev_i32_e32 v3, 31, v2
	v_lshl_add_u64 v[2:3], v[2:3], 1, s[22:23]
	global_store_short v[2:3], v15, off sc1
	v_or_b32_e32 v2, v58, v175
	v_ashrrev_i32_e32 v3, 31, v2
	v_lshl_add_u64 v[2:3], v[2:3], 1, s[22:23]
	v_add_u32_e32 v58, 0x300, v61
	global_store_short v[2:3], v60, off sc1
	v_or_b32_e32 v2, v58, v174
	v_ashrrev_i32_e32 v3, 31, v2
	v_lshl_add_u64 v[2:3], v[2:3], 1, s[22:23]
	global_store_short v[2:3], v15, off sc1
	v_or_b32_e32 v2, v58, v175
	v_pk_mul_f32 v[58:59], v[48:49], v[48:49]
	v_ashrrev_i32_e32 v3, 31, v2
	v_add_f32_e32 v58, v59, v58
	s_nop 1
	v_mov_b32_dpp v59, v58 quad_perm:[1,0,3,2] row_mask:0xf bank_mask:0xf
	v_lshl_add_u64 v[2:3], v[2:3], 1, s[22:23]
	v_add_u32_e32 v62, 0x3c0, v61
	global_store_short v[2:3], v60, off sc1
	v_add_u32_e32 v2, v62, v174
	s_waitcnt lgkmcnt(0)
	v_add_f32_e32 v58, v58, v59
	s_nop 1
	v_mov_b32_dpp v59, v58 quad_perm:[2,3,0,1] row_mask:0xf bank_mask:0xf
	v_ashrrev_i32_e32 v3, 31, v2
	v_lshl_add_u64 v[2:3], v[2:3], 1, s[22:23]
	global_store_short v[2:3], v15, off sc1
	v_add_u32_e32 v2, v62, v175
	s_waitcnt lgkmcnt(0)
	v_add_f32_e32 v58, v58, v59
	s_nop 1
	v_mov_b32_dpp v59, v58 row_half_mirror row_mask:0xf bank_mask:0xf
	v_ashrrev_i32_e32 v3, 31, v2
	v_lshl_add_u64 v[2:3], v[2:3], 1, s[22:23]
	v_add_u32_e32 v62, 0x480, v61
	global_store_short v[2:3], v60, off sc1
	s_waitcnt lgkmcnt(0)
	v_add_f32_e32 v58, v58, v59
	s_nop 1
	v_mov_b32_dpp v59, v58 row_mirror row_mask:0xf bank_mask:0xf
	v_add_u32_e32 v2, v62, v174
	v_ashrrev_i32_e32 v3, 31, v2
	v_lshl_add_u64 v[2:3], v[2:3], 1, s[22:23]
	global_store_short v[2:3], v15, off sc1
	v_add_u32_e32 v2, v62, v175
	s_waitcnt lgkmcnt(0)
	v_add_f32_e32 v58, v58, v59
	v_ashrrev_i32_e32 v3, 31, v2
	v_mov_b32_e32 v59, v58
	s_nop 1
	v_permlane16_swap_b32_e32 v58, v59
	s_nop 0
	v_lshl_add_u64 v[2:3], v[2:3], 1, s[22:23]
	v_add_u32_e32 v61, 0x540, v61
	global_store_short v[2:3], v60, off sc1
	v_or_b32_e32 v2, v61, v174
	v_ashrrev_i32_e32 v3, 31, v2
	v_lshl_add_u64 v[2:3], v[2:3], 1, s[22:23]
	global_store_short v[2:3], v15, off sc1
	s_waitcnt lgkmcnt(0)
	v_add_f32_e32 v3, v58, v59
	v_fmamk_f32 v3, v3, 0x3c800000, v209
	v_rsq_f32_e32 v58, v3
	v_or_b32_e32 v2, v61, v175
	v_ashrrev_i32_e32 v3, 31, v2
	v_lshl_add_u64 v[2:3], v[2:3], 1, s[22:23]
	global_store_short v[2:3], v60, off sc1
	v_pk_mul_f32 v[2:3], v[0:1], v[58:59] op_sel_hi:[1,0]
	s_and_b64 vcc, exec, s[4:5]
	v_pk_mul_f32 v[2:3], v[48:49], v[2:3]
	s_mov_b64 s[80:81], -1
	s_cbranch_vccnz .LBB0_310
	v_add_u32_e32 v15, s76, v185
	v_lshl_or_b32 v58, v15, 6, v156
	v_ashrrev_i32_e32 v59, 31, v58
	v_lshl_add_u64 v[58:59], v[58:59], 2, s[24:25]
	s_mov_b64 s[80:81], 0
	global_store_dword v[58:59], v3, off sc1
	global_store_dword v[58:59], v2, off offset:128 sc1

.LBB0_312:
	v_cvt_pk_bf16_f32 v60, v2, s0
	v_add_u32_e32 v2, s11, v185
	v_mul_lo_u32 v61, v2, s94
	v_or_b32_e32 v2, v61, v174
	v_cvt_pk_bf16_f32 v15, v3, s0
	v_ashrrev_i32_e32 v3, 31, v2
	v_lshl_add_u64 v[2:3], v[2:3], 1, s[22:23]
	global_store_short v[2:3], v15, off sc1
	v_or_b32_e32 v2, v61, v175
	v_ashrrev_i32_e32 v3, 31, v2
	v_lshl_add_u64 v[2:3], v[2:3], 1, s[22:23]
	v_or_b32_e32 v58, 0xc0, v61
	global_store_short v[2:3], v60, off sc1
	v_add_u32_e32 v2, v58, v174
	v_ashrrev_i32_e32 v3, 31, v2
	v_lshl_add_u64 v[2:3], v[2:3], 1, s[22:23]
	global_store_short v[2:3], v15, off sc1
	v_add_u32_e32 v2, v58, v175
	v_ashrrev_i32_e32 v3, 31, v2
	v_lshl_add_u64 v[2:3], v[2:3], 1, s[22:23]
	v_or_b32_e32 v58, 0x180, v61
	global_store_short v[2:3], v60, off sc1
	v_add_u32_e32 v2, v58, v174
	v_ashrrev_i32_e32 v3, 31, v2
	v_lshl_add_u64 v[2:3], v[2:3], 1, s[22:23]
	global_store_short v[2:3], v15, off sc1
	v_add_u32_e32 v2, v58, v175
	v_ashrrev_i32_e32 v3, 31, v2
	v_lshl_add_u64 v[2:3], v[2:3], 1, s[22:23]
	v_add_u32_e32 v58, 0x240, v61
	global_store_short v[2:3], v60, off sc1
	v_or_b32_e32 v2, v58, v174
	v_ashrrev_i32_e32 v3, 31, v2
	v_lshl_add_u64 v[2:3], v[2:3], 1, s[22:23]
	global_store_short v[2:3], v15, off sc1
	v_or_b32_e32 v2, v58, v175
	v_ashrrev_i32_e32 v3, 31, v2
	v_lshl_add_u64 v[2:3], v[2:3], 1, s[22:23]
	v_add_u32_e32 v58, 0x300, v61
	global_store_short v[2:3], v60, off sc1
	v_or_b32_e32 v2, v58, v174
	v_ashrrev_i32_e32 v3, 31, v2
	v_lshl_add_u64 v[2:3], v[2:3], 1, s[22:23]
	global_store_short v[2:3], v15, off sc1
	v_or_b32_e32 v2, v58, v175
	v_pk_mul_f32 v[58:59], v[40:41], v[40:41]
	v_ashrrev_i32_e32 v3, 31, v2
	v_add_f32_e32 v58, v59, v58
	s_nop 1
	v_mov_b32_dpp v59, v58 quad_perm:[1,0,3,2] row_mask:0xf bank_mask:0xf
	v_lshl_add_u64 v[2:3], v[2:3], 1, s[22:23]
	v_add_u32_e32 v62, 0x3c0, v61
	global_store_short v[2:3], v60, off sc1
	v_add_u32_e32 v2, v62, v174
	s_waitcnt lgkmcnt(0)
	v_add_f32_e32 v58, v58, v59
	s_nop 1
	v_mov_b32_dpp v59, v58 quad_perm:[2,3,0,1] row_mask:0xf bank_mask:0xf
	v_ashrrev_i32_e32 v3, 31, v2
	v_lshl_add_u64 v[2:3], v[2:3], 1, s[22:23]
	global_store_short v[2:3], v15, off sc1
	v_add_u32_e32 v2, v62, v175
	s_waitcnt lgkmcnt(0)
	v_add_f32_e32 v58, v58, v59
	s_nop 1
	v_mov_b32_dpp v59, v58 row_half_mirror row_mask:0xf bank_mask:0xf
	v_ashrrev_i32_e32 v3, 31, v2
	v_lshl_add_u64 v[2:3], v[2:3], 1, s[22:23]
	v_add_u32_e32 v62, 0x480, v61
	global_store_short v[2:3], v60, off sc1
	s_waitcnt lgkmcnt(0)
	v_add_f32_e32 v58, v58, v59
	s_nop 1
	v_mov_b32_dpp v59, v58 row_mirror row_mask:0xf bank_mask:0xf
	v_add_u32_e32 v2, v62, v174
	v_ashrrev_i32_e32 v3, 31, v2
	v_lshl_add_u64 v[2:3], v[2:3], 1, s[22:23]
	global_store_short v[2:3], v15, off sc1
	v_add_u32_e32 v2, v62, v175
	s_waitcnt lgkmcnt(0)
	v_add_f32_e32 v58, v58, v59
	v_ashrrev_i32_e32 v3, 31, v2
	v_mov_b32_e32 v59, v58
	s_nop 1
	v_permlane16_swap_b32_e32 v58, v59
	s_nop 0
	v_lshl_add_u64 v[2:3], v[2:3], 1, s[22:23]
	v_add_u32_e32 v61, 0x540, v61
	global_store_short v[2:3], v60, off sc1
	v_or_b32_e32 v2, v61, v174
	v_ashrrev_i32_e32 v3, 31, v2
	v_lshl_add_u64 v[2:3], v[2:3], 1, s[22:23]
	global_store_short v[2:3], v15, off sc1
	s_waitcnt lgkmcnt(0)
	v_add_f32_e32 v3, v58, v59
	v_fmamk_f32 v3, v3, 0x3c800000, v209
	v_rsq_f32_e32 v58, v3
	v_or_b32_e32 v2, v61, v175
	v_ashrrev_i32_e32 v3, 31, v2
	v_lshl_add_u64 v[2:3], v[2:3], 1, s[22:23]
	global_store_short v[2:3], v60, off sc1
	v_pk_mul_f32 v[2:3], v[0:1], v[58:59] op_sel_hi:[1,0]
	s_and_b64 vcc, exec, s[4:5]
	v_pk_mul_f32 v[2:3], v[40:41], v[2:3]
	s_mov_b64 s[80:81], -1
	s_cbranch_vccnz .LBB0_314
	v_add_u32_e32 v15, s76, v186
	v_lshl_or_b32 v58, v15, 6, v156
	v_ashrrev_i32_e32 v59, 31, v58
	v_lshl_add_u64 v[58:59], v[58:59], 2, s[24:25]
	s_mov_b64 s[80:81], 0
	global_store_dword v[58:59], v3, off sc1
	global_store_dword v[58:59], v2, off offset:128 sc1

.LBB0_316:
	v_cvt_pk_bf16_f32 v60, v2, s0
	v_add_u32_e32 v2, s11, v186
	v_mul_lo_u32 v61, v2, s94
	v_or_b32_e32 v2, v61, v174
	v_cvt_pk_bf16_f32 v15, v3, s0
	v_ashrrev_i32_e32 v3, 31, v2
	v_lshl_add_u64 v[2:3], v[2:3], 1, s[22:23]
	global_store_short v[2:3], v15, off sc1
	v_or_b32_e32 v2, v61, v175
	v_ashrrev_i32_e32 v3, 31, v2
	v_lshl_add_u64 v[2:3], v[2:3], 1, s[22:23]
	v_or_b32_e32 v58, 0xc0, v61
	global_store_short v[2:3], v60, off sc1
	v_add_u32_e32 v2, v58, v174
	v_ashrrev_i32_e32 v3, 31, v2
	v_lshl_add_u64 v[2:3], v[2:3], 1, s[22:23]
	global_store_short v[2:3], v15, off sc1
	v_add_u32_e32 v2, v58, v175
	v_ashrrev_i32_e32 v3, 31, v2
	v_lshl_add_u64 v[2:3], v[2:3], 1, s[22:23]
	v_or_b32_e32 v58, 0x180, v61
	global_store_short v[2:3], v60, off sc1
	v_add_u32_e32 v2, v58, v174
	v_ashrrev_i32_e32 v3, 31, v2
	v_lshl_add_u64 v[2:3], v[2:3], 1, s[22:23]
	global_store_short v[2:3], v15, off sc1
	v_add_u32_e32 v2, v58, v175
	v_ashrrev_i32_e32 v3, 31, v2
	v_lshl_add_u64 v[2:3], v[2:3], 1, s[22:23]
	v_add_u32_e32 v58, 0x240, v61
	global_store_short v[2:3], v60, off sc1
	v_or_b32_e32 v2, v58, v174
	v_ashrrev_i32_e32 v3, 31, v2
	v_lshl_add_u64 v[2:3], v[2:3], 1, s[22:23]
	global_store_short v[2:3], v15, off sc1
	v_or_b32_e32 v2, v58, v175
	v_ashrrev_i32_e32 v3, 31, v2
	v_lshl_add_u64 v[2:3], v[2:3], 1, s[22:23]
	v_add_u32_e32 v58, 0x300, v61
	global_store_short v[2:3], v60, off sc1
	v_or_b32_e32 v2, v58, v174
	v_ashrrev_i32_e32 v3, 31, v2
	v_lshl_add_u64 v[2:3], v[2:3], 1, s[22:23]
	global_store_short v[2:3], v15, off sc1
	v_or_b32_e32 v2, v58, v175
	v_pk_mul_f32 v[58:59], v[38:39], v[38:39]
	v_ashrrev_i32_e32 v3, 31, v2
	v_add_f32_e32 v58, v59, v58
	s_nop 1
	v_mov_b32_dpp v59, v58 quad_perm:[1,0,3,2] row_mask:0xf bank_mask:0xf
	v_lshl_add_u64 v[2:3], v[2:3], 1, s[22:23]
	v_add_u32_e32 v62, 0x3c0, v61
	global_store_short v[2:3], v60, off sc1
	v_add_u32_e32 v2, v62, v174
	s_waitcnt lgkmcnt(0)
	v_add_f32_e32 v58, v58, v59
	s_nop 1
	v_mov_b32_dpp v59, v58 quad_perm:[2,3,0,1] row_mask:0xf bank_mask:0xf
	v_ashrrev_i32_e32 v3, 31, v2
	v_lshl_add_u64 v[2:3], v[2:3], 1, s[22:23]
	global_store_short v[2:3], v15, off sc1
	v_add_u32_e32 v2, v62, v175
	s_waitcnt lgkmcnt(0)
	v_add_f32_e32 v58, v58, v59
	s_nop 1
	v_mov_b32_dpp v59, v58 row_half_mirror row_mask:0xf bank_mask:0xf
	v_ashrrev_i32_e32 v3, 31, v2
	v_lshl_add_u64 v[2:3], v[2:3], 1, s[22:23]
	v_add_u32_e32 v62, 0x480, v61
	global_store_short v[2:3], v60, off sc1
	s_waitcnt lgkmcnt(0)
	v_add_f32_e32 v58, v58, v59
	s_nop 1
	v_mov_b32_dpp v59, v58 row_mirror row_mask:0xf bank_mask:0xf
	v_add_u32_e32 v2, v62, v174
	v_ashrrev_i32_e32 v3, 31, v2
	v_lshl_add_u64 v[2:3], v[2:3], 1, s[22:23]
	global_store_short v[2:3], v15, off sc1
	v_add_u32_e32 v2, v62, v175
	s_waitcnt lgkmcnt(0)
	v_add_f32_e32 v58, v58, v59
	v_ashrrev_i32_e32 v3, 31, v2
	v_mov_b32_e32 v59, v58
	s_nop 1
	v_permlane16_swap_b32_e32 v58, v59
	s_nop 0
	v_lshl_add_u64 v[2:3], v[2:3], 1, s[22:23]
	v_add_u32_e32 v61, 0x540, v61
	global_store_short v[2:3], v60, off sc1
	v_or_b32_e32 v2, v61, v174
	v_ashrrev_i32_e32 v3, 31, v2
	v_lshl_add_u64 v[2:3], v[2:3], 1, s[22:23]
	global_store_short v[2:3], v15, off sc1
	s_waitcnt lgkmcnt(0)
	v_add_f32_e32 v3, v58, v59
	v_fmamk_f32 v3, v3, 0x3c800000, v209
	v_rsq_f32_e32 v58, v3
	v_or_b32_e32 v2, v61, v175
	v_ashrrev_i32_e32 v3, 31, v2
	v_lshl_add_u64 v[2:3], v[2:3], 1, s[22:23]
	global_store_short v[2:3], v60, off sc1
	v_pk_mul_f32 v[2:3], v[0:1], v[58:59] op_sel_hi:[1,0]
	s_and_b64 vcc, exec, s[4:5]
	v_pk_mul_f32 v[2:3], v[38:39], v[2:3]
	s_mov_b64 s[80:81], -1
	s_cbranch_vccnz .LBB0_318
	v_add_u32_e32 v15, s76, v187
	v_lshl_or_b32 v58, v15, 6, v156
	v_ashrrev_i32_e32 v59, 31, v58
	v_lshl_add_u64 v[58:59], v[58:59], 2, s[24:25]
	s_mov_b64 s[80:81], 0
	global_store_dword v[58:59], v3, off sc1
	global_store_dword v[58:59], v2, off offset:128 sc1

.LBB0_320:
	v_cvt_pk_bf16_f32 v60, v2, s0
	v_add_u32_e32 v2, s11, v187
	v_mul_lo_u32 v61, v2, s94
	v_or_b32_e32 v2, v61, v174
	v_cvt_pk_bf16_f32 v15, v3, s0
	v_ashrrev_i32_e32 v3, 31, v2
	v_lshl_add_u64 v[2:3], v[2:3], 1, s[22:23]
	global_store_short v[2:3], v15, off sc1
	v_or_b32_e32 v2, v61, v175
	v_ashrrev_i32_e32 v3, 31, v2
	v_lshl_add_u64 v[2:3], v[2:3], 1, s[22:23]
	v_or_b32_e32 v58, 0xc0, v61
	global_store_short v[2:3], v60, off sc1
	v_add_u32_e32 v2, v58, v174
	v_ashrrev_i32_e32 v3, 31, v2
	v_lshl_add_u64 v[2:3], v[2:3], 1, s[22:23]
	global_store_short v[2:3], v15, off sc1
	v_add_u32_e32 v2, v58, v175
	v_ashrrev_i32_e32 v3, 31, v2
	v_lshl_add_u64 v[2:3], v[2:3], 1, s[22:23]
	v_or_b32_e32 v58, 0x180, v61
	global_store_short v[2:3], v60, off sc1
	v_add_u32_e32 v2, v58, v174
	v_ashrrev_i32_e32 v3, 31, v2
	v_lshl_add_u64 v[2:3], v[2:3], 1, s[22:23]
	global_store_short v[2:3], v15, off sc1
	v_add_u32_e32 v2, v58, v175
	v_ashrrev_i32_e32 v3, 31, v2
	v_lshl_add_u64 v[2:3], v[2:3], 1, s[22:23]
	v_add_u32_e32 v58, 0x240, v61
	global_store_short v[2:3], v60, off sc1
	v_or_b32_e32 v2, v58, v174
	v_ashrrev_i32_e32 v3, 31, v2
	v_lshl_add_u64 v[2:3], v[2:3], 1, s[22:23]
	global_store_short v[2:3], v15, off sc1
	v_or_b32_e32 v2, v58, v175
	v_ashrrev_i32_e32 v3, 31, v2
	v_lshl_add_u64 v[2:3], v[2:3], 1, s[22:23]
	v_add_u32_e32 v58, 0x300, v61
	global_store_short v[2:3], v60, off sc1
	v_or_b32_e32 v2, v58, v174
	v_ashrrev_i32_e32 v3, 31, v2
	v_lshl_add_u64 v[2:3], v[2:3], 1, s[22:23]
	global_store_short v[2:3], v15, off sc1
	v_or_b32_e32 v2, v58, v175
	v_pk_mul_f32 v[58:59], v[36:37], v[36:37]
	v_ashrrev_i32_e32 v3, 31, v2
	v_add_f32_e32 v58, v59, v58
	s_nop 1
	v_mov_b32_dpp v59, v58 quad_perm:[1,0,3,2] row_mask:0xf bank_mask:0xf
	v_lshl_add_u64 v[2:3], v[2:3], 1, s[22:23]
	v_add_u32_e32 v62, 0x3c0, v61
	global_store_short v[2:3], v60, off sc1
	v_add_u32_e32 v2, v62, v174
	s_waitcnt lgkmcnt(0)
	v_add_f32_e32 v58, v58, v59
	s_nop 1
	v_mov_b32_dpp v59, v58 quad_perm:[2,3,0,1] row_mask:0xf bank_mask:0xf
	v_ashrrev_i32_e32 v3, 31, v2
	v_lshl_add_u64 v[2:3], v[2:3], 1, s[22:23]
	global_store_short v[2:3], v15, off sc1
	v_add_u32_e32 v2, v62, v175
	s_waitcnt lgkmcnt(0)
	v_add_f32_e32 v58, v58, v59
	s_nop 1
	v_mov_b32_dpp v59, v58 row_half_mirror row_mask:0xf bank_mask:0xf
	v_ashrrev_i32_e32 v3, 31, v2
	v_lshl_add_u64 v[2:3], v[2:3], 1, s[22:23]
	v_add_u32_e32 v62, 0x480, v61
	global_store_short v[2:3], v60, off sc1
	s_waitcnt lgkmcnt(0)
	v_add_f32_e32 v58, v58, v59
	s_nop 1
	v_mov_b32_dpp v59, v58 row_mirror row_mask:0xf bank_mask:0xf
	v_add_u32_e32 v2, v62, v174
	v_ashrrev_i32_e32 v3, 31, v2
	v_lshl_add_u64 v[2:3], v[2:3], 1, s[22:23]
	global_store_short v[2:3], v15, off sc1
	v_add_u32_e32 v2, v62, v175
	s_waitcnt lgkmcnt(0)
	v_add_f32_e32 v58, v58, v59
	v_ashrrev_i32_e32 v3, 31, v2
	v_mov_b32_e32 v59, v58
	s_nop 1
	v_permlane16_swap_b32_e32 v58, v59
	s_nop 0
	v_lshl_add_u64 v[2:3], v[2:3], 1, s[22:23]
	v_add_u32_e32 v61, 0x540, v61
	global_store_short v[2:3], v60, off sc1
	v_or_b32_e32 v2, v61, v174
	v_ashrrev_i32_e32 v3, 31, v2
	v_lshl_add_u64 v[2:3], v[2:3], 1, s[22:23]
	global_store_short v[2:3], v15, off sc1
	s_waitcnt lgkmcnt(0)
	v_add_f32_e32 v3, v58, v59
	v_fmamk_f32 v3, v3, 0x3c800000, v209
	v_rsq_f32_e32 v58, v3
	v_or_b32_e32 v2, v61, v175
	v_ashrrev_i32_e32 v3, 31, v2
	v_lshl_add_u64 v[2:3], v[2:3], 1, s[22:23]
	global_store_short v[2:3], v60, off sc1
	v_pk_mul_f32 v[2:3], v[0:1], v[58:59] op_sel_hi:[1,0]
	s_and_b64 vcc, exec, s[4:5]
	v_pk_mul_f32 v[2:3], v[36:37], v[2:3]
	s_mov_b64 s[80:81], -1
	s_cbranch_vccnz .LBB0_322
	v_add_u32_e32 v15, s76, v188
	v_lshl_or_b32 v58, v15, 6, v156
	v_ashrrev_i32_e32 v59, 31, v58
	v_lshl_add_u64 v[58:59], v[58:59], 2, s[24:25]
	s_mov_b64 s[80:81], 0
	global_store_dword v[58:59], v3, off sc1
	global_store_dword v[58:59], v2, off offset:128 sc1

.LBB0_324:
	v_cvt_pk_bf16_f32 v60, v2, s0
	v_add_u32_e32 v2, s11, v188
	v_mul_lo_u32 v61, v2, s94
	v_or_b32_e32 v2, v61, v174
	v_cvt_pk_bf16_f32 v15, v3, s0
	v_ashrrev_i32_e32 v3, 31, v2
	v_lshl_add_u64 v[2:3], v[2:3], 1, s[22:23]
	global_store_short v[2:3], v15, off sc1
	v_or_b32_e32 v2, v61, v175
	v_ashrrev_i32_e32 v3, 31, v2
	v_lshl_add_u64 v[2:3], v[2:3], 1, s[22:23]
	v_or_b32_e32 v58, 0xc0, v61
	global_store_short v[2:3], v60, off sc1
	v_add_u32_e32 v2, v58, v174
	v_ashrrev_i32_e32 v3, 31, v2
	v_lshl_add_u64 v[2:3], v[2:3], 1, s[22:23]
	global_store_short v[2:3], v15, off sc1
	v_add_u32_e32 v2, v58, v175
	v_ashrrev_i32_e32 v3, 31, v2
	v_lshl_add_u64 v[2:3], v[2:3], 1, s[22:23]
	v_or_b32_e32 v58, 0x180, v61
	global_store_short v[2:3], v60, off sc1
	v_add_u32_e32 v2, v58, v174
	v_ashrrev_i32_e32 v3, 31, v2
	v_lshl_add_u64 v[2:3], v[2:3], 1, s[22:23]
	global_store_short v[2:3], v15, off sc1
	v_add_u32_e32 v2, v58, v175
	v_ashrrev_i32_e32 v3, 31, v2
	v_lshl_add_u64 v[2:3], v[2:3], 1, s[22:23]
	v_add_u32_e32 v58, 0x240, v61
	global_store_short v[2:3], v60, off sc1
	v_or_b32_e32 v2, v58, v174
	v_ashrrev_i32_e32 v3, 31, v2
	v_lshl_add_u64 v[2:3], v[2:3], 1, s[22:23]
	global_store_short v[2:3], v15, off sc1
	v_or_b32_e32 v2, v58, v175
	v_ashrrev_i32_e32 v3, 31, v2
	v_lshl_add_u64 v[2:3], v[2:3], 1, s[22:23]
	v_add_u32_e32 v58, 0x300, v61
	global_store_short v[2:3], v60, off sc1
	v_or_b32_e32 v2, v58, v174
	v_ashrrev_i32_e32 v3, 31, v2
	v_lshl_add_u64 v[2:3], v[2:3], 1, s[22:23]
	global_store_short v[2:3], v15, off sc1
	v_or_b32_e32 v2, v58, v175
	v_pk_mul_f32 v[58:59], v[34:35], v[34:35]
	v_ashrrev_i32_e32 v3, 31, v2
	v_add_f32_e32 v58, v59, v58
	s_nop 1
	v_mov_b32_dpp v59, v58 quad_perm:[1,0,3,2] row_mask:0xf bank_mask:0xf
	v_lshl_add_u64 v[2:3], v[2:3], 1, s[22:23]
	v_add_u32_e32 v62, 0x3c0, v61
	global_store_short v[2:3], v60, off sc1
	v_add_u32_e32 v2, v62, v174
	s_waitcnt lgkmcnt(0)
	v_add_f32_e32 v58, v58, v59
	s_nop 1
	v_mov_b32_dpp v59, v58 quad_perm:[2,3,0,1] row_mask:0xf bank_mask:0xf
	v_ashrrev_i32_e32 v3, 31, v2
	v_lshl_add_u64 v[2:3], v[2:3], 1, s[22:23]
	global_store_short v[2:3], v15, off sc1
	v_add_u32_e32 v2, v62, v175
	s_waitcnt lgkmcnt(0)
	v_add_f32_e32 v58, v58, v59
	s_nop 1
	v_mov_b32_dpp v59, v58 row_half_mirror row_mask:0xf bank_mask:0xf
	v_ashrrev_i32_e32 v3, 31, v2
	v_lshl_add_u64 v[2:3], v[2:3], 1, s[22:23]
	v_add_u32_e32 v62, 0x480, v61
	global_store_short v[2:3], v60, off sc1
	s_waitcnt lgkmcnt(0)
	v_add_f32_e32 v58, v58, v59
	s_nop 1
	v_mov_b32_dpp v59, v58 row_mirror row_mask:0xf bank_mask:0xf
	v_add_u32_e32 v2, v62, v174
	v_ashrrev_i32_e32 v3, 31, v2
	v_lshl_add_u64 v[2:3], v[2:3], 1, s[22:23]
	global_store_short v[2:3], v15, off sc1
	v_add_u32_e32 v2, v62, v175
	s_waitcnt lgkmcnt(0)
	v_add_f32_e32 v58, v58, v59
	v_ashrrev_i32_e32 v3, 31, v2
	v_mov_b32_e32 v59, v58
	s_nop 1
	v_permlane16_swap_b32_e32 v58, v59
	s_nop 0
	v_lshl_add_u64 v[2:3], v[2:3], 1, s[22:23]
	v_add_u32_e32 v61, 0x540, v61
	global_store_short v[2:3], v60, off sc1
	v_or_b32_e32 v2, v61, v174
	v_ashrrev_i32_e32 v3, 31, v2
	v_lshl_add_u64 v[2:3], v[2:3], 1, s[22:23]
	global_store_short v[2:3], v15, off sc1
	s_waitcnt lgkmcnt(0)
	v_add_f32_e32 v3, v58, v59
	v_fmamk_f32 v3, v3, 0x3c800000, v209
	v_rsq_f32_e32 v58, v3
	v_or_b32_e32 v2, v61, v175
	v_ashrrev_i32_e32 v3, 31, v2
	v_lshl_add_u64 v[2:3], v[2:3], 1, s[22:23]
	global_store_short v[2:3], v60, off sc1
	v_pk_mul_f32 v[2:3], v[0:1], v[58:59] op_sel_hi:[1,0]
	s_and_b64 vcc, exec, s[4:5]
	v_pk_mul_f32 v[2:3], v[34:35], v[2:3]
	s_mov_b64 s[80:81], -1
	s_cbranch_vccnz .LBB0_326
	v_add_u32_e32 v15, s76, v189
	v_lshl_or_b32 v58, v15, 6, v156
	v_ashrrev_i32_e32 v59, 31, v58
	v_lshl_add_u64 v[58:59], v[58:59], 2, s[24:25]
	s_mov_b64 s[80:81], 0
	global_store_dword v[58:59], v3, off sc1
	global_store_dword v[58:59], v2, off offset:128 sc1

.LBB0_328:
	v_cvt_pk_bf16_f32 v60, v2, s0
	v_add_u32_e32 v2, s11, v189
	v_mul_lo_u32 v61, v2, s94
	v_or_b32_e32 v2, v61, v174
	v_cvt_pk_bf16_f32 v15, v3, s0
	v_ashrrev_i32_e32 v3, 31, v2
	v_lshl_add_u64 v[2:3], v[2:3], 1, s[22:23]
	global_store_short v[2:3], v15, off sc1
	v_or_b32_e32 v2, v61, v175
	v_ashrrev_i32_e32 v3, 31, v2
	v_lshl_add_u64 v[2:3], v[2:3], 1, s[22:23]
	v_or_b32_e32 v58, 0xc0, v61
	global_store_short v[2:3], v60, off sc1
	v_add_u32_e32 v2, v58, v174
	v_ashrrev_i32_e32 v3, 31, v2
	v_lshl_add_u64 v[2:3], v[2:3], 1, s[22:23]
	global_store_short v[2:3], v15, off sc1
	v_add_u32_e32 v2, v58, v175
	v_ashrrev_i32_e32 v3, 31, v2
	v_lshl_add_u64 v[2:3], v[2:3], 1, s[22:23]
	v_or_b32_e32 v58, 0x180, v61
	global_store_short v[2:3], v60, off sc1
	v_add_u32_e32 v2, v58, v174
	v_ashrrev_i32_e32 v3, 31, v2
	v_lshl_add_u64 v[2:3], v[2:3], 1, s[22:23]
	global_store_short v[2:3], v15, off sc1
	v_add_u32_e32 v2, v58, v175
	v_ashrrev_i32_e32 v3, 31, v2
	v_lshl_add_u64 v[2:3], v[2:3], 1, s[22:23]
	v_add_u32_e32 v58, 0x240, v61
	global_store_short v[2:3], v60, off sc1
	v_or_b32_e32 v2, v58, v174
	v_ashrrev_i32_e32 v3, 31, v2
	v_lshl_add_u64 v[2:3], v[2:3], 1, s[22:23]
	global_store_short v[2:3], v15, off sc1
	v_or_b32_e32 v2, v58, v175
	v_ashrrev_i32_e32 v3, 31, v2
	v_lshl_add_u64 v[2:3], v[2:3], 1, s[22:23]
	v_add_u32_e32 v58, 0x300, v61
	global_store_short v[2:3], v60, off sc1
	v_or_b32_e32 v2, v58, v174
	v_ashrrev_i32_e32 v3, 31, v2
	v_lshl_add_u64 v[2:3], v[2:3], 1, s[22:23]
	global_store_short v[2:3], v15, off sc1
	v_or_b32_e32 v2, v58, v175
	v_pk_mul_f32 v[58:59], v[32:33], v[32:33]
	v_ashrrev_i32_e32 v3, 31, v2
	v_add_f32_e32 v58, v59, v58
	s_nop 1
	v_mov_b32_dpp v14, v58 quad_perm:[1,0,3,2] row_mask:0xf bank_mask:0xf
	v_lshl_add_u64 v[2:3], v[2:3], 1, s[22:23]
	v_add_u32_e32 v62, 0x3c0, v61
	global_store_short v[2:3], v60, off sc1
	v_add_u32_e32 v2, v62, v174
	s_waitcnt lgkmcnt(0)
	v_add_f32_e32 v14, v58, v14
	s_nop 1
	v_mov_b32_dpp v10, v14 quad_perm:[2,3,0,1] row_mask:0xf bank_mask:0xf
	v_ashrrev_i32_e32 v3, 31, v2
	v_lshl_add_u64 v[2:3], v[2:3], 1, s[22:23]
	global_store_short v[2:3], v15, off sc1
	v_add_u32_e32 v2, v62, v175
	s_waitcnt lgkmcnt(0)
	v_add_f32_e32 v10, v14, v10
	s_nop 1
	v_mov_b32_dpp v11, v10 row_half_mirror row_mask:0xf bank_mask:0xf
	v_ashrrev_i32_e32 v3, 31, v2
	v_lshl_add_u64 v[2:3], v[2:3], 1, s[22:23]
	v_add_u32_e32 v58, 0x480, v61
	global_store_short v[2:3], v60, off sc1
	s_waitcnt lgkmcnt(0)
	v_add_f32_e32 v10, v10, v11
	s_nop 1
	v_mov_b32_dpp v11, v10 row_mirror row_mask:0xf bank_mask:0xf
	v_add_u32_e32 v2, v58, v174
	v_ashrrev_i32_e32 v3, 31, v2
	v_lshl_add_u64 v[2:3], v[2:3], 1, s[22:23]
	global_store_short v[2:3], v15, off sc1
	v_add_u32_e32 v2, v58, v175
	s_waitcnt lgkmcnt(0)
	v_add_f32_e32 v10, v10, v11
	v_ashrrev_i32_e32 v3, 31, v2
	v_mov_b32_e32 v11, v10
	s_nop 1
	v_permlane16_swap_b32_e32 v10, v11
	s_nop 0
	v_lshl_add_u64 v[2:3], v[2:3], 1, s[22:23]
	v_add_u32_e32 v12, 0x540, v61
	global_store_short v[2:3], v60, off sc1
	v_or_b32_e32 v2, v12, v174
	v_ashrrev_i32_e32 v3, 31, v2
	v_lshl_add_u64 v[2:3], v[2:3], 1, s[22:23]
	global_store_short v[2:3], v15, off sc1
	s_waitcnt lgkmcnt(0)
	v_add_f32_e32 v3, v10, v11
	v_fmamk_f32 v3, v3, 0x3c800000, v209
	v_rsq_f32_e32 v10, v3
	v_or_b32_e32 v2, v12, v175
	v_ashrrev_i32_e32 v3, 31, v2
	v_lshl_add_u64 v[2:3], v[2:3], 1, s[22:23]
	v_pk_mul_f32 v[0:1], v[0:1], v[10:11] op_sel_hi:[1,0]
	s_and_b64 vcc, exec, s[4:5]
	v_pk_mul_f32 v[0:1], v[32:33], v[0:1]
	s_mov_b64 s[80:81], -1
	global_store_short v[2:3], v60, off sc1
	s_cbranch_vccnz .LBB0_330
	v_add_u32_e32 v2, s76, v190
	v_lshl_or_b32 v2, v2, 6, v156
	v_ashrrev_i32_e32 v3, 31, v2
	v_lshl_add_u64 v[2:3], v[2:3], 2, s[24:25]
	s_mov_b64 s[80:81], 0
	global_store_dword v[2:3], v1, off sc1
	global_store_dword v[2:3], v0, off offset:128 sc1

.LBB0_576:
	s_mul_hi_i32 s0, s71, 0x2aaaaaab
	s_lshr_b32 s1, s0, 31
	s_ashr_i32 s0, s0, 4
	s_add_i32 s0, s0, s1
	s_lshl_b32 s1, s0, 3
	s_mulk_i32 s0, 0xffa0
	s_add_i32 s66, s71, s0
	s_ashr_i32 s0, s66, 31
	s_lshr_b32 s0, s0, 29
	s_add_i32 s0, s66, s0
	s_ashr_i32 s72, s0, 3
	s_and_b32 s0, s0, -8
	s_sub_i32 s74, s66, s0
	s_add_i32 s74, s74, s1
	s_lshl_b32 s73, s74, 7
	v_readfirstlane_b32 s85, v100
	s_lshl_b32 s67, s72, 7
	v_mad_i64_i32 v[72:73], s[0:1], s73, v99, v[66:67]
	s_mov_b32 m0, s85
	v_readfirstlane_b32 s78, v101
	v_mad_i64_i32 v[70:71], s[0:1], s67, v99, v[68:69]
	global_load_lds_dwordx4 v[72:73], off
	s_mov_b32 m0, s78
	v_readfirstlane_b32 s79, v102
	global_load_lds_dwordx4 v[70:71], off
	v_lshl_add_u64 v[0:1], v[72:73], 0, s[18:19]
	s_mov_b32 m0, s79
	v_readfirstlane_b32 s80, v103
	global_load_lds_dwordx4 v[0:1], off
	v_lshl_add_u64 v[0:1], v[70:71], 0, s[18:19]
	s_mov_b32 m0, s80
	v_readfirstlane_b32 s81, v104
	global_load_lds_dwordx4 v[0:1], off
	v_lshl_add_u64 v[0:1], v[72:73], 0, s[20:21]
	s_mov_b32 m0, s81
	v_readfirstlane_b32 s82, v105
	global_load_lds_dwordx4 v[0:1], off
	v_lshl_add_u64 v[0:1], v[70:71], 0, s[20:21]
	s_mov_b32 m0, s82
	v_readfirstlane_b32 s83, v106
	global_load_lds_dwordx4 v[0:1], off
	v_lshl_add_u64 v[0:1], v[72:73], 0, s[22:23]
	s_mov_b32 m0, s83
	v_readfirstlane_b32 s84, v107
	global_load_lds_dwordx4 v[0:1], off
	v_lshl_add_u64 v[0:1], v[70:71], 0, s[22:23]
	s_mov_b32 m0, s84
	v_readfirstlane_b32 s77, v108
	global_load_lds_dwordx4 v[0:1], off
	v_lshl_add_u64 v[0:1], v[72:73], 0, s[24:25]
	s_mov_b32 m0, s77
	v_readfirstlane_b32 s0, v109
	s_waitcnt vmcnt(0)
	s_waitcnt vmcnt(0) lgkmcnt(0)
	s_barrier
	v_lshl_add_u64 v[2:3], v[70:71], 0, s[24:25]
	global_load_lds_dwordx4 v[0:1], off
	s_mov_b32 m0, s0
	v_readfirstlane_b32 s1, v110
	global_load_lds_dwordx4 v[2:3], off
	v_lshl_add_u64 v[0:1], v[72:73], 0, s[26:27]
	s_mov_b32 m0, s1
	v_readfirstlane_b32 s67, v111
	global_load_lds_dwordx4 v[0:1], off
	v_lshl_add_u64 v[0:1], v[70:71], 0, s[26:27]
	s_mov_b32 m0, s67
	v_readfirstlane_b32 s68, v112
	global_load_lds_dwordx4 v[0:1], off
	v_lshl_add_u64 v[0:1], v[72:73], 0, s[28:29]
	s_mov_b32 m0, s68
	v_readfirstlane_b32 s69, v113
	global_load_lds_dwordx4 v[0:1], off
	v_lshl_add_u64 v[0:1], v[70:71], 0, s[28:29]
	s_mov_b32 m0, s69
	v_readfirstlane_b32 s75, v114
	global_load_lds_dwordx4 v[0:1], off
	v_lshl_add_u64 v[0:1], v[72:73], 0, s[30:31]
	s_mov_b32 m0, s75
	v_readfirstlane_b32 s76, v115
	global_load_lds_dwordx4 v[0:1], off
	v_lshl_add_u64 v[0:1], v[70:71], 0, s[30:31]
	s_mov_b32 m0, s76
	v_add_u32_e32 v121, v75, v77
	global_load_lds_dwordx4 v[0:1], off
	ds_read_b128 v[0:3], v116
	ds_read_b128 v[4:7], v117 offset:16384
	ds_read_b128 v[8:11], v117 offset:20480
	ds_read_b128 v[12:15], v117 offset:24576
	ds_read_b128 v[122:125], v117 offset:28672
	ds_read_b128 v[126:129], v118
	ds_read_b128 v[130:133], v121 offset:16384
	ds_read_b128 v[134:137], v121 offset:20480
	ds_read_b128 v[138:141], v121 offset:24576
	ds_read_b128 v[142:145], v121 offset:28672
	s_setprio 1
	s_waitcnt lgkmcnt(0)
	v_mfma_f32_32x32x16_bf16 v[48:63], v[0:3], v[4:7], 0
	v_mfma_f32_32x32x16_bf16 v[32:47], v[0:3], v[8:11], 0
	v_mfma_f32_32x32x16_bf16 v[16:31], v[0:3], v[12:15], 0
	v_mfma_f32_32x32x16_bf16 v[0:15], v[0:3], v[122:125], 0
	s_setprio 0
	v_add_u32_e32 v162, v76, v78
	v_add_u32_e32 v163, v75, v78
	ds_read_b128 v[122:125], v162
	ds_read_b128 v[146:149], v163 offset:16384
	ds_read_b128 v[150:153], v163 offset:20480
	ds_read_b128 v[154:157], v163 offset:24576
	ds_read_b128 v[158:161], v163 offset:28672
	s_setprio 1
	v_mfma_f32_32x32x16_bf16 v[48:63], v[126:129], v[130:133], v[48:63]
	v_mfma_f32_32x32x16_bf16 v[32:47], v[126:129], v[134:137], v[32:47]
	v_mfma_f32_32x32x16_bf16 v[16:31], v[126:129], v[138:141], v[16:31]
	v_mfma_f32_32x32x16_bf16 v[0:15], v[126:129], v[142:145], v[0:15]
	s_setprio 0
	v_add_u32_e32 v164, v76, v79
	v_add_u32_e32 v165, v75, v79
	ds_read_b128 v[126:129], v164
	ds_read_b128 v[130:133], v165 offset:16384
	ds_read_b128 v[134:137], v165 offset:20480
	ds_read_b128 v[138:141], v165 offset:24576
	ds_read_b128 v[142:145], v165 offset:28672
	s_setprio 1
	s_waitcnt lgkmcnt(0)
	v_mfma_f32_32x32x16_bf16 v[48:63], v[122:125], v[146:149], v[48:63]
	v_mfma_f32_32x32x16_bf16 v[32:47], v[122:125], v[150:153], v[32:47]
	v_mfma_f32_32x32x16_bf16 v[16:31], v[122:125], v[154:157], v[16:31]
	v_mfma_f32_32x32x16_bf16 v[0:15], v[122:125], v[158:161], v[0:15]
	s_setprio 0
	s_setprio 1
	v_mfma_f32_32x32x16_bf16 v[48:63], v[126:129], v[130:133], v[48:63]
	v_mfma_f32_32x32x16_bf16 v[32:47], v[126:129], v[134:137], v[32:47]
	v_mfma_f32_32x32x16_bf16 v[16:31], v[126:129], v[138:141], v[16:31]
	v_mfma_f32_32x32x16_bf16 v[0:15], v[126:129], v[142:145], v[0:15]
	s_setprio 0
	s_mov_b32 m0, s85
	v_lshl_add_u64 v[122:123], v[72:73], 0, s[34:35]
	s_waitcnt vmcnt(0)
	s_waitcnt vmcnt(0)
	s_barrier
	v_lshl_add_u64 v[124:125], v[70:71], 0, s[34:35]
	global_load_lds_dwordx4 v[122:123], off
	s_mov_b32 m0, s78
	v_lshl_add_u64 v[122:123], v[72:73], 0, s[36:37]
	global_load_lds_dwordx4 v[124:125], off
	s_mov_b32 m0, s79
	s_nop 0
	global_load_lds_dwordx4 v[122:123], off
	v_lshl_add_u64 v[122:123], v[70:71], 0, s[36:37]
	s_mov_b32 m0, s80
	s_nop 0
	global_load_lds_dwordx4 v[122:123], off
	v_lshl_add_u64 v[122:123], v[72:73], 0, s[38:39]
	s_mov_b32 m0, s81
	s_nop 0
	global_load_lds_dwordx4 v[122:123], off
	v_lshl_add_u64 v[122:123], v[70:71], 0, s[38:39]
	s_mov_b32 m0, s82
	s_nop 0
	global_load_lds_dwordx4 v[122:123], off
	v_lshl_add_u64 v[122:123], v[72:73], 0, s[40:41]
	s_mov_b32 m0, s83
	s_nop 0
	global_load_lds_dwordx4 v[122:123], off
	v_lshl_add_u64 v[122:123], v[70:71], 0, s[40:41]
	s_mov_b32 m0, s84
	s_nop 0
	global_load_lds_dwordx4 v[122:123], off
	ds_read_b128 v[122:125], v116 offset:32768
	ds_read_b128 v[126:129], v117 offset:49152
	ds_read_b128 v[130:133], v117 offset:53248
	ds_read_b128 v[134:137], v117 offset:57344
	ds_read_b128 v[138:141], v117 offset:61440
	ds_read_b128 v[142:145], v118 offset:32768
	ds_read_b128 v[146:149], v121 offset:49152
	ds_read_b128 v[150:153], v121 offset:53248
	ds_read_b128 v[154:157], v121 offset:57344
	ds_read_b128 v[158:161], v121 offset:61440
	s_setprio 1
	s_waitcnt lgkmcnt(0)
	v_mfma_f32_32x32x16_bf16 v[48:63], v[122:125], v[126:129], v[48:63]
	v_mfma_f32_32x32x16_bf16 v[32:47], v[122:125], v[130:133], v[32:47]
	v_mfma_f32_32x32x16_bf16 v[16:31], v[122:125], v[134:137], v[16:31]
	v_mfma_f32_32x32x16_bf16 v[0:15], v[122:125], v[138:141], v[0:15]
	s_setprio 0
	ds_read_b128 v[122:125], v162 offset:32768
	ds_read_b128 v[126:129], v163 offset:49152
	ds_read_b128 v[130:133], v163 offset:53248
	ds_read_b128 v[134:137], v163 offset:57344
	ds_read_b128 v[138:141], v163 offset:61440
	s_setprio 1
	v_mfma_f32_32x32x16_bf16 v[48:63], v[142:145], v[146:149], v[48:63]
	v_mfma_f32_32x32x16_bf16 v[32:47], v[142:145], v[150:153], v[32:47]
	v_mfma_f32_32x32x16_bf16 v[16:31], v[142:145], v[154:157], v[16:31]
	v_mfma_f32_32x32x16_bf16 v[0:15], v[142:145], v[158:161], v[0:15]
	s_setprio 0
	ds_read_b128 v[142:145], v164 offset:32768
	ds_read_b128 v[146:149], v165 offset:49152
	ds_read_b128 v[150:153], v165 offset:53248
	ds_read_b128 v[154:157], v165 offset:57344
	ds_read_b128 v[158:161], v165 offset:61440
	s_setprio 1
	s_waitcnt lgkmcnt(0)
	v_mfma_f32_32x32x16_bf16 v[48:63], v[122:125], v[126:129], v[48:63]
	v_mfma_f32_32x32x16_bf16 v[32:47], v[122:125], v[130:133], v[32:47]
	v_mfma_f32_32x32x16_bf16 v[16:31], v[122:125], v[134:137], v[16:31]
	v_mfma_f32_32x32x16_bf16 v[0:15], v[122:125], v[138:141], v[0:15]
	s_setprio 0
	s_setprio 1
	v_mfma_f32_32x32x16_bf16 v[48:63], v[142:145], v[146:149], v[48:63]
	v_mfma_f32_32x32x16_bf16 v[32:47], v[142:145], v[150:153], v[32:47]
	v_mfma_f32_32x32x16_bf16 v[16:31], v[142:145], v[154:157], v[16:31]
	v_mfma_f32_32x32x16_bf16 v[0:15], v[142:145], v[158:161], v[0:15]
	s_setprio 0
	s_mov_b32 m0, s77
	v_lshl_add_u64 v[122:123], v[72:73], 0, s[42:43]
	s_waitcnt vmcnt(0)
	s_waitcnt vmcnt(0)
	s_barrier
	v_lshl_add_u64 v[124:125], v[70:71], 0, s[42:43]
	global_load_lds_dwordx4 v[122:123], off
	s_mov_b32 m0, s0
	v_lshl_add_u64 v[122:123], v[72:73], 0, s[44:45]
	global_load_lds_dwordx4 v[124:125], off
	s_mov_b32 m0, s1
	s_nop 0
	global_load_lds_dwordx4 v[122:123], off
	v_lshl_add_u64 v[122:123], v[70:71], 0, s[44:45]
	s_mov_b32 m0, s67
	s_nop 0
	global_load_lds_dwordx4 v[122:123], off
	v_lshl_add_u64 v[122:123], v[72:73], 0, s[46:47]
	s_mov_b32 m0, s68
	s_nop 0
	global_load_lds_dwordx4 v[122:123], off
	v_lshl_add_u64 v[122:123], v[70:71], 0, s[46:47]
	s_mov_b32 m0, s69
	s_nop 0
	global_load_lds_dwordx4 v[122:123], off
	v_lshl_add_u64 v[122:123], v[72:73], 0, s[48:49]
	s_mov_b32 m0, s75
	s_nop 0
	global_load_lds_dwordx4 v[122:123], off
	v_lshl_add_u64 v[122:123], v[70:71], 0, s[48:49]
	s_mov_b32 m0, s76
	s_nop 0
	global_load_lds_dwordx4 v[122:123], off
	ds_read_b128 v[122:125], v116
	ds_read_b128 v[126:129], v117 offset:16384
	ds_read_b128 v[130:133], v117 offset:20480
	ds_read_b128 v[134:137], v117 offset:24576
	ds_read_b128 v[138:141], v117 offset:28672
	ds_read_b128 v[142:145], v118
	ds_read_b128 v[146:149], v121 offset:16384
	ds_read_b128 v[150:153], v121 offset:20480
	ds_read_b128 v[154:157], v121 offset:24576
	ds_read_b128 v[158:161], v121 offset:28672
	s_setprio 1
	s_waitcnt lgkmcnt(0)
	v_mfma_f32_32x32x16_bf16 v[48:63], v[122:125], v[126:129], v[48:63]
	v_mfma_f32_32x32x16_bf16 v[32:47], v[122:125], v[130:133], v[32:47]
	v_mfma_f32_32x32x16_bf16 v[16:31], v[122:125], v[134:137], v[16:31]
	v_mfma_f32_32x32x16_bf16 v[0:15], v[122:125], v[138:141], v[0:15]
	s_setprio 0
	ds_read_b128 v[122:125], v162
	ds_read_b128 v[126:129], v163 offset:16384
	ds_read_b128 v[130:133], v163 offset:20480
	ds_read_b128 v[134:137], v163 offset:24576
	ds_read_b128 v[138:141], v163 offset:28672
	s_setprio 1
	v_mfma_f32_32x32x16_bf16 v[48:63], v[142:145], v[146:149], v[48:63]
	v_mfma_f32_32x32x16_bf16 v[32:47], v[142:145], v[150:153], v[32:47]
	v_mfma_f32_32x32x16_bf16 v[16:31], v[142:145], v[154:157], v[16:31]
	v_mfma_f32_32x32x16_bf16 v[0:15], v[142:145], v[158:161], v[0:15]
	s_setprio 0
	ds_read_b128 v[142:145], v164
	ds_read_b128 v[146:149], v165 offset:16384
	ds_read_b128 v[150:153], v165 offset:20480
	ds_read_b128 v[154:157], v165 offset:24576
	ds_read_b128 v[158:161], v165 offset:28672
	s_setprio 1
	s_waitcnt lgkmcnt(0)
	v_mfma_f32_32x32x16_bf16 v[48:63], v[122:125], v[126:129], v[48:63]
	v_mfma_f32_32x32x16_bf16 v[32:47], v[122:125], v[130:133], v[32:47]
	v_mfma_f32_32x32x16_bf16 v[16:31], v[122:125], v[134:137], v[16:31]
	v_mfma_f32_32x32x16_bf16 v[0:15], v[122:125], v[138:141], v[0:15]
	s_setprio 0
	s_setprio 1
	v_mfma_f32_32x32x16_bf16 v[48:63], v[142:145], v[146:149], v[48:63]
	v_mfma_f32_32x32x16_bf16 v[32:47], v[142:145], v[150:153], v[32:47]
	v_mfma_f32_32x32x16_bf16 v[16:31], v[142:145], v[154:157], v[16:31]
	v_mfma_f32_32x32x16_bf16 v[0:15], v[142:145], v[158:161], v[0:15]
	s_setprio 0
	s_mov_b32 m0, s85
	v_lshl_add_u64 v[122:123], v[72:73], 0, s[50:51]
	s_waitcnt vmcnt(0)
	s_waitcnt vmcnt(0)
	s_barrier
	v_lshl_add_u64 v[124:125], v[70:71], 0, s[50:51]
	global_load_lds_dwordx4 v[122:123], off
	s_mov_b32 m0, s78
	v_lshl_add_u64 v[122:123], v[72:73], 0, s[52:53]
	global_load_lds_dwordx4 v[124:125], off
	s_mov_b32 m0, s79
	s_nop 0
	global_load_lds_dwordx4 v[122:123], off
	v_lshl_add_u64 v[122:123], v[70:71], 0, s[52:53]
	s_mov_b32 m0, s80
	s_nop 0
	global_load_lds_dwordx4 v[122:123], off
	v_lshl_add_u64 v[122:123], v[72:73], 0, s[54:55]
	s_mov_b32 m0, s81
	s_nop 0
	global_load_lds_dwordx4 v[122:123], off
	v_lshl_add_u64 v[122:123], v[70:71], 0, s[54:55]
	s_mov_b32 m0, s82
	s_nop 0
	global_load_lds_dwordx4 v[122:123], off
	v_lshl_add_u64 v[122:123], v[72:73], 0, s[56:57]
	s_mov_b32 m0, s83
	s_nop 0
	global_load_lds_dwordx4 v[122:123], off
	v_lshl_add_u64 v[122:123], v[70:71], 0, s[56:57]
	s_mov_b32 m0, s84
	s_nop 0
	global_load_lds_dwordx4 v[122:123], off
	ds_read_b128 v[122:125], v116 offset:32768
	ds_read_b128 v[126:129], v117 offset:49152
	ds_read_b128 v[130:133], v117 offset:53248
	ds_read_b128 v[134:137], v117 offset:57344
	ds_read_b128 v[138:141], v117 offset:61440
	ds_read_b128 v[142:145], v118 offset:32768
	ds_read_b128 v[146:149], v121 offset:49152
	ds_read_b128 v[150:153], v121 offset:53248
	ds_read_b128 v[154:157], v121 offset:57344
	ds_read_b128 v[158:161], v121 offset:61440
	s_setprio 1
	s_waitcnt lgkmcnt(0)
	v_mfma_f32_32x32x16_bf16 v[48:63], v[122:125], v[126:129], v[48:63]
	v_mfma_f32_32x32x16_bf16 v[32:47], v[122:125], v[130:133], v[32:47]
	v_mfma_f32_32x32x16_bf16 v[16:31], v[122:125], v[134:137], v[16:31]
	v_mfma_f32_32x32x16_bf16 v[0:15], v[122:125], v[138:141], v[0:15]
	s_setprio 0
	ds_read_b128 v[122:125], v162 offset:32768
	ds_read_b128 v[126:129], v163 offset:49152
	ds_read_b128 v[130:133], v163 offset:53248
	ds_read_b128 v[134:137], v163 offset:57344
	ds_read_b128 v[138:141], v163 offset:61440
	s_setprio 1
	v_mfma_f32_32x32x16_bf16 v[48:63], v[142:145], v[146:149], v[48:63]
	v_mfma_f32_32x32x16_bf16 v[32:47], v[142:145], v[150:153], v[32:47]
	v_mfma_f32_32x32x16_bf16 v[16:31], v[142:145], v[154:157], v[16:31]
	v_mfma_f32_32x32x16_bf16 v[0:15], v[142:145], v[158:161], v[0:15]
	s_setprio 0
	ds_read_b128 v[142:145], v164 offset:32768
	ds_read_b128 v[146:149], v165 offset:49152
	ds_read_b128 v[150:153], v165 offset:53248
	ds_read_b128 v[154:157], v165 offset:57344
	ds_read_b128 v[158:161], v165 offset:61440
	s_setprio 1
	s_waitcnt lgkmcnt(0)
	v_mfma_f32_32x32x16_bf16 v[48:63], v[122:125], v[126:129], v[48:63]
	v_mfma_f32_32x32x16_bf16 v[32:47], v[122:125], v[130:133], v[32:47]
	v_mfma_f32_32x32x16_bf16 v[16:31], v[122:125], v[134:137], v[16:31]
	v_mfma_f32_32x32x16_bf16 v[0:15], v[122:125], v[138:141], v[0:15]
	s_setprio 0
	s_setprio 1
	v_mfma_f32_32x32x16_bf16 v[48:63], v[142:145], v[146:149], v[48:63]
	v_mfma_f32_32x32x16_bf16 v[32:47], v[142:145], v[150:153], v[32:47]
	v_mfma_f32_32x32x16_bf16 v[16:31], v[142:145], v[154:157], v[16:31]
	v_mfma_f32_32x32x16_bf16 v[0:15], v[142:145], v[158:161], v[0:15]
	s_setprio 0
	s_mov_b32 m0, s77
	v_lshl_add_u64 v[122:123], v[72:73], 0, s[58:59]
	s_waitcnt vmcnt(0)
	s_waitcnt vmcnt(0)
	s_barrier
	v_lshl_add_u64 v[124:125], v[70:71], 0, s[58:59]
	global_load_lds_dwordx4 v[122:123], off
	s_mov_b32 m0, s0
	v_lshl_add_u64 v[122:123], v[72:73], 0, s[60:61]
	global_load_lds_dwordx4 v[124:125], off
	s_mov_b32 m0, s1
	s_nop 0
	global_load_lds_dwordx4 v[122:123], off
	v_lshl_add_u64 v[122:123], v[70:71], 0, s[60:61]
	s_mov_b32 m0, s67
	s_nop 0
	global_load_lds_dwordx4 v[122:123], off
	v_lshl_add_u64 v[122:123], v[72:73], 0, s[62:63]
	s_mov_b32 m0, s68
	v_lshl_add_u64 v[72:73], v[72:73], 0, s[64:65]
	global_load_lds_dwordx4 v[122:123], off
	v_lshl_add_u64 v[122:123], v[70:71], 0, s[62:63]
	s_mov_b32 m0, s69
	v_lshl_add_u64 v[70:71], v[70:71], 0, s[64:65]
	global_load_lds_dwordx4 v[122:123], off
	s_mov_b32 m0, s75
	s_nop 0
	global_load_lds_dwordx4 v[72:73], off
	s_mov_b32 m0, s76
	s_nop 0
	global_load_lds_dwordx4 v[70:71], off
	ds_read_b128 v[70:73], v116
	ds_read_b128 v[122:125], v117 offset:16384
	ds_read_b128 v[126:129], v117 offset:20480
	ds_read_b128 v[130:133], v117 offset:24576
	ds_read_b128 v[134:137], v117 offset:28672
	ds_read_b128 v[138:141], v118
	ds_read_b128 v[142:145], v121 offset:16384
	ds_read_b128 v[146:149], v121 offset:20480
	ds_read_b128 v[150:153], v121 offset:24576
	ds_read_b128 v[154:157], v121 offset:28672
	s_setprio 1
	s_waitcnt lgkmcnt(0)
	v_mfma_f32_32x32x16_bf16 v[48:63], v[70:73], v[122:125], v[48:63]
	v_mfma_f32_32x32x16_bf16 v[32:47], v[70:73], v[126:129], v[32:47]
	v_mfma_f32_32x32x16_bf16 v[16:31], v[70:73], v[130:133], v[16:31]
	v_mfma_f32_32x32x16_bf16 v[0:15], v[70:73], v[134:137], v[0:15]
	s_setprio 0
	ds_read_b128 v[70:73], v162
	ds_read_b128 v[122:125], v163 offset:16384
	ds_read_b128 v[126:129], v163 offset:20480
	ds_read_b128 v[130:133], v163 offset:24576
	ds_read_b128 v[134:137], v163 offset:28672
	s_setprio 1
	v_mfma_f32_32x32x16_bf16 v[48:63], v[138:141], v[142:145], v[48:63]
	v_mfma_f32_32x32x16_bf16 v[32:47], v[138:141], v[146:149], v[32:47]
	v_mfma_f32_32x32x16_bf16 v[16:31], v[138:141], v[150:153], v[16:31]
	v_mfma_f32_32x32x16_bf16 v[0:15], v[138:141], v[154:157], v[0:15]
	s_setprio 0
	ds_read_b128 v[138:141], v164
	ds_read_b128 v[142:145], v165 offset:16384
	ds_read_b128 v[146:149], v165 offset:20480
	ds_read_b128 v[150:153], v165 offset:24576
	ds_read_b128 v[154:157], v165 offset:28672
	s_setprio 1
	s_waitcnt lgkmcnt(0)
	v_mfma_f32_32x32x16_bf16 v[48:63], v[70:73], v[122:125], v[48:63]
	v_mfma_f32_32x32x16_bf16 v[32:47], v[70:73], v[126:129], v[32:47]
	v_mfma_f32_32x32x16_bf16 v[16:31], v[70:73], v[130:133], v[16:31]
	v_mfma_f32_32x32x16_bf16 v[0:15], v[70:73], v[134:137], v[0:15]
	s_setprio 0
	s_setprio 1
	v_mfma_f32_32x32x16_bf16 v[48:63], v[138:141], v[142:145], v[48:63]
	v_mfma_f32_32x32x16_bf16 v[32:47], v[138:141], v[146:149], v[32:47]
	v_mfma_f32_32x32x16_bf16 v[16:31], v[138:141], v[150:153], v[16:31]
	v_mfma_f32_32x32x16_bf16 v[0:15], v[138:141], v[154:157], v[0:15]
	s_setprio 0
	s_waitcnt vmcnt(0)
	s_waitcnt vmcnt(0)
	s_barrier
	ds_read_b128 v[70:73], v121 offset:61440
	ds_read_b128 v[122:125], v121 offset:57344
	ds_read_b128 v[126:129], v121 offset:53248
	ds_read_b128 v[130:133], v121 offset:49152
	ds_read_b128 v[134:137], v118 offset:32768
	ds_read_b128 v[138:141], v117 offset:61440
	ds_read_b128 v[142:145], v117 offset:57344
	ds_read_b128 v[146:149], v117 offset:53248
	ds_read_b128 v[150:153], v117 offset:49152
	ds_read_b128 v[154:157], v116 offset:32768
	s_setprio 1
	s_waitcnt lgkmcnt(0)
	v_mfma_f32_32x32x16_bf16 v[48:63], v[154:157], v[150:153], v[48:63]
	v_mfma_f32_32x32x16_bf16 v[32:47], v[154:157], v[146:149], v[32:47]
	v_mfma_f32_32x32x16_bf16 v[16:31], v[154:157], v[142:145], v[16:31]
	v_mfma_f32_32x32x16_bf16 v[0:15], v[154:157], v[138:141], v[0:15]
	s_setprio 0
	ds_read_b128 v[138:141], v162 offset:32768
	ds_read_b128 v[142:145], v163 offset:49152
	ds_read_b128 v[146:149], v163 offset:53248
	ds_read_b128 v[150:153], v163 offset:57344
	ds_read_b128 v[154:157], v163 offset:61440
	s_setprio 1
	v_mfma_f32_32x32x16_bf16 v[48:63], v[134:137], v[130:133], v[48:63]
	v_mfma_f32_32x32x16_bf16 v[32:47], v[134:137], v[126:129], v[32:47]
	v_mfma_f32_32x32x16_bf16 v[16:31], v[134:137], v[122:125], v[16:31]
	v_mfma_f32_32x32x16_bf16 v[0:15], v[134:137], v[70:73], v[0:15]
	s_setprio 0
	ds_read_b128 v[70:73], v164 offset:32768
	ds_read_b128 v[122:125], v165 offset:49152
	ds_read_b128 v[126:129], v165 offset:53248
	ds_read_b128 v[130:133], v165 offset:57344
	ds_read_b128 v[134:137], v165 offset:61440
	s_setprio 1
	s_waitcnt lgkmcnt(8)
	v_mfma_f32_32x32x16_bf16 v[48:63], v[138:141], v[142:145], v[48:63]
	s_waitcnt lgkmcnt(7)
	v_mfma_f32_32x32x16_bf16 v[32:47], v[138:141], v[146:149], v[32:47]
	s_waitcnt lgkmcnt(6)
	v_mfma_f32_32x32x16_bf16 v[16:31], v[138:141], v[150:153], v[16:31]
	s_waitcnt lgkmcnt(5)
	v_mfma_f32_32x32x16_bf16 v[0:15], v[138:141], v[154:157], v[0:15]
	s_setprio 0
	s_setprio 1
	s_waitcnt lgkmcnt(3)
	v_mfma_f32_32x32x16_bf16 v[48:63], v[70:73], v[122:125], v[48:63]
	s_waitcnt lgkmcnt(2)
	v_mfma_f32_32x32x16_bf16 v[32:47], v[70:73], v[126:129], v[32:47]
	s_waitcnt lgkmcnt(1)
	v_mfma_f32_32x32x16_bf16 v[16:31], v[70:73], v[130:133], v[16:31]
	s_waitcnt lgkmcnt(0)
	v_mfma_f32_32x32x16_bf16 v[0:15], v[70:73], v[134:137], v[0:15]
	s_setprio 0
	v_mov_b32_e32 v70, s10
	ds_read_b64 v[70:71], v70
	s_mov_b64 s[0:1], -1
	s_cmp_gt_i32 s66, 63
	v_lshlrev_b32_e32 v121, 2, v64
	v_mbcnt_hi_u32_b32 v122, -1, v120
	s_waitcnt lgkmcnt(0)
	v_readfirstlane_b32 s66, v70
	v_readfirstlane_b32 s67, v71
	s_cbranch_scc0 .LBB0_642
	s_nop 3
	global_load_dword v71, v121, s[66:67] offset:512
	global_load_dword v70, v121, s[66:67] offset:640
	v_and_b32_e32 v124, 64, v122
	v_xor_b32_e32 v123, 1, v122
	v_add_u32_e32 v128, 64, v124
	v_mov_b32_e32 v72, v48
	v_mov_b32_e32 v73, v32
	v_cmp_lt_i32_e32 vcc, v123, v128
	v_pk_mul_f32 v[72:73], v[72:73], v[72:73]
	v_xor_b32_e32 v125, 2, v122
	v_cndmask_b32_e32 v123, v122, v123, vcc
	v_add_f32_e32 v72, v72, v73
	v_lshlrev_b32_e32 v123, 2, v123
	s_nop 1
	v_mov_b32_dpp v73, v72 quad_perm:[1,0,3,2] row_mask:0xf bank_mask:0xf
	v_cmp_lt_i32_e32 vcc, v125, v128
	v_xor_b32_e32 v126, 4, v122
	v_xor_b32_e32 v127, 8, v122
	v_cndmask_b32_e32 v124, v122, v125, vcc
	v_lshlrev_b32_e32 v124, 2, v124
	s_waitcnt lgkmcnt(0)
	v_add_f32_e32 v72, v72, v73
	s_nop 1
	v_mov_b32_dpp v73, v72 quad_perm:[2,3,0,1] row_mask:0xf bank_mask:0xf
	v_cmp_lt_i32_e32 vcc, v126, v128
	v_xor_b32_e32 v129, 16, v122
	s_cmp_gt_i32 s74, 63
	v_cndmask_b32_e32 v125, v122, v126, vcc
	v_lshlrev_b32_e32 v125, 2, v125
	s_waitcnt lgkmcnt(0)
	v_add_f32_e32 v73, v72, v73
	s_nop 1
	v_mov_b32_dpp v126, v73 row_half_mirror row_mask:0xf bank_mask:0xf
	v_cmp_lt_i32_e32 vcc, v127, v128
	s_cselect_b64 s[68:69], -1, 0
	s_and_b64 s[0:1], s[68:69], exec
	v_cndmask_b32_e32 v127, v122, v127, vcc
	v_lshlrev_b32_e32 v127, 2, v127
	s_waitcnt lgkmcnt(0)
	v_add_f32_e32 v130, v73, v126
	s_nop 1
	v_mov_b32_dpp v131, v130 row_mirror row_mask:0xf bank_mask:0xf
	v_cmp_lt_i32_e32 vcc, v129, v128
	s_cselect_b32 s0, s11, 0x80
	s_and_b32 s76, s0, s73
	v_cndmask_b32_e32 v126, v122, v129, vcc
	v_lshlrev_b32_e32 v126, 2, v126
	s_waitcnt lgkmcnt(0)
	v_add_f32_e32 v128, v130, v131
	v_mov_b32_e32 v129, v128
	s_nop 1
	v_permlane16_swap_b32_e32 v128, v129
	s_nop 0
	v_mov_b32_e32 v72, v32
	v_mov_b32_e32 v73, v48
	v_lshlrev_b32_e32 v142, 3, v64
	v_add_u32_e32 v130, s76, v80
	s_waitcnt lgkmcnt(0)
	v_add_f32_e32 v128, v128, v129
	v_fmamk_f32 v128, v128, 0x3c800000, v119
	v_rsq_f32_e32 v128, v128
	s_cmp_lt_i32 s74, 64
	s_waitcnt vmcnt(0)
	v_pk_mul_f32 v[128:129], v[70:71], v[128:129] op_sel_hi:[1,0]
	s_nop 0
	v_pk_mul_f32 v[72:73], v[72:73], v[128:129]
	v_lshl_or_b32 v128, v130, 8, v142
	s_cbranch_scc1 .LBB0_579
	global_load_dwordx2 v[130:131], v128, s[8:9]
	s_waitcnt vmcnt(0)
	v_pk_mul_f32 v[134:135], v[72:73], v[130:131] op_sel_hi:[0,1]
	v_pk_mul_f32 v[132:133], v[72:73], v[130:131] op_sel:[1,1] op_sel_hi:[1,0]
	v_pk_fma_f32 v[72:73], v[72:73], v[130:131], v[134:135] op_sel:[1,1,0] op_sel_hi:[1,0,1] neg_lo:[0,0,1] neg_hi:[0,0,1]
	s_nop 0
	v_add_f32_e32 v72, v132, v134
.LBB0_579:
	v_mov_b32_e32 v130, v49
	v_mov_b32_e32 v131, v33
	v_pk_mul_f32 v[130:131], v[130:131], v[130:131]
	s_mul_i32 s74, s72, 0x180
	v_add_f32_e32 v129, v130, v131
	s_nop 1
	v_mov_b32_dpp v130, v129 quad_perm:[1,0,3,2] row_mask:0xf bank_mask:0xf
	v_add_u32_e32 v131, s73, v80
	v_cndmask_b32_e64 v133, 0, 1, s[68:69]
	s_add_i32 s75, s74, 0xfffff400
	v_cvt_pk_bf16_f32 v135, v73, s0
	s_waitcnt lgkmcnt(0)
	v_add_f32_e32 v129, v129, v130
	s_nop 1
	v_mov_b32_dpp v130, v129 quad_perm:[2,3,0,1] row_mask:0xf bank_mask:0xf
	v_cvt_pk_bf16_f32 v136, v72, s0
	v_cmp_ne_u32_e64 s[0:1], 1, v133
	v_mov_b32_e32 v72, v33
	v_mov_b32_e32 v73, v49
	s_waitcnt lgkmcnt(0)
	v_add_f32_e32 v130, v129, v130
	s_nop 1
	v_mov_b32_dpp v132, v130 row_half_mirror row_mask:0xf bank_mask:0xf
	v_mul_lo_u32 v129, v131, s70
	v_add_u32_e32 v133, s75, v129
	v_add_u32_e32 v137, s76, v83
	s_andn2_b64 vcc, exec, s[68:69]
	s_waitcnt lgkmcnt(0)
	v_add_f32_e32 v131, v130, v132
	s_nop 1
	v_mov_b32_dpp v132, v131 row_mirror row_mask:0xf bank_mask:0xf
	v_add_u32_e32 v130, v133, v81
	s_waitcnt lgkmcnt(0)
	v_add_f32_e32 v134, v131, v132
	v_mov_b32_e32 v138, v134
	s_nop 1
	v_permlane16_swap_b32_e32 v134, v138
	s_nop 0
	v_add_u32_e32 v132, v133, v82
	v_ashrrev_i32_e32 v131, 31, v130
	v_ashrrev_i32_e32 v133, 31, v132
	v_lshl_add_u64 v[130:131], v[130:131], 1, s[6:7]
	s_waitcnt lgkmcnt(0)
	v_add_f32_e32 v134, v134, v138
	v_fmamk_f32 v134, v134, 0x3c800000, v119
	v_rsq_f32_e32 v134, v134
	v_lshl_add_u64 v[132:133], v[132:133], 1, s[6:7]
	global_store_short v[130:131], v135, off sc1
	global_store_short v[132:133], v136, off sc1
	v_pk_mul_f32 v[130:131], v[70:71], v[134:135] op_sel_hi:[1,0]
	s_nop 0
	v_pk_mul_f32 v[72:73], v[72:73], v[130:131]
	v_lshl_or_b32 v130, v137, 8, v142
	s_cbranch_vccnz .LBB0_581
	global_load_dwordx2 v[132:133], v130, s[8:9]
	s_waitcnt vmcnt(0)
	v_pk_mul_f32 v[136:137], v[72:73], v[132:133] op_sel_hi:[0,1]
	v_pk_mul_f32 v[134:135], v[72:73], v[132:133] op_sel:[1,1] op_sel_hi:[1,0]
	v_pk_fma_f32 v[72:73], v[72:73], v[132:133], v[136:137] op_sel:[1,1,0] op_sel_hi:[1,0,1] neg_lo:[0,0,1] neg_hi:[0,0,1]
	s_nop 0
	v_add_f32_e32 v72, v134, v136
.LBB0_581:
	v_mov_b32_e32 v132, v50
	v_mov_b32_e32 v133, v34
	v_pk_mul_f32 v[132:133], v[132:133], v[132:133]
	v_cvt_pk_bf16_f32 v138, v73, s0
	v_add_f32_e32 v131, v132, v133
	s_nop 1
	v_mov_b32_dpp v132, v131 quad_perm:[1,0,3,2] row_mask:0xf bank_mask:0xf
	v_add_u32_e32 v133, s73, v83
	v_mul_lo_u32 v133, v133, s70
	v_add_u32_e32 v135, s75, v133
	v_add_u32_e32 v134, v135, v81
	s_waitcnt lgkmcnt(0)
	v_add_f32_e32 v131, v131, v132
	s_nop 1
	v_mov_b32_dpp v132, v131 quad_perm:[2,3,0,1] row_mask:0xf bank_mask:0xf
	v_add_u32_e32 v136, v135, v82
	v_ashrrev_i32_e32 v135, 31, v134
	v_ashrrev_i32_e32 v137, 31, v136
	v_lshl_add_u64 v[134:135], v[134:135], 1, s[6:7]
	s_waitcnt lgkmcnt(0)
	v_add_f32_e32 v131, v131, v132
	s_nop 1
	v_mov_b32_dpp v132, v131 row_half_mirror row_mask:0xf bank_mask:0xf
	v_cvt_pk_bf16_f32 v139, v72, s0
	v_mov_b32_e32 v72, v34
	v_mov_b32_e32 v73, v50
	v_add_u32_e32 v140, s76, v84
	s_waitcnt lgkmcnt(0)
	v_add_f32_e32 v131, v131, v132
	s_nop 1
	v_mov_b32_dpp v132, v131 row_mirror row_mask:0xf bank_mask:0xf
	v_lshl_add_u64 v[136:137], v[136:137], 1, s[6:7]
	global_store_short v[134:135], v138, off sc1
	global_store_short v[136:137], v139, off sc1
	s_and_b64 vcc, exec, s[0:1]
	s_waitcnt lgkmcnt(0)
	v_add_f32_e32 v131, v131, v132
	v_mov_b32_e32 v132, v131
	s_nop 1
	v_permlane16_swap_b32_e32 v131, v132
	s_nop 0
	s_waitcnt lgkmcnt(0)
	v_add_f32_e32 v131, v131, v132
	v_fmamk_f32 v131, v131, 0x3c800000, v119
	v_rsq_f32_e32 v132, v131
	v_lshl_or_b32 v131, v140, 8, v142
	v_pk_mul_f32 v[134:135], v[70:71], v[132:133] op_sel_hi:[1,0]
	s_nop 0
	v_pk_mul_f32 v[72:73], v[72:73], v[134:135]
	s_cbranch_vccnz .LBB0_583
	global_load_dwordx2 v[134:135], v131, s[8:9]
	s_waitcnt vmcnt(0)
	v_pk_mul_f32 v[138:139], v[72:73], v[134:135] op_sel_hi:[0,1]
	v_pk_mul_f32 v[136:137], v[72:73], v[134:135] op_sel:[1,1] op_sel_hi:[1,0]
	v_pk_fma_f32 v[72:73], v[72:73], v[134:135], v[138:139] op_sel:[1,1,0] op_sel_hi:[1,0,1] neg_lo:[0,0,1] neg_hi:[0,0,1]
	s_nop 0
	v_add_f32_e32 v72, v136, v138
.LBB0_583:
	v_mov_b32_e32 v134, v51
	v_mov_b32_e32 v135, v35
	v_pk_mul_f32 v[134:135], v[134:135], v[134:135]
	v_cvt_pk_bf16_f32 v140, v73, s0
	v_add_f32_e32 v132, v134, v135
	s_nop 1
	v_mov_b32_dpp v134, v132 quad_perm:[1,0,3,2] row_mask:0xf bank_mask:0xf
	v_add_u32_e32 v135, s73, v84
	v_mul_lo_u32 v135, v135, s70
	v_add_u32_e32 v137, s75, v135
	v_add_u32_e32 v136, v137, v81
	s_waitcnt lgkmcnt(0)
	v_add_f32_e32 v132, v132, v134
	s_nop 1
	v_mov_b32_dpp v134, v132 quad_perm:[2,3,0,1] row_mask:0xf bank_mask:0xf
	v_add_u32_e32 v138, v137, v82
	v_ashrrev_i32_e32 v137, 31, v136
	v_ashrrev_i32_e32 v139, 31, v138
	v_lshl_add_u64 v[136:137], v[136:137], 1, s[6:7]
	s_waitcnt lgkmcnt(0)
	v_add_f32_e32 v132, v132, v134
	s_nop 1
	v_mov_b32_dpp v134, v132 row_half_mirror row_mask:0xf bank_mask:0xf
	v_cvt_pk_bf16_f32 v141, v72, s0
	v_mov_b32_e32 v72, v35
	v_mov_b32_e32 v73, v51
	v_add_u32_e32 v143, s76, v85
	s_waitcnt lgkmcnt(0)
	v_add_f32_e32 v132, v132, v134
	s_nop 1
	v_mov_b32_dpp v134, v132 row_mirror row_mask:0xf bank_mask:0xf
	v_lshl_add_u64 v[138:139], v[138:139], 1, s[6:7]
	global_store_short v[136:137], v140, off sc1
	global_store_short v[138:139], v141, off sc1
	s_and_b64 vcc, exec, s[0:1]
	s_waitcnt lgkmcnt(0)
	v_add_f32_e32 v132, v132, v134
	v_mov_b32_e32 v134, v132
	s_nop 1
	v_permlane16_swap_b32_e32 v132, v134
	s_nop 0
	s_waitcnt lgkmcnt(0)
	v_add_f32_e32 v132, v132, v134
	v_fmamk_f32 v132, v132, 0x3c800000, v119
	v_rsq_f32_e32 v132, v132
	s_nop 0
	v_pk_mul_f32 v[136:137], v[70:71], v[132:133] op_sel_hi:[1,0]
	s_nop 0
	v_pk_mul_f32 v[72:73], v[72:73], v[136:137]
	v_lshl_or_b32 v132, v143, 8, v142
	s_cbranch_vccnz .LBB0_585
	global_load_dwordx2 v[136:137], v132, s[8:9]
	s_waitcnt vmcnt(0)
	v_pk_mul_f32 v[140:141], v[72:73], v[136:137] op_sel_hi:[0,1]
	v_pk_mul_f32 v[138:139], v[72:73], v[136:137] op_sel:[1,1] op_sel_hi:[1,0]
	v_pk_fma_f32 v[72:73], v[72:73], v[136:137], v[140:141] op_sel:[1,1,0] op_sel_hi:[1,0,1] neg_lo:[0,0,1] neg_hi:[0,0,1]
	s_nop 0
	v_add_f32_e32 v72, v138, v140
.LBB0_585:
	v_mov_b32_e32 v136, v52
	v_mov_b32_e32 v137, v36
	v_pk_mul_f32 v[136:137], v[136:137], v[136:137]
	v_cvt_pk_bf16_f32 v143, v73, s0
	v_add_f32_e32 v134, v136, v137
	s_nop 1
	v_mov_b32_dpp v136, v134 quad_perm:[1,0,3,2] row_mask:0xf bank_mask:0xf
	v_add_u32_e32 v137, s73, v85
	v_mul_lo_u32 v137, v137, s70
	v_add_u32_e32 v139, s75, v137
	v_add_u32_e32 v138, v139, v81
	s_waitcnt lgkmcnt(0)
	v_add_f32_e32 v134, v134, v136
	s_nop 1
	v_mov_b32_dpp v136, v134 quad_perm:[2,3,0,1] row_mask:0xf bank_mask:0xf
	v_add_u32_e32 v140, v139, v82
	v_ashrrev_i32_e32 v139, 31, v138
	v_ashrrev_i32_e32 v141, 31, v140
	v_lshl_add_u64 v[138:139], v[138:139], 1, s[6:7]
	s_waitcnt lgkmcnt(0)
	v_add_f32_e32 v134, v134, v136
	s_nop 1
	v_mov_b32_dpp v136, v134 row_half_mirror row_mask:0xf bank_mask:0xf
	v_cvt_pk_bf16_f32 v144, v72, s0
	v_mov_b32_e32 v72, v36
	v_mov_b32_e32 v73, v52
	v_add_u32_e32 v145, s76, v86
	s_waitcnt lgkmcnt(0)
	v_add_f32_e32 v134, v134, v136
	s_nop 1
	v_mov_b32_dpp v136, v134 row_mirror row_mask:0xf bank_mask:0xf
	v_lshl_add_u64 v[140:141], v[140:141], 1, s[6:7]
	global_store_short v[138:139], v143, off sc1
	global_store_short v[140:141], v144, off sc1
	s_and_b64 vcc, exec, s[0:1]
	s_waitcnt lgkmcnt(0)
	v_add_f32_e32 v134, v134, v136
	v_mov_b32_e32 v136, v134
	s_nop 1
	v_permlane16_swap_b32_e32 v134, v136
	s_nop 0
	s_waitcnt lgkmcnt(0)
	v_add_f32_e32 v134, v134, v136
	v_fmamk_f32 v134, v134, 0x3c800000, v119
	v_rsq_f32_e32 v134, v134
	s_nop 0
	v_pk_mul_f32 v[138:139], v[70:71], v[134:135] op_sel_hi:[1,0]
	s_nop 0
	v_pk_mul_f32 v[72:73], v[72:73], v[138:139]
	v_lshl_or_b32 v134, v145, 8, v142
	s_cbranch_vccnz .LBB0_587
	global_load_dwordx2 v[138:139], v134, s[8:9]
	s_waitcnt vmcnt(0)
	v_pk_mul_f32 v[144:145], v[72:73], v[138:139] op_sel_hi:[0,1]
	v_pk_mul_f32 v[140:141], v[72:73], v[138:139] op_sel:[1,1] op_sel_hi:[1,0]
	v_pk_fma_f32 v[72:73], v[72:73], v[138:139], v[144:145] op_sel:[1,1,0] op_sel_hi:[1,0,1] neg_lo:[0,0,1] neg_hi:[0,0,1]
	s_nop 0
	v_add_f32_e32 v72, v140, v144
.LBB0_587:
	v_mov_b32_e32 v138, v53
	v_mov_b32_e32 v139, v37
	v_pk_mul_f32 v[138:139], v[138:139], v[138:139]
	v_cvt_pk_bf16_f32 v143, v73, s0
	v_add_f32_e32 v136, v138, v139
	s_nop 1
	v_mov_b32_dpp v138, v136 quad_perm:[1,0,3,2] row_mask:0xf bank_mask:0xf
	v_add_u32_e32 v139, s73, v86
	v_mul_lo_u32 v139, v139, s70
	v_add_u32_e32 v141, s75, v139
	v_add_u32_e32 v140, v141, v81
	s_waitcnt lgkmcnt(0)
	v_add_f32_e32 v136, v136, v138
	s_nop 1
	v_mov_b32_dpp v138, v136 quad_perm:[2,3,0,1] row_mask:0xf bank_mask:0xf
	v_add_u32_e32 v144, v141, v82
	v_ashrrev_i32_e32 v141, 31, v140
	v_ashrrev_i32_e32 v145, 31, v144
	v_lshl_add_u64 v[140:141], v[140:141], 1, s[6:7]
	s_waitcnt lgkmcnt(0)
	v_add_f32_e32 v136, v136, v138
	s_nop 1
	v_mov_b32_dpp v138, v136 row_half_mirror row_mask:0xf bank_mask:0xf
	v_cvt_pk_bf16_f32 v146, v72, s0
	v_mov_b32_e32 v72, v37
	v_mov_b32_e32 v73, v53
	v_add_u32_e32 v147, s76, v87
	s_waitcnt lgkmcnt(0)
	v_add_f32_e32 v136, v136, v138
	s_nop 1
	v_mov_b32_dpp v138, v136 row_mirror row_mask:0xf bank_mask:0xf
	v_lshl_add_u64 v[144:145], v[144:145], 1, s[6:7]
	global_store_short v[140:141], v143, off sc1
	global_store_short v[144:145], v146, off sc1
	s_and_b64 vcc, exec, s[0:1]
	s_waitcnt lgkmcnt(0)
	v_add_f32_e32 v136, v136, v138
	v_mov_b32_e32 v138, v136
	s_nop 1
	v_permlane16_swap_b32_e32 v136, v138
	s_nop 0
	s_waitcnt lgkmcnt(0)
	v_add_f32_e32 v136, v136, v138
	v_fmamk_f32 v136, v136, 0x3c800000, v119
	v_rsq_f32_e32 v136, v136
	s_nop 0
	v_pk_mul_f32 v[140:141], v[70:71], v[136:137] op_sel_hi:[1,0]
	s_nop 0
	v_pk_mul_f32 v[72:73], v[72:73], v[140:141]
	v_lshl_or_b32 v136, v147, 8, v142
	s_cbranch_vccnz .LBB0_589
	global_load_dwordx2 v[140:141], v136, s[8:9]
	s_waitcnt vmcnt(0)
	v_pk_mul_f32 v[146:147], v[72:73], v[140:141] op_sel_hi:[0,1]
	v_pk_mul_f32 v[144:145], v[72:73], v[140:141] op_sel:[1,1] op_sel_hi:[1,0]
	v_pk_fma_f32 v[72:73], v[72:73], v[140:141], v[146:147] op_sel:[1,1,0] op_sel_hi:[1,0,1] neg_lo:[0,0,1] neg_hi:[0,0,1]
	s_nop 0
	v_add_f32_e32 v72, v144, v146
.LBB0_589:
	v_mov_b32_e32 v140, v54
	v_mov_b32_e32 v141, v38
	v_pk_mul_f32 v[140:141], v[140:141], v[140:141]
	v_cvt_pk_bf16_f32 v143, v73, s0
	v_add_f32_e32 v138, v140, v141
	s_nop 1
	v_mov_b32_dpp v140, v138 quad_perm:[1,0,3,2] row_mask:0xf bank_mask:0xf
	v_add_u32_e32 v141, s73, v87
	v_mul_lo_u32 v141, v141, s70
	v_add_u32_e32 v145, s75, v141
	v_add_u32_e32 v144, v145, v81
	s_waitcnt lgkmcnt(0)
	v_add_f32_e32 v138, v138, v140
	s_nop 1
	v_mov_b32_dpp v140, v138 quad_perm:[2,3,0,1] row_mask:0xf bank_mask:0xf
	v_add_u32_e32 v146, v145, v82
	v_ashrrev_i32_e32 v145, 31, v144
	v_ashrrev_i32_e32 v147, 31, v146
	v_lshl_add_u64 v[144:145], v[144:145], 1, s[6:7]
	s_waitcnt lgkmcnt(0)
	v_add_f32_e32 v138, v138, v140
	s_nop 1
	v_mov_b32_dpp v140, v138 row_half_mirror row_mask:0xf bank_mask:0xf
	v_cvt_pk_bf16_f32 v148, v72, s0
	v_mov_b32_e32 v72, v38
	v_mov_b32_e32 v73, v54
	v_add_u32_e32 v149, s76, v88
	s_waitcnt lgkmcnt(0)
	v_add_f32_e32 v138, v138, v140
	s_nop 1
	v_mov_b32_dpp v140, v138 row_mirror row_mask:0xf bank_mask:0xf
	v_lshl_add_u64 v[146:147], v[146:147], 1, s[6:7]
	global_store_short v[144:145], v143, off sc1
	global_store_short v[146:147], v148, off sc1
	s_and_b64 vcc, exec, s[0:1]
	s_waitcnt lgkmcnt(0)
	v_add_f32_e32 v138, v138, v140
	v_mov_b32_e32 v140, v138
	s_nop 1
	v_permlane16_swap_b32_e32 v138, v140
	s_nop 0
	s_waitcnt lgkmcnt(0)
	v_add_f32_e32 v138, v138, v140
	v_fmamk_f32 v138, v138, 0x3c800000, v119
	v_rsq_f32_e32 v138, v138
	s_nop 0
	v_pk_mul_f32 v[144:145], v[70:71], v[138:139] op_sel_hi:[1,0]
	s_nop 0
	v_pk_mul_f32 v[72:73], v[72:73], v[144:145]
	v_lshl_or_b32 v138, v149, 8, v142
	s_cbranch_vccnz .LBB0_591
	global_load_dwordx2 v[144:145], v138, s[8:9]
	s_waitcnt vmcnt(0)
	v_pk_mul_f32 v[148:149], v[72:73], v[144:145] op_sel_hi:[0,1]
	v_pk_mul_f32 v[146:147], v[72:73], v[144:145] op_sel:[1,1] op_sel_hi:[1,0]
	v_pk_fma_f32 v[72:73], v[72:73], v[144:145], v[148:149] op_sel:[1,1,0] op_sel_hi:[1,0,1] neg_lo:[0,0,1] neg_hi:[0,0,1]
	s_nop 0
	v_add_f32_e32 v72, v146, v148
.LBB0_591:
	v_mov_b32_e32 v144, v55
	v_mov_b32_e32 v145, v39
	v_pk_mul_f32 v[144:145], v[144:145], v[144:145]
	v_cvt_pk_bf16_f32 v150, v72, s0
	v_add_f32_e32 v140, v144, v145
	s_nop 1
	v_mov_b32_dpp v143, v140 quad_perm:[1,0,3,2] row_mask:0xf bank_mask:0xf
	v_add_u32_e32 v144, s73, v88
	v_mul_lo_u32 v144, v144, s70
	v_add_u32_e32 v147, s75, v144
	v_add_u32_e32 v146, v147, v81
	s_waitcnt lgkmcnt(0)
	v_add_f32_e32 v140, v140, v143
	s_nop 1
	v_mov_b32_dpp v143, v140 quad_perm:[2,3,0,1] row_mask:0xf bank_mask:0xf
	v_add_u32_e32 v148, v147, v82
	v_ashrrev_i32_e32 v147, 31, v146
	v_cvt_pk_bf16_f32 v145, v73, s0
	v_ashrrev_i32_e32 v149, 31, v148
	s_waitcnt lgkmcnt(0)
	v_add_f32_e32 v140, v140, v143
	s_nop 1
	v_mov_b32_dpp v143, v140 row_half_mirror row_mask:0xf bank_mask:0xf
	v_lshl_add_u64 v[146:147], v[146:147], 1, s[6:7]
	v_mov_b32_e32 v72, v39
	v_mov_b32_e32 v73, v55
	v_add_u32_e32 v151, s76, v89
	s_waitcnt lgkmcnt(0)
	v_add_f32_e32 v140, v140, v143
	s_nop 1
	v_mov_b32_dpp v143, v140 row_mirror row_mask:0xf bank_mask:0xf
	v_lshl_add_u64 v[148:149], v[148:149], 1, s[6:7]
	global_store_short v[146:147], v145, off sc1
	global_store_short v[148:149], v150, off sc1
	s_and_b64 vcc, exec, s[0:1]
	s_waitcnt lgkmcnt(0)
	v_add_f32_e32 v140, v140, v143
	v_mov_b32_e32 v143, v140
	s_nop 1
	v_permlane16_swap_b32_e32 v140, v143
	s_nop 0
	s_waitcnt lgkmcnt(0)
	v_add_f32_e32 v140, v140, v143
	v_fmamk_f32 v140, v140, 0x3c800000, v119
	v_rsq_f32_e32 v140, v140
	s_nop 0
	v_pk_mul_f32 v[146:147], v[70:71], v[140:141] op_sel_hi:[1,0]
	s_nop 0
	v_pk_mul_f32 v[72:73], v[72:73], v[146:147]
	v_lshl_or_b32 v140, v151, 8, v142
	s_cbranch_vccnz .LBB0_593
	global_load_dwordx2 v[146:147], v140, s[8:9]
	s_waitcnt vmcnt(0)
	v_pk_mul_f32 v[150:151], v[72:73], v[146:147] op_sel_hi:[0,1]
	v_pk_mul_f32 v[148:149], v[72:73], v[146:147] op_sel:[1,1] op_sel_hi:[1,0]
	v_pk_fma_f32 v[72:73], v[72:73], v[146:147], v[150:151] op_sel:[1,1,0] op_sel_hi:[1,0,1] neg_lo:[0,0,1] neg_hi:[0,0,1]
	s_nop 0
	v_add_f32_e32 v72, v148, v150
.LBB0_593:
	v_mov_b32_e32 v146, v56
	v_mov_b32_e32 v147, v40
	v_pk_mul_f32 v[146:147], v[146:147], v[146:147]
	v_cvt_pk_bf16_f32 v153, v72, s0
	v_add_f32_e32 v143, v146, v147
	s_nop 1
	v_mov_b32_dpp v145, v143 quad_perm:[1,0,3,2] row_mask:0xf bank_mask:0xf
	v_add_u32_e32 v146, s73, v89
	v_mul_lo_u32 v146, v146, s70
	v_add_u32_e32 v149, s75, v146
	v_add_u32_e32 v148, v149, v81
	s_waitcnt lgkmcnt(0)
	v_add_f32_e32 v143, v143, v145
	s_nop 1
	v_mov_b32_dpp v145, v143 quad_perm:[2,3,0,1] row_mask:0xf bank_mask:0xf
	v_add_u32_e32 v150, v149, v82
	v_ashrrev_i32_e32 v149, 31, v148
	v_cvt_pk_bf16_f32 v147, v73, s0
	v_ashrrev_i32_e32 v151, 31, v150
	s_waitcnt lgkmcnt(0)
	v_add_f32_e32 v143, v143, v145
	s_nop 1
	v_mov_b32_dpp v145, v143 row_half_mirror row_mask:0xf bank_mask:0xf
	v_lshl_add_u64 v[148:149], v[148:149], 1, s[6:7]
	v_mov_b32_e32 v72, v40
	v_mov_b32_e32 v73, v56
	v_add_u32_e32 v154, s76, v90
	s_waitcnt lgkmcnt(0)
	v_add_f32_e32 v143, v143, v145
	s_nop 1
	v_mov_b32_dpp v145, v143 row_mirror row_mask:0xf bank_mask:0xf
	v_lshl_add_u64 v[150:151], v[150:151], 1, s[6:7]
	global_store_short v[148:149], v147, off sc1
	global_store_short v[150:151], v153, off sc1
	s_and_b64 vcc, exec, s[0:1]
	s_waitcnt lgkmcnt(0)
	v_add_f32_e32 v143, v143, v145
	v_mov_b32_e32 v145, v143
	s_nop 1
	v_permlane16_swap_b32_e32 v143, v145
	s_nop 0
	s_waitcnt lgkmcnt(0)
	v_add_f32_e32 v143, v143, v145
	v_fmamk_f32 v143, v143, 0x3c800000, v119
	v_rsq_f32_e32 v152, v143
	v_lshl_or_b32 v143, v154, 8, v142
	v_pk_mul_f32 v[148:149], v[70:71], v[152:153] op_sel_hi:[1,0]
	s_nop 0
	v_pk_mul_f32 v[72:73], v[72:73], v[148:149]
	s_cbranch_vccnz .LBB0_595
	global_load_dwordx2 v[148:149], v143, s[8:9]
	s_waitcnt vmcnt(0)
	v_pk_mul_f32 v[152:153], v[72:73], v[148:149] op_sel_hi:[0,1]
	v_pk_mul_f32 v[150:151], v[72:73], v[148:149] op_sel:[1,1] op_sel_hi:[1,0]
	v_pk_fma_f32 v[72:73], v[72:73], v[148:149], v[152:153] op_sel:[1,1,0] op_sel_hi:[1,0,1] neg_lo:[0,0,1] neg_hi:[0,0,1]
	s_nop 0
	v_add_f32_e32 v72, v150, v152
.LBB0_595:
	v_mov_b32_e32 v148, v57
	v_mov_b32_e32 v149, v41
	v_pk_mul_f32 v[148:149], v[148:149], v[148:149]
	v_cvt_pk_bf16_f32 v155, v72, s0
	v_add_f32_e32 v145, v148, v149
	s_nop 1
	v_mov_b32_dpp v147, v145 quad_perm:[1,0,3,2] row_mask:0xf bank_mask:0xf
	v_add_u32_e32 v148, s73, v90
	v_mul_lo_u32 v148, v148, s70
	v_add_u32_e32 v151, s75, v148
	v_add_u32_e32 v150, v151, v81
	s_waitcnt lgkmcnt(0)
	v_add_f32_e32 v145, v145, v147
	s_nop 1
	v_mov_b32_dpp v147, v145 quad_perm:[2,3,0,1] row_mask:0xf bank_mask:0xf
	v_add_u32_e32 v152, v151, v82
	v_ashrrev_i32_e32 v151, 31, v150
	v_cvt_pk_bf16_f32 v149, v73, s0
	v_ashrrev_i32_e32 v153, 31, v152
	s_waitcnt lgkmcnt(0)
	v_add_f32_e32 v145, v145, v147
	s_nop 1
	v_mov_b32_dpp v147, v145 row_half_mirror row_mask:0xf bank_mask:0xf
	v_lshl_add_u64 v[150:151], v[150:151], 1, s[6:7]
	v_mov_b32_e32 v72, v41
	v_mov_b32_e32 v73, v57
	v_add_u32_e32 v156, s76, v91
	s_waitcnt lgkmcnt(0)
	v_add_f32_e32 v145, v145, v147
	s_nop 1
	v_mov_b32_dpp v147, v145 row_mirror row_mask:0xf bank_mask:0xf
	v_lshl_add_u64 v[152:153], v[152:153], 1, s[6:7]
	global_store_short v[150:151], v149, off sc1
	global_store_short v[152:153], v155, off sc1
	s_and_b64 vcc, exec, s[0:1]
	s_waitcnt lgkmcnt(0)
	v_add_f32_e32 v145, v145, v147
	v_mov_b32_e32 v147, v145
	s_nop 1
	v_permlane16_swap_b32_e32 v145, v147
	s_nop 0
	s_waitcnt lgkmcnt(0)
	v_add_f32_e32 v145, v145, v147
	v_fmamk_f32 v145, v145, 0x3c800000, v119
	v_rsq_f32_e32 v154, v145
	v_lshl_or_b32 v145, v156, 8, v142
	v_pk_mul_f32 v[150:151], v[70:71], v[154:155] op_sel_hi:[1,0]
	s_nop 0
	v_pk_mul_f32 v[72:73], v[72:73], v[150:151]
	s_cbranch_vccnz .LBB0_597
	global_load_dwordx2 v[150:151], v145, s[8:9]
	s_waitcnt vmcnt(0)
	v_pk_mul_f32 v[154:155], v[72:73], v[150:151] op_sel_hi:[0,1]
	v_pk_mul_f32 v[152:153], v[72:73], v[150:151] op_sel:[1,1] op_sel_hi:[1,0]
	v_pk_fma_f32 v[72:73], v[72:73], v[150:151], v[154:155] op_sel:[1,1,0] op_sel_hi:[1,0,1] neg_lo:[0,0,1] neg_hi:[0,0,1]
	s_nop 0
	v_add_f32_e32 v72, v152, v154
.LBB0_597:
	v_mov_b32_e32 v150, v58
	v_mov_b32_e32 v151, v42
	v_pk_mul_f32 v[150:151], v[150:151], v[150:151]
	v_cvt_pk_bf16_f32 v157, v72, s0
	v_add_f32_e32 v147, v150, v151
	s_nop 1
	v_mov_b32_dpp v149, v147 quad_perm:[1,0,3,2] row_mask:0xf bank_mask:0xf
	v_add_u32_e32 v150, s73, v91
	v_mul_lo_u32 v150, v150, s70
	v_add_u32_e32 v153, s75, v150
	v_add_u32_e32 v152, v153, v81
	s_waitcnt lgkmcnt(0)
	v_add_f32_e32 v147, v147, v149
	s_nop 1
	v_mov_b32_dpp v149, v147 quad_perm:[2,3,0,1] row_mask:0xf bank_mask:0xf
	v_add_u32_e32 v154, v153, v82
	v_ashrrev_i32_e32 v153, 31, v152
	v_cvt_pk_bf16_f32 v151, v73, s0
	v_ashrrev_i32_e32 v155, 31, v154
	s_waitcnt lgkmcnt(0)
	v_add_f32_e32 v147, v147, v149
	s_nop 1
	v_mov_b32_dpp v149, v147 row_half_mirror row_mask:0xf bank_mask:0xf
	v_lshl_add_u64 v[152:153], v[152:153], 1, s[6:7]
	v_mov_b32_e32 v72, v42
	v_mov_b32_e32 v73, v58
	v_add_u32_e32 v158, s76, v92
	s_waitcnt lgkmcnt(0)
	v_add_f32_e32 v147, v147, v149
	s_nop 1
	v_mov_b32_dpp v149, v147 row_mirror row_mask:0xf bank_mask:0xf
	v_lshl_add_u64 v[154:155], v[154:155], 1, s[6:7]
	global_store_short v[152:153], v151, off sc1
	global_store_short v[154:155], v157, off sc1
	s_and_b64 vcc, exec, s[0:1]
	s_waitcnt lgkmcnt(0)
	v_add_f32_e32 v147, v147, v149
	v_mov_b32_e32 v149, v147
	s_nop 1
	v_permlane16_swap_b32_e32 v147, v149
	s_nop 0
	s_waitcnt lgkmcnt(0)
	v_add_f32_e32 v147, v147, v149
	v_fmamk_f32 v147, v147, 0x3c800000, v119
	v_rsq_f32_e32 v156, v147
	v_lshl_or_b32 v147, v158, 8, v142
	v_pk_mul_f32 v[152:153], v[70:71], v[156:157] op_sel_hi:[1,0]
	s_nop 0
	v_pk_mul_f32 v[72:73], v[72:73], v[152:153]
	s_cbranch_vccnz .LBB0_599
	global_load_dwordx2 v[152:153], v147, s[8:9]
	s_waitcnt vmcnt(0)
	v_pk_mul_f32 v[156:157], v[72:73], v[152:153] op_sel_hi:[0,1]
	v_pk_mul_f32 v[154:155], v[72:73], v[152:153] op_sel:[1,1] op_sel_hi:[1,0]
	v_pk_fma_f32 v[72:73], v[72:73], v[152:153], v[156:157] op_sel:[1,1,0] op_sel_hi:[1,0,1] neg_lo:[0,0,1] neg_hi:[0,0,1]
	s_nop 0
	v_add_f32_e32 v72, v154, v156
.LBB0_599:
	v_mov_b32_e32 v152, v59
	v_mov_b32_e32 v153, v43
	v_pk_mul_f32 v[152:153], v[152:153], v[152:153]
	v_cvt_pk_bf16_f32 v159, v72, s0
	v_add_f32_e32 v149, v152, v153
	s_nop 1
	v_mov_b32_dpp v151, v149 quad_perm:[1,0,3,2] row_mask:0xf bank_mask:0xf
	v_add_u32_e32 v152, s73, v92
	v_mul_lo_u32 v152, v152, s70
	v_add_u32_e32 v155, s75, v152
	v_add_u32_e32 v154, v155, v81
	s_waitcnt lgkmcnt(0)
	v_add_f32_e32 v149, v149, v151
	s_nop 1
	v_mov_b32_dpp v151, v149 quad_perm:[2,3,0,1] row_mask:0xf bank_mask:0xf
	v_add_u32_e32 v156, v155, v82
	v_ashrrev_i32_e32 v155, 31, v154
	v_cvt_pk_bf16_f32 v153, v73, s0
	v_ashrrev_i32_e32 v157, 31, v156
	s_waitcnt lgkmcnt(0)
	v_add_f32_e32 v149, v149, v151
	s_nop 1
	v_mov_b32_dpp v151, v149 row_half_mirror row_mask:0xf bank_mask:0xf
	v_lshl_add_u64 v[154:155], v[154:155], 1, s[6:7]
	v_mov_b32_e32 v72, v43
	v_mov_b32_e32 v73, v59
	v_add_u32_e32 v160, s76, v93
	s_waitcnt lgkmcnt(0)
	v_add_f32_e32 v149, v149, v151
	s_nop 1
	v_mov_b32_dpp v151, v149 row_mirror row_mask:0xf bank_mask:0xf
	v_lshl_add_u64 v[156:157], v[156:157], 1, s[6:7]
	global_store_short v[154:155], v153, off sc1
	global_store_short v[156:157], v159, off sc1
	s_and_b64 vcc, exec, s[0:1]
	s_waitcnt lgkmcnt(0)
	v_add_f32_e32 v149, v149, v151
	v_mov_b32_e32 v151, v149
	s_nop 1
	v_permlane16_swap_b32_e32 v149, v151
	s_nop 0
	s_waitcnt lgkmcnt(0)
	v_add_f32_e32 v149, v149, v151
	v_fmamk_f32 v149, v149, 0x3c800000, v119
	v_rsq_f32_e32 v158, v149
	v_lshl_or_b32 v149, v160, 8, v142
	v_pk_mul_f32 v[154:155], v[70:71], v[158:159] op_sel_hi:[1,0]
	s_nop 0
	v_pk_mul_f32 v[72:73], v[72:73], v[154:155]
	s_cbranch_vccnz .LBB0_601
	global_load_dwordx2 v[154:155], v149, s[8:9]
	s_waitcnt vmcnt(0)
	v_pk_mul_f32 v[158:159], v[72:73], v[154:155] op_sel_hi:[0,1]
	v_pk_mul_f32 v[156:157], v[72:73], v[154:155] op_sel:[1,1] op_sel_hi:[1,0]
	v_pk_fma_f32 v[72:73], v[72:73], v[154:155], v[158:159] op_sel:[1,1,0] op_sel_hi:[1,0,1] neg_lo:[0,0,1] neg_hi:[0,0,1]
	s_nop 0
	v_add_f32_e32 v72, v156, v158
.LBB0_601:
	v_mov_b32_e32 v154, v60
	v_mov_b32_e32 v155, v44
	v_pk_mul_f32 v[154:155], v[154:155], v[154:155]
	v_cvt_pk_bf16_f32 v161, v72, s0
	v_add_f32_e32 v151, v154, v155
	s_nop 1
	v_mov_b32_dpp v153, v151 quad_perm:[1,0,3,2] row_mask:0xf bank_mask:0xf
	v_add_u32_e32 v154, s73, v93
	v_mul_lo_u32 v154, v154, s70
	v_add_u32_e32 v157, s75, v154
	v_add_u32_e32 v156, v157, v81
	s_waitcnt lgkmcnt(0)
	v_add_f32_e32 v151, v151, v153
	s_nop 1
	v_mov_b32_dpp v153, v151 quad_perm:[2,3,0,1] row_mask:0xf bank_mask:0xf
	v_add_u32_e32 v158, v157, v82
	v_ashrrev_i32_e32 v157, 31, v156
	v_cvt_pk_bf16_f32 v155, v73, s0
	v_ashrrev_i32_e32 v159, 31, v158
	s_waitcnt lgkmcnt(0)
	v_add_f32_e32 v151, v151, v153
	s_nop 1
	v_mov_b32_dpp v153, v151 row_half_mirror row_mask:0xf bank_mask:0xf
	v_lshl_add_u64 v[156:157], v[156:157], 1, s[6:7]
	v_mov_b32_e32 v72, v44
	v_mov_b32_e32 v73, v60
	v_add_u32_e32 v162, s76, v94
	s_waitcnt lgkmcnt(0)
	v_add_f32_e32 v151, v151, v153
	s_nop 1
	v_mov_b32_dpp v153, v151 row_mirror row_mask:0xf bank_mask:0xf
	v_lshl_add_u64 v[158:159], v[158:159], 1, s[6:7]
	global_store_short v[156:157], v155, off sc1
	global_store_short v[158:159], v161, off sc1
	s_and_b64 vcc, exec, s[0:1]
	s_waitcnt lgkmcnt(0)
	v_add_f32_e32 v151, v151, v153
	v_mov_b32_e32 v153, v151
	s_nop 1
	v_permlane16_swap_b32_e32 v151, v153
	s_nop 0
	s_waitcnt lgkmcnt(0)
	v_add_f32_e32 v151, v151, v153
	v_fmamk_f32 v151, v151, 0x3c800000, v119
	v_rsq_f32_e32 v160, v151
	v_lshl_or_b32 v151, v162, 8, v142
	v_pk_mul_f32 v[156:157], v[70:71], v[160:161] op_sel_hi:[1,0]
	s_nop 0
	v_pk_mul_f32 v[72:73], v[72:73], v[156:157]
	s_cbranch_vccnz .LBB0_603
	global_load_dwordx2 v[156:157], v151, s[8:9]
	s_waitcnt vmcnt(0)
	v_pk_mul_f32 v[160:161], v[72:73], v[156:157] op_sel_hi:[0,1]
	v_pk_mul_f32 v[158:159], v[72:73], v[156:157] op_sel:[1,1] op_sel_hi:[1,0]
	v_pk_fma_f32 v[72:73], v[72:73], v[156:157], v[160:161] op_sel:[1,1,0] op_sel_hi:[1,0,1] neg_lo:[0,0,1] neg_hi:[0,0,1]
	s_nop 0
	v_add_f32_e32 v72, v158, v160
.LBB0_603:
	v_mov_b32_e32 v156, v61
	v_mov_b32_e32 v157, v45
	v_pk_mul_f32 v[156:157], v[156:157], v[156:157]
	v_cvt_pk_bf16_f32 v163, v72, s0
	v_add_f32_e32 v153, v156, v157
	s_nop 1
	v_mov_b32_dpp v155, v153 quad_perm:[1,0,3,2] row_mask:0xf bank_mask:0xf
	v_add_u32_e32 v156, s73, v94
	v_mul_lo_u32 v156, v156, s70
	v_add_u32_e32 v159, s75, v156
	v_add_u32_e32 v158, v159, v81
	s_waitcnt lgkmcnt(0)
	v_add_f32_e32 v153, v153, v155
	s_nop 1
	v_mov_b32_dpp v155, v153 quad_perm:[2,3,0,1] row_mask:0xf bank_mask:0xf
	v_add_u32_e32 v160, v159, v82
	v_ashrrev_i32_e32 v159, 31, v158
	v_cvt_pk_bf16_f32 v157, v73, s0
	v_ashrrev_i32_e32 v161, 31, v160
	s_waitcnt lgkmcnt(0)
	v_add_f32_e32 v153, v153, v155
	s_nop 1
	v_mov_b32_dpp v155, v153 row_half_mirror row_mask:0xf bank_mask:0xf
	v_lshl_add_u64 v[158:159], v[158:159], 1, s[6:7]
	v_mov_b32_e32 v72, v45
	v_mov_b32_e32 v73, v61
	v_add_u32_e32 v164, s76, v95
	s_waitcnt lgkmcnt(0)
	v_add_f32_e32 v153, v153, v155
	s_nop 1
	v_mov_b32_dpp v155, v153 row_mirror row_mask:0xf bank_mask:0xf
	v_lshl_add_u64 v[160:161], v[160:161], 1, s[6:7]
	global_store_short v[158:159], v157, off sc1
	global_store_short v[160:161], v163, off sc1
	s_and_b64 vcc, exec, s[0:1]
	s_waitcnt lgkmcnt(0)
	v_add_f32_e32 v153, v153, v155
	v_mov_b32_e32 v155, v153
	s_nop 1
	v_permlane16_swap_b32_e32 v153, v155
	s_nop 0
	s_waitcnt lgkmcnt(0)
	v_add_f32_e32 v153, v153, v155
	v_fmamk_f32 v153, v153, 0x3c800000, v119
	v_rsq_f32_e32 v162, v153
	v_lshl_or_b32 v153, v164, 8, v142
	v_pk_mul_f32 v[158:159], v[70:71], v[162:163] op_sel_hi:[1,0]
	s_nop 0
	v_pk_mul_f32 v[72:73], v[72:73], v[158:159]
	s_cbranch_vccnz .LBB0_605
	global_load_dwordx2 v[158:159], v153, s[8:9]
	s_waitcnt vmcnt(0)
	v_pk_mul_f32 v[162:163], v[72:73], v[158:159] op_sel_hi:[0,1]
	v_pk_mul_f32 v[160:161], v[72:73], v[158:159] op_sel:[1,1] op_sel_hi:[1,0]
	v_pk_fma_f32 v[72:73], v[72:73], v[158:159], v[162:163] op_sel:[1,1,0] op_sel_hi:[1,0,1] neg_lo:[0,0,1] neg_hi:[0,0,1]
	s_nop 0
	v_add_f32_e32 v72, v160, v162
.LBB0_605:
	v_mov_b32_e32 v158, v62
	v_mov_b32_e32 v159, v46
	v_pk_mul_f32 v[158:159], v[158:159], v[158:159]
	v_cvt_pk_bf16_f32 v163, v73, s0
	v_add_f32_e32 v155, v158, v159
	s_nop 1
	v_mov_b32_dpp v157, v155 quad_perm:[1,0,3,2] row_mask:0xf bank_mask:0xf
	v_add_u32_e32 v158, s73, v95
	v_cvt_pk_bf16_f32 v164, v72, s0
	v_mov_b32_e32 v72, v46
	v_mov_b32_e32 v73, v62
	s_waitcnt lgkmcnt(0)
	v_add_f32_e32 v155, v155, v157
	s_nop 1
	v_mov_b32_dpp v157, v155 quad_perm:[2,3,0,1] row_mask:0xf bank_mask:0xf
	v_add_u32_e32 v165, s76, v96
	s_and_b64 vcc, exec, s[0:1]
	s_waitcnt lgkmcnt(0)
	v_add_f32_e32 v155, v155, v157
	s_nop 1
	v_mov_b32_dpp v157, v155 row_half_mirror row_mask:0xf bank_mask:0xf
	s_waitcnt lgkmcnt(0)
	v_add_f32_e32 v155, v155, v157
	s_nop 1
	v_mov_b32_dpp v159, v155 row_mirror row_mask:0xf bank_mask:0xf
	v_mul_lo_u32 v157, v158, s70
	v_add_u32_e32 v160, s75, v157
	v_add_u32_e32 v158, v160, v81
	v_add_u32_e32 v160, v160, v82
	s_waitcnt lgkmcnt(0)
	v_add_f32_e32 v155, v155, v159
	v_mov_b32_e32 v162, v155
	s_nop 1
	v_permlane16_swap_b32_e32 v155, v162
	s_nop 0
	v_ashrrev_i32_e32 v159, 31, v158
	v_ashrrev_i32_e32 v161, 31, v160
	v_lshl_add_u64 v[158:159], v[158:159], 1, s[6:7]
	v_lshl_add_u64 v[160:161], v[160:161], 1, s[6:7]
	s_waitcnt lgkmcnt(0)
	v_add_f32_e32 v155, v155, v162
	v_fmamk_f32 v155, v155, 0x3c800000, v119
	v_rsq_f32_e32 v162, v155
	global_store_short v[158:159], v163, off sc1
	global_store_short v[160:161], v164, off sc1
	v_lshl_or_b32 v155, v165, 8, v142
	v_pk_mul_f32 v[158:159], v[70:71], v[162:163] op_sel_hi:[1,0]
	s_nop 0
	v_pk_mul_f32 v[72:73], v[72:73], v[158:159]
	s_cbranch_vccnz .LBB0_607
	global_load_dwordx2 v[158:159], v155, s[8:9]
	s_waitcnt vmcnt(0)
	v_pk_mul_f32 v[162:163], v[72:73], v[158:159] op_sel_hi:[0,1]
	v_pk_mul_f32 v[160:161], v[72:73], v[158:159] op_sel:[1,1] op_sel_hi:[1,0]
	v_pk_fma_f32 v[72:73], v[72:73], v[158:159], v[162:163] op_sel:[1,1,0] op_sel_hi:[1,0,1] neg_lo:[0,0,1] neg_hi:[0,0,1]
	s_nop 0
	v_add_f32_e32 v72, v160, v162
.LBB0_607:
	v_mov_b32_e32 v158, v63
	v_mov_b32_e32 v159, v47
	v_pk_mul_f32 v[158:159], v[158:159], v[158:159]
	v_add_u32_e32 v160, s73, v96
	v_add_f32_e32 v158, v158, v159
	s_nop 1
	v_mov_b32_dpp v159, v158 quad_perm:[1,0,3,2] row_mask:0xf bank_mask:0xf
	v_cvt_pk_bf16_f32 v165, v73, s0
	v_cvt_pk_bf16_f32 v166, v72, s0
	v_mov_b32_e32 v72, v47
	v_mov_b32_e32 v73, v63
	s_waitcnt lgkmcnt(0)
	v_add_f32_e32 v158, v158, v159
	s_nop 1
	v_mov_b32_dpp v159, v158 quad_perm:[2,3,0,1] row_mask:0xf bank_mask:0xf
	v_add_u32_e32 v167, s76, v97
	s_and_b64 vcc, exec, s[0:1]
	v_lshl_or_b32 v142, v167, 8, v142
	s_waitcnt lgkmcnt(0)
	v_add_f32_e32 v158, v158, v159
	s_nop 1
	v_mov_b32_dpp v159, v158 row_half_mirror row_mask:0xf bank_mask:0xf
	s_waitcnt lgkmcnt(0)
	v_add_f32_e32 v159, v158, v159
	s_nop 1
	v_mov_b32_dpp v161, v159 row_mirror row_mask:0xf bank_mask:0xf
	v_mul_lo_u32 v158, v160, s70
	v_add_u32_e32 v162, s75, v158
	v_add_u32_e32 v160, v162, v81
	v_add_u32_e32 v162, v162, v82
	s_waitcnt lgkmcnt(0)
	v_add_f32_e32 v159, v159, v161
	v_mov_b32_e32 v164, v159
	s_nop 1
	v_permlane16_swap_b32_e32 v159, v164
	s_nop 0
	v_ashrrev_i32_e32 v161, 31, v160
	v_ashrrev_i32_e32 v163, 31, v162
	v_lshl_add_u64 v[160:161], v[160:161], 1, s[6:7]
	v_lshl_add_u64 v[162:163], v[162:163], 1, s[6:7]
	s_waitcnt lgkmcnt(0)
	v_add_f32_e32 v159, v159, v164
	v_fmamk_f32 v159, v159, 0x3c800000, v119
	v_rsq_f32_e32 v164, v159
	global_store_short v[160:161], v165, off sc1
	global_store_short v[162:163], v166, off sc1
	v_pk_mul_f32 v[160:161], v[70:71], v[164:165] op_sel_hi:[1,0]
	s_nop 0
	v_pk_mul_f32 v[72:73], v[72:73], v[160:161]
	s_cbranch_vccnz .LBB0_609
	global_load_dwordx2 v[160:161], v142, s[8:9]
	s_waitcnt vmcnt(0)
	v_pk_mul_f32 v[164:165], v[72:73], v[160:161] op_sel_hi:[0,1]
	v_pk_mul_f32 v[162:163], v[72:73], v[160:161] op_sel:[1,1] op_sel_hi:[1,0]
	v_pk_fma_f32 v[72:73], v[72:73], v[160:161], v[164:165] op_sel:[1,1,0] op_sel_hi:[1,0,1] neg_lo:[0,0,1] neg_hi:[0,0,1]
	s_nop 0
	v_add_f32_e32 v72, v162, v164
.LBB0_609:
	v_mov_b32_e32 v160, v16
	v_mov_b32_e32 v161, v0
	v_pk_mul_f32 v[160:161], v[160:161], v[160:161]
	v_cvt_pk_bf16_f32 v165, v73, s0
	v_add_f32_e32 v159, v160, v161
	s_nop 1
	v_mov_b32_dpp v160, v159 quad_perm:[1,0,3,2] row_mask:0xf bank_mask:0xf
	v_add_u32_e32 v161, s73, v97
	v_cvt_pk_bf16_f32 v166, v72, s0
	v_mov_b32_e32 v72, v0
	v_mov_b32_e32 v73, v16
	s_waitcnt lgkmcnt(0)
	v_add_f32_e32 v159, v159, v160
	s_nop 1
	v_mov_b32_dpp v160, v159 quad_perm:[2,3,0,1] row_mask:0xf bank_mask:0xf
	s_and_b64 vcc, exec, s[0:1]
	s_waitcnt lgkmcnt(0)
	v_add_f32_e32 v159, v159, v160
	s_nop 1
	v_mov_b32_dpp v160, v159 row_half_mirror row_mask:0xf bank_mask:0xf
	s_waitcnt lgkmcnt(0)
	v_add_f32_e32 v162, v159, v160
	s_nop 1
	v_mov_b32_dpp v163, v162 row_mirror row_mask:0xf bank_mask:0xf
	v_mul_lo_u32 v159, v161, s70
	v_add_u32_e32 v161, s75, v159
	v_add_u32_e32 v160, v161, v81
	s_waitcnt lgkmcnt(0)
	v_add_f32_e32 v164, v162, v163
	v_mov_b32_e32 v167, v164
	s_nop 1
	v_permlane16_swap_b32_e32 v164, v167
	s_nop 0
	v_add_u32_e32 v162, v161, v82
	v_ashrrev_i32_e32 v161, 31, v160
	v_ashrrev_i32_e32 v163, 31, v162
	v_lshl_add_u64 v[160:161], v[160:161], 1, s[6:7]
	s_waitcnt lgkmcnt(0)
	v_add_f32_e32 v164, v164, v167
	v_fmamk_f32 v164, v164, 0x3c800000, v119
	v_rsq_f32_e32 v164, v164
	v_lshl_add_u64 v[162:163], v[162:163], 1, s[6:7]
	global_store_short v[160:161], v165, off sc1
	global_store_short v[162:163], v166, off sc1
	v_pk_mul_f32 v[160:161], v[70:71], v[164:165] op_sel_hi:[1,0]
	s_nop 0
	v_pk_mul_f32 v[72:73], v[72:73], v[160:161]
	s_cbranch_vccnz .LBB0_611
	global_load_dwordx2 v[160:161], v128, s[8:9]
	s_waitcnt vmcnt(0)
	v_pk_mul_f32 v[164:165], v[72:73], v[160:161] op_sel_hi:[0,1]
	v_pk_mul_f32 v[162:163], v[72:73], v[160:161] op_sel:[1,1] op_sel_hi:[1,0]
	v_pk_fma_f32 v[72:73], v[72:73], v[160:161], v[164:165] op_sel:[1,1,0] op_sel_hi:[1,0,1] neg_lo:[0,0,1] neg_hi:[0,0,1]
	s_nop 0
	v_add_f32_e32 v72, v162, v164
.LBB0_611:
	v_mov_b32_e32 v160, v17
	v_mov_b32_e32 v161, v1
	v_pk_mul_f32 v[160:161], v[160:161], v[160:161]
	s_addk_i32 s74, 0xf4c0
	v_add_f32_e32 v128, v160, v161
	s_nop 1
	v_mov_b32_dpp v160, v128 quad_perm:[1,0,3,2] row_mask:0xf bank_mask:0xf
	v_add_u32_e32 v129, s74, v129
	v_cvt_pk_bf16_f32 v163, v73, s0
	v_cvt_pk_bf16_f32 v164, v72, s0
	v_mov_b32_e32 v72, v1
	s_waitcnt lgkmcnt(0)
	v_add_f32_e32 v128, v128, v160
	s_nop 1
	v_mov_b32_dpp v160, v128 quad_perm:[2,3,0,1] row_mask:0xf bank_mask:0xf
	v_mov_b32_e32 v73, v17
	s_and_b64 vcc, exec, s[0:1]
	s_waitcnt lgkmcnt(0)
	v_add_f32_e32 v128, v128, v160
	s_nop 1
	v_mov_b32_dpp v160, v128 row_half_mirror row_mask:0xf bank_mask:0xf
	s_waitcnt lgkmcnt(0)
	v_add_f32_e32 v160, v128, v160
	s_nop 1
	v_mov_b32_dpp v161, v160 row_mirror row_mask:0xf bank_mask:0xf
	v_add_u32_e32 v128, v129, v81
	s_waitcnt lgkmcnt(0)
	v_add_f32_e32 v162, v160, v161
	v_mov_b32_e32 v165, v162
	s_nop 1
	v_permlane16_swap_b32_e32 v162, v165
	s_nop 0
	v_add_u32_e32 v160, v129, v82
	v_ashrrev_i32_e32 v129, 31, v128
	v_ashrrev_i32_e32 v161, 31, v160
	v_lshl_add_u64 v[128:129], v[128:129], 1, s[6:7]
	s_waitcnt lgkmcnt(0)
	v_add_f32_e32 v162, v162, v165
	v_fmamk_f32 v162, v162, 0x3c800000, v119
	v_rsq_f32_e32 v162, v162
	v_lshl_add_u64 v[160:161], v[160:161], 1, s[6:7]
	global_store_short v[128:129], v163, off sc1
	global_store_short v[160:161], v164, off sc1
	v_pk_mul_f32 v[128:129], v[70:71], v[162:163] op_sel_hi:[1,0]
	s_nop 0
	v_pk_mul_f32 v[72:73], v[72:73], v[128:129]
	s_cbranch_vccnz .LBB0_613
	global_load_dwordx2 v[128:129], v130, s[8:9]
	s_waitcnt vmcnt(0)
	v_pk_mul_f32 v[162:163], v[72:73], v[128:129] op_sel_hi:[0,1]
	v_pk_mul_f32 v[160:161], v[72:73], v[128:129] op_sel:[1,1] op_sel_hi:[1,0]
	v_pk_fma_f32 v[72:73], v[72:73], v[128:129], v[162:163] op_sel:[1,1,0] op_sel_hi:[1,0,1] neg_lo:[0,0,1] neg_hi:[0,0,1]
	s_nop 0
	v_add_f32_e32 v72, v160, v162

.LBB0_615:
	v_mov_b32_e32 v128, v19
	v_mov_b32_e32 v129, v3
	v_pk_mul_f32 v[128:129], v[128:129], v[128:129]
	v_add_u32_e32 v130, s74, v135
	v_add_f32_e32 v128, v128, v129
	s_nop 1
	v_mov_b32_dpp v129, v128 quad_perm:[1,0,3,2] row_mask:0xf bank_mask:0xf
	v_cvt_pk_bf16_f32 v133, v73, s0
	v_cvt_pk_bf16_f32 v135, v72, s0
	v_mov_b32_e32 v72, v3
	v_mov_b32_e32 v73, v19
	s_waitcnt lgkmcnt(0)
	v_add_f32_e32 v128, v128, v129
	s_nop 1
	v_mov_b32_dpp v129, v128 quad_perm:[2,3,0,1] row_mask:0xf bank_mask:0xf
	s_and_b64 vcc, exec, s[0:1]
	s_waitcnt lgkmcnt(0)
	v_add_f32_e32 v128, v128, v129
	s_nop 1
	v_mov_b32_dpp v129, v128 row_half_mirror row_mask:0xf bank_mask:0xf
	s_waitcnt lgkmcnt(0)
	v_add_f32_e32 v129, v128, v129
	s_nop 1
	v_mov_b32_dpp v131, v129 row_mirror row_mask:0xf bank_mask:0xf
	v_add_u32_e32 v128, v130, v81
	v_add_u32_e32 v130, v130, v82
	s_waitcnt lgkmcnt(0)
	v_add_f32_e32 v160, v129, v131
	v_mov_b32_e32 v161, v160
	s_nop 1
	v_permlane16_swap_b32_e32 v160, v161
	s_nop 0
	v_ashrrev_i32_e32 v129, 31, v128
	v_ashrrev_i32_e32 v131, 31, v130
	v_lshl_add_u64 v[128:129], v[128:129], 1, s[6:7]
	v_lshl_add_u64 v[130:131], v[130:131], 1, s[6:7]
	s_waitcnt lgkmcnt(0)
	v_add_f32_e32 v160, v160, v161
	v_fmamk_f32 v160, v160, 0x3c800000, v119
	v_rsq_f32_e32 v160, v160
	global_store_short v[128:129], v133, off sc1
	global_store_short v[130:131], v135, off sc1
	v_pk_mul_f32 v[128:129], v[70:71], v[160:161] op_sel_hi:[1,0]
	s_nop 0
	v_pk_mul_f32 v[72:73], v[72:73], v[128:129]
	s_cbranch_vccnz .LBB0_617
	global_load_dwordx2 v[128:129], v132, s[8:9]
	s_waitcnt vmcnt(0)
	v_pk_mul_f32 v[132:133], v[72:73], v[128:129] op_sel_hi:[0,1]
	v_pk_mul_f32 v[130:131], v[72:73], v[128:129] op_sel:[1,1] op_sel_hi:[1,0]
	v_pk_fma_f32 v[72:73], v[72:73], v[128:129], v[132:133] op_sel:[1,1,0] op_sel_hi:[1,0,1] neg_lo:[0,0,1] neg_hi:[0,0,1]
	s_nop 0
	v_add_f32_e32 v72, v130, v132
.LBB0_617:
	v_mov_b32_e32 v128, v20
	v_mov_b32_e32 v129, v4
	v_pk_mul_f32 v[128:129], v[128:129], v[128:129]
	v_add_u32_e32 v130, s74, v137
	v_add_f32_e32 v128, v128, v129
	s_nop 1
	v_mov_b32_dpp v129, v128 quad_perm:[1,0,3,2] row_mask:0xf bank_mask:0xf
	v_cvt_pk_bf16_f32 v133, v73, s0
	v_cvt_pk_bf16_f32 v135, v72, s0
	v_mov_b32_e32 v72, v4
	v_mov_b32_e32 v73, v20
	s_waitcnt lgkmcnt(0)
	v_add_f32_e32 v128, v128, v129
	s_nop 1
	v_mov_b32_dpp v129, v128 quad_perm:[2,3,0,1] row_mask:0xf bank_mask:0xf
	s_and_b64 vcc, exec, s[0:1]
	s_waitcnt lgkmcnt(0)
	v_add_f32_e32 v128, v128, v129
	s_nop 1
	v_mov_b32_dpp v129, v128 row_half_mirror row_mask:0xf bank_mask:0xf
	s_waitcnt lgkmcnt(0)
	v_add_f32_e32 v129, v128, v129
	s_nop 1
	v_mov_b32_dpp v131, v129 row_mirror row_mask:0xf bank_mask:0xf
	v_add_u32_e32 v128, v130, v81
	v_add_u32_e32 v130, v130, v82
	s_waitcnt lgkmcnt(0)
	v_add_f32_e32 v132, v129, v131
	v_mov_b32_e32 v137, v132
	s_nop 1
	v_permlane16_swap_b32_e32 v132, v137
	s_nop 0
	v_ashrrev_i32_e32 v129, 31, v128
	v_ashrrev_i32_e32 v131, 31, v130
	v_lshl_add_u64 v[128:129], v[128:129], 1, s[6:7]
	v_lshl_add_u64 v[130:131], v[130:131], 1, s[6:7]
	s_waitcnt lgkmcnt(0)
	v_add_f32_e32 v132, v132, v137
	v_fmamk_f32 v132, v132, 0x3c800000, v119
	v_rsq_f32_e32 v132, v132
	global_store_short v[128:129], v133, off sc1
	global_store_short v[130:131], v135, off sc1
	v_pk_mul_f32 v[128:129], v[70:71], v[132:133] op_sel_hi:[1,0]
	s_nop 0
	v_pk_mul_f32 v[72:73], v[72:73], v[128:129]
	s_cbranch_vccnz .LBB0_619
	global_load_dwordx2 v[128:129], v134, s[8:9]
	s_waitcnt vmcnt(0)
	v_pk_mul_f32 v[132:133], v[72:73], v[128:129] op_sel_hi:[0,1]
	v_pk_mul_f32 v[130:131], v[72:73], v[128:129] op_sel:[1,1] op_sel_hi:[1,0]
	v_pk_fma_f32 v[72:73], v[72:73], v[128:129], v[132:133] op_sel:[1,1,0] op_sel_hi:[1,0,1] neg_lo:[0,0,1] neg_hi:[0,0,1]
	s_nop 0
	v_add_f32_e32 v72, v130, v132
.LBB0_619:
	v_mov_b32_e32 v128, v21
	v_mov_b32_e32 v129, v5
	v_pk_mul_f32 v[128:129], v[128:129], v[128:129]
	v_add_u32_e32 v130, s74, v139
	v_add_f32_e32 v128, v128, v129
	s_nop 1
	v_mov_b32_dpp v129, v128 quad_perm:[1,0,3,2] row_mask:0xf bank_mask:0xf
	v_cvt_pk_bf16_f32 v133, v73, s0
	v_cvt_pk_bf16_f32 v134, v72, s0
	v_mov_b32_e32 v72, v5
	v_mov_b32_e32 v73, v21
	s_waitcnt lgkmcnt(0)
	v_add_f32_e32 v128, v128, v129
	s_nop 1
	v_mov_b32_dpp v129, v128 quad_perm:[2,3,0,1] row_mask:0xf bank_mask:0xf
	s_and_b64 vcc, exec, s[0:1]
	s_waitcnt lgkmcnt(0)
	v_add_f32_e32 v128, v128, v129
	s_nop 1
	v_mov_b32_dpp v129, v128 row_half_mirror row_mask:0xf bank_mask:0xf
	s_waitcnt lgkmcnt(0)
	v_add_f32_e32 v129, v128, v129
	s_nop 1
	v_mov_b32_dpp v131, v129 row_mirror row_mask:0xf bank_mask:0xf
	v_add_u32_e32 v128, v130, v81
	v_add_u32_e32 v130, v130, v82
	s_waitcnt lgkmcnt(0)
	v_add_f32_e32 v132, v129, v131
	v_mov_b32_e32 v135, v132
	s_nop 1
	v_permlane16_swap_b32_e32 v132, v135
	s_nop 0
	v_ashrrev_i32_e32 v129, 31, v128
	v_ashrrev_i32_e32 v131, 31, v130
	v_lshl_add_u64 v[128:129], v[128:129], 1, s[6:7]
	v_lshl_add_u64 v[130:131], v[130:131], 1, s[6:7]
	s_waitcnt lgkmcnt(0)
	v_add_f32_e32 v132, v132, v135
	v_fmamk_f32 v132, v132, 0x3c800000, v119
	v_rsq_f32_e32 v132, v132
	global_store_short v[128:129], v133, off sc1
	global_store_short v[130:131], v134, off sc1
	v_pk_mul_f32 v[128:129], v[70:71], v[132:133] op_sel_hi:[1,0]
	s_nop 0
	v_pk_mul_f32 v[72:73], v[72:73], v[128:129]
	s_cbranch_vccnz .LBB0_621
	global_load_dwordx2 v[128:129], v136, s[8:9]
	s_waitcnt vmcnt(0)
	v_pk_mul_f32 v[132:133], v[72:73], v[128:129] op_sel_hi:[0,1]
	v_pk_mul_f32 v[130:131], v[72:73], v[128:129] op_sel:[1,1] op_sel_hi:[1,0]
	v_pk_fma_f32 v[72:73], v[72:73], v[128:129], v[132:133] op_sel:[1,1,0] op_sel_hi:[1,0,1] neg_lo:[0,0,1] neg_hi:[0,0,1]
	s_nop 0
	v_add_f32_e32 v72, v130, v132
.LBB0_621:
	v_mov_b32_e32 v128, v22
	v_mov_b32_e32 v129, v6
	v_pk_mul_f32 v[128:129], v[128:129], v[128:129]
	v_add_u32_e32 v130, s74, v141
	v_add_f32_e32 v128, v128, v129
	s_nop 1
	v_mov_b32_dpp v129, v128 quad_perm:[1,0,3,2] row_mask:0xf bank_mask:0xf
	v_cvt_pk_bf16_f32 v133, v73, s0
	v_cvt_pk_bf16_f32 v134, v72, s0
	v_mov_b32_e32 v72, v6
	v_mov_b32_e32 v73, v22
	s_waitcnt lgkmcnt(0)
	v_add_f32_e32 v128, v128, v129
	s_nop 1
	v_mov_b32_dpp v129, v128 quad_perm:[2,3,0,1] row_mask:0xf bank_mask:0xf
	s_and_b64 vcc, exec, s[0:1]
	s_waitcnt lgkmcnt(0)
	v_add_f32_e32 v128, v128, v129
	s_nop 1
	v_mov_b32_dpp v129, v128 row_half_mirror row_mask:0xf bank_mask:0xf
	s_waitcnt lgkmcnt(0)
	v_add_f32_e32 v129, v128, v129
	s_nop 1
	v_mov_b32_dpp v131, v129 row_mirror row_mask:0xf bank_mask:0xf
	v_add_u32_e32 v128, v130, v81
	v_add_u32_e32 v130, v130, v82
	s_waitcnt lgkmcnt(0)
	v_add_f32_e32 v132, v129, v131
	v_mov_b32_e32 v135, v132
	s_nop 1
	v_permlane16_swap_b32_e32 v132, v135
	s_nop 0
	v_ashrrev_i32_e32 v129, 31, v128
	v_ashrrev_i32_e32 v131, 31, v130
	v_lshl_add_u64 v[128:129], v[128:129], 1, s[6:7]
	v_lshl_add_u64 v[130:131], v[130:131], 1, s[6:7]
	s_waitcnt lgkmcnt(0)
	v_add_f32_e32 v132, v132, v135
	v_fmamk_f32 v132, v132, 0x3c800000, v119
	v_rsq_f32_e32 v132, v132
	global_store_short v[128:129], v133, off sc1
	global_store_short v[130:131], v134, off sc1
	v_pk_mul_f32 v[128:129], v[70:71], v[132:133] op_sel_hi:[1,0]
	s_nop 0
	v_pk_mul_f32 v[72:73], v[72:73], v[128:129]
	s_cbranch_vccnz .LBB0_623
	global_load_dwordx2 v[128:129], v138, s[8:9]
	s_waitcnt vmcnt(0)
	v_pk_mul_f32 v[132:133], v[72:73], v[128:129] op_sel_hi:[0,1]
	v_pk_mul_f32 v[130:131], v[72:73], v[128:129] op_sel:[1,1] op_sel_hi:[1,0]
	v_pk_fma_f32 v[72:73], v[72:73], v[128:129], v[132:133] op_sel:[1,1,0] op_sel_hi:[1,0,1] neg_lo:[0,0,1] neg_hi:[0,0,1]
	s_nop 0
	v_add_f32_e32 v72, v130, v132
.LBB0_623:
	v_mov_b32_e32 v128, v23
	v_mov_b32_e32 v129, v7
	v_pk_mul_f32 v[128:129], v[128:129], v[128:129]
	v_add_u32_e32 v130, s74, v144
	v_add_f32_e32 v128, v128, v129
	s_nop 1
	v_mov_b32_dpp v129, v128 quad_perm:[1,0,3,2] row_mask:0xf bank_mask:0xf
	v_cvt_pk_bf16_f32 v133, v73, s0
	v_cvt_pk_bf16_f32 v134, v72, s0
	v_mov_b32_e32 v72, v7
	v_mov_b32_e32 v73, v23
	s_waitcnt lgkmcnt(0)
	v_add_f32_e32 v128, v128, v129
	s_nop 1
	v_mov_b32_dpp v129, v128 quad_perm:[2,3,0,1] row_mask:0xf bank_mask:0xf
	s_and_b64 vcc, exec, s[0:1]
	s_waitcnt lgkmcnt(0)
	v_add_f32_e32 v128, v128, v129
	s_nop 1
	v_mov_b32_dpp v129, v128 row_half_mirror row_mask:0xf bank_mask:0xf
	s_waitcnt lgkmcnt(0)
	v_add_f32_e32 v129, v128, v129
	s_nop 1
	v_mov_b32_dpp v131, v129 row_mirror row_mask:0xf bank_mask:0xf
	v_add_u32_e32 v128, v130, v81
	v_add_u32_e32 v130, v130, v82
	s_waitcnt lgkmcnt(0)
	v_add_f32_e32 v132, v129, v131
	v_mov_b32_e32 v135, v132
	s_nop 1
	v_permlane16_swap_b32_e32 v132, v135
	s_nop 0
	v_ashrrev_i32_e32 v129, 31, v128
	v_ashrrev_i32_e32 v131, 31, v130
	v_lshl_add_u64 v[128:129], v[128:129], 1, s[6:7]
	v_lshl_add_u64 v[130:131], v[130:131], 1, s[6:7]
	s_waitcnt lgkmcnt(0)
	v_add_f32_e32 v132, v132, v135
	v_fmamk_f32 v132, v132, 0x3c800000, v119
	v_rsq_f32_e32 v132, v132
	global_store_short v[128:129], v133, off sc1
	global_store_short v[130:131], v134, off sc1
	v_pk_mul_f32 v[128:129], v[70:71], v[132:133] op_sel_hi:[1,0]
	s_nop 0
	v_pk_mul_f32 v[72:73], v[72:73], v[128:129]
	s_cbranch_vccnz .LBB0_625
	global_load_dwordx2 v[128:129], v140, s[8:9]
	s_waitcnt vmcnt(0)
	v_pk_mul_f32 v[132:133], v[72:73], v[128:129] op_sel_hi:[0,1]
	v_pk_mul_f32 v[130:131], v[72:73], v[128:129] op_sel:[1,1] op_sel_hi:[1,0]
	v_pk_fma_f32 v[72:73], v[72:73], v[128:129], v[132:133] op_sel:[1,1,0] op_sel_hi:[1,0,1] neg_lo:[0,0,1] neg_hi:[0,0,1]
	s_nop 0
	v_add_f32_e32 v72, v130, v132
.LBB0_625:
	v_mov_b32_e32 v128, v24
	v_mov_b32_e32 v129, v8
	v_pk_mul_f32 v[128:129], v[128:129], v[128:129]
	v_add_u32_e32 v130, s74, v146
	v_add_f32_e32 v128, v128, v129
	s_nop 1
	v_mov_b32_dpp v129, v128 quad_perm:[1,0,3,2] row_mask:0xf bank_mask:0xf
	v_cvt_pk_bf16_f32 v133, v73, s0
	v_cvt_pk_bf16_f32 v134, v72, s0
	v_mov_b32_e32 v72, v8
	v_mov_b32_e32 v73, v24
	s_waitcnt lgkmcnt(0)
	v_add_f32_e32 v128, v128, v129
	s_nop 1
	v_mov_b32_dpp v129, v128 quad_perm:[2,3,0,1] row_mask:0xf bank_mask:0xf
	s_and_b64 vcc, exec, s[0:1]
	s_waitcnt lgkmcnt(0)
	v_add_f32_e32 v128, v128, v129
	s_nop 1
	v_mov_b32_dpp v129, v128 row_half_mirror row_mask:0xf bank_mask:0xf
	s_waitcnt lgkmcnt(0)
	v_add_f32_e32 v129, v128, v129
	s_nop 1
	v_mov_b32_dpp v131, v129 row_mirror row_mask:0xf bank_mask:0xf
	v_add_u32_e32 v128, v130, v81
	v_add_u32_e32 v130, v130, v82
	s_waitcnt lgkmcnt(0)
	v_add_f32_e32 v132, v129, v131
	v_mov_b32_e32 v135, v132
	s_nop 1
	v_permlane16_swap_b32_e32 v132, v135
	s_nop 0
	v_ashrrev_i32_e32 v129, 31, v128
	v_ashrrev_i32_e32 v131, 31, v130
	v_lshl_add_u64 v[128:129], v[128:129], 1, s[6:7]
	v_lshl_add_u64 v[130:131], v[130:131], 1, s[6:7]
	s_waitcnt lgkmcnt(0)
	v_add_f32_e32 v132, v132, v135
	v_fmamk_f32 v132, v132, 0x3c800000, v119
	v_rsq_f32_e32 v132, v132
	global_store_short v[128:129], v133, off sc1
	global_store_short v[130:131], v134, off sc1
	v_pk_mul_f32 v[128:129], v[70:71], v[132:133] op_sel_hi:[1,0]
	s_nop 0
	v_pk_mul_f32 v[72:73], v[72:73], v[128:129]
	s_cbranch_vccnz .LBB0_627
	global_load_dwordx2 v[128:129], v143, s[8:9]
	s_waitcnt vmcnt(0)
	v_pk_mul_f32 v[132:133], v[72:73], v[128:129] op_sel_hi:[0,1]
	v_pk_mul_f32 v[130:131], v[72:73], v[128:129] op_sel:[1,1] op_sel_hi:[1,0]
	v_pk_fma_f32 v[72:73], v[72:73], v[128:129], v[132:133] op_sel:[1,1,0] op_sel_hi:[1,0,1] neg_lo:[0,0,1] neg_hi:[0,0,1]
	s_nop 0
	v_add_f32_e32 v72, v130, v132
.LBB0_627:
	v_mov_b32_e32 v128, v25
	v_mov_b32_e32 v129, v9
	v_pk_mul_f32 v[128:129], v[128:129], v[128:129]
	v_add_u32_e32 v130, s74, v148
	v_add_f32_e32 v128, v128, v129
	s_nop 1
	v_mov_b32_dpp v129, v128 quad_perm:[1,0,3,2] row_mask:0xf bank_mask:0xf
	v_cvt_pk_bf16_f32 v133, v73, s0
	v_cvt_pk_bf16_f32 v134, v72, s0
	v_mov_b32_e32 v72, v9
	v_mov_b32_e32 v73, v25
	s_waitcnt lgkmcnt(0)
	v_add_f32_e32 v128, v128, v129
	s_nop 1
	v_mov_b32_dpp v129, v128 quad_perm:[2,3,0,1] row_mask:0xf bank_mask:0xf
	s_and_b64 vcc, exec, s[0:1]
	s_waitcnt lgkmcnt(0)
	v_add_f32_e32 v128, v128, v129
	s_nop 1
	v_mov_b32_dpp v129, v128 row_half_mirror row_mask:0xf bank_mask:0xf
	s_waitcnt lgkmcnt(0)
	v_add_f32_e32 v129, v128, v129
	s_nop 1
	v_mov_b32_dpp v131, v129 row_mirror row_mask:0xf bank_mask:0xf
	v_add_u32_e32 v128, v130, v81
	v_add_u32_e32 v130, v130, v82
	s_waitcnt lgkmcnt(0)
	v_add_f32_e32 v132, v129, v131
	v_mov_b32_e32 v135, v132
	s_nop 1
	v_permlane16_swap_b32_e32 v132, v135
	s_nop 0
	v_ashrrev_i32_e32 v129, 31, v128
	v_ashrrev_i32_e32 v131, 31, v130
	v_lshl_add_u64 v[128:129], v[128:129], 1, s[6:7]
	v_lshl_add_u64 v[130:131], v[130:131], 1, s[6:7]
	s_waitcnt lgkmcnt(0)
	v_add_f32_e32 v132, v132, v135
	v_fmamk_f32 v132, v132, 0x3c800000, v119
	v_rsq_f32_e32 v132, v132
	global_store_short v[128:129], v133, off sc1
	global_store_short v[130:131], v134, off sc1
	v_pk_mul_f32 v[128:129], v[70:71], v[132:133] op_sel_hi:[1,0]
	s_nop 0
	v_pk_mul_f32 v[72:73], v[72:73], v[128:129]
	s_cbranch_vccnz .LBB0_629
	global_load_dwordx2 v[128:129], v145, s[8:9]
	s_waitcnt vmcnt(0)
	v_pk_mul_f32 v[132:133], v[72:73], v[128:129] op_sel_hi:[0,1]
	v_pk_mul_f32 v[130:131], v[72:73], v[128:129] op_sel:[1,1] op_sel_hi:[1,0]
	v_pk_fma_f32 v[72:73], v[72:73], v[128:129], v[132:133] op_sel:[1,1,0] op_sel_hi:[1,0,1] neg_lo:[0,0,1] neg_hi:[0,0,1]
	s_nop 0
	v_add_f32_e32 v72, v130, v132
.LBB0_629:
	v_mov_b32_e32 v128, v26
	v_mov_b32_e32 v129, v10
	v_pk_mul_f32 v[128:129], v[128:129], v[128:129]
	v_add_u32_e32 v130, s74, v150
	v_add_f32_e32 v128, v128, v129
	s_nop 1
	v_mov_b32_dpp v129, v128 quad_perm:[1,0,3,2] row_mask:0xf bank_mask:0xf
	v_cvt_pk_bf16_f32 v133, v73, s0
	v_cvt_pk_bf16_f32 v134, v72, s0
	v_mov_b32_e32 v72, v10
	v_mov_b32_e32 v73, v26
	s_waitcnt lgkmcnt(0)
	v_add_f32_e32 v128, v128, v129
	s_nop 1
	v_mov_b32_dpp v129, v128 quad_perm:[2,3,0,1] row_mask:0xf bank_mask:0xf
	s_and_b64 vcc, exec, s[0:1]
	s_waitcnt lgkmcnt(0)
	v_add_f32_e32 v128, v128, v129
	s_nop 1
	v_mov_b32_dpp v129, v128 row_half_mirror row_mask:0xf bank_mask:0xf
	s_waitcnt lgkmcnt(0)
	v_add_f32_e32 v129, v128, v129
	s_nop 1
	v_mov_b32_dpp v131, v129 row_mirror row_mask:0xf bank_mask:0xf
	v_add_u32_e32 v128, v130, v81
	v_add_u32_e32 v130, v130, v82
	s_waitcnt lgkmcnt(0)
	v_add_f32_e32 v132, v129, v131
	v_mov_b32_e32 v135, v132
	s_nop 1
	v_permlane16_swap_b32_e32 v132, v135
	s_nop 0
	v_ashrrev_i32_e32 v129, 31, v128
	v_ashrrev_i32_e32 v131, 31, v130
	v_lshl_add_u64 v[128:129], v[128:129], 1, s[6:7]
	v_lshl_add_u64 v[130:131], v[130:131], 1, s[6:7]
	s_waitcnt lgkmcnt(0)
	v_add_f32_e32 v132, v132, v135
	v_fmamk_f32 v132, v132, 0x3c800000, v119
	v_rsq_f32_e32 v132, v132
	global_store_short v[128:129], v133, off sc1
	global_store_short v[130:131], v134, off sc1
	v_pk_mul_f32 v[128:129], v[70:71], v[132:133] op_sel_hi:[1,0]
	s_nop 0
	v_pk_mul_f32 v[72:73], v[72:73], v[128:129]
	s_cbranch_vccnz .LBB0_631
	global_load_dwordx2 v[128:129], v147, s[8:9]
	s_waitcnt vmcnt(0)
	v_pk_mul_f32 v[132:133], v[72:73], v[128:129] op_sel_hi:[0,1]
	v_pk_mul_f32 v[130:131], v[72:73], v[128:129] op_sel:[1,1] op_sel_hi:[1,0]
	v_pk_fma_f32 v[72:73], v[72:73], v[128:129], v[132:133] op_sel:[1,1,0] op_sel_hi:[1,0,1] neg_lo:[0,0,1] neg_hi:[0,0,1]
	s_nop 0
	v_add_f32_e32 v72, v130, v132
.LBB0_631:
	v_mov_b32_e32 v128, v27
	v_mov_b32_e32 v129, v11
	v_pk_mul_f32 v[128:129], v[128:129], v[128:129]
	v_add_u32_e32 v130, s74, v152
	v_add_f32_e32 v128, v128, v129
	s_nop 1
	v_mov_b32_dpp v129, v128 quad_perm:[1,0,3,2] row_mask:0xf bank_mask:0xf
	v_cvt_pk_bf16_f32 v133, v73, s0
	v_cvt_pk_bf16_f32 v134, v72, s0
	v_mov_b32_e32 v72, v11
	v_mov_b32_e32 v73, v27
	s_waitcnt lgkmcnt(0)
	v_add_f32_e32 v128, v128, v129
	s_nop 1
	v_mov_b32_dpp v129, v128 quad_perm:[2,3,0,1] row_mask:0xf bank_mask:0xf
	s_and_b64 vcc, exec, s[0:1]
	s_waitcnt lgkmcnt(0)
	v_add_f32_e32 v128, v128, v129
	s_nop 1
	v_mov_b32_dpp v129, v128 row_half_mirror row_mask:0xf bank_mask:0xf
	s_waitcnt lgkmcnt(0)
	v_add_f32_e32 v129, v128, v129
	s_nop 1
	v_mov_b32_dpp v131, v129 row_mirror row_mask:0xf bank_mask:0xf
	v_add_u32_e32 v128, v130, v81
	v_add_u32_e32 v130, v130, v82
	s_waitcnt lgkmcnt(0)
	v_add_f32_e32 v132, v129, v131
	v_mov_b32_e32 v135, v132
	s_nop 1
	v_permlane16_swap_b32_e32 v132, v135
	s_nop 0
	v_ashrrev_i32_e32 v129, 31, v128
	v_ashrrev_i32_e32 v131, 31, v130
	v_lshl_add_u64 v[128:129], v[128:129], 1, s[6:7]
	v_lshl_add_u64 v[130:131], v[130:131], 1, s[6:7]
	s_waitcnt lgkmcnt(0)
	v_add_f32_e32 v132, v132, v135
	v_fmamk_f32 v132, v132, 0x3c800000, v119
	v_rsq_f32_e32 v132, v132
	global_store_short v[128:129], v133, off sc1
	global_store_short v[130:131], v134, off sc1
	v_pk_mul_f32 v[128:129], v[70:71], v[132:133] op_sel_hi:[1,0]
	s_nop 0
	v_pk_mul_f32 v[72:73], v[72:73], v[128:129]
	s_cbranch_vccnz .LBB0_633
	global_load_dwordx2 v[128:129], v149, s[8:9]
	s_waitcnt vmcnt(0)
	v_pk_mul_f32 v[132:133], v[72:73], v[128:129] op_sel_hi:[0,1]
	v_pk_mul_f32 v[130:131], v[72:73], v[128:129] op_sel:[1,1] op_sel_hi:[1,0]
	v_pk_fma_f32 v[72:73], v[72:73], v[128:129], v[132:133] op_sel:[1,1,0] op_sel_hi:[1,0,1] neg_lo:[0,0,1] neg_hi:[0,0,1]
	s_nop 0
	v_add_f32_e32 v72, v130, v132
.LBB0_633:
	v_mov_b32_e32 v128, v28
	v_mov_b32_e32 v129, v12
	v_pk_mul_f32 v[128:129], v[128:129], v[128:129]
	v_add_u32_e32 v130, s74, v154
	v_add_f32_e32 v128, v128, v129
	s_nop 1
	v_mov_b32_dpp v129, v128 quad_perm:[1,0,3,2] row_mask:0xf bank_mask:0xf
	v_cvt_pk_bf16_f32 v133, v73, s0
	v_cvt_pk_bf16_f32 v134, v72, s0
	v_mov_b32_e32 v72, v12
	v_mov_b32_e32 v73, v28
	s_waitcnt lgkmcnt(0)
	v_add_f32_e32 v128, v128, v129
	s_nop 1
	v_mov_b32_dpp v129, v128 quad_perm:[2,3,0,1] row_mask:0xf bank_mask:0xf
	s_and_b64 vcc, exec, s[0:1]
	s_waitcnt lgkmcnt(0)
	v_add_f32_e32 v128, v128, v129
	s_nop 1
	v_mov_b32_dpp v129, v128 row_half_mirror row_mask:0xf bank_mask:0xf
	s_waitcnt lgkmcnt(0)
	v_add_f32_e32 v129, v128, v129
	s_nop 1
	v_mov_b32_dpp v131, v129 row_mirror row_mask:0xf bank_mask:0xf
	v_add_u32_e32 v128, v130, v81
	v_add_u32_e32 v130, v130, v82
	s_waitcnt lgkmcnt(0)
	v_add_f32_e32 v132, v129, v131
	v_mov_b32_e32 v135, v132
	s_nop 1
	v_permlane16_swap_b32_e32 v132, v135
	s_nop 0
	v_ashrrev_i32_e32 v129, 31, v128
	v_ashrrev_i32_e32 v131, 31, v130
	v_lshl_add_u64 v[128:129], v[128:129], 1, s[6:7]
	v_lshl_add_u64 v[130:131], v[130:131], 1, s[6:7]
	s_waitcnt lgkmcnt(0)
	v_add_f32_e32 v132, v132, v135
	v_fmamk_f32 v132, v132, 0x3c800000, v119
	v_rsq_f32_e32 v132, v132
	global_store_short v[128:129], v133, off sc1
	global_store_short v[130:131], v134, off sc1
	v_pk_mul_f32 v[128:129], v[70:71], v[132:133] op_sel_hi:[1,0]
	s_nop 0
	v_pk_mul_f32 v[72:73], v[72:73], v[128:129]
	s_cbranch_vccnz .LBB0_635
	global_load_dwordx2 v[128:129], v151, s[8:9]
	s_waitcnt vmcnt(0)
	v_pk_mul_f32 v[132:133], v[72:73], v[128:129] op_sel_hi:[0,1]
	v_pk_mul_f32 v[130:131], v[72:73], v[128:129] op_sel:[1,1] op_sel_hi:[1,0]
	v_pk_fma_f32 v[72:73], v[72:73], v[128:129], v[132:133] op_sel:[1,1,0] op_sel_hi:[1,0,1] neg_lo:[0,0,1] neg_hi:[0,0,1]
	s_nop 0
	v_add_f32_e32 v72, v130, v132
.LBB0_635:
	v_mov_b32_e32 v128, v29
	v_mov_b32_e32 v129, v13
	v_pk_mul_f32 v[128:129], v[128:129], v[128:129]
	v_add_u32_e32 v130, s74, v156
	v_add_f32_e32 v128, v128, v129
	s_nop 1
	v_mov_b32_dpp v129, v128 quad_perm:[1,0,3,2] row_mask:0xf bank_mask:0xf
	v_cvt_pk_bf16_f32 v133, v73, s0
	v_cvt_pk_bf16_f32 v134, v72, s0
	v_mov_b32_e32 v72, v13
	v_mov_b32_e32 v73, v29
	s_waitcnt lgkmcnt(0)
	v_add_f32_e32 v128, v128, v129
	s_nop 1
	v_mov_b32_dpp v129, v128 quad_perm:[2,3,0,1] row_mask:0xf bank_mask:0xf
	s_and_b64 vcc, exec, s[0:1]
	s_waitcnt lgkmcnt(0)
	v_add_f32_e32 v128, v128, v129
	s_nop 1
	v_mov_b32_dpp v129, v128 row_half_mirror row_mask:0xf bank_mask:0xf
	s_waitcnt lgkmcnt(0)
	v_add_f32_e32 v129, v128, v129
	s_nop 1
	v_mov_b32_dpp v131, v129 row_mirror row_mask:0xf bank_mask:0xf
	v_add_u32_e32 v128, v130, v81
	v_add_u32_e32 v130, v130, v82
	s_waitcnt lgkmcnt(0)
	v_add_f32_e32 v132, v129, v131
	v_mov_b32_e32 v135, v132
	s_nop 1
	v_permlane16_swap_b32_e32 v132, v135
	s_nop 0
	v_ashrrev_i32_e32 v129, 31, v128
	v_ashrrev_i32_e32 v131, 31, v130
	v_lshl_add_u64 v[128:129], v[128:129], 1, s[6:7]
	v_lshl_add_u64 v[130:131], v[130:131], 1, s[6:7]
	s_waitcnt lgkmcnt(0)
	v_add_f32_e32 v132, v132, v135
	v_fmamk_f32 v132, v132, 0x3c800000, v119
	v_rsq_f32_e32 v132, v132
	global_store_short v[128:129], v133, off sc1
	global_store_short v[130:131], v134, off sc1
	v_pk_mul_f32 v[128:129], v[70:71], v[132:133] op_sel_hi:[1,0]
	s_nop 0
	v_pk_mul_f32 v[72:73], v[72:73], v[128:129]
	s_cbranch_vccnz .LBB0_637
	global_load_dwordx2 v[128:129], v153, s[8:9]
	s_waitcnt vmcnt(0)
	v_pk_mul_f32 v[132:133], v[72:73], v[128:129] op_sel_hi:[0,1]
	v_pk_mul_f32 v[130:131], v[72:73], v[128:129] op_sel:[1,1] op_sel_hi:[1,0]
	v_pk_fma_f32 v[72:73], v[72:73], v[128:129], v[132:133] op_sel:[1,1,0] op_sel_hi:[1,0,1] neg_lo:[0,0,1] neg_hi:[0,0,1]
	s_nop 0
	v_add_f32_e32 v72, v130, v132
.LBB0_637:
	v_mov_b32_e32 v128, v30
	v_mov_b32_e32 v129, v14
	v_pk_mul_f32 v[128:129], v[128:129], v[128:129]
	v_add_u32_e32 v130, s74, v157
	v_add_f32_e32 v128, v128, v129
	s_nop 1
	v_mov_b32_dpp v129, v128 quad_perm:[1,0,3,2] row_mask:0xf bank_mask:0xf
	v_cvt_pk_bf16_f32 v133, v73, s0
	v_cvt_pk_bf16_f32 v134, v72, s0
	v_mov_b32_e32 v72, v14
	v_mov_b32_e32 v73, v30
	s_waitcnt lgkmcnt(0)
	v_add_f32_e32 v128, v128, v129
	s_nop 1
	v_mov_b32_dpp v129, v128 quad_perm:[2,3,0,1] row_mask:0xf bank_mask:0xf
	s_and_b64 vcc, exec, s[0:1]
	s_waitcnt lgkmcnt(0)
	v_add_f32_e32 v128, v128, v129
	s_nop 1
	v_mov_b32_dpp v129, v128 row_half_mirror row_mask:0xf bank_mask:0xf
	s_waitcnt lgkmcnt(0)
	v_add_f32_e32 v129, v128, v129
	s_nop 1
	v_mov_b32_dpp v131, v129 row_mirror row_mask:0xf bank_mask:0xf
	v_add_u32_e32 v128, v130, v81
	v_add_u32_e32 v130, v130, v82
	s_waitcnt lgkmcnt(0)
	v_add_f32_e32 v132, v129, v131
	v_mov_b32_e32 v135, v132
	s_nop 1
	v_permlane16_swap_b32_e32 v132, v135
	s_nop 0
	v_ashrrev_i32_e32 v129, 31, v128
	v_ashrrev_i32_e32 v131, 31, v130
	v_lshl_add_u64 v[128:129], v[128:129], 1, s[6:7]
	v_lshl_add_u64 v[130:131], v[130:131], 1, s[6:7]
	s_waitcnt lgkmcnt(0)
	v_add_f32_e32 v132, v132, v135
	v_fmamk_f32 v132, v132, 0x3c800000, v119
	v_rsq_f32_e32 v132, v132
	global_store_short v[128:129], v133, off sc1
	global_store_short v[130:131], v134, off sc1
	v_pk_mul_f32 v[128:129], v[70:71], v[132:133] op_sel_hi:[1,0]
	s_nop 0
	v_pk_mul_f32 v[72:73], v[72:73], v[128:129]
	s_cbranch_vccnz .LBB0_639
	global_load_dwordx2 v[128:129], v155, s[8:9]
	s_waitcnt vmcnt(0)
	v_pk_mul_f32 v[132:133], v[72:73], v[128:129] op_sel_hi:[0,1]
	v_pk_mul_f32 v[130:131], v[72:73], v[128:129] op_sel:[1,1] op_sel_hi:[1,0]
	v_pk_fma_f32 v[72:73], v[72:73], v[128:129], v[132:133] op_sel:[1,1,0] op_sel_hi:[1,0,1] neg_lo:[0,0,1] neg_hi:[0,0,1]
	s_nop 0
	v_add_f32_e32 v72, v130, v132
.LBB0_639:
	v_mov_b32_e32 v128, v31
	v_mov_b32_e32 v129, v15
	v_pk_mul_f32 v[128:129], v[128:129], v[128:129]
	v_cvt_pk_bf16_f32 v130, v72, s0
	v_add_f32_e32 v128, v128, v129
	s_nop 1
	v_mov_b32_dpp v123, v128 quad_perm:[1,0,3,2] row_mask:0xf bank_mask:0xf
	v_cvt_pk_bf16_f32 v129, v73, s0
	v_mov_b32_e32 v72, v15
	v_mov_b32_e32 v73, v31
	s_and_b64 vcc, exec, s[0:1]
	s_waitcnt lgkmcnt(0)
	v_add_f32_e32 v123, v128, v123
	s_nop 1
	v_mov_b32_dpp v124, v123 quad_perm:[2,3,0,1] row_mask:0xf bank_mask:0xf
	s_waitcnt lgkmcnt(0)
	v_add_f32_e32 v123, v123, v124
	s_nop 1
	v_mov_b32_dpp v124, v123 row_half_mirror row_mask:0xf bank_mask:0xf
	v_add_u32_e32 v125, s74, v158
	s_waitcnt lgkmcnt(0)
	v_add_f32_e32 v123, v123, v124
	s_nop 1
	v_mov_b32_dpp v127, v123 row_mirror row_mask:0xf bank_mask:0xf
	v_add_u32_e32 v124, v125, v81
	s_waitcnt lgkmcnt(0)
	v_add_f32_e32 v123, v123, v127
	v_mov_b32_e32 v128, v123
	s_nop 1
	v_permlane16_swap_b32_e32 v123, v128
	s_nop 0
	v_add_u32_e32 v126, v125, v82
	v_ashrrev_i32_e32 v125, 31, v124
	v_ashrrev_i32_e32 v127, 31, v126
	v_lshl_add_u64 v[124:125], v[124:125], 1, s[6:7]
	s_waitcnt lgkmcnt(0)
	v_add_f32_e32 v123, v123, v128
	v_fmamk_f32 v123, v123, 0x3c800000, v119
	v_rsq_f32_e32 v128, v123
	v_lshl_add_u64 v[126:127], v[126:127], 1, s[6:7]
	global_store_short v[124:125], v129, off sc1
	global_store_short v[126:127], v130, off sc1
	v_pk_mul_f32 v[70:71], v[70:71], v[128:129] op_sel_hi:[1,0]
	s_nop 0
	v_pk_mul_f32 v[70:71], v[72:73], v[70:71]
	s_cbranch_vccnz .LBB0_641
	global_load_dwordx2 v[72:73], v142, s[8:9]
	s_waitcnt vmcnt(0)
	v_pk_mul_f32 v[126:127], v[70:71], v[72:73] op_sel_hi:[0,1]
	v_pk_mul_f32 v[124:125], v[70:71], v[72:73] op_sel:[1,1] op_sel_hi:[1,0]
	v_pk_fma_f32 v[70:71], v[70:71], v[72:73], v[126:127] op_sel:[1,1,0] op_sel_hi:[1,0,1] neg_lo:[0,0,1] neg_hi:[0,0,1]
	s_nop 0
	v_add_f32_e32 v70, v124, v126

.LBB0_642:
	s_and_b64 vcc, exec, s[0:1]
	s_cbranch_vccz .LBB0_575
	v_and_b32_e32 v71, 64, v122
	v_xor_b32_e32 v70, 1, v122
	v_add_u32_e32 v71, 64, v71
	v_mul_f32_e32 v72, v32, v32
	v_cmp_lt_i32_e32 vcc, v70, v71
	v_fmac_f32_e32 v72, v48, v48
	v_fmac_f32_e32 v72, v16, v16
	v_cndmask_b32_e32 v70, v122, v70, vcc
	v_lshlrev_b32_e32 v132, 2, v70
	v_fmac_f32_e32 v72, v0, v0
	s_nop 1
	v_mov_b32_dpp v73, v72 quad_perm:[1,0,3,2] row_mask:0xf bank_mask:0xf
	v_xor_b32_e32 v70, 2, v122
	v_cmp_lt_i32_e32 vcc, v70, v71
	v_mul_f32_e32 v123, v33, v33
	v_fmac_f32_e32 v123, v49, v49
	v_cndmask_b32_e32 v70, v122, v70, vcc
	v_lshlrev_b32_e32 v133, 2, v70
	s_waitcnt lgkmcnt(0)
	v_add_f32_e32 v72, v72, v73
	v_xor_b32_e32 v70, 4, v122
	s_nop 1
	v_mov_b32_dpp v73, v72 quad_perm:[2,3,0,1] row_mask:0xf bank_mask:0xf
	v_cmp_lt_i32_e32 vcc, v70, v71
	v_fmac_f32_e32 v123, v17, v17
	v_fmac_f32_e32 v123, v1, v1
	v_cndmask_b32_e32 v70, v122, v70, vcc
	v_lshlrev_b32_e32 v135, 2, v70
	v_xor_b32_e32 v70, 8, v122
	v_cmp_lt_i32_e32 vcc, v70, v71
	s_waitcnt lgkmcnt(0)
	v_add_f32_e32 v72, v72, v73
	s_nop 1
	v_mov_b32_dpp v73, v72 row_half_mirror row_mask:0xf bank_mask:0xf
	v_cndmask_b32_e32 v70, v122, v70, vcc
	v_lshlrev_b32_e32 v136, 2, v70
	v_xor_b32_e32 v70, 16, v122
	s_nop 1
	v_mov_b32_dpp v124, v123 quad_perm:[1,0,3,2] row_mask:0xf bank_mask:0xf
	v_cmp_lt_i32_e32 vcc, v70, v71
	v_mul_f32_e32 v128, v40, v40
	v_fmac_f32_e32 v128, v56, v56
	v_cndmask_b32_e32 v70, v122, v70, vcc
	v_mul_f32_e32 v122, v34, v34
	v_fmac_f32_e32 v122, v50, v50
	v_fmac_f32_e32 v122, v18, v18
	v_lshlrev_b32_e32 v137, 2, v70
	s_waitcnt lgkmcnt(0)
	v_add_f32_e32 v70, v72, v73
	s_waitcnt lgkmcnt(0)
	v_add_f32_e32 v72, v123, v124
	v_fmac_f32_e32 v122, v2, v2
	s_nop 1
	v_mov_b32_dpp v71, v70 row_mirror row_mask:0xf bank_mask:0xf
	s_nop 1
	v_mov_b32_dpp v73, v72 quad_perm:[2,3,0,1] row_mask:0xf bank_mask:0xf
	s_nop 1
	v_mov_b32_dpp v123, v122 quad_perm:[1,0,3,2] row_mask:0xf bank_mask:0xf
	v_fmac_f32_e32 v128, v24, v24
	v_fmac_f32_e32 v128, v8, v8
	s_waitcnt lgkmcnt(0)
	v_add_f32_e32 v70, v70, v71
	s_waitcnt lgkmcnt(0)
	v_add_f32_e32 v72, v72, v73
	s_waitcnt lgkmcnt(0)
	v_add_f32_e32 v122, v122, v123
	v_mov_b32_e32 v71, v70
	s_nop 1
	v_permlane16_swap_b32_e32 v70, v71
	s_nop 0
	s_nop 1
	v_mov_b32_dpp v73, v72 row_half_mirror row_mask:0xf bank_mask:0xf
	s_nop 1
	v_mov_b32_dpp v123, v122 quad_perm:[2,3,0,1] row_mask:0xf bank_mask:0xf
	s_nop 1
	v_mov_b32_dpp v129, v128 quad_perm:[1,0,3,2] row_mask:0xf bank_mask:0xf
	v_mul_f32_e32 v141, v46, v46
	s_waitcnt lgkmcnt(0)
	v_add_f32_e32 v70, v70, v71
	s_waitcnt lgkmcnt(0)
	v_add_f32_e32 v71, v72, v73
	s_waitcnt lgkmcnt(0)
	v_add_f32_e32 v73, v122, v123
	v_mul_f32_e32 v123, v35, v35
	v_fmac_f32_e32 v123, v51, v51
	v_fmac_f32_e32 v123, v19, v19
	v_fmac_f32_e32 v123, v3, v3
	s_nop 1
	v_mov_b32_dpp v72, v71 row_mirror row_mask:0xf bank_mask:0xf
	s_nop 1
	v_mov_b32_dpp v122, v73 row_half_mirror row_mask:0xf bank_mask:0xf
	s_nop 1
	v_mov_b32_dpp v124, v123 quad_perm:[1,0,3,2] row_mask:0xf bank_mask:0xf
	v_fmamk_f32 v70, v70, 0x3c000000, v119
	s_waitcnt lgkmcnt(0)
	v_add_f32_e32 v128, v128, v129
	s_waitcnt lgkmcnt(0)
	v_add_f32_e32 v72, v71, v72
	s_waitcnt lgkmcnt(0)
	v_add_f32_e32 v73, v73, v122
	s_waitcnt lgkmcnt(0)
	v_add_f32_e32 v123, v123, v124
	v_mov_b32_e32 v125, v72
	s_nop 1
	v_permlane16_swap_b32_e32 v72, v125
	s_nop 0
	s_nop 1
	v_mov_b32_dpp v122, v73 row_mirror row_mask:0xf bank_mask:0xf
	s_nop 1
	v_mov_b32_dpp v124, v123 quad_perm:[2,3,0,1] row_mask:0xf bank_mask:0xf
	v_rsq_f32_e32 v71, v70
	s_nop 1
	v_mov_b32_dpp v129, v128 quad_perm:[2,3,0,1] row_mask:0xf bank_mask:0xf
	s_waitcnt lgkmcnt(0)
	v_add_f32_e32 v70, v72, v125
	s_waitcnt lgkmcnt(0)
	v_add_f32_e32 v72, v73, v122
	s_waitcnt lgkmcnt(0)
	v_add_f32_e32 v122, v123, v124
	v_mov_b32_e32 v73, v72
	s_nop 1
	v_permlane16_swap_b32_e32 v72, v73
	s_nop 0
	s_nop 1
	v_mov_b32_dpp v123, v122 row_half_mirror row_mask:0xf bank_mask:0xf
	v_mul_f32_e32 v125, v37, v37
	v_fmac_f32_e32 v125, v53, v53
	v_fmac_f32_e32 v125, v21, v21
	s_waitcnt lgkmcnt(0)
	v_add_f32_e32 v72, v72, v73
	s_waitcnt lgkmcnt(0)
	v_add_f32_e32 v73, v122, v123
	v_mul_f32_e32 v123, v36, v36
	v_fmac_f32_e32 v123, v52, v52
	v_fmac_f32_e32 v123, v20, v20
	v_fmac_f32_e32 v123, v4, v4
	v_fmac_f32_e32 v125, v5, v5
	s_nop 1
	v_mov_b32_dpp v122, v73 row_mirror row_mask:0xf bank_mask:0xf
	s_nop 1
	v_mov_b32_dpp v124, v123 quad_perm:[1,0,3,2] row_mask:0xf bank_mask:0xf
	s_nop 1
	v_mov_b32_dpp v126, v125 quad_perm:[1,0,3,2] row_mask:0xf bank_mask:0xf
	v_fmamk_f32 v72, v72, 0x3c000000, v119
	v_mul_f32_e32 v143, v47, v47
	s_waitcnt lgkmcnt(0)
	v_add_f32_e32 v122, v73, v122
	s_waitcnt lgkmcnt(0)
	v_add_f32_e32 v123, v123, v124
	s_waitcnt lgkmcnt(0)
	v_add_f32_e32 v125, v125, v126
	v_mov_b32_e32 v127, v122
	s_nop 1
	v_permlane16_swap_b32_e32 v122, v127
	s_nop 0
	s_nop 1
	v_mov_b32_dpp v124, v123 quad_perm:[2,3,0,1] row_mask:0xf bank_mask:0xf
	s_nop 1
	v_mov_b32_dpp v126, v125 quad_perm:[2,3,0,1] row_mask:0xf bank_mask:0xf
	v_rsq_f32_e32 v73, v72
	v_fmac_f32_e32 v141, v62, v62
	s_waitcnt lgkmcnt(0)
	v_add_f32_e32 v72, v122, v127
	s_waitcnt lgkmcnt(0)
	v_add_f32_e32 v122, v123, v124
	s_waitcnt lgkmcnt(0)
	v_add_f32_e32 v124, v125, v126
	s_nop 1
	v_mov_b32_dpp v123, v122 row_half_mirror row_mask:0xf bank_mask:0xf
	s_nop 1
	v_mov_b32_dpp v125, v124 row_half_mirror row_mask:0xf bank_mask:0xf
	v_mul_f32_e32 v126, v38, v38
	v_fmac_f32_e32 v126, v54, v54
	v_fmac_f32_e32 v126, v22, v22
	s_waitcnt lgkmcnt(0)
	v_add_f32_e32 v122, v122, v123
	s_waitcnt lgkmcnt(0)
	v_add_f32_e32 v124, v124, v125
	v_fmac_f32_e32 v126, v6, v6
	s_nop 1
	v_mov_b32_dpp v123, v122 row_mirror row_mask:0xf bank_mask:0xf
	s_nop 1
	v_mov_b32_dpp v125, v124 row_mirror row_mask:0xf bank_mask:0xf
	s_nop 1
	v_mov_b32_dpp v127, v126 quad_perm:[1,0,3,2] row_mask:0xf bank_mask:0xf
	v_fmac_f32_e32 v143, v63, v63
	v_fmac_f32_e32 v141, v30, v30
	s_waitcnt lgkmcnt(0)
	v_add_f32_e32 v122, v122, v123
	s_waitcnt lgkmcnt(0)
	v_add_f32_e32 v124, v124, v125
	s_waitcnt lgkmcnt(0)
	v_add_f32_e32 v126, v126, v127
	v_mov_b32_e32 v123, v122
	s_nop 1
	v_permlane16_swap_b32_e32 v122, v123
	s_nop 0
	v_mov_b32_e32 v125, v124
	s_nop 1
	v_permlane16_swap_b32_e32 v124, v125
	s_nop 0
	s_nop 1
	v_mov_b32_dpp v127, v126 quad_perm:[2,3,0,1] row_mask:0xf bank_mask:0xf
	v_fmac_f32_e32 v141, v14, v14
	s_nop 1
	v_mov_b32_dpp v142, v141 quad_perm:[1,0,3,2] row_mask:0xf bank_mask:0xf
	s_waitcnt lgkmcnt(0)
	v_add_f32_e32 v122, v122, v123
	s_waitcnt lgkmcnt(0)
	v_add_f32_e32 v123, v124, v125
	s_waitcnt lgkmcnt(0)
	v_add_f32_e32 v124, v126, v127
	v_mul_f32_e32 v126, v39, v39
	v_fmac_f32_e32 v126, v55, v55
	v_fmac_f32_e32 v126, v23, v23
	v_fmac_f32_e32 v126, v7, v7
	s_nop 1
	v_mov_b32_dpp v125, v124 row_half_mirror row_mask:0xf bank_mask:0xf
	s_nop 1
	v_mov_b32_dpp v127, v126 quad_perm:[1,0,3,2] row_mask:0xf bank_mask:0xf
	s_mulk_i32 s72, 0xc0
	v_fmamk_f32 v70, v70, 0x3c000000, v119
	v_rsq_f32_e32 v70, v70
	s_waitcnt lgkmcnt(0)
	v_add_f32_e32 v124, v124, v125
	s_waitcnt lgkmcnt(0)
	v_add_f32_e32 v126, v126, v127
	s_nop 1
	v_mov_b32_dpp v125, v124 row_mirror row_mask:0xf bank_mask:0xf
	s_nop 1
	v_mov_b32_dpp v127, v126 quad_perm:[2,3,0,1] row_mask:0xf bank_mask:0xf
	v_mul_f32_e32 v49, v49, v70
	v_fmamk_f32 v72, v72, 0x3c000000, v119
	v_rsq_f32_e32 v72, v72
	s_waitcnt lgkmcnt(0)
	v_add_f32_e32 v124, v124, v125
	s_waitcnt lgkmcnt(0)
	v_add_f32_e32 v126, v126, v127
	v_mov_b32_e32 v125, v124
	s_nop 1
	v_permlane16_swap_b32_e32 v124, v125
	s_nop 0
	s_nop 1
	v_mov_b32_dpp v127, v126 row_half_mirror row_mask:0xf bank_mask:0xf
	v_fmamk_f32 v122, v122, 0x3c000000, v119
	v_rsq_f32_e32 v122, v122
	v_fmamk_f32 v123, v123, 0x3c000000, v119
	s_waitcnt lgkmcnt(0)
	v_add_f32_e32 v124, v124, v125
	s_waitcnt lgkmcnt(0)
	v_add_f32_e32 v125, v126, v127
	v_add_f32_e32 v127, v128, v129
	v_mul_f32_e32 v129, v41, v41
	v_fmac_f32_e32 v129, v57, v57
	v_fmac_f32_e32 v129, v25, v25
	v_fmac_f32_e32 v129, v9, v9
	s_nop 1
	v_mov_b32_dpp v126, v125 row_mirror row_mask:0xf bank_mask:0xf
	s_nop 1
	v_mov_b32_dpp v130, v129 quad_perm:[1,0,3,2] row_mask:0xf bank_mask:0xf
	s_nop 1
	v_mov_b32_dpp v128, v127 row_half_mirror row_mask:0xf bank_mask:0xf
	v_rsq_f32_e32 v123, v123
	v_fmamk_f32 v124, v124, 0x3c000000, v119
	s_waitcnt lgkmcnt(0)
	v_add_f32_e32 v125, v125, v126
	s_waitcnt lgkmcnt(0)
	v_add_f32_e32 v129, v129, v130
	v_mov_b32_e32 v126, v125
	s_nop 1
	v_permlane16_swap_b32_e32 v125, v126
	s_nop 0
	s_waitcnt lgkmcnt(0)
	v_add_f32_e32 v127, v127, v128
	s_nop 1
	v_mov_b32_dpp v130, v129 quad_perm:[2,3,0,1] row_mask:0xf bank_mask:0xf
	s_nop 1
	v_mov_b32_dpp v128, v127 row_mirror row_mask:0xf bank_mask:0xf
	v_rsq_f32_e32 v124, v124
	s_waitcnt lgkmcnt(0)
	v_add_f32_e32 v125, v125, v126
	v_fmamk_f32 v125, v125, 0x3c000000, v119
	s_waitcnt lgkmcnt(0)
	v_add_f32_e32 v126, v129, v130
	s_waitcnt lgkmcnt(0)
	v_add_f32_e32 v127, v127, v128
	s_nop 1
	v_mov_b32_dpp v128, v126 row_half_mirror row_mask:0xf bank_mask:0xf
	v_mul_f32_e32 v129, v42, v42
	v_fmac_f32_e32 v129, v58, v58
	v_fmac_f32_e32 v129, v26, v26
	v_fmac_f32_e32 v129, v10, v10
	s_waitcnt lgkmcnt(0)
	v_add_f32_e32 v128, v126, v128
	s_nop 1
	v_mov_b32_dpp v130, v129 quad_perm:[1,0,3,2] row_mask:0xf bank_mask:0xf
	s_nop 1
	v_mov_b32_dpp v134, v128 row_mirror row_mask:0xf bank_mask:0xf
	v_rsq_f32_e32 v126, v125
	v_mov_b32_e32 v131, v127
	s_nop 1
	v_permlane16_swap_b32_e32 v127, v131
	s_nop 0
	v_mul_f32_e32 v32, v32, v71
	s_waitcnt lgkmcnt(0)
	v_add_f32_e32 v125, v129, v130
	s_waitcnt lgkmcnt(0)
	v_add_f32_e32 v128, v128, v134
	v_mul_f32_e32 v134, v44, v44
	s_nop 1
	v_mov_b32_dpp v129, v125 quad_perm:[2,3,0,1] row_mask:0xf bank_mask:0xf
	v_fmac_f32_e32 v134, v60, v60
	v_fmac_f32_e32 v134, v28, v28
	v_fmac_f32_e32 v134, v12, v12
	v_mov_b32_e32 v130, v128
	s_nop 1
	v_permlane16_swap_b32_e32 v128, v130
	s_nop 0
	s_nop 1
	v_mov_b32_dpp v138, v134 quad_perm:[1,0,3,2] row_mask:0xf bank_mask:0xf
	s_waitcnt lgkmcnt(0)
	v_add_f32_e32 v129, v125, v129
	v_add_f32_e32 v127, v127, v131
	s_nop 1
	v_mov_b32_dpp v131, v129 row_half_mirror row_mask:0xf bank_mask:0xf
	s_waitcnt lgkmcnt(0)
	v_add_f32_e32 v125, v128, v130
	v_mul_f32_e32 v130, v43, v43
	s_waitcnt lgkmcnt(0)
	v_add_f32_e32 v138, v134, v138
	global_load_dword v134, v121, s[66:67]
	v_fmac_f32_e32 v130, v59, v59
	v_fmac_f32_e32 v130, v27, v27
	s_waitcnt lgkmcnt(0)
	v_add_f32_e32 v128, v129, v131
	v_fmac_f32_e32 v130, v11, v11
	s_nop 1
	v_mov_b32_dpp v129, v128 row_mirror row_mask:0xf bank_mask:0xf
	s_nop 1
	v_mov_b32_dpp v131, v130 quad_perm:[1,0,3,2] row_mask:0xf bank_mask:0xf
	s_nop 1
	v_mov_b32_dpp v139, v138 quad_perm:[2,3,0,1] row_mask:0xf bank_mask:0xf
	v_fmamk_f32 v127, v127, 0x3c000000, v119
	v_rsq_f32_e32 v127, v127
	s_waitcnt lgkmcnt(0)
	v_add_f32_e32 v128, v128, v129
	s_waitcnt lgkmcnt(0)
	v_add_f32_e32 v130, v130, v131
	v_mov_b32_e32 v129, v128
	s_nop 1
	v_permlane16_swap_b32_e32 v128, v129
	s_nop 0
	s_nop 1
	v_mov_b32_dpp v131, v130 quad_perm:[2,3,0,1] row_mask:0xf bank_mask:0xf
	v_fmamk_f32 v125, v125, 0x3c000000, v119
	v_rsq_f32_e32 v125, v125
	v_mul_f32_e32 v16, v16, v71
	s_waitcnt lgkmcnt(0)
	v_add_f32_e32 v128, v128, v129
	s_waitcnt lgkmcnt(0)
	v_add_f32_e32 v129, v130, v131
	v_add_f32_e32 v131, v138, v139
	s_nop 1
	v_mov_b32_dpp v130, v129 row_half_mirror row_mask:0xf bank_mask:0xf
	s_nop 1
	v_mov_b32_dpp v138, v131 row_half_mirror row_mask:0xf bank_mask:0xf
	v_mul_f32_e32 v139, v45, v45
	v_fmac_f32_e32 v139, v61, v61
	v_fmac_f32_e32 v139, v29, v29
	s_waitcnt lgkmcnt(0)
	v_add_f32_e32 v129, v129, v130
	s_waitcnt lgkmcnt(0)
	v_add_f32_e32 v131, v131, v138
	s_nop 1
	v_mov_b32_dpp v130, v129 row_mirror row_mask:0xf bank_mask:0xf
	s_nop 1
	v_mov_b32_dpp v138, v131 row_mirror row_mask:0xf bank_mask:0xf
	v_fmac_f32_e32 v139, v13, v13
	s_nop 1
	v_mov_b32_dpp v140, v139 quad_perm:[1,0,3,2] row_mask:0xf bank_mask:0xf
	v_fmamk_f32 v128, v128, 0x3c000000, v119
	s_waitcnt lgkmcnt(0)
	v_add_f32_e32 v129, v129, v130
	s_waitcnt lgkmcnt(0)
	v_add_f32_e32 v131, v131, v138
	v_mov_b32_e32 v130, v129
	s_nop 1
	v_permlane16_swap_b32_e32 v129, v130
	s_nop 0
	v_mov_b32_e32 v138, v131
	s_nop 1
	v_permlane16_swap_b32_e32 v131, v138
	s_nop 0
	s_waitcnt lgkmcnt(0)
	v_add_f32_e32 v139, v139, v140
	s_nop 1
	v_mov_b32_dpp v140, v139 quad_perm:[2,3,0,1] row_mask:0xf bank_mask:0xf
	v_rsq_f32_e32 v128, v128
	s_waitcnt lgkmcnt(0)
	v_add_f32_e32 v129, v129, v130
	s_waitcnt lgkmcnt(0)
	v_add_f32_e32 v138, v131, v138
	v_mov_b32_e32 v130, v31
	v_mov_b32_e32 v131, v15
	v_pk_mul_f32 v[130:131], v[130:131], v[130:131]
	s_waitcnt lgkmcnt(0)
	v_add_f32_e32 v139, v139, v140
	v_add_f32_e32 v130, v143, v130
	v_add_f32_e32 v130, v130, v131
	s_nop 1
	v_mov_b32_dpp v140, v139 row_half_mirror row_mask:0xf bank_mask:0xf
	s_nop 1
	v_mov_b32_dpp v131, v130 quad_perm:[1,0,3,2] row_mask:0xf bank_mask:0xf
	v_fmamk_f32 v129, v129, 0x3c000000, v119
	v_rsq_f32_e32 v129, v129
	v_mul_f32_e32 v0, v0, v71
	s_waitcnt lgkmcnt(0)
	v_add_f32_e32 v132, v139, v140
	v_add_f32_e32 v139, v141, v142
	s_waitcnt lgkmcnt(0)
	v_add_f32_e32 v130, v130, v131
	s_nop 1
	v_mov_b32_dpp v140, v139 quad_perm:[2,3,0,1] row_mask:0xf bank_mask:0xf
	s_nop 1
	v_mov_b32_dpp v131, v130 quad_perm:[2,3,0,1] row_mask:0xf bank_mask:0xf
	v_fmamk_f32 v133, v138, 0x3c000000, v119
	s_nop 1
	v_mov_b32_dpp v141, v132 row_mirror row_mask:0xf bank_mask:0xf
	s_waitcnt lgkmcnt(0)
	v_add_f32_e32 v138, v139, v140
	s_waitcnt lgkmcnt(0)
	v_add_f32_e32 v130, v130, v131
	s_nop 1
	v_mov_b32_dpp v139, v138 row_half_mirror row_mask:0xf bank_mask:0xf
	s_nop 1
	v_mov_b32_dpp v131, v130 row_half_mirror row_mask:0xf bank_mask:0xf
	s_waitcnt lgkmcnt(0)
	v_add_f32_e32 v140, v132, v141
	v_mov_b32_e32 v135, v140
	s_nop 1
	v_permlane16_swap_b32_e32 v140, v135
	s_nop 0
	v_rsq_f32_e32 v132, v133
	s_waitcnt lgkmcnt(0)
	v_add_f32_e32 v138, v138, v139
	s_waitcnt lgkmcnt(0)
	v_add_f32_e32 v130, v130, v131
	s_nop 1
	v_mov_b32_dpp v139, v138 row_mirror row_mask:0xf bank_mask:0xf
	s_nop 1
	v_mov_b32_dpp v131, v130 row_mirror row_mask:0xf bank_mask:0xf
	s_waitcnt lgkmcnt(0)
	v_add_f32_e32 v133, v140, v135
	v_fmamk_f32 v133, v133, 0x3c000000, v119
	v_rsq_f32_e32 v133, v133
	s_waitcnt lgkmcnt(0)
	v_add_f32_e32 v135, v138, v139
	s_waitcnt lgkmcnt(0)
	v_add_f32_e32 v130, v130, v131
	v_mov_b32_e32 v136, v135
	s_nop 1
	v_permlane16_swap_b32_e32 v135, v136
	s_nop 0
	v_mov_b32_e32 v137, v130
	s_nop 1
	v_permlane16_swap_b32_e32 v130, v137
	s_nop 0
	s_waitcnt vmcnt(0)
	v_mul_f32_e32 v49, v49, v134
	s_waitcnt lgkmcnt(0)
	v_add_f32_e32 v131, v135, v136
	s_waitcnt lgkmcnt(0)
	v_add_f32_e32 v130, v130, v137
	v_mul_f32_e32 v137, v48, v71
	global_load_dword v48, v121, s[66:67] offset:128
	global_load_dword v138, v121, s[66:67] offset:256
	s_nop 0
	global_load_dword v121, v121, s[66:67] offset:384
	v_add_u32_e32 v136, s73, v80
	v_or_b32_e32 v135, s72, v64
	v_mul_lo_u32 v140, v136, s70
	v_mul_f32_e32 v137, v137, v134
	v_add_u32_e32 v136, v140, v135
	v_cvt_pk_bf16_f32 v139, v137, s0
	v_ashrrev_i32_e32 v137, 31, v136
	v_lshl_add_u64 v[136:137], v[136:137], 1, s[6:7]
	global_store_short v[136:137], v139, off sc1
	v_or_b32_e32 v139, 0x600, v140
	v_add_u32_e32 v136, v139, v135
	v_ashrrev_i32_e32 v137, 31, v136
	v_cvt_pk_bf16_f32 v49, v49, s0
	v_lshl_add_u64 v[136:137], v[136:137], 1, s[6:7]
	v_add_u32_e32 v141, 0xc00, v140
	global_store_short v[136:137], v49, off sc1
	v_mul_f32_e32 v49, v50, v73
	v_add_u32_e32 v136, v141, v135
	v_mul_f32_e32 v49, v49, v134
	v_ashrrev_i32_e32 v137, 31, v136
	v_cvt_pk_bf16_f32 v49, v49, s0
	v_lshl_add_u64 v[136:137], v[136:137], 1, s[6:7]
	global_store_short v[136:137], v49, off sc1
	v_add_u32_e32 v136, 0x1200, v140
	v_mul_f32_e32 v49, v51, v72
	v_add_u32_e32 v50, v136, v135
	v_mul_f32_e32 v49, v49, v134
	v_ashrrev_i32_e32 v51, 31, v50
	v_cvt_pk_bf16_f32 v49, v49, s0
	v_lshl_add_u64 v[50:51], v[50:51], 1, s[6:7]
	global_store_short v[50:51], v49, off sc1
	v_mul_f32_e32 v49, v52, v122
	v_add_u32_e32 v52, 0x3000, v140
	v_add_u32_e32 v50, v52, v135
	v_mul_f32_e32 v49, v49, v134
	v_ashrrev_i32_e32 v51, 31, v50
	v_cvt_pk_bf16_f32 v49, v49, s0
	v_lshl_add_u64 v[50:51], v[50:51], 1, s[6:7]
	global_store_short v[50:51], v49, off sc1
	v_mul_f32_e32 v49, v53, v123
	v_add_u32_e32 v53, 0x3600, v140
	v_add_u32_e32 v50, v53, v135
	v_mul_f32_e32 v49, v49, v134
	v_ashrrev_i32_e32 v51, 31, v50
	v_cvt_pk_bf16_f32 v49, v49, s0
	v_lshl_add_u64 v[50:51], v[50:51], 1, s[6:7]
	global_store_short v[50:51], v49, off sc1
	v_mul_f32_e32 v49, v54, v124
	v_add_u32_e32 v54, 0x3c00, v140
	v_add_u32_e32 v50, v54, v135
	v_mul_f32_e32 v49, v49, v134
	v_ashrrev_i32_e32 v51, 31, v50
	v_cvt_pk_bf16_f32 v49, v49, s0
	v_lshl_add_u64 v[50:51], v[50:51], 1, s[6:7]
	global_store_short v[50:51], v49, off sc1
	v_mul_f32_e32 v49, v55, v126
	v_add_u32_e32 v55, 0x4200, v140
	v_add_u32_e32 v50, v55, v135
	v_mul_f32_e32 v49, v49, v134
	v_ashrrev_i32_e32 v51, 31, v50
	v_cvt_pk_bf16_f32 v49, v49, s0
	v_lshl_add_u64 v[50:51], v[50:51], 1, s[6:7]
	global_store_short v[50:51], v49, off sc1
	v_mul_f32_e32 v49, v56, v127
	v_add_u32_e32 v56, 0x6000, v140
	v_add_u32_e32 v50, v56, v135
	v_mul_f32_e32 v49, v49, v134
	v_ashrrev_i32_e32 v51, 31, v50
	v_cvt_pk_bf16_f32 v49, v49, s0
	v_lshl_add_u64 v[50:51], v[50:51], 1, s[6:7]
	global_store_short v[50:51], v49, off sc1
	v_mul_f32_e32 v49, v57, v125
	v_add_u32_e32 v57, 0x6600, v140
	v_add_u32_e32 v50, v57, v135
	v_mul_f32_e32 v49, v49, v134
	v_ashrrev_i32_e32 v51, 31, v50
	v_cvt_pk_bf16_f32 v49, v49, s0
	v_lshl_add_u64 v[50:51], v[50:51], 1, s[6:7]
	global_store_short v[50:51], v49, off sc1
	v_mul_f32_e32 v49, v58, v128
	v_add_u32_e32 v58, 0x6c00, v140
	v_add_u32_e32 v50, v58, v135
	v_mul_f32_e32 v49, v49, v134
	v_ashrrev_i32_e32 v51, 31, v50
	v_cvt_pk_bf16_f32 v49, v49, s0
	v_lshl_add_u64 v[50:51], v[50:51], 1, s[6:7]
	global_store_short v[50:51], v49, off sc1
	v_mul_f32_e32 v49, v59, v129
	v_add_u32_e32 v59, 0x7200, v140
	v_add_u32_e32 v50, v59, v135
	v_mul_f32_e32 v49, v49, v134
	v_ashrrev_i32_e32 v51, 31, v50
	v_cvt_pk_bf16_f32 v49, v49, s0
	v_lshl_add_u64 v[50:51], v[50:51], 1, s[6:7]
	global_store_short v[50:51], v49, off sc1
	v_mul_f32_e32 v49, v60, v132
	v_add_u32_e32 v60, 0x9000, v140
	v_add_u32_e32 v50, v60, v135
	v_mul_f32_e32 v49, v49, v134
	v_ashrrev_i32_e32 v51, 31, v50
	v_fmamk_f32 v131, v131, 0x3c000000, v119
	v_cvt_pk_bf16_f32 v49, v49, s0
	v_lshl_add_u64 v[50:51], v[50:51], 1, s[6:7]
	v_rsq_f32_e32 v131, v131
	global_store_short v[50:51], v49, off sc1
	v_mul_f32_e32 v49, v61, v133
	v_add_u32_e32 v61, 0x9600, v140
	v_add_u32_e32 v50, v61, v135
	v_mul_f32_e32 v49, v49, v134
	v_ashrrev_i32_e32 v51, 31, v50
	v_fmamk_f32 v130, v130, 0x3c000000, v119
	v_cvt_pk_bf16_f32 v49, v49, s0
	v_lshl_add_u64 v[50:51], v[50:51], 1, s[6:7]
	v_rsq_f32_e32 v130, v130
	global_store_short v[50:51], v49, off sc1
	v_mul_f32_e32 v49, v62, v131
	v_add_u32_e32 v62, 0x9c00, v140
	v_add_u32_e32 v50, v62, v135
	v_mul_f32_e32 v49, v134, v49
	v_ashrrev_i32_e32 v51, 31, v50
	v_cvt_pk_bf16_f32 v49, v49, s0
	v_lshl_add_u64 v[50:51], v[50:51], 1, s[6:7]
	global_store_short v[50:51], v49, off sc1
	v_mul_f32_e32 v49, v63, v130
	v_add_u32_e32 v63, 0xa200, v140
	v_add_u32_e32 v50, v63, v135
	v_mul_f32_e32 v49, v134, v49
	v_ashrrev_i32_e32 v51, 31, v50
	v_cvt_pk_bf16_f32 v49, v49, s0
	v_lshl_add_u64 v[50:51], v[50:51], 1, s[6:7]
	global_store_short v[50:51], v49, off sc1
	v_or_b32_e32 v49, s72, v65
	v_add_u32_e32 v50, v140, v49
	s_waitcnt vmcnt(18)
	v_mul_f32_e32 v32, v32, v48
	v_ashrrev_i32_e32 v51, 31, v50
	v_cvt_pk_bf16_f32 v32, v32, s0
	v_lshl_add_u64 v[50:51], v[50:51], 1, s[6:7]
	global_store_short v[50:51], v32, off sc1
	v_mul_f32_e32 v32, v33, v70
	v_mul_f32_e32 v32, v32, v48
	v_cvt_pk_bf16_f32 v50, v32, s0
	v_add_u32_e32 v32, v139, v49
	v_ashrrev_i32_e32 v33, 31, v32
	v_lshl_add_u64 v[32:33], v[32:33], 1, s[6:7]
	global_store_short v[32:33], v50, off sc1
	v_mul_f32_e32 v32, v34, v73
	v_mul_f32_e32 v32, v32, v48
	v_cvt_pk_bf16_f32 v34, v32, s0
	v_add_u32_e32 v32, v141, v49
	v_ashrrev_i32_e32 v33, 31, v32
	v_lshl_add_u64 v[32:33], v[32:33], 1, s[6:7]
	global_store_short v[32:33], v34, off sc1
	v_mul_f32_e32 v32, v35, v72
	v_mul_f32_e32 v32, v32, v48
	v_cvt_pk_bf16_f32 v34, v32, s0
	v_add_u32_e32 v32, v136, v49
	v_ashrrev_i32_e32 v33, 31, v32
	v_lshl_add_u64 v[32:33], v[32:33], 1, s[6:7]
	global_store_short v[32:33], v34, off sc1
	v_mul_f32_e32 v32, v36, v122
	v_mul_f32_e32 v32, v32, v48
	v_cvt_pk_bf16_f32 v34, v32, s0
	v_add_u32_e32 v32, v52, v49
	v_ashrrev_i32_e32 v33, 31, v32
	v_lshl_add_u64 v[32:33], v[32:33], 1, s[6:7]
	global_store_short v[32:33], v34, off sc1
	v_mul_f32_e32 v32, v37, v123
	v_mul_f32_e32 v32, v32, v48
	v_cvt_pk_bf16_f32 v34, v32, s0
	v_add_u32_e32 v32, v53, v49
	v_ashrrev_i32_e32 v33, 31, v32
	v_lshl_add_u64 v[32:33], v[32:33], 1, s[6:7]
	global_store_short v[32:33], v34, off sc1
	v_mul_f32_e32 v32, v38, v124
	v_mul_f32_e32 v32, v32, v48
	v_cvt_pk_bf16_f32 v34, v32, s0
	v_add_u32_e32 v32, v54, v49
	v_ashrrev_i32_e32 v33, 31, v32
	v_lshl_add_u64 v[32:33], v[32:33], 1, s[6:7]
	global_store_short v[32:33], v34, off sc1
	v_mul_f32_e32 v32, v39, v126
	v_mul_f32_e32 v32, v32, v48
	v_cvt_pk_bf16_f32 v34, v32, s0
	v_add_u32_e32 v32, v55, v49
	v_ashrrev_i32_e32 v33, 31, v32
	v_lshl_add_u64 v[32:33], v[32:33], 1, s[6:7]
	global_store_short v[32:33], v34, off sc1
	v_mul_f32_e32 v32, v40, v127
	v_mul_f32_e32 v32, v32, v48
	v_cvt_pk_bf16_f32 v34, v32, s0
	v_add_u32_e32 v32, v56, v49
	v_ashrrev_i32_e32 v33, 31, v32
	v_lshl_add_u64 v[32:33], v[32:33], 1, s[6:7]
	global_store_short v[32:33], v34, off sc1
	v_mul_f32_e32 v32, v41, v125
	v_mul_f32_e32 v32, v32, v48
	v_cvt_pk_bf16_f32 v34, v32, s0
	v_add_u32_e32 v32, v57, v49
	v_ashrrev_i32_e32 v33, 31, v32
	v_lshl_add_u64 v[32:33], v[32:33], 1, s[6:7]
	global_store_short v[32:33], v34, off sc1
	v_mul_f32_e32 v32, v42, v128
	v_mul_f32_e32 v32, v32, v48
	v_cvt_pk_bf16_f32 v34, v32, s0
	v_add_u32_e32 v32, v58, v49
	v_ashrrev_i32_e32 v33, 31, v32
	v_lshl_add_u64 v[32:33], v[32:33], 1, s[6:7]
	global_store_short v[32:33], v34, off sc1
	v_mul_f32_e32 v32, v43, v129
	v_mul_f32_e32 v32, v32, v48
	v_cvt_pk_bf16_f32 v34, v32, s0
	v_add_u32_e32 v32, v59, v49
	v_ashrrev_i32_e32 v33, 31, v32
	v_lshl_add_u64 v[32:33], v[32:33], 1, s[6:7]
	global_store_short v[32:33], v34, off sc1
	v_mul_f32_e32 v32, v44, v132
	v_mul_f32_e32 v32, v32, v48
	v_cvt_pk_bf16_f32 v34, v32, s0
	v_add_u32_e32 v32, v60, v49
	v_ashrrev_i32_e32 v33, 31, v32
	v_lshl_add_u64 v[32:33], v[32:33], 1, s[6:7]
	global_store_short v[32:33], v34, off sc1
	v_mul_f32_e32 v32, v45, v133
	v_mul_f32_e32 v32, v32, v48
	v_cvt_pk_bf16_f32 v34, v32, s0
	v_add_u32_e32 v32, v61, v49
	v_ashrrev_i32_e32 v33, 31, v32
	v_lshl_add_u64 v[32:33], v[32:33], 1, s[6:7]
	global_store_short v[32:33], v34, off sc1
	v_mul_f32_e32 v32, v46, v131
	v_mul_f32_e32 v32, v32, v48
	v_cvt_pk_bf16_f32 v34, v32, s0
	v_add_u32_e32 v32, v62, v49
	v_ashrrev_i32_e32 v33, 31, v32
	v_lshl_add_u64 v[32:33], v[32:33], 1, s[6:7]
	global_store_short v[32:33], v34, off sc1
	v_mul_f32_e32 v32, v47, v130
	v_mul_f32_e32 v32, v32, v48
	v_cvt_pk_bf16_f32 v34, v32, s0
	v_add_u32_e32 v32, v63, v49
	v_ashrrev_i32_e32 v33, 31, v32
	v_lshl_add_u64 v[32:33], v[32:33], 1, s[6:7]
	global_store_short v[32:33], v34, off sc1
	v_add_u32_e32 v34, s72, v74
	v_add_u32_e32 v32, v140, v34
	s_waitcnt vmcnt(33)
	v_mul_f32_e32 v16, v16, v138
	v_ashrrev_i32_e32 v33, 31, v32
	v_cvt_pk_bf16_f32 v16, v16, s0
	v_lshl_add_u64 v[32:33], v[32:33], 1, s[6:7]
	global_store_short v[32:33], v16, off sc1
	v_mul_f32_e32 v16, v17, v70
	v_mul_f32_e32 v16, v16, v138
	v_cvt_pk_bf16_f32 v32, v16, s0
	v_add_u32_e32 v16, v139, v34
	v_ashrrev_i32_e32 v17, 31, v16
	v_lshl_add_u64 v[16:17], v[16:17], 1, s[6:7]
	global_store_short v[16:17], v32, off sc1
	v_mul_f32_e32 v16, v18, v73
	v_mul_f32_e32 v16, v16, v138
	v_cvt_pk_bf16_f32 v18, v16, s0
	v_add_u32_e32 v16, v141, v34
	v_ashrrev_i32_e32 v17, 31, v16
	v_lshl_add_u64 v[16:17], v[16:17], 1, s[6:7]
	global_store_short v[16:17], v18, off sc1
	v_mul_f32_e32 v16, v19, v72
	v_mul_f32_e32 v16, v16, v138
	v_cvt_pk_bf16_f32 v18, v16, s0
	v_add_u32_e32 v16, v136, v34
	v_ashrrev_i32_e32 v17, 31, v16
	v_lshl_add_u64 v[16:17], v[16:17], 1, s[6:7]
	global_store_short v[16:17], v18, off sc1
	v_mul_f32_e32 v16, v20, v122
	v_mul_f32_e32 v16, v16, v138
	v_cvt_pk_bf16_f32 v18, v16, s0
	v_add_u32_e32 v16, v52, v34
	v_ashrrev_i32_e32 v17, 31, v16
	v_lshl_add_u64 v[16:17], v[16:17], 1, s[6:7]
	global_store_short v[16:17], v18, off sc1
	v_mul_f32_e32 v16, v21, v123
	v_mul_f32_e32 v16, v16, v138
	v_cvt_pk_bf16_f32 v18, v16, s0
	v_add_u32_e32 v16, v53, v34
	v_ashrrev_i32_e32 v17, 31, v16
	v_lshl_add_u64 v[16:17], v[16:17], 1, s[6:7]
	global_store_short v[16:17], v18, off sc1
	v_mul_f32_e32 v16, v22, v124
	v_mul_f32_e32 v16, v16, v138
	v_cvt_pk_bf16_f32 v18, v16, s0
	v_add_u32_e32 v16, v54, v34
	v_ashrrev_i32_e32 v17, 31, v16
	v_lshl_add_u64 v[16:17], v[16:17], 1, s[6:7]
	global_store_short v[16:17], v18, off sc1
	v_mul_f32_e32 v16, v23, v126
	v_mul_f32_e32 v16, v16, v138
	v_cvt_pk_bf16_f32 v18, v16, s0
	v_add_u32_e32 v16, v55, v34
	v_ashrrev_i32_e32 v17, 31, v16
	v_lshl_add_u64 v[16:17], v[16:17], 1, s[6:7]
	global_store_short v[16:17], v18, off sc1
	v_mul_f32_e32 v16, v24, v127
	v_mul_f32_e32 v16, v16, v138
	v_cvt_pk_bf16_f32 v18, v16, s0
	v_add_u32_e32 v16, v56, v34
	v_ashrrev_i32_e32 v17, 31, v16
	v_lshl_add_u64 v[16:17], v[16:17], 1, s[6:7]
	global_store_short v[16:17], v18, off sc1
	v_mul_f32_e32 v16, v25, v125
	v_mul_f32_e32 v16, v16, v138
	v_cvt_pk_bf16_f32 v18, v16, s0
	v_add_u32_e32 v16, v57, v34
	v_ashrrev_i32_e32 v17, 31, v16
	v_lshl_add_u64 v[16:17], v[16:17], 1, s[6:7]
	global_store_short v[16:17], v18, off sc1
	v_mul_f32_e32 v16, v26, v128
	v_mul_f32_e32 v16, v16, v138
	v_cvt_pk_bf16_f32 v18, v16, s0
	v_add_u32_e32 v16, v58, v34
	v_ashrrev_i32_e32 v17, 31, v16
	v_lshl_add_u64 v[16:17], v[16:17], 1, s[6:7]
	global_store_short v[16:17], v18, off sc1
	v_mul_f32_e32 v16, v27, v129
	v_mul_f32_e32 v16, v16, v138
	v_cvt_pk_bf16_f32 v18, v16, s0
	v_add_u32_e32 v16, v59, v34
	v_ashrrev_i32_e32 v17, 31, v16
	v_lshl_add_u64 v[16:17], v[16:17], 1, s[6:7]
	global_store_short v[16:17], v18, off sc1
	v_mul_f32_e32 v16, v28, v132
	v_mul_f32_e32 v16, v16, v138
	v_cvt_pk_bf16_f32 v18, v16, s0
	v_add_u32_e32 v16, v60, v34
	v_ashrrev_i32_e32 v17, 31, v16
	v_lshl_add_u64 v[16:17], v[16:17], 1, s[6:7]
	global_store_short v[16:17], v18, off sc1
	v_mul_f32_e32 v16, v29, v133
	v_mul_f32_e32 v16, v16, v138
	v_cvt_pk_bf16_f32 v18, v16, s0
	v_add_u32_e32 v16, v61, v34
	v_ashrrev_i32_e32 v17, 31, v16
	v_lshl_add_u64 v[16:17], v[16:17], 1, s[6:7]
	global_store_short v[16:17], v18, off sc1
	v_mul_f32_e32 v16, v30, v131
	v_mul_f32_e32 v16, v16, v138
	v_cvt_pk_bf16_f32 v18, v16, s0
	v_add_u32_e32 v16, v62, v34
	v_ashrrev_i32_e32 v17, 31, v16
	v_lshl_add_u64 v[16:17], v[16:17], 1, s[6:7]
	global_store_short v[16:17], v18, off sc1
	v_mul_f32_e32 v16, v31, v130
	v_mul_f32_e32 v16, v16, v138
	v_cvt_pk_bf16_f32 v18, v16, s0
	v_add_u32_e32 v16, v63, v34
	v_ashrrev_i32_e32 v17, 31, v16
	v_lshl_add_u64 v[16:17], v[16:17], 1, s[6:7]
	global_store_short v[16:17], v18, off sc1
	v_add_u32_e32 v18, s72, v98
	v_add_u32_e32 v16, v140, v18
	s_waitcnt vmcnt(48)
	v_mul_f32_e32 v0, v0, v121
	v_ashrrev_i32_e32 v17, 31, v16
	v_cvt_pk_bf16_f32 v0, v0, s0
	v_lshl_add_u64 v[16:17], v[16:17], 1, s[6:7]
	global_store_short v[16:17], v0, off sc1
	v_mul_f32_e32 v0, v1, v70
	v_mul_f32_e32 v0, v0, v121
	v_cvt_pk_bf16_f32 v16, v0, s0
	v_add_u32_e32 v0, v139, v18
	v_ashrrev_i32_e32 v1, 31, v0
	v_lshl_add_u64 v[0:1], v[0:1], 1, s[6:7]
	global_store_short v[0:1], v16, off sc1
	v_mul_f32_e32 v0, v2, v73
	v_mul_f32_e32 v0, v0, v121
	v_cvt_pk_bf16_f32 v2, v0, s0
	v_add_u32_e32 v0, v141, v18
	v_ashrrev_i32_e32 v1, 31, v0
	v_lshl_add_u64 v[0:1], v[0:1], 1, s[6:7]
	global_store_short v[0:1], v2, off sc1
	v_mul_f32_e32 v0, v3, v72
	v_mul_f32_e32 v0, v0, v121
	v_cvt_pk_bf16_f32 v2, v0, s0
	v_add_u32_e32 v0, v136, v18
	v_ashrrev_i32_e32 v1, 31, v0
	v_lshl_add_u64 v[0:1], v[0:1], 1, s[6:7]
	global_store_short v[0:1], v2, off sc1
	v_mul_f32_e32 v0, v4, v122
	v_mul_f32_e32 v0, v0, v121
	v_cvt_pk_bf16_f32 v2, v0, s0
	v_add_u32_e32 v0, v52, v18
	v_ashrrev_i32_e32 v1, 31, v0
	v_lshl_add_u64 v[0:1], v[0:1], 1, s[6:7]
	global_store_short v[0:1], v2, off sc1
	v_mul_f32_e32 v0, v5, v123
	v_mul_f32_e32 v0, v0, v121
	v_cvt_pk_bf16_f32 v2, v0, s0
	v_add_u32_e32 v0, v53, v18
	v_ashrrev_i32_e32 v1, 31, v0
	v_lshl_add_u64 v[0:1], v[0:1], 1, s[6:7]
	global_store_short v[0:1], v2, off sc1
	v_mul_f32_e32 v0, v6, v124
	v_mul_f32_e32 v0, v0, v121
	v_cvt_pk_bf16_f32 v2, v0, s0
	v_add_u32_e32 v0, v54, v18
	v_ashrrev_i32_e32 v1, 31, v0
	v_lshl_add_u64 v[0:1], v[0:1], 1, s[6:7]
	global_store_short v[0:1], v2, off sc1
	v_mul_f32_e32 v0, v7, v126
	v_mul_f32_e32 v0, v0, v121
	v_cvt_pk_bf16_f32 v2, v0, s0
	v_add_u32_e32 v0, v55, v18
	v_ashrrev_i32_e32 v1, 31, v0
	v_lshl_add_u64 v[0:1], v[0:1], 1, s[6:7]
	global_store_short v[0:1], v2, off sc1
	v_mul_f32_e32 v0, v8, v127
	v_mul_f32_e32 v0, v0, v121
	v_cvt_pk_bf16_f32 v2, v0, s0
	v_add_u32_e32 v0, v56, v18
	v_ashrrev_i32_e32 v1, 31, v0
	v_lshl_add_u64 v[0:1], v[0:1], 1, s[6:7]
	global_store_short v[0:1], v2, off sc1
	v_mul_f32_e32 v0, v9, v125
	v_mul_f32_e32 v0, v0, v121
	v_cvt_pk_bf16_f32 v2, v0, s0
	v_add_u32_e32 v0, v57, v18
	v_ashrrev_i32_e32 v1, 31, v0
	v_lshl_add_u64 v[0:1], v[0:1], 1, s[6:7]
	global_store_short v[0:1], v2, off sc1
	v_mul_f32_e32 v0, v10, v128
	v_mul_f32_e32 v0, v0, v121
	v_cvt_pk_bf16_f32 v2, v0, s0
	v_add_u32_e32 v0, v58, v18
	v_ashrrev_i32_e32 v1, 31, v0
	v_lshl_add_u64 v[0:1], v[0:1], 1, s[6:7]
	global_store_short v[0:1], v2, off sc1
	v_mul_f32_e32 v0, v11, v129
	v_mul_f32_e32 v0, v0, v121
	v_cvt_pk_bf16_f32 v2, v0, s0
	v_add_u32_e32 v0, v59, v18
	v_ashrrev_i32_e32 v1, 31, v0
	v_lshl_add_u64 v[0:1], v[0:1], 1, s[6:7]
	global_store_short v[0:1], v2, off sc1
	v_mul_f32_e32 v0, v12, v132
	v_mul_f32_e32 v0, v0, v121
	v_cvt_pk_bf16_f32 v2, v0, s0
	v_add_u32_e32 v0, v60, v18
	v_ashrrev_i32_e32 v1, 31, v0
	v_lshl_add_u64 v[0:1], v[0:1], 1, s[6:7]
	global_store_short v[0:1], v2, off sc1
	v_mul_f32_e32 v0, v13, v133
	v_mul_f32_e32 v0, v0, v121
	v_cvt_pk_bf16_f32 v2, v0, s0
	v_add_u32_e32 v0, v61, v18
	v_ashrrev_i32_e32 v1, 31, v0
	v_lshl_add_u64 v[0:1], v[0:1], 1, s[6:7]
	global_store_short v[0:1], v2, off sc1
	v_mul_f32_e32 v0, v14, v131
	v_mul_f32_e32 v0, v0, v121
	v_cvt_pk_bf16_f32 v2, v0, s0
	v_add_u32_e32 v0, v62, v18
	v_ashrrev_i32_e32 v1, 31, v0
	v_lshl_add_u64 v[0:1], v[0:1], 1, s[6:7]
	global_store_short v[0:1], v2, off sc1
	v_mul_f32_e32 v0, v15, v130
	v_mul_f32_e32 v70, v0, v121
	v_add_u32_e32 v72, v63, v18
	s_branch .LBB0_575
.LBB0_644:
	s_cmpk_gt_i32 s3, 0x83f
	s_cbranch_scc1 .LBB0_655
	v_lshrrev_b32_e32 v0, 3, v199
	v_lshrrev_b32_e32 v1, 5, v199
	v_bfe_u32 v4, v199, 1, 3
	v_lshlrev_b32_e32 v5, 4, v199
	v_bfe_u32 v2, v199, 5, 1
	v_xor_b32_e32 v6, v5, v199
	v_lshlrev_b32_e32 v7, 9, v0
	s_movk_i32 s0, 0x70
	v_bitop3_b32 v1, v1, v4, 1 bitop3:0x6c
	v_and_or_b32 v66, v6, s0, v7
	v_lshlrev_b32_e32 v7, 4, v1
	v_bitop3_b32 v1, v2, v4, 2 bitop3:0x36
	s_add_u32 s10, s14, 0x13e1f000
	v_lshrrev_b32_e32 v3, 1, v199
	v_lshlrev_b32_e32 v8, 4, v1
	v_bitop3_b32 v1, v2, v4, 4 bitop3:0x36
	s_addc_u32 s11, s15, 0
	v_mov_b32_e32 v67, 0
	v_and_b32_e32 v3, 0x1e0, v3
	v_lshlrev_b32_e32 v9, 4, v1
	v_bitop3_b32 v1, v2, v4, 6 bitop3:0x36
	s_add_u32 s52, s14, 0x2a0000
	v_lshlrev_b32_e32 v2, 4, v1
	v_and_or_b32 v72, v0, 4, v3
	v_lshlrev_b32_e32 v0, 1, v64
	v_mov_b32_e32 v1, v67
	s_addc_u32 s53, s15, 0
	v_or_b32_e32 v6, v3, v64
	v_lshl_add_u64 v[0:1], s[14:15], 0, v[0:1]
	s_mov_b64 s[0:1], 0xdf9f000
	v_lshl_add_u32 v6, v6, 7, 0
	v_or_b32_e32 v78, 0x60, v64
	s_add_u32 s6, s14, 0x1111f000
	v_lshl_add_u64 v[68:69], v[0:1], 0, s[0:1]
	s_waitcnt lgkmcnt(0)
	v_add_u32_e32 v80, 0, v5
	v_mbcnt_lo_u32_b32 v0, -1, 0
	v_lshlrev_b32_e32 v73, 8, v64
	v_lshlrev_b32_e32 v76, 8, v65
	v_lshlrev_b32_e32 v77, 8, v74
	v_lshlrev_b32_e32 v79, 8, v78
	s_addc_u32 s7, s15, 0
	v_add_u32_e32 v81, 0x4000, v80
	s_mov_b64 s[8:9], 0x4000
	s_movk_i32 s54, 0x1000
	s_waitcnt lgkmcnt(0)
	v_add_u32_e32 v82, 0x1000, v80
	s_waitcnt lgkmcnt(0)
	v_add_u32_e32 v83, 0x5000, v80
	s_mov_b64 s[18:19], 0x8000
	s_movk_i32 s55, 0x2000
	v_add_u32_e32 v84, 0x2000, v80
	s_movk_i32 s56, 0x6000
	v_add_u32_e32 v85, 0x6000, v80
	s_mov_b64 s[20:21], 0xc000
	v_add_u32_e32 v86, 0x3000, v80
	s_movk_i32 s57, 0x7000
	v_add_u32_e32 v87, 0x7000, v80
	s_mov_b64 s[22:23], 0x80
	s_mov_b32 s58, 0x8000
	v_add_u32_e32 v88, 0x8000, v80
	s_mov_b32 s59, 0xc000
	v_add_u32_e32 v89, 0xc000, v80
	s_mov_b64 s[24:25], 0x4080
	v_add_u32_e32 v90, 0x9000, v80
	s_mov_b32 s60, 0xd000
	v_add_u32_e32 v91, 0xd000, v80
	s_mov_b64 s[26:27], 0x8080
	v_add_u32_e32 v92, 0xa000, v80
	s_mov_b32 s61, 0xe000
	v_add_u32_e32 v93, 0xe000, v80
	s_mov_b64 s[28:29], 0xc080
	v_add_u32_e32 v94, 0xb000, v80
	v_add_u32_e32 v95, 0xf000, v80
	v_add_u32_e32 v96, v6, v7
	v_add_u32_e32 v97, v75, v7
	v_add_u32_e32 v98, v6, v8
	v_add_u32_e32 v99, v75, v8
	v_add_u32_e32 v100, v6, v9
	v_add_u32_e32 v101, v75, v9
	v_add_u32_e32 v102, v6, v2
	v_add_u32_e32 v75, v75, v2
	s_mov_b64 s[30:31], 0x100
	s_mov_b64 s[34:35], 0x4100
	s_mov_b64 s[36:37], 0x8100
	s_mov_b64 s[38:39], 0xc100
	s_mov_b64 s[40:41], 0x180
	s_mov_b64 s[42:43], 0x4180
	s_mov_b64 s[44:45], 0x8180
	s_mov_b64 s[46:47], 0xc180
	s_movk_i32 s62, 0x1100
	s_add_i32 s63, 0, 0x120b0
	v_lshlrev_b32_e32 v103, 2, v64
	v_mov_b32_e32 v104, 0x358637bd
	s_movk_i32 s64, 0x600
	s_mov_b32 s65, 0x12000
	s_mov_b32 s66, 0x13000
	s_mov_b32 s67, 0x14000
	v_mbcnt_hi_u32_b32 v105, -1, v0
	s_branch .LBB0_647

.LBB0_653:
	s_and_b64 vcc, exec, s[0:1]
	s_cbranch_vccz .LBB0_646
	v_mov_b32_e32 v70, s63
	ds_read_b64 v[70:71], v70
	v_xor_b32_e32 v110, 2, v105
	v_add_u32_e32 v114, s48, v72
	v_xor_b32_e32 v111, 4, v105
	v_mul_f32_e32 v115, v32, v32
	s_waitcnt lgkmcnt(0)
	v_readfirstlane_b32 s0, v70
	v_readfirstlane_b32 s1, v71
	s_nop 4
	global_load_dword v109, v103, s[0:1] offset:768
	global_load_dword v108, v103, s[0:1] offset:896
	global_load_dword v107, v103, s[0:1] offset:1024
	global_load_dword v106, v103, s[0:1] offset:1152
	v_and_b32_e32 v70, 64, v105
	v_xor_b32_e32 v71, 1, v105
	v_add_u32_e32 v116, 64, v70
	v_cmp_lt_i32_e32 vcc, v71, v116
	v_mul_lo_u32 v70, v114, s64
	v_xor_b32_e32 v112, 8, v105
	v_cndmask_b32_e32 v114, v105, v71, vcc
	v_cmp_lt_i32_e32 vcc, v110, v116
	v_fmac_f32_e32 v115, v48, v48
	v_fmac_f32_e32 v115, v16, v16
	v_cndmask_b32_e32 v110, v105, v110, vcc
	v_cmp_lt_i32_e32 vcc, v111, v116
	v_fmac_f32_e32 v115, v0, v0
	v_xor_b32_e32 v113, 16, v105
	v_cndmask_b32_e32 v111, v105, v111, vcc
	v_cmp_lt_i32_e32 vcc, v112, v116
	v_mul_f32_e32 v118, v33, v33
	v_fmac_f32_e32 v118, v49, v49
	v_cndmask_b32_e32 v120, v105, v112, vcc
	v_lshlrev_b32_e32 v112, 2, v114
	s_nop 1
	v_mov_b32_dpp v114, v115 quad_perm:[1,0,3,2] row_mask:0xf bank_mask:0xf
	v_cmp_lt_i32_e32 vcc, v113, v116
	v_fmac_f32_e32 v118, v17, v17
	v_fmac_f32_e32 v118, v1, v1
	v_cndmask_b32_e32 v121, v105, v113, vcc
	v_lshlrev_b32_e32 v113, 2, v110
	s_waitcnt lgkmcnt(0)
	v_add_f32_e32 v110, v115, v114
	s_nop 1
	v_mov_b32_dpp v115, v110 quad_perm:[2,3,0,1] row_mask:0xf bank_mask:0xf
	v_lshlrev_b32_e32 v114, 2, v111
	s_nop 1
	v_mov_b32_dpp v122, v118 quad_perm:[1,0,3,2] row_mask:0xf bank_mask:0xf
	v_lshlrev_b32_e32 v111, 2, v120
	v_mul_f32_e32 v119, v34, v34
	s_waitcnt lgkmcnt(0)
	v_add_f32_e32 v115, v110, v115
	s_nop 1
	v_mov_b32_dpp v123, v115 row_half_mirror row_mask:0xf bank_mask:0xf
	v_lshlrev_b32_e32 v110, 2, v121
	s_waitcnt lgkmcnt(0)
	v_add_f32_e32 v118, v118, v122
	s_nop 1
	v_mov_b32_dpp v122, v118 quad_perm:[2,3,0,1] row_mask:0xf bank_mask:0xf
	v_fmac_f32_e32 v119, v50, v50
	s_waitcnt lgkmcnt(0)
	v_add_f32_e32 v115, v115, v123
	s_nop 1
	v_mov_b32_dpp v121, v115 row_mirror row_mask:0xf bank_mask:0xf
	v_fmac_f32_e32 v119, v18, v18
	s_waitcnt lgkmcnt(0)
	v_add_f32_e32 v118, v118, v122
	s_nop 1
	v_mov_b32_dpp v120, v118 row_half_mirror row_mask:0xf bank_mask:0xf
	v_fmac_f32_e32 v119, v2, v2
	s_waitcnt lgkmcnt(0)
	v_add_f32_e32 v115, v115, v121
	v_mov_b32_e32 v121, v115
	s_nop 1
	v_permlane16_swap_b32_e32 v115, v121
	s_nop 0
	s_nop 1
	v_mov_b32_dpp v122, v119 quad_perm:[1,0,3,2] row_mask:0xf bank_mask:0xf
	s_waitcnt lgkmcnt(0)
	v_add_f32_e32 v118, v118, v120
	s_nop 1
	v_mov_b32_dpp v120, v118 row_mirror row_mask:0xf bank_mask:0xf
	s_mul_i32 s0, s49, 0xc0
	s_waitcnt lgkmcnt(0)
	v_add_f32_e32 v115, v115, v121
	v_fmamk_f32 v115, v115, 0x3c000000, v104
	v_rsq_f32_e32 v115, v115
	s_ashr_i32 s1, s0, 31
	v_lshl_add_u64 v[116:117], s[0:1], 1, v[68:69]
	v_ashrrev_i32_e32 v71, 31, v70
	v_mul_f32_e32 v48, v48, v115
	v_mul_f32_e32 v16, v16, v115
	v_mul_f32_e32 v32, v32, v115
	v_lshl_add_u64 v[70:71], v[70:71], 1, v[116:117]
	s_waitcnt lgkmcnt(0)
	v_add_f32_e32 v116, v118, v120
	v_add_f32_e32 v118, v119, v122
	v_mov_b32_e32 v117, v116
	s_nop 1
	v_permlane16_swap_b32_e32 v116, v117
	s_nop 0
	v_mul_f32_e32 v0, v0, v115
	s_waitcnt lgkmcnt(0)
	v_add_f32_e32 v116, v116, v117
	v_fmamk_f32 v116, v116, 0x3c000000, v104
	v_rsq_f32_e32 v116, v116
	s_waitcnt vmcnt(3)
	v_mul_f32_e32 v48, v109, v48
	s_waitcnt vmcnt(2)
	v_mul_f32_e32 v32, v108, v32
	s_waitcnt vmcnt(1)
	v_mul_f32_e32 v16, v107, v16
	v_cvt_pk_bf16_f32 v48, v48, s0
	v_cvt_pk_bf16_f32 v16, v16, s0
	v_cvt_pk_bf16_f32 v32, v32, s0
	global_store_short v[70:71], v48, off sc1
	global_store_short v[70:71], v32, off offset:64 sc1
	global_store_short v[70:71], v16, off offset:128 sc1
	s_nop 1
	v_mov_b32_dpp v16, v118 quad_perm:[2,3,0,1] row_mask:0xf bank_mask:0xf
	s_waitcnt vmcnt(3)
	v_mul_f32_e32 v0, v106, v0
	v_cvt_pk_bf16_f32 v0, v0, s0
	global_store_short v[70:71], v0, off offset:192 sc1
	v_mul_f32_e32 v0, v49, v116
	s_waitcnt lgkmcnt(0)
	v_add_f32_e32 v16, v118, v16
	s_nop 1
	v_mov_b32_dpp v32, v16 row_half_mirror row_mask:0xf bank_mask:0xf
	v_mul_f32_e32 v0, v109, v0
	v_cvt_pk_bf16_f32 v0, v0, s0
	global_store_short v[70:71], v0, off offset:3072 sc1
	v_mul_f32_e32 v0, v33, v116
	s_waitcnt lgkmcnt(0)
	v_add_f32_e32 v16, v16, v32
	s_nop 1
	v_mov_b32_dpp v32, v16 row_mirror row_mask:0xf bank_mask:0xf
	v_mul_f32_e32 v0, v108, v0
	v_cvt_pk_bf16_f32 v0, v0, s0
	global_store_short v[70:71], v0, off offset:3136 sc1
	v_mul_f32_e32 v0, v17, v116
	s_waitcnt lgkmcnt(0)
	v_add_f32_e32 v16, v16, v32
	v_mov_b32_e32 v17, v16
	s_nop 1
	v_permlane16_swap_b32_e32 v16, v17
	s_nop 0
	v_mul_f32_e32 v0, v107, v0
	v_cvt_pk_bf16_f32 v0, v0, s0
	global_store_short v[70:71], v0, off offset:3200 sc1
	v_mul_f32_e32 v0, v1, v116
	s_waitcnt lgkmcnt(0)
	v_add_f32_e32 v1, v16, v17
	v_fmamk_f32 v1, v1, 0x3c000000, v104
	v_rsq_f32_e32 v16, v1
	v_mul_f32_e32 v1, v35, v35
	v_fmac_f32_e32 v1, v51, v51
	v_fmac_f32_e32 v1, v19, v19
	v_fmac_f32_e32 v1, v3, v3
	s_nop 1
	v_mov_b32_dpp v17, v1 quad_perm:[1,0,3,2] row_mask:0xf bank_mask:0xf
	v_mul_f32_e32 v0, v106, v0
	v_cvt_pk_bf16_f32 v0, v0, s0
	global_store_short v[70:71], v0, off offset:3264 sc1
	v_mul_f32_e32 v0, v50, v16
	s_waitcnt lgkmcnt(0)
	v_add_f32_e32 v17, v1, v17
	s_nop 1
	v_mov_b32_dpp v33, v17 quad_perm:[2,3,0,1] row_mask:0xf bank_mask:0xf
	v_mul_f32_e32 v0, v109, v0
	v_cvt_pk_bf16_f32 v32, v0, s0
	v_add_co_u32_e32 v0, vcc, s54, v70
	s_waitcnt lgkmcnt(0)
	v_add_f32_e32 v17, v17, v33
	s_nop 1
	v_mov_b32_dpp v33, v17 row_half_mirror row_mask:0xf bank_mask:0xf
	v_addc_co_u32_e32 v1, vcc, 0, v71, vcc
	global_store_short v[0:1], v32, off offset:2048 sc1
	v_mul_f32_e32 v32, v34, v16
	s_waitcnt lgkmcnt(0)
	v_add_f32_e32 v17, v17, v33
	s_nop 1
	v_mov_b32_dpp v33, v17 row_mirror row_mask:0xf bank_mask:0xf
	v_mul_f32_e32 v32, v108, v32
	v_cvt_pk_bf16_f32 v32, v32, s0
	global_store_short v[0:1], v32, off offset:2112 sc1
	v_mul_f32_e32 v18, v18, v16
	s_waitcnt lgkmcnt(0)
	v_add_f32_e32 v17, v17, v33
	v_mov_b32_e32 v32, v17
	s_nop 1
	v_permlane16_swap_b32_e32 v17, v32
	s_nop 0
	v_mul_f32_e32 v2, v2, v16
	v_mul_f32_e32 v18, v107, v18
	v_cvt_pk_bf16_f32 v18, v18, s0
	global_store_short v[0:1], v18, off offset:2176 sc1
	s_waitcnt lgkmcnt(0)
	v_add_f32_e32 v16, v17, v32
	v_mul_f32_e32 v17, v36, v36
	v_fmac_f32_e32 v17, v52, v52
	v_fmac_f32_e32 v17, v20, v20
	v_fmac_f32_e32 v17, v4, v4
	s_nop 1
	v_mov_b32_dpp v18, v17 quad_perm:[1,0,3,2] row_mask:0xf bank_mask:0xf
	v_fmamk_f32 v16, v16, 0x3c000000, v104
	v_rsq_f32_e32 v16, v16
	v_mul_f32_e32 v2, v106, v2
	v_cvt_pk_bf16_f32 v2, v2, s0
	s_waitcnt lgkmcnt(0)
	v_add_f32_e32 v17, v17, v18
	s_nop 1
	v_mov_b32_dpp v18, v17 quad_perm:[2,3,0,1] row_mask:0xf bank_mask:0xf
	global_store_short v[0:1], v2, off offset:2240 sc1
	v_mul_f32_e32 v0, v51, v16
	v_mul_f32_e32 v0, v109, v0
	v_cvt_pk_bf16_f32 v2, v0, s0
	s_waitcnt lgkmcnt(0)
	v_add_f32_e32 v17, v17, v18
	s_nop 1
	v_mov_b32_dpp v18, v17 row_half_mirror row_mask:0xf bank_mask:0xf
	v_add_co_u32_e32 v0, vcc, s55, v70
	s_waitcnt lgkmcnt(0)
	v_add_f32_e32 v17, v17, v18
	v_addc_co_u32_e32 v1, vcc, 0, v71, vcc
	s_nop 1
	v_mov_b32_dpp v18, v17 row_mirror row_mask:0xf bank_mask:0xf
	global_store_short v[0:1], v2, off offset:1024 sc1
	v_mul_f32_e32 v2, v35, v16
	v_mul_f32_e32 v2, v108, v2
	v_cvt_pk_bf16_f32 v2, v2, s0
	global_store_short v[0:1], v2, off offset:1088 sc1
	v_mul_f32_e32 v2, v19, v16
	v_mul_f32_e32 v2, v107, v2
	s_waitcnt lgkmcnt(0)
	v_add_f32_e32 v17, v17, v18
	v_cvt_pk_bf16_f32 v2, v2, s0
	v_mov_b32_e32 v18, v17
	s_nop 1
	v_permlane16_swap_b32_e32 v17, v18
	s_nop 0
	global_store_short v[0:1], v2, off offset:1152 sc1
	v_mul_f32_e32 v2, v3, v16
	v_mul_f32_e32 v16, v37, v37
	v_fmac_f32_e32 v16, v53, v53
	v_fmac_f32_e32 v16, v21, v21
	v_fmac_f32_e32 v16, v5, v5
	s_waitcnt lgkmcnt(0)
	v_add_f32_e32 v3, v17, v18
	s_nop 1
	v_mov_b32_dpp v17, v16 quad_perm:[1,0,3,2] row_mask:0xf bank_mask:0xf
	v_fmamk_f32 v3, v3, 0x3c000000, v104
	v_rsq_f32_e32 v3, v3
	v_mul_f32_e32 v2, v106, v2
	v_cvt_pk_bf16_f32 v2, v2, s0
	s_waitcnt lgkmcnt(0)
	v_add_f32_e32 v16, v16, v17
	s_nop 1
	v_mov_b32_dpp v17, v16 quad_perm:[2,3,0,1] row_mask:0xf bank_mask:0xf
	global_store_short v[0:1], v2, off offset:1216 sc1
	v_mul_f32_e32 v0, v52, v3
	v_mul_f32_e32 v0, v109, v0
	v_cvt_pk_bf16_f32 v2, v0, s0
	s_waitcnt lgkmcnt(0)
	v_add_f32_e32 v16, v16, v17
	s_nop 1
	v_mov_b32_dpp v17, v16 row_half_mirror row_mask:0xf bank_mask:0xf
	v_add_co_u32_e32 v0, vcc, s56, v70
	s_waitcnt lgkmcnt(0)
	v_add_f32_e32 v16, v16, v17
	v_addc_co_u32_e32 v1, vcc, 0, v71, vcc
	global_store_short v[0:1], v2, off sc1
	v_mul_f32_e32 v2, v36, v3
	v_mul_f32_e32 v2, v108, v2
	s_nop 1
	v_mov_b32_dpp v17, v16 row_mirror row_mask:0xf bank_mask:0xf
	v_cvt_pk_bf16_f32 v2, v2, s0
	global_store_short v[0:1], v2, off offset:64 sc1
	v_mul_f32_e32 v2, v20, v3
	v_mul_f32_e32 v2, v107, v2
	v_cvt_pk_bf16_f32 v2, v2, s0
	global_store_short v[0:1], v2, off offset:128 sc1
	v_mul_f32_e32 v2, v4, v3
	s_waitcnt lgkmcnt(0)
	v_add_f32_e32 v3, v16, v17
	v_mul_f32_e32 v16, v38, v38
	v_fmac_f32_e32 v16, v54, v54
	v_fmac_f32_e32 v16, v22, v22
	v_fmac_f32_e32 v16, v6, v6
	v_mov_b32_e32 v4, v3
	s_nop 1
	v_permlane16_swap_b32_e32 v3, v4
	s_nop 0
	s_nop 1
	v_mov_b32_dpp v17, v16 quad_perm:[1,0,3,2] row_mask:0xf bank_mask:0xf
	v_mul_f32_e32 v2, v106, v2
	v_cvt_pk_bf16_f32 v2, v2, s0
	global_store_short v[0:1], v2, off offset:192 sc1
	s_waitcnt lgkmcnt(0)
	v_add_f32_e32 v3, v3, v4
	s_waitcnt lgkmcnt(0)
	v_add_f32_e32 v4, v16, v17
	s_nop 1
	v_mov_b32_dpp v16, v4 quad_perm:[2,3,0,1] row_mask:0xf bank_mask:0xf
	v_fmamk_f32 v3, v3, 0x3c000000, v104
	v_rsq_f32_e32 v3, v3
	s_waitcnt lgkmcnt(0)
	v_add_f32_e32 v4, v4, v16
	s_nop 1
	v_mov_b32_dpp v16, v4 row_half_mirror row_mask:0xf bank_mask:0xf
	v_mul_f32_e32 v2, v53, v3
	v_mul_f32_e32 v2, v109, v2
	v_cvt_pk_bf16_f32 v2, v2, s0
	global_store_short v[0:1], v2, off offset:3072 sc1
	s_waitcnt lgkmcnt(0)
	v_add_f32_e32 v4, v4, v16
	s_nop 1
	v_mov_b32_dpp v16, v4 row_mirror row_mask:0xf bank_mask:0xf
	v_mul_f32_e32 v2, v37, v3
	v_mul_f32_e32 v2, v108, v2
	v_cvt_pk_bf16_f32 v2, v2, s0
	global_store_short v[0:1], v2, off offset:3136 sc1
	s_waitcnt lgkmcnt(0)
	v_add_f32_e32 v4, v4, v16
	v_mov_b32_e32 v16, v4
	s_nop 1
	v_permlane16_swap_b32_e32 v4, v16
	s_nop 0
	v_mul_f32_e32 v2, v21, v3
	v_mul_f32_e32 v2, v107, v2
	v_cvt_pk_bf16_f32 v2, v2, s0
	global_store_short v[0:1], v2, off offset:3200 sc1
	v_mul_f32_e32 v2, v5, v3
	s_waitcnt lgkmcnt(0)
	v_add_f32_e32 v3, v4, v16
	v_mul_f32_e32 v4, v39, v39
	v_fmac_f32_e32 v4, v55, v55
	v_fmac_f32_e32 v4, v23, v23
	v_fmac_f32_e32 v4, v7, v7
	s_nop 1
	v_mov_b32_dpp v5, v4 quad_perm:[1,0,3,2] row_mask:0xf bank_mask:0xf
	v_fmamk_f32 v3, v3, 0x3c000000, v104
	v_rsq_f32_e32 v3, v3
	v_mul_f32_e32 v2, v106, v2
	v_cvt_pk_bf16_f32 v2, v2, s0
	s_waitcnt lgkmcnt(0)
	v_add_f32_e32 v4, v4, v5
	s_nop 1
	v_mov_b32_dpp v5, v4 quad_perm:[2,3,0,1] row_mask:0xf bank_mask:0xf
	global_store_short v[0:1], v2, off offset:3264 sc1
	v_mul_f32_e32 v0, v54, v3
	v_mul_f32_e32 v0, v109, v0
	v_cvt_pk_bf16_f32 v2, v0, s0
	s_waitcnt lgkmcnt(0)
	v_add_f32_e32 v4, v4, v5
	s_nop 1
	v_mov_b32_dpp v5, v4 row_half_mirror row_mask:0xf bank_mask:0xf
	v_add_co_u32_e32 v0, vcc, s57, v70
	s_waitcnt lgkmcnt(0)
	v_add_f32_e32 v4, v4, v5
	s_nop 1
	v_mov_b32_dpp v5, v4 row_mirror row_mask:0xf bank_mask:0xf
	v_addc_co_u32_e32 v1, vcc, 0, v71, vcc
	global_store_short v[0:1], v2, off offset:2048 sc1
	v_mul_f32_e32 v2, v38, v3
	s_waitcnt lgkmcnt(0)
	v_add_f32_e32 v4, v4, v5
	v_mul_f32_e32 v2, v108, v2
	v_mov_b32_e32 v5, v4
	s_nop 1
	v_permlane16_swap_b32_e32 v4, v5
	s_nop 0
	v_cvt_pk_bf16_f32 v2, v2, s0
	global_store_short v[0:1], v2, off offset:2112 sc1
	v_mul_f32_e32 v2, v22, v3
	v_mul_f32_e32 v2, v107, v2
	v_cvt_pk_bf16_f32 v2, v2, s0
	global_store_short v[0:1], v2, off offset:2176 sc1
	v_mul_f32_e32 v2, v6, v3
	s_waitcnt lgkmcnt(0)
	v_add_f32_e32 v3, v4, v5
	v_mul_f32_e32 v4, v40, v40
	v_fmac_f32_e32 v4, v56, v56
	v_fmac_f32_e32 v4, v24, v24
	v_fmac_f32_e32 v4, v8, v8
	s_nop 1
	v_mov_b32_dpp v5, v4 quad_perm:[1,0,3,2] row_mask:0xf bank_mask:0xf
	v_fmamk_f32 v3, v3, 0x3c000000, v104
	v_rsq_f32_e32 v3, v3
	v_mul_f32_e32 v2, v106, v2
	v_cvt_pk_bf16_f32 v2, v2, s0
	s_waitcnt lgkmcnt(0)
	v_add_f32_e32 v4, v4, v5
	s_nop 1
	v_mov_b32_dpp v5, v4 quad_perm:[2,3,0,1] row_mask:0xf bank_mask:0xf
	global_store_short v[0:1], v2, off offset:2240 sc1
	v_mul_f32_e32 v0, v55, v3
	v_mul_f32_e32 v0, v109, v0
	v_cvt_pk_bf16_f32 v2, v0, s0
	s_waitcnt lgkmcnt(0)
	v_add_f32_e32 v4, v4, v5
	s_nop 1
	v_mov_b32_dpp v5, v4 row_half_mirror row_mask:0xf bank_mask:0xf
	v_add_co_u32_e32 v0, vcc, s58, v70
	s_waitcnt lgkmcnt(0)
	v_add_f32_e32 v4, v4, v5
	s_nop 1
	v_mov_b32_dpp v5, v4 row_mirror row_mask:0xf bank_mask:0xf
	v_addc_co_u32_e32 v1, vcc, 0, v71, vcc
	global_store_short v[0:1], v2, off offset:1024 sc1
	v_mul_f32_e32 v2, v39, v3
	s_waitcnt lgkmcnt(0)
	v_add_f32_e32 v4, v4, v5
	v_mul_f32_e32 v2, v108, v2
	v_mov_b32_e32 v5, v4
	s_nop 1
	v_permlane16_swap_b32_e32 v4, v5
	s_nop 0
	v_cvt_pk_bf16_f32 v2, v2, s0
	global_store_short v[0:1], v2, off offset:1088 sc1
	v_mul_f32_e32 v2, v23, v3
	v_mul_f32_e32 v2, v107, v2
	v_cvt_pk_bf16_f32 v2, v2, s0
	global_store_short v[0:1], v2, off offset:1152 sc1
	v_mul_f32_e32 v2, v7, v3
	s_waitcnt lgkmcnt(0)
	v_add_f32_e32 v3, v4, v5
	v_mul_f32_e32 v4, v41, v41
	v_fmac_f32_e32 v4, v57, v57
	v_fmac_f32_e32 v4, v25, v25
	v_fmac_f32_e32 v4, v9, v9
	s_nop 1
	v_mov_b32_dpp v5, v4 quad_perm:[1,0,3,2] row_mask:0xf bank_mask:0xf
	v_fmamk_f32 v3, v3, 0x3c000000, v104
	v_rsq_f32_e32 v3, v3
	v_mul_f32_e32 v2, v106, v2
	v_cvt_pk_bf16_f32 v2, v2, s0
	s_waitcnt lgkmcnt(0)
	v_add_f32_e32 v4, v4, v5
	s_nop 1
	v_mov_b32_dpp v5, v4 quad_perm:[2,3,0,1] row_mask:0xf bank_mask:0xf
	global_store_short v[0:1], v2, off offset:1216 sc1
	v_mul_f32_e32 v0, v56, v3
	v_mul_f32_e32 v0, v109, v0
	v_cvt_pk_bf16_f32 v2, v0, s0
	s_waitcnt lgkmcnt(0)
	v_add_f32_e32 v4, v4, v5
	s_nop 1
	v_mov_b32_dpp v5, v4 row_half_mirror row_mask:0xf bank_mask:0xf
	v_add_co_u32_e32 v0, vcc, s59, v70
	s_waitcnt lgkmcnt(0)
	v_add_f32_e32 v4, v4, v5
	v_addc_co_u32_e32 v1, vcc, 0, v71, vcc
	global_store_short v[0:1], v2, off sc1
	v_mul_f32_e32 v2, v40, v3
	v_mul_f32_e32 v2, v108, v2
	s_nop 1
	v_mov_b32_dpp v5, v4 row_mirror row_mask:0xf bank_mask:0xf
	v_cvt_pk_bf16_f32 v2, v2, s0
	global_store_short v[0:1], v2, off offset:64 sc1
	v_mul_f32_e32 v2, v24, v3
	v_mul_f32_e32 v2, v107, v2
	v_cvt_pk_bf16_f32 v2, v2, s0
	global_store_short v[0:1], v2, off offset:128 sc1
	v_mul_f32_e32 v2, v8, v3
	s_waitcnt lgkmcnt(0)
	v_add_f32_e32 v3, v4, v5
	v_mul_f32_e32 v5, v42, v42
	v_fmac_f32_e32 v5, v58, v58
	v_fmac_f32_e32 v5, v26, v26
	v_fmac_f32_e32 v5, v10, v10
	v_mov_b32_e32 v4, v3
	s_nop 1
	v_permlane16_swap_b32_e32 v3, v4
	s_nop 0
	s_nop 1
	v_mov_b32_dpp v6, v5 quad_perm:[1,0,3,2] row_mask:0xf bank_mask:0xf
	v_mul_f32_e32 v2, v106, v2
	v_cvt_pk_bf16_f32 v2, v2, s0
	global_store_short v[0:1], v2, off offset:192 sc1
	s_waitcnt lgkmcnt(0)
	v_add_f32_e32 v3, v3, v4
	s_waitcnt lgkmcnt(0)
	v_add_f32_e32 v4, v5, v6
	s_nop 1
	v_mov_b32_dpp v5, v4 quad_perm:[2,3,0,1] row_mask:0xf bank_mask:0xf
	v_fmamk_f32 v3, v3, 0x3c000000, v104
	v_rsq_f32_e32 v3, v3
	s_waitcnt lgkmcnt(0)
	v_add_f32_e32 v4, v4, v5
	s_nop 1
	v_mov_b32_dpp v5, v4 row_half_mirror row_mask:0xf bank_mask:0xf
	v_mul_f32_e32 v2, v57, v3
	v_mul_f32_e32 v2, v109, v2
	v_cvt_pk_bf16_f32 v2, v2, s0
	global_store_short v[0:1], v2, off offset:3072 sc1
	s_waitcnt lgkmcnt(0)
	v_add_f32_e32 v4, v4, v5
	s_nop 1
	v_mov_b32_dpp v5, v4 row_mirror row_mask:0xf bank_mask:0xf
	v_mul_f32_e32 v2, v41, v3
	v_mul_f32_e32 v2, v108, v2
	v_cvt_pk_bf16_f32 v2, v2, s0
	global_store_short v[0:1], v2, off offset:3136 sc1
	s_waitcnt lgkmcnt(0)
	v_add_f32_e32 v4, v4, v5
	v_mov_b32_e32 v5, v4
	s_nop 1
	v_permlane16_swap_b32_e32 v4, v5
	s_nop 0
	v_mul_f32_e32 v2, v25, v3
	v_mul_f32_e32 v2, v107, v2
	v_cvt_pk_bf16_f32 v2, v2, s0
	global_store_short v[0:1], v2, off offset:3200 sc1
	v_mul_f32_e32 v2, v9, v3
	s_waitcnt lgkmcnt(0)
	v_add_f32_e32 v3, v4, v5
	v_mul_f32_e32 v4, v43, v43
	v_fmac_f32_e32 v4, v59, v59
	v_fmac_f32_e32 v4, v27, v27
	v_fmac_f32_e32 v4, v11, v11
	s_nop 1
	v_mov_b32_dpp v5, v4 quad_perm:[1,0,3,2] row_mask:0xf bank_mask:0xf
	v_fmamk_f32 v3, v3, 0x3c000000, v104
	v_rsq_f32_e32 v3, v3
	v_mul_f32_e32 v2, v106, v2
	v_cvt_pk_bf16_f32 v2, v2, s0
	s_waitcnt lgkmcnt(0)
	v_add_f32_e32 v4, v4, v5
	s_nop 1
	v_mov_b32_dpp v5, v4 quad_perm:[2,3,0,1] row_mask:0xf bank_mask:0xf
	global_store_short v[0:1], v2, off offset:3264 sc1
	v_mul_f32_e32 v0, v58, v3
	v_mul_f32_e32 v0, v109, v0
	v_cvt_pk_bf16_f32 v2, v0, s0
	s_waitcnt lgkmcnt(0)
	v_add_f32_e32 v4, v4, v5
	s_nop 1
	v_mov_b32_dpp v5, v4 row_half_mirror row_mask:0xf bank_mask:0xf
	v_add_co_u32_e32 v0, vcc, s60, v70
	s_waitcnt lgkmcnt(0)
	v_add_f32_e32 v4, v4, v5
	s_nop 1
	v_mov_b32_dpp v5, v4 row_mirror row_mask:0xf bank_mask:0xf
	v_addc_co_u32_e32 v1, vcc, 0, v71, vcc
	global_store_short v[0:1], v2, off offset:2048 sc1
	v_mul_f32_e32 v2, v42, v3
	s_waitcnt lgkmcnt(0)
	v_add_f32_e32 v4, v4, v5
	v_mul_f32_e32 v2, v108, v2
	v_mov_b32_e32 v5, v4
	s_nop 1
	v_permlane16_swap_b32_e32 v4, v5
	s_nop 0
	v_cvt_pk_bf16_f32 v2, v2, s0
	global_store_short v[0:1], v2, off offset:2112 sc1
	v_mul_f32_e32 v2, v26, v3
	v_mul_f32_e32 v2, v107, v2
	v_cvt_pk_bf16_f32 v2, v2, s0
	global_store_short v[0:1], v2, off offset:2176 sc1
	v_mul_f32_e32 v2, v10, v3
	s_waitcnt lgkmcnt(0)
	v_add_f32_e32 v3, v4, v5
	v_mul_f32_e32 v4, v44, v44
	v_fmac_f32_e32 v4, v60, v60
	v_fmac_f32_e32 v4, v28, v28
	v_fmac_f32_e32 v4, v12, v12
	s_nop 1
	v_mov_b32_dpp v5, v4 quad_perm:[1,0,3,2] row_mask:0xf bank_mask:0xf
	v_fmamk_f32 v3, v3, 0x3c000000, v104
	v_rsq_f32_e32 v3, v3
	v_mul_f32_e32 v2, v106, v2
	v_cvt_pk_bf16_f32 v2, v2, s0
	s_waitcnt lgkmcnt(0)
	v_add_f32_e32 v4, v4, v5
	s_nop 1
	v_mov_b32_dpp v5, v4 quad_perm:[2,3,0,1] row_mask:0xf bank_mask:0xf
	global_store_short v[0:1], v2, off offset:2240 sc1
	v_mul_f32_e32 v0, v59, v3
	v_mul_f32_e32 v0, v109, v0
	v_cvt_pk_bf16_f32 v2, v0, s0
	s_waitcnt lgkmcnt(0)
	v_add_f32_e32 v4, v4, v5
	s_nop 1
	v_mov_b32_dpp v5, v4 row_half_mirror row_mask:0xf bank_mask:0xf
	v_add_co_u32_e32 v0, vcc, s61, v70
	s_waitcnt lgkmcnt(0)
	v_add_f32_e32 v4, v4, v5
	v_addc_co_u32_e32 v1, vcc, 0, v71, vcc
	global_store_short v[0:1], v2, off offset:1024 sc1
	v_mul_f32_e32 v2, v43, v3
	v_mul_f32_e32 v2, v108, v2
	s_nop 1
	v_mov_b32_dpp v5, v4 row_mirror row_mask:0xf bank_mask:0xf
	v_cvt_pk_bf16_f32 v2, v2, s0
	global_store_short v[0:1], v2, off offset:1088 sc1
	v_mul_f32_e32 v2, v27, v3
	v_mul_f32_e32 v2, v107, v2
	v_cvt_pk_bf16_f32 v2, v2, s0
	global_store_short v[0:1], v2, off offset:1152 sc1
	v_mul_f32_e32 v2, v11, v3
	s_waitcnt lgkmcnt(0)
	v_add_f32_e32 v3, v4, v5
	v_mul_f32_e32 v5, v45, v45
	v_fmac_f32_e32 v5, v61, v61
	v_fmac_f32_e32 v5, v29, v29
	v_fmac_f32_e32 v5, v13, v13
	v_mov_b32_e32 v4, v3
	s_nop 1
	v_permlane16_swap_b32_e32 v3, v4
	s_nop 0
	s_nop 1
	v_mov_b32_dpp v6, v5 quad_perm:[1,0,3,2] row_mask:0xf bank_mask:0xf
	v_mul_f32_e32 v2, v106, v2
	v_cvt_pk_bf16_f32 v2, v2, s0
	global_store_short v[0:1], v2, off offset:1216 sc1
	s_waitcnt lgkmcnt(0)
	v_add_f32_e32 v3, v3, v4
	s_waitcnt lgkmcnt(0)
	v_add_f32_e32 v4, v5, v6
	s_nop 1
	v_mov_b32_dpp v5, v4 quad_perm:[2,3,0,1] row_mask:0xf bank_mask:0xf
	v_fmamk_f32 v3, v3, 0x3c000000, v104
	v_rsq_f32_e32 v3, v3
	s_waitcnt lgkmcnt(0)
	v_add_f32_e32 v4, v4, v5
	s_nop 1
	v_mov_b32_dpp v5, v4 row_half_mirror row_mask:0xf bank_mask:0xf
	v_mul_f32_e32 v0, v60, v3
	v_mul_f32_e32 v0, v109, v0
	v_cvt_pk_bf16_f32 v2, v0, s0
	v_add_co_u32_e32 v0, vcc, s65, v70
	s_waitcnt lgkmcnt(0)
	v_add_f32_e32 v4, v4, v5
	s_nop 1
	v_mov_b32_dpp v5, v4 row_mirror row_mask:0xf bank_mask:0xf
	v_addc_co_u32_e32 v1, vcc, 0, v71, vcc
	global_store_short v[0:1], v2, off sc1
	v_mul_f32_e32 v2, v44, v3
	s_waitcnt lgkmcnt(0)
	v_add_f32_e32 v4, v4, v5
	v_mul_f32_e32 v2, v108, v2
	v_mov_b32_e32 v5, v4
	s_nop 1
	v_permlane16_swap_b32_e32 v4, v5
	s_nop 0
	v_cvt_pk_bf16_f32 v2, v2, s0
	global_store_short v[0:1], v2, off offset:64 sc1
	v_mul_f32_e32 v2, v28, v3
	v_mul_f32_e32 v2, v107, v2
	v_cvt_pk_bf16_f32 v2, v2, s0
	global_store_short v[0:1], v2, off offset:128 sc1
	v_mul_f32_e32 v2, v12, v3
	s_waitcnt lgkmcnt(0)
	v_add_f32_e32 v3, v4, v5
	v_mul_f32_e32 v4, v46, v46
	v_fmac_f32_e32 v4, v62, v62
	v_fmac_f32_e32 v4, v30, v30
	v_fmac_f32_e32 v4, v14, v14
	s_nop 1
	v_mov_b32_dpp v5, v4 quad_perm:[1,0,3,2] row_mask:0xf bank_mask:0xf
	v_fmamk_f32 v3, v3, 0x3c000000, v104
	v_rsq_f32_e32 v3, v3
	v_mul_f32_e32 v2, v106, v2
	v_cvt_pk_bf16_f32 v2, v2, s0
	s_waitcnt lgkmcnt(0)
	v_add_f32_e32 v4, v4, v5
	s_nop 1
	v_mov_b32_dpp v5, v4 quad_perm:[2,3,0,1] row_mask:0xf bank_mask:0xf
	global_store_short v[0:1], v2, off offset:192 sc1
	v_mul_f32_e32 v2, v61, v3
	v_mul_f32_e32 v2, v109, v2
	v_cvt_pk_bf16_f32 v2, v2, s0
	s_waitcnt lgkmcnt(0)
	v_add_f32_e32 v4, v4, v5
	s_nop 1
	v_mov_b32_dpp v5, v4 row_half_mirror row_mask:0xf bank_mask:0xf
	global_store_short v[0:1], v2, off offset:3072 sc1
	v_mul_f32_e32 v2, v45, v3
	v_mul_f32_e32 v2, v108, v2
	v_cvt_pk_bf16_f32 v2, v2, s0
	s_waitcnt lgkmcnt(0)
	v_add_f32_e32 v4, v4, v5
	s_nop 1
	v_mov_b32_dpp v5, v4 row_mirror row_mask:0xf bank_mask:0xf
	global_store_short v[0:1], v2, off offset:3136 sc1
	v_mul_f32_e32 v2, v29, v3
	v_mul_f32_e32 v2, v107, v2
	v_cvt_pk_bf16_f32 v2, v2, s0
	global_store_short v[0:1], v2, off offset:3200 sc1
	v_mul_f32_e32 v2, v13, v3
	s_waitcnt lgkmcnt(0)
	v_add_f32_e32 v3, v4, v5
	v_mul_f32_e32 v5, v47, v47
	v_fmac_f32_e32 v5, v63, v63
	v_fmac_f32_e32 v5, v31, v31
	v_fmac_f32_e32 v5, v15, v15
	v_mov_b32_e32 v4, v3
	s_nop 1
	v_permlane16_swap_b32_e32 v3, v4
	s_nop 0
	s_nop 1
	v_mov_b32_dpp v6, v5 quad_perm:[1,0,3,2] row_mask:0xf bank_mask:0xf
	v_mul_f32_e32 v2, v106, v2
	v_cvt_pk_bf16_f32 v2, v2, s0
	global_store_short v[0:1], v2, off offset:3264 sc1
	s_waitcnt lgkmcnt(0)
	v_add_f32_e32 v3, v3, v4
	s_waitcnt lgkmcnt(0)
	v_add_f32_e32 v4, v5, v6
	s_nop 1
	v_mov_b32_dpp v5, v4 quad_perm:[2,3,0,1] row_mask:0xf bank_mask:0xf
	v_fmamk_f32 v3, v3, 0x3c000000, v104
	v_rsq_f32_e32 v3, v3
	s_waitcnt lgkmcnt(0)
	v_add_f32_e32 v4, v4, v5
	s_nop 1
	v_mov_b32_dpp v5, v4 row_half_mirror row_mask:0xf bank_mask:0xf
	v_mul_f32_e32 v0, v62, v3
	v_mul_f32_e32 v0, v109, v0
	v_cvt_pk_bf16_f32 v2, v0, s0
	v_add_co_u32_e32 v0, vcc, s66, v70
	s_waitcnt lgkmcnt(0)
	v_add_f32_e32 v4, v4, v5
	s_nop 1
	v_mov_b32_dpp v5, v4 row_mirror row_mask:0xf bank_mask:0xf
	v_addc_co_u32_e32 v1, vcc, 0, v71, vcc
	global_store_short v[0:1], v2, off offset:2048 sc1
	v_mul_f32_e32 v2, v46, v3
	s_waitcnt lgkmcnt(0)
	v_add_f32_e32 v4, v4, v5
	v_mul_f32_e32 v2, v108, v2
	ds_bpermute_b32 v5, v110, v4
	v_cvt_pk_bf16_f32 v2, v2, s0
	global_store_short v[0:1], v2, off offset:2112 sc1
	v_mul_f32_e32 v2, v30, v3
	v_mul_f32_e32 v2, v107, v2
	v_cvt_pk_bf16_f32 v2, v2, s0
	global_store_short v[0:1], v2, off offset:2176 sc1
	v_mul_f32_e32 v2, v14, v3
	s_waitcnt lgkmcnt(0)
	v_add_f32_e32 v3, v4, v5
	v_fmamk_f32 v3, v3, 0x3c000000, v104
	v_rsq_f32_e32 v3, v3
	v_mul_f32_e32 v2, v106, v2
	v_cvt_pk_bf16_f32 v2, v2, s0
	global_store_short v[0:1], v2, off offset:2240 sc1
	v_mul_f32_e32 v0, v63, v3
	v_mul_f32_e32 v0, v109, v0
	v_cvt_pk_bf16_f32 v2, v0, s0
	v_add_co_u32_e32 v0, vcc, s67, v70
	s_nop 1
	v_addc_co_u32_e32 v1, vcc, 0, v71, vcc
	global_store_short v[0:1], v2, off offset:1024 sc1
	v_mul_f32_e32 v2, v47, v3
	v_mul_f32_e32 v2, v108, v2
	v_cvt_pk_bf16_f32 v2, v2, s0
	global_store_short v[0:1], v2, off offset:1088 sc1
	v_mul_f32_e32 v2, v31, v3
	v_mul_f32_e32 v2, v107, v2
	v_cvt_pk_bf16_f32 v2, v2, s0
	global_store_short v[0:1], v2, off offset:1152 sc1
	v_mul_f32_e32 v2, v15, v3
	v_mul_f32_e32 v2, v106, v2
	v_cvt_pk_bf16_f32 v2, v2, s0
	global_store_short v[0:1], v2, off offset:1216 sc1
	s_branch .LBB0_646

.LBB0_846:
	s_and_b64 vcc, exec, s[0:1]
	s_cbranch_vccz .LBB0_827
	v_mov_b32_e32 v10, s84
	ds_read_b64 v[10:11], v10
	s_lshl_b32 s0, s8, 6
	s_ashr_i32 s1, s0, 31
	s_lshl_b64 s[0:1], s[0:1], 2
	v_and_b32_e32 v15, 64, v204
	s_waitcnt lgkmcnt(0)
	v_readfirstlane_b32 s70, v10
	v_readfirstlane_b32 s71, v11
	s_add_u32 s0, s70, s0
	s_addc_u32 s1, s71, s1
	global_load_dword v11, v197, s[0:1]
	global_load_dword v10, v197, s[0:1] offset:128
	v_xor_b32_e32 v14, 1, v204
	v_add_u32_e32 v15, 64, v15
	v_pk_mul_f32 v[12:13], v[86:87], v[86:87]
	v_cmp_lt_i32_e32 vcc, v14, v15
	v_add_f32_e32 v12, v13, v12
	s_cmp_eq_u32 s8, 1
	v_cndmask_b32_e32 v13, v204, v14, vcc
	v_lshlrev_b32_e32 v100, 2, v13
	s_nop 1
	v_mov_b32_dpp v13, v12 quad_perm:[1,0,3,2] row_mask:0xf bank_mask:0xf
	v_xor_b32_e32 v14, 2, v204
	v_cmp_lt_i32_e32 vcc, v14, v15
	s_cselect_b64 s[0:1], -1, 0
	s_xor_b64 s[70:71], s[4:5], -1
	v_cndmask_b32_e32 v14, v204, v14, vcc
	v_lshlrev_b32_e32 v101, 2, v14
	s_waitcnt lgkmcnt(0)
	v_add_f32_e32 v12, v12, v13
	s_nop 1
	v_mov_b32_dpp v13, v12 quad_perm:[2,3,0,1] row_mask:0xf bank_mask:0xf
	v_xor_b32_e32 v14, 4, v204
	v_cmp_lt_i32_e32 vcc, v14, v15
	s_and_b64 s[70:71], s[70:71], s[0:1]
	v_lshl_or_b32 v134, s72, 7, v140
	v_cndmask_b32_e32 v14, v204, v14, vcc
	v_lshlrev_b32_e32 v102, 2, v14
	s_waitcnt lgkmcnt(0)
	v_add_f32_e32 v12, v12, v13
	s_nop 1
	v_mov_b32_dpp v13, v12 row_half_mirror row_mask:0xf bank_mask:0xf
	v_xor_b32_e32 v14, 8, v204
	v_cmp_lt_i32_e32 vcc, v14, v15
	s_waitcnt lgkmcnt(0)
	v_add_f32_e32 v12, v12, v13
	v_cndmask_b32_e32 v14, v204, v14, vcc
	v_lshlrev_b32_e32 v103, 2, v14
	s_nop 1
	v_mov_b32_dpp v13, v12 row_mirror row_mask:0xf bank_mask:0xf
	v_xor_b32_e32 v14, 16, v204
	v_cmp_lt_i32_e32 vcc, v14, v15
	s_waitcnt lgkmcnt(0)
	v_add_f32_e32 v12, v12, v13
	v_cndmask_b32_e32 v14, v204, v14, vcc
	v_lshlrev_b32_e32 v104, 2, v14
	v_mov_b32_e32 v13, v12
	s_nop 1
	v_permlane16_swap_b32_e32 v12, v13
	s_nop 0
	s_and_b64 vcc, exec, s[70:71]
	s_waitcnt lgkmcnt(0)
	v_add_f32_e32 v12, v12, v13
	v_fmamk_f32 v12, v12, 0x3c800000, v196
	v_rsq_f32_e32 v12, v12
	v_add_u32_e32 v144, s69, v160
	v_lshl_or_b32 v144, v144, 5, v140
	v_lshlrev_b32_e32 v144, 3, v144
	global_load_dwordx2 v[144:145], v144, s[24:25]
	v_add_u32_e32 v146, s69, v168
	v_lshl_or_b32 v146, v146, 5, v140
	v_lshlrev_b32_e32 v146, 3, v146
	global_load_dwordx2 v[146:147], v146, s[24:25]
	v_add_u32_e32 v184, s69, v169
	v_lshl_or_b32 v184, v184, 5, v140
	v_lshlrev_b32_e32 v184, 3, v184
	global_load_dwordx2 v[184:185], v184, s[24:25]
	v_add_u32_e32 v186, s69, v170
	v_lshl_or_b32 v186, v186, 5, v140
	v_lshlrev_b32_e32 v186, 3, v186
	global_load_dwordx2 v[186:187], v186, s[24:25]
	v_add_u32_e32 v226, s69, v171
	v_lshl_or_b32 v226, v226, 5, v140
	v_lshlrev_b32_e32 v226, 3, v226
	global_load_dwordx2 v[226:227], v226, s[24:25]
	v_add_u32_e32 v230, s69, v172
	v_lshl_or_b32 v230, v230, 5, v140
	v_lshlrev_b32_e32 v230, 3, v230
	global_load_dwordx2 v[230:231], v230, s[24:25]
	v_add_u32_e32 v232, s69, v173
	v_lshl_or_b32 v232, v232, 5, v140
	v_lshlrev_b32_e32 v232, 3, v232
	global_load_dwordx2 v[232:233], v232, s[24:25]
	v_add_u32_e32 v234, s69, v174
	v_lshl_or_b32 v234, v234, 5, v140
	v_lshlrev_b32_e32 v234, 3, v234
	global_load_dwordx2 v[234:235], v234, s[24:25]
	v_add_u32_e32 v236, s69, v175
	v_lshl_or_b32 v236, v236, 5, v140
	v_lshlrev_b32_e32 v236, 3, v236
	global_load_dwordx2 v[236:237], v236, s[24:25]
	v_add_u32_e32 v238, s69, v176
	v_lshl_or_b32 v238, v238, 5, v140
	v_lshlrev_b32_e32 v238, 3, v238
	global_load_dwordx2 v[238:239], v238, s[24:25]
	v_add_u32_e32 v240, s69, v177
	v_lshl_or_b32 v240, v240, 5, v140
	v_lshlrev_b32_e32 v240, 3, v240
	global_load_dwordx2 v[240:241], v240, s[24:25]
	v_add_u32_e32 v242, s69, v178
	v_lshl_or_b32 v242, v242, 5, v140
	v_lshlrev_b32_e32 v242, 3, v242
	global_load_dwordx2 v[242:243], v242, s[24:25]
	v_add_u32_e32 v244, s69, v179
	v_lshl_or_b32 v244, v244, 5, v140
	v_lshlrev_b32_e32 v244, 3, v244
	global_load_dwordx2 v[244:245], v244, s[24:25]
	v_add_u32_e32 v246, s69, v180
	v_lshl_or_b32 v246, v246, 5, v140
	v_lshlrev_b32_e32 v246, 3, v246
	global_load_dwordx2 v[246:247], v246, s[24:25]
	v_add_u32_e32 v248, s69, v181
	v_lshl_or_b32 v248, v248, 5, v140
	v_lshlrev_b32_e32 v248, 3, v248
	global_load_dwordx2 v[248:249], v248, s[24:25]
	v_add_u32_e32 v250, s69, v182
	v_lshl_or_b32 v250, v250, 5, v140
	v_lshlrev_b32_e32 v250, 3, v250
	global_load_dwordx2 v[250:251], v250, s[24:25]
	s_waitcnt vmcnt(0)
	v_pk_mul_f32 v[12:13], v[10:11], v[12:13] op_sel_hi:[1,0]
	s_nop 0
	v_pk_mul_f32 v[14:15], v[86:87], v[12:13]
	s_cbranch_vccz .LBB0_849
	v_lshl_or_b32 v12, v148, 10, v134
	v_ashrrev_i32_e32 v13, 31, v12
	v_lshl_add_u64 v[12:13], v[12:13], 2, s[26:27]
	global_store_dword v[12:13], v15, off sc1
	global_store_dword v[12:13], v14, off offset:128 sc1

.LBB0_851:
	v_pk_mul_f32 v[24:25], v[82:83], v[82:83]
	v_cvt_pk_bf16_f32 v28, v14, s0
	v_add_f32_e32 v13, v25, v24
	s_nop 1
	v_mov_b32_dpp v24, v13 quad_perm:[1,0,3,2] row_mask:0xf bank_mask:0xf
	s_cmp_lt_u32 s86, 8
	s_cselect_b64 s[4:5], -1, 0
	s_and_b64 s[4:5], s[4:5], exec
	s_cselect_b32 s8, s68, s74
	s_waitcnt lgkmcnt(0)
	v_add_f32_e32 v13, v13, v24
	s_nop 1
	v_mov_b32_dpp v24, v13 quad_perm:[2,3,0,1] row_mask:0xf bank_mask:0xf
	s_cselect_b32 s4, s85, 0xdf9f000
	s_add_u32 s4, s14, s4
	s_addc_u32 s5, s15, 0
	v_cvt_pk_bf16_f32 v25, v15, s0
	s_waitcnt lgkmcnt(0)
	v_add_f32_e32 v13, v13, v24
	s_nop 1
	v_mov_b32_dpp v24, v13 row_half_mirror row_mask:0xf bank_mask:0xf
	v_add_u32_e32 v15, s68, v168
	s_and_b64 vcc, exec, s[70:71]
	s_waitcnt lgkmcnt(0)
	v_add_f32_e32 v13, v13, v24
	s_nop 1
	v_mov_b32_dpp v14, v13 row_mirror row_mask:0xf bank_mask:0xf
	v_add_lshl_u32 v24, s8, v160, 10
	v_or_b32_e32 v26, v24, v134
	v_ashrrev_i32_e32 v27, 31, v26
	v_lshl_add_u64 v[26:27], v[26:27], 1, s[4:5]
	s_waitcnt lgkmcnt(0)
	v_add_f32_e32 v13, v13, v14
	v_mov_b32_e32 v14, v13
	s_nop 1
	v_permlane16_swap_b32_e32 v13, v14
	s_nop 0
	global_store_short v[26:27], v25, off sc1
	global_store_short v[26:27], v28, off offset:64 sc1
	s_waitcnt lgkmcnt(0)
	v_add_f32_e32 v13, v13, v14
	v_fmamk_f32 v13, v13, 0x3c800000, v196
	v_rsq_f32_e32 v14, v13
	s_nop 0
	v_pk_mul_f32 v[26:27], v[10:11], v[14:15] op_sel_hi:[1,0]
	s_nop 0
	v_pk_mul_f32 v[28:29], v[82:83], v[26:27]
	s_cbranch_vccz .LBB0_853
	v_lshl_or_b32 v26, v15, 10, v134
	v_ashrrev_i32_e32 v27, 31, v26
	v_lshl_add_u64 v[26:27], v[26:27], 2, s[26:27]
	global_store_dword v[26:27], v29, off sc1
	global_store_dword v[26:27], v28, off offset:128 sc1

.LBB0_855:
	v_pk_mul_f32 v[30:31], v[78:79], v[78:79]
	v_cvt_pk_bf16_f32 v58, v28, s0
	v_add_f32_e32 v13, v31, v30
	s_nop 1
	v_mov_b32_dpp v14, v13 quad_perm:[1,0,3,2] row_mask:0xf bank_mask:0xf
	v_cvt_pk_bf16_f32 v27, v29, s0
	v_add_u32_e32 v29, s68, v169
	s_and_b64 vcc, exec, s[70:71]
	s_waitcnt lgkmcnt(0)
	v_add_f32_e32 v13, v13, v14
	s_nop 1
	v_mov_b32_dpp v14, v13 quad_perm:[2,3,0,1] row_mask:0xf bank_mask:0xf
	s_waitcnt lgkmcnt(0)
	v_add_f32_e32 v13, v13, v14
	s_nop 1
	v_mov_b32_dpp v14, v13 row_half_mirror row_mask:0xf bank_mask:0xf
	s_waitcnt lgkmcnt(0)
	v_add_f32_e32 v13, v13, v14
	s_nop 1
	v_mov_b32_dpp v25, v13 row_mirror row_mask:0xf bank_mask:0xf
	v_add_lshl_u32 v14, s8, v168, 10
	v_or_b32_e32 v30, v14, v134
	v_ashrrev_i32_e32 v31, 31, v30
	v_lshl_add_u64 v[30:31], v[30:31], 1, s[4:5]
	s_waitcnt lgkmcnt(0)
	v_add_f32_e32 v13, v13, v25
	v_mov_b32_e32 v25, v13
	s_nop 1
	v_permlane16_swap_b32_e32 v13, v25
	s_nop 0
	global_store_short v[30:31], v27, off sc1
	global_store_short v[30:31], v58, off offset:64 sc1
	s_waitcnt lgkmcnt(0)
	v_add_f32_e32 v13, v13, v25
	v_fmamk_f32 v13, v13, 0x3c800000, v196
	v_rsq_f32_e32 v28, v13
	s_nop 0
	v_pk_mul_f32 v[30:31], v[10:11], v[28:29] op_sel_hi:[1,0]
	s_nop 0
	v_pk_mul_f32 v[58:59], v[78:79], v[30:31]
	s_cbranch_vccz .LBB0_857
	v_lshl_or_b32 v30, v29, 10, v134
	v_ashrrev_i32_e32 v31, 31, v30
	v_lshl_add_u64 v[30:31], v[30:31], 2, s[26:27]
	global_store_dword v[30:31], v59, off sc1
	global_store_dword v[30:31], v58, off offset:128 sc1

.LBB0_859:
	v_pk_mul_f32 v[60:61], v[74:75], v[74:75]
	v_add_lshl_u32 v28, s8, v169, 10
	v_add_f32_e32 v13, v61, v60
	s_nop 1
	v_mov_b32_dpp v25, v13 quad_perm:[1,0,3,2] row_mask:0xf bank_mask:0xf
	v_cvt_pk_bf16_f32 v31, v58, s0
	v_or_b32_e32 v60, v28, v134
	v_ashrrev_i32_e32 v61, 31, v60
	v_cvt_pk_bf16_f32 v27, v59, s0
	s_waitcnt lgkmcnt(0)
	v_add_f32_e32 v13, v13, v25
	s_nop 1
	v_mov_b32_dpp v25, v13 quad_perm:[2,3,0,1] row_mask:0xf bank_mask:0xf
	v_add_u32_e32 v59, s68, v170
	v_lshl_add_u64 v[60:61], v[60:61], 1, s[4:5]
	global_store_short v[60:61], v27, off sc1
	global_store_short v[60:61], v31, off offset:64 sc1
	s_and_b64 vcc, exec, s[70:71]
	s_waitcnt lgkmcnt(0)
	v_add_f32_e32 v13, v13, v25
	s_nop 1
	v_mov_b32_dpp v25, v13 row_half_mirror row_mask:0xf bank_mask:0xf
	s_waitcnt lgkmcnt(0)
	v_add_f32_e32 v13, v13, v25
	s_nop 1
	v_mov_b32_dpp v25, v13 row_mirror row_mask:0xf bank_mask:0xf
	s_waitcnt lgkmcnt(0)
	v_add_f32_e32 v13, v13, v25
	v_mov_b32_e32 v25, v13
	s_nop 1
	v_permlane16_swap_b32_e32 v13, v25
	s_nop 0
	s_waitcnt lgkmcnt(0)
	v_add_f32_e32 v13, v13, v25
	v_fmamk_f32 v13, v13, 0x3c800000, v196
	v_rsq_f32_e32 v58, v13
	s_nop 0
	v_pk_mul_f32 v[60:61], v[10:11], v[58:59] op_sel_hi:[1,0]
	s_nop 0
	v_pk_mul_f32 v[62:63], v[74:75], v[60:61]
	s_cbranch_vccz .LBB0_861
	v_lshl_or_b32 v60, v59, 10, v134
	v_ashrrev_i32_e32 v61, 31, v60
	v_lshl_add_u64 v[60:61], v[60:61], 2, s[26:27]
	global_store_dword v[60:61], v63, off sc1
	global_store_dword v[60:61], v62, off offset:128 sc1

.LBB0_863:
	v_pk_mul_f32 v[74:75], v[70:71], v[70:71]
	v_add_lshl_u32 v58, s8, v170, 10
	v_add_f32_e32 v13, v75, v74
	s_nop 1
	v_mov_b32_dpp v25, v13 quad_perm:[1,0,3,2] row_mask:0xf bank_mask:0xf
	v_cvt_pk_bf16_f32 v31, v62, s0
	v_or_b32_e32 v74, v58, v134
	v_ashrrev_i32_e32 v75, 31, v74
	v_cvt_pk_bf16_f32 v27, v63, s0
	s_waitcnt lgkmcnt(0)
	v_add_f32_e32 v13, v13, v25
	s_nop 1
	v_mov_b32_dpp v25, v13 quad_perm:[2,3,0,1] row_mask:0xf bank_mask:0xf
	v_add_u32_e32 v63, s68, v171
	v_lshl_add_u64 v[74:75], v[74:75], 1, s[4:5]
	global_store_short v[74:75], v27, off sc1
	global_store_short v[74:75], v31, off offset:64 sc1
	s_and_b64 vcc, exec, s[70:71]
	s_waitcnt lgkmcnt(0)
	v_add_f32_e32 v13, v13, v25
	s_nop 1
	v_mov_b32_dpp v25, v13 row_half_mirror row_mask:0xf bank_mask:0xf
	s_waitcnt lgkmcnt(0)
	v_add_f32_e32 v13, v13, v25
	s_nop 1
	v_mov_b32_dpp v25, v13 row_mirror row_mask:0xf bank_mask:0xf
	s_waitcnt lgkmcnt(0)
	v_add_f32_e32 v13, v13, v25
	v_mov_b32_e32 v25, v13
	s_nop 1
	v_permlane16_swap_b32_e32 v13, v25
	s_nop 0
	s_waitcnt lgkmcnt(0)
	v_add_f32_e32 v13, v13, v25
	v_fmamk_f32 v13, v13, 0x3c800000, v196
	v_rsq_f32_e32 v62, v13
	s_nop 0
	v_pk_mul_f32 v[74:75], v[10:11], v[62:63] op_sel_hi:[1,0]
	s_nop 0
	v_pk_mul_f32 v[74:75], v[70:71], v[74:75]
	s_cbranch_vccz .LBB0_865
	v_lshl_or_b32 v70, v63, 10, v134
	v_ashrrev_i32_e32 v71, 31, v70
	v_lshl_add_u64 v[70:71], v[70:71], 2, s[26:27]
	global_store_dword v[70:71], v75, off sc1
	global_store_dword v[70:71], v74, off offset:128 sc1

.LBB0_867:
	v_pk_mul_f32 v[78:79], v[72:73], v[72:73]
	v_add_lshl_u32 v62, s8, v171, 10
	v_add_f32_e32 v13, v79, v78
	s_nop 1
	v_mov_b32_dpp v25, v13 quad_perm:[1,0,3,2] row_mask:0xf bank_mask:0xf
	v_cvt_pk_bf16_f32 v31, v74, s0
	v_or_b32_e32 v74, v62, v134
	v_cvt_pk_bf16_f32 v27, v75, s0
	v_ashrrev_i32_e32 v75, 31, v74
	s_waitcnt lgkmcnt(0)
	v_add_f32_e32 v13, v13, v25
	s_nop 1
	v_mov_b32_dpp v25, v13 quad_perm:[2,3,0,1] row_mask:0xf bank_mask:0xf
	v_lshl_add_u64 v[74:75], v[74:75], 1, s[4:5]
	global_store_short v[74:75], v27, off sc1
	global_store_short v[74:75], v31, off offset:64 sc1
	s_and_b64 vcc, exec, s[70:71]
	v_add_u32_e32 v105, s68, v172
	s_waitcnt lgkmcnt(0)
	v_add_f32_e32 v13, v13, v25
	s_nop 1
	v_mov_b32_dpp v25, v13 row_half_mirror row_mask:0xf bank_mask:0xf
	s_waitcnt lgkmcnt(0)
	v_add_f32_e32 v13, v13, v25
	s_nop 1
	v_mov_b32_dpp v25, v13 row_mirror row_mask:0xf bank_mask:0xf
	s_waitcnt lgkmcnt(0)
	v_add_f32_e32 v13, v13, v25
	v_mov_b32_e32 v25, v13
	s_nop 1
	v_permlane16_swap_b32_e32 v13, v25
	s_nop 0
	s_waitcnt lgkmcnt(0)
	v_add_f32_e32 v13, v13, v25
	v_fmamk_f32 v13, v13, 0x3c800000, v196
	v_rsq_f32_e32 v78, v13
	s_nop 0
	v_pk_mul_f32 v[74:75], v[10:11], v[78:79] op_sel_hi:[1,0]
	s_nop 0
	v_pk_mul_f32 v[78:79], v[72:73], v[74:75]
	s_cbranch_vccz .LBB0_869
	v_lshl_or_b32 v72, v105, 10, v134
	v_ashrrev_i32_e32 v73, 31, v72
	v_lshl_add_u64 v[72:73], v[72:73], 2, s[26:27]
	global_store_dword v[72:73], v79, off sc1
	global_store_dword v[72:73], v78, off offset:128 sc1

.LBB0_871:
	v_pk_mul_f32 v[72:73], v[76:77], v[76:77]
	v_cvt_pk_bf16_f32 v31, v78, s0
	v_add_f32_e32 v13, v73, v72
	s_nop 1
	v_mov_b32_dpp v25, v13 quad_perm:[1,0,3,2] row_mask:0xf bank_mask:0xf
	v_add_lshl_u32 v72, s8, v172, 10
	v_or_b32_e32 v78, v72, v134
	v_cvt_pk_bf16_f32 v27, v79, s0
	v_ashrrev_i32_e32 v79, 31, v78
	s_waitcnt lgkmcnt(0)
	v_add_f32_e32 v13, v13, v25
	s_nop 1
	v_mov_b32_dpp v25, v13 quad_perm:[2,3,0,1] row_mask:0xf bank_mask:0xf
	v_lshl_add_u64 v[78:79], v[78:79], 1, s[4:5]
	global_store_short v[78:79], v27, off sc1
	global_store_short v[78:79], v31, off offset:64 sc1
	s_and_b64 vcc, exec, s[70:71]
	v_add_u32_e32 v106, s68, v173
	s_waitcnt lgkmcnt(0)
	v_add_f32_e32 v13, v13, v25
	s_nop 1
	v_mov_b32_dpp v25, v13 row_half_mirror row_mask:0xf bank_mask:0xf
	s_waitcnt lgkmcnt(0)
	v_add_f32_e32 v13, v13, v25
	s_nop 1
	v_mov_b32_dpp v25, v13 row_mirror row_mask:0xf bank_mask:0xf
	s_waitcnt lgkmcnt(0)
	v_add_f32_e32 v13, v13, v25
	v_mov_b32_e32 v25, v13
	s_nop 1
	v_permlane16_swap_b32_e32 v13, v25
	s_nop 0
	s_waitcnt lgkmcnt(0)
	v_add_f32_e32 v13, v13, v25
	v_fmamk_f32 v13, v13, 0x3c800000, v196
	v_rsq_f32_e32 v80, v13
	s_nop 0
	v_pk_mul_f32 v[78:79], v[10:11], v[80:81] op_sel_hi:[1,0]
	s_nop 0
	v_pk_mul_f32 v[80:81], v[76:77], v[78:79]
	s_cbranch_vccz .LBB0_873
	v_lshl_or_b32 v76, v106, 10, v134
	v_ashrrev_i32_e32 v77, 31, v76
	v_lshl_add_u64 v[76:77], v[76:77], 2, s[26:27]
	global_store_dword v[76:77], v81, off sc1
	global_store_dword v[76:77], v80, off offset:128 sc1

.LBB0_875:
	v_pk_mul_f32 v[76:77], v[68:69], v[68:69]
	v_cvt_pk_bf16_f32 v31, v80, s0
	v_add_f32_e32 v13, v77, v76
	s_nop 1
	v_mov_b32_dpp v25, v13 quad_perm:[1,0,3,2] row_mask:0xf bank_mask:0xf
	v_add_lshl_u32 v76, s8, v173, 10
	v_or_b32_e32 v80, v76, v134
	v_cvt_pk_bf16_f32 v27, v81, s0
	v_ashrrev_i32_e32 v81, 31, v80
	s_waitcnt lgkmcnt(0)
	v_add_f32_e32 v13, v13, v25
	s_nop 1
	v_mov_b32_dpp v25, v13 quad_perm:[2,3,0,1] row_mask:0xf bank_mask:0xf
	v_lshl_add_u64 v[80:81], v[80:81], 1, s[4:5]
	global_store_short v[80:81], v27, off sc1
	global_store_short v[80:81], v31, off offset:64 sc1
	s_and_b64 vcc, exec, s[70:71]
	v_add_u32_e32 v107, s68, v174
	s_waitcnt lgkmcnt(0)
	v_add_f32_e32 v13, v13, v25
	s_nop 1
	v_mov_b32_dpp v25, v13 row_half_mirror row_mask:0xf bank_mask:0xf
	s_waitcnt lgkmcnt(0)
	v_add_f32_e32 v13, v13, v25
	s_nop 1
	v_mov_b32_dpp v25, v13 row_mirror row_mask:0xf bank_mask:0xf
	s_waitcnt lgkmcnt(0)
	v_add_f32_e32 v13, v13, v25
	v_mov_b32_e32 v25, v13
	s_nop 1
	v_permlane16_swap_b32_e32 v13, v25
	s_nop 0
	s_waitcnt lgkmcnt(0)
	v_add_f32_e32 v13, v13, v25
	v_fmamk_f32 v13, v13, 0x3c800000, v196
	v_rsq_f32_e32 v82, v13
	s_nop 0
	v_pk_mul_f32 v[80:81], v[10:11], v[82:83] op_sel_hi:[1,0]
	s_nop 0
	v_pk_mul_f32 v[82:83], v[68:69], v[80:81]
	s_cbranch_vccz .LBB0_877
	v_lshl_or_b32 v68, v107, 10, v134
	v_ashrrev_i32_e32 v69, 31, v68
	v_lshl_add_u64 v[68:69], v[68:69], 2, s[26:27]
	global_store_dword v[68:69], v83, off sc1
	global_store_dword v[68:69], v82, off offset:128 sc1

.LBB0_879:
	v_pk_mul_f32 v[68:69], v[66:67], v[66:67]
	v_cvt_pk_bf16_f32 v31, v82, s0
	v_add_f32_e32 v13, v69, v68
	s_nop 1
	v_mov_b32_dpp v25, v13 quad_perm:[1,0,3,2] row_mask:0xf bank_mask:0xf
	v_add_lshl_u32 v68, s8, v174, 10
	v_or_b32_e32 v82, v68, v134
	v_cvt_pk_bf16_f32 v27, v83, s0
	v_ashrrev_i32_e32 v83, 31, v82
	s_waitcnt lgkmcnt(0)
	v_add_f32_e32 v13, v13, v25
	s_nop 1
	v_mov_b32_dpp v25, v13 quad_perm:[2,3,0,1] row_mask:0xf bank_mask:0xf
	v_lshl_add_u64 v[82:83], v[82:83], 1, s[4:5]
	global_store_short v[82:83], v27, off sc1
	global_store_short v[82:83], v31, off offset:64 sc1
	s_and_b64 vcc, exec, s[70:71]
	v_add_u32_e32 v108, s68, v175
	s_waitcnt lgkmcnt(0)
	v_add_f32_e32 v13, v13, v25
	s_nop 1
	v_mov_b32_dpp v25, v13 row_half_mirror row_mask:0xf bank_mask:0xf
	s_waitcnt lgkmcnt(0)
	v_add_f32_e32 v13, v13, v25
	s_nop 1
	v_mov_b32_dpp v25, v13 row_mirror row_mask:0xf bank_mask:0xf
	s_waitcnt lgkmcnt(0)
	v_add_f32_e32 v13, v13, v25
	v_mov_b32_e32 v25, v13
	s_nop 1
	v_permlane16_swap_b32_e32 v13, v25
	s_nop 0
	s_waitcnt lgkmcnt(0)
	v_add_f32_e32 v13, v13, v25
	v_fmamk_f32 v13, v13, 0x3c800000, v196
	v_rsq_f32_e32 v84, v13
	s_nop 0
	v_pk_mul_f32 v[82:83], v[10:11], v[84:85] op_sel_hi:[1,0]
	s_nop 0
	v_pk_mul_f32 v[84:85], v[66:67], v[82:83]
	s_cbranch_vccz .LBB0_881
	v_lshl_or_b32 v66, v108, 10, v134
	v_ashrrev_i32_e32 v67, 31, v66
	v_lshl_add_u64 v[66:67], v[66:67], 2, s[26:27]
	global_store_dword v[66:67], v85, off sc1
	global_store_dword v[66:67], v84, off offset:128 sc1

.LBB0_883:
	v_pk_mul_f32 v[66:67], v[64:65], v[64:65]
	v_cvt_pk_bf16_f32 v31, v84, s0
	v_add_f32_e32 v13, v67, v66
	s_nop 1
	v_mov_b32_dpp v25, v13 quad_perm:[1,0,3,2] row_mask:0xf bank_mask:0xf
	v_add_lshl_u32 v66, s8, v175, 10
	v_or_b32_e32 v84, v66, v134
	v_cvt_pk_bf16_f32 v27, v85, s0
	v_ashrrev_i32_e32 v85, 31, v84
	s_waitcnt lgkmcnt(0)
	v_add_f32_e32 v13, v13, v25
	s_nop 1
	v_mov_b32_dpp v25, v13 quad_perm:[2,3,0,1] row_mask:0xf bank_mask:0xf
	v_lshl_add_u64 v[84:85], v[84:85], 1, s[4:5]
	global_store_short v[84:85], v27, off sc1
	global_store_short v[84:85], v31, off offset:64 sc1
	s_and_b64 vcc, exec, s[70:71]
	v_add_u32_e32 v109, s68, v176
	s_waitcnt lgkmcnt(0)
	v_add_f32_e32 v13, v13, v25
	s_nop 1
	v_mov_b32_dpp v25, v13 row_half_mirror row_mask:0xf bank_mask:0xf
	s_waitcnt lgkmcnt(0)
	v_add_f32_e32 v13, v13, v25
	s_nop 1
	v_mov_b32_dpp v25, v13 row_mirror row_mask:0xf bank_mask:0xf
	s_waitcnt lgkmcnt(0)
	v_add_f32_e32 v13, v13, v25
	v_mov_b32_e32 v25, v13
	s_nop 1
	v_permlane16_swap_b32_e32 v13, v25
	s_nop 0
	s_waitcnt lgkmcnt(0)
	v_add_f32_e32 v13, v13, v25
	v_fmamk_f32 v13, v13, 0x3c800000, v196
	v_rsq_f32_e32 v86, v13
	s_nop 0
	v_pk_mul_f32 v[84:85], v[10:11], v[86:87] op_sel_hi:[1,0]
	s_nop 0
	v_pk_mul_f32 v[86:87], v[64:65], v[84:85]
	s_cbranch_vccz .LBB0_885
	v_lshl_or_b32 v64, v109, 10, v134
	v_ashrrev_i32_e32 v65, 31, v64
	v_lshl_add_u64 v[64:65], v[64:65], 2, s[26:27]
	global_store_dword v[64:65], v87, off sc1
	global_store_dword v[64:65], v86, off offset:128 sc1

.LBB0_887:
	v_pk_mul_f32 v[64:65], v[56:57], v[56:57]
	v_cvt_pk_bf16_f32 v31, v86, s0
	v_add_f32_e32 v13, v65, v64
	s_nop 1
	v_mov_b32_dpp v25, v13 quad_perm:[1,0,3,2] row_mask:0xf bank_mask:0xf
	v_add_lshl_u32 v64, s8, v176, 10
	v_or_b32_e32 v86, v64, v134
	v_cvt_pk_bf16_f32 v27, v87, s0
	v_ashrrev_i32_e32 v87, 31, v86
	s_waitcnt lgkmcnt(0)
	v_add_f32_e32 v13, v13, v25
	s_nop 1
	v_mov_b32_dpp v25, v13 quad_perm:[2,3,0,1] row_mask:0xf bank_mask:0xf
	v_lshl_add_u64 v[86:87], v[86:87], 1, s[4:5]
	global_store_short v[86:87], v27, off sc1
	global_store_short v[86:87], v31, off offset:64 sc1
	s_and_b64 vcc, exec, s[70:71]
	v_add_u32_e32 v110, s68, v177
	s_waitcnt lgkmcnt(0)
	v_add_f32_e32 v13, v13, v25
	s_nop 1
	v_mov_b32_dpp v25, v13 row_half_mirror row_mask:0xf bank_mask:0xf
	s_waitcnt lgkmcnt(0)
	v_add_f32_e32 v13, v13, v25
	s_nop 1
	v_mov_b32_dpp v25, v13 row_mirror row_mask:0xf bank_mask:0xf
	s_waitcnt lgkmcnt(0)
	v_add_f32_e32 v13, v13, v25
	v_mov_b32_e32 v25, v13
	s_nop 1
	v_permlane16_swap_b32_e32 v13, v25
	s_nop 0
	s_waitcnt lgkmcnt(0)
	v_add_f32_e32 v13, v13, v25
	v_fmamk_f32 v13, v13, 0x3c800000, v196
	v_rsq_f32_e32 v88, v13
	s_nop 0
	v_pk_mul_f32 v[86:87], v[10:11], v[88:89] op_sel_hi:[1,0]
	s_nop 0
	v_pk_mul_f32 v[88:89], v[56:57], v[86:87]
	s_cbranch_vccz .LBB0_889
	v_lshl_or_b32 v56, v110, 10, v134
	v_ashrrev_i32_e32 v57, 31, v56
	v_lshl_add_u64 v[56:57], v[56:57], 2, s[26:27]
	global_store_dword v[56:57], v89, off sc1
	global_store_dword v[56:57], v88, off offset:128 sc1

.LBB0_891:
	v_pk_mul_f32 v[56:57], v[54:55], v[54:55]
	v_cvt_pk_bf16_f32 v31, v88, s0
	v_add_f32_e32 v13, v57, v56
	s_nop 1
	v_mov_b32_dpp v25, v13 quad_perm:[1,0,3,2] row_mask:0xf bank_mask:0xf
	v_add_lshl_u32 v56, s8, v177, 10
	v_or_b32_e32 v88, v56, v134
	v_cvt_pk_bf16_f32 v27, v89, s0
	v_ashrrev_i32_e32 v89, 31, v88
	s_waitcnt lgkmcnt(0)
	v_add_f32_e32 v13, v13, v25
	s_nop 1
	v_mov_b32_dpp v25, v13 quad_perm:[2,3,0,1] row_mask:0xf bank_mask:0xf
	v_lshl_add_u64 v[88:89], v[88:89], 1, s[4:5]
	global_store_short v[88:89], v27, off sc1
	global_store_short v[88:89], v31, off offset:64 sc1
	s_and_b64 vcc, exec, s[70:71]
	v_add_u32_e32 v111, s68, v178
	s_waitcnt lgkmcnt(0)
	v_add_f32_e32 v13, v13, v25
	s_nop 1
	v_mov_b32_dpp v25, v13 row_half_mirror row_mask:0xf bank_mask:0xf
	s_waitcnt lgkmcnt(0)
	v_add_f32_e32 v13, v13, v25
	s_nop 1
	v_mov_b32_dpp v25, v13 row_mirror row_mask:0xf bank_mask:0xf
	s_waitcnt lgkmcnt(0)
	v_add_f32_e32 v13, v13, v25
	v_mov_b32_e32 v25, v13
	s_nop 1
	v_permlane16_swap_b32_e32 v13, v25
	s_nop 0
	s_waitcnt lgkmcnt(0)
	v_add_f32_e32 v13, v13, v25
	v_fmamk_f32 v13, v13, 0x3c800000, v196
	v_rsq_f32_e32 v90, v13
	s_nop 0
	v_pk_mul_f32 v[88:89], v[10:11], v[90:91] op_sel_hi:[1,0]
	s_nop 0
	v_pk_mul_f32 v[90:91], v[54:55], v[88:89]
	s_cbranch_vccz .LBB0_893
	v_lshl_or_b32 v54, v111, 10, v134
	v_ashrrev_i32_e32 v55, 31, v54
	v_lshl_add_u64 v[54:55], v[54:55], 2, s[26:27]
	global_store_dword v[54:55], v91, off sc1
	global_store_dword v[54:55], v90, off offset:128 sc1

.LBB0_895:
	v_pk_mul_f32 v[54:55], v[52:53], v[52:53]
	v_cvt_pk_bf16_f32 v31, v90, s0
	v_add_f32_e32 v13, v55, v54
	s_nop 1
	v_mov_b32_dpp v25, v13 quad_perm:[1,0,3,2] row_mask:0xf bank_mask:0xf
	v_add_lshl_u32 v54, s8, v178, 10
	v_or_b32_e32 v90, v54, v134
	v_cvt_pk_bf16_f32 v27, v91, s0
	v_ashrrev_i32_e32 v91, 31, v90
	s_waitcnt lgkmcnt(0)
	v_add_f32_e32 v13, v13, v25
	s_nop 1
	v_mov_b32_dpp v25, v13 quad_perm:[2,3,0,1] row_mask:0xf bank_mask:0xf
	v_lshl_add_u64 v[90:91], v[90:91], 1, s[4:5]
	global_store_short v[90:91], v27, off sc1
	global_store_short v[90:91], v31, off offset:64 sc1
	s_and_b64 vcc, exec, s[70:71]
	v_add_u32_e32 v112, s68, v179
	s_waitcnt lgkmcnt(0)
	v_add_f32_e32 v13, v13, v25
	s_nop 1
	v_mov_b32_dpp v25, v13 row_half_mirror row_mask:0xf bank_mask:0xf
	s_waitcnt lgkmcnt(0)
	v_add_f32_e32 v13, v13, v25
	s_nop 1
	v_mov_b32_dpp v25, v13 row_mirror row_mask:0xf bank_mask:0xf
	s_waitcnt lgkmcnt(0)
	v_add_f32_e32 v13, v13, v25
	v_mov_b32_e32 v25, v13
	s_nop 1
	v_permlane16_swap_b32_e32 v13, v25
	s_nop 0
	s_waitcnt lgkmcnt(0)
	v_add_f32_e32 v13, v13, v25
	v_fmamk_f32 v13, v13, 0x3c800000, v196
	v_rsq_f32_e32 v92, v13
	s_nop 0
	v_pk_mul_f32 v[90:91], v[10:11], v[92:93] op_sel_hi:[1,0]
	s_nop 0
	v_pk_mul_f32 v[92:93], v[52:53], v[90:91]
	s_cbranch_vccz .LBB0_897
	v_lshl_or_b32 v52, v112, 10, v134
	v_ashrrev_i32_e32 v53, 31, v52
	v_lshl_add_u64 v[52:53], v[52:53], 2, s[26:27]
	global_store_dword v[52:53], v93, off sc1
	global_store_dword v[52:53], v92, off offset:128 sc1

.LBB0_899:
	v_pk_mul_f32 v[52:53], v[50:51], v[50:51]
	v_cvt_pk_bf16_f32 v31, v92, s0
	v_add_f32_e32 v13, v53, v52
	s_nop 1
	v_mov_b32_dpp v25, v13 quad_perm:[1,0,3,2] row_mask:0xf bank_mask:0xf
	v_add_lshl_u32 v52, s8, v179, 10
	v_or_b32_e32 v92, v52, v134
	v_cvt_pk_bf16_f32 v27, v93, s0
	v_ashrrev_i32_e32 v93, 31, v92
	s_waitcnt lgkmcnt(0)
	v_add_f32_e32 v13, v13, v25
	s_nop 1
	v_mov_b32_dpp v25, v13 quad_perm:[2,3,0,1] row_mask:0xf bank_mask:0xf
	v_lshl_add_u64 v[92:93], v[92:93], 1, s[4:5]
	global_store_short v[92:93], v27, off sc1
	global_store_short v[92:93], v31, off offset:64 sc1
	s_and_b64 vcc, exec, s[70:71]
	v_add_u32_e32 v113, s68, v180
	s_waitcnt lgkmcnt(0)
	v_add_f32_e32 v13, v13, v25
	s_nop 1
	v_mov_b32_dpp v25, v13 row_half_mirror row_mask:0xf bank_mask:0xf
	s_waitcnt lgkmcnt(0)
	v_add_f32_e32 v13, v13, v25
	s_nop 1
	v_mov_b32_dpp v25, v13 row_mirror row_mask:0xf bank_mask:0xf
	s_waitcnt lgkmcnt(0)
	v_add_f32_e32 v13, v13, v25
	v_mov_b32_e32 v25, v13
	s_nop 1
	v_permlane16_swap_b32_e32 v13, v25
	s_nop 0
	s_waitcnt lgkmcnt(0)
	v_add_f32_e32 v13, v13, v25
	v_fmamk_f32 v13, v13, 0x3c800000, v196
	v_rsq_f32_e32 v94, v13
	s_nop 0
	v_pk_mul_f32 v[92:93], v[10:11], v[94:95] op_sel_hi:[1,0]
	s_nop 0
	v_pk_mul_f32 v[94:95], v[50:51], v[92:93]
	s_cbranch_vccz .LBB0_901
	v_lshl_or_b32 v50, v113, 10, v134
	v_ashrrev_i32_e32 v51, 31, v50
	v_lshl_add_u64 v[50:51], v[50:51], 2, s[26:27]
	global_store_dword v[50:51], v95, off sc1
	global_store_dword v[50:51], v94, off offset:128 sc1

.LBB0_903:
	v_pk_mul_f32 v[50:51], v[48:49], v[48:49]
	v_cvt_pk_bf16_f32 v31, v94, s0
	v_add_f32_e32 v13, v51, v50
	s_nop 1
	v_mov_b32_dpp v25, v13 quad_perm:[1,0,3,2] row_mask:0xf bank_mask:0xf
	v_add_lshl_u32 v50, s8, v180, 10
	v_or_b32_e32 v94, v50, v134
	v_cvt_pk_bf16_f32 v27, v95, s0
	v_ashrrev_i32_e32 v95, 31, v94
	s_waitcnt lgkmcnt(0)
	v_add_f32_e32 v13, v13, v25
	s_nop 1
	v_mov_b32_dpp v25, v13 quad_perm:[2,3,0,1] row_mask:0xf bank_mask:0xf
	v_lshl_add_u64 v[94:95], v[94:95], 1, s[4:5]
	global_store_short v[94:95], v27, off sc1
	global_store_short v[94:95], v31, off offset:64 sc1
	s_and_b64 vcc, exec, s[70:71]
	v_add_u32_e32 v114, s68, v181
	s_waitcnt lgkmcnt(0)
	v_add_f32_e32 v13, v13, v25
	s_nop 1
	v_mov_b32_dpp v25, v13 row_half_mirror row_mask:0xf bank_mask:0xf
	s_waitcnt lgkmcnt(0)
	v_add_f32_e32 v13, v13, v25
	s_nop 1
	v_mov_b32_dpp v25, v13 row_mirror row_mask:0xf bank_mask:0xf
	s_waitcnt lgkmcnt(0)
	v_add_f32_e32 v13, v13, v25
	v_mov_b32_e32 v25, v13
	s_nop 1
	v_permlane16_swap_b32_e32 v13, v25
	s_nop 0
	s_waitcnt lgkmcnt(0)
	v_add_f32_e32 v13, v13, v25
	v_fmamk_f32 v13, v13, 0x3c800000, v196
	v_rsq_f32_e32 v96, v13
	s_nop 0
	v_pk_mul_f32 v[94:95], v[10:11], v[96:97] op_sel_hi:[1,0]
	s_nop 0
	v_pk_mul_f32 v[96:97], v[48:49], v[94:95]
	s_cbranch_vccz .LBB0_905
	v_lshl_or_b32 v48, v114, 10, v134
	v_ashrrev_i32_e32 v49, 31, v48
	v_lshl_add_u64 v[48:49], v[48:49], 2, s[26:27]
	global_store_dword v[48:49], v97, off sc1
	global_store_dword v[48:49], v96, off offset:128 sc1

.LBB0_907:
	v_pk_mul_f32 v[48:49], v[46:47], v[46:47]
	v_cvt_pk_bf16_f32 v31, v96, s0
	v_add_f32_e32 v13, v49, v48
	s_nop 1
	v_mov_b32_dpp v25, v13 quad_perm:[1,0,3,2] row_mask:0xf bank_mask:0xf
	v_add_lshl_u32 v48, s8, v181, 10
	v_or_b32_e32 v98, v48, v134
	v_ashrrev_i32_e32 v99, 31, v98
	v_cvt_pk_bf16_f32 v27, v97, s0
	s_waitcnt lgkmcnt(0)
	v_add_f32_e32 v13, v13, v25
	s_nop 1
	v_mov_b32_dpp v25, v13 quad_perm:[2,3,0,1] row_mask:0xf bank_mask:0xf
	v_add_u32_e32 v97, s68, v182
	v_lshl_add_u64 v[98:99], v[98:99], 1, s[4:5]
	global_store_short v[98:99], v27, off sc1
	global_store_short v[98:99], v31, off offset:64 sc1
	s_and_b64 vcc, exec, s[70:71]
	s_waitcnt lgkmcnt(0)
	v_add_f32_e32 v13, v13, v25
	s_nop 1
	v_mov_b32_dpp v25, v13 row_half_mirror row_mask:0xf bank_mask:0xf
	s_waitcnt lgkmcnt(0)
	v_add_f32_e32 v13, v13, v25
	s_nop 1
	v_mov_b32_dpp v25, v13 row_mirror row_mask:0xf bank_mask:0xf
	s_waitcnt lgkmcnt(0)
	v_add_f32_e32 v13, v13, v25
	v_mov_b32_e32 v25, v13
	s_nop 1
	v_permlane16_swap_b32_e32 v13, v25
	s_nop 0
	s_waitcnt lgkmcnt(0)
	v_add_f32_e32 v13, v13, v25
	v_fmamk_f32 v13, v13, 0x3c800000, v196
	v_rsq_f32_e32 v96, v13
	s_nop 0
	v_pk_mul_f32 v[98:99], v[10:11], v[96:97] op_sel_hi:[1,0]
	s_nop 0
	v_pk_mul_f32 v[98:99], v[46:47], v[98:99]
	s_cbranch_vccz .LBB0_909
	v_lshl_or_b32 v46, v97, 10, v134
	v_ashrrev_i32_e32 v47, 31, v46
	v_lshl_add_u64 v[46:47], v[46:47], 2, s[26:27]
	global_store_dword v[46:47], v99, off sc1
	global_store_dword v[46:47], v98, off offset:128 sc1

.LBB0_911:
	v_pk_mul_f32 v[116:117], v[44:45], v[44:45]
	v_add_lshl_u32 v96, s8, v182, 10
	v_add_f32_e32 v13, v117, v116
	s_nop 1
	v_mov_b32_dpp v25, v13 quad_perm:[1,0,3,2] row_mask:0xf bank_mask:0xf
	v_cvt_pk_bf16_f32 v31, v98, s0
	v_or_b32_e32 v98, v96, v134
	v_cvt_pk_bf16_f32 v27, v99, s0
	v_ashrrev_i32_e32 v99, 31, v98
	s_waitcnt lgkmcnt(0)
	v_add_f32_e32 v13, v13, v25
	s_nop 1
	v_mov_b32_dpp v25, v13 quad_perm:[2,3,0,1] row_mask:0xf bank_mask:0xf
	v_lshl_add_u64 v[98:99], v[98:99], 1, s[4:5]
	global_store_short v[98:99], v27, off sc1
	global_store_short v[98:99], v31, off offset:64 sc1
	v_or_b32_e32 v47, 64, v134
	s_and_b64 vcc, exec, s[70:71]
	s_waitcnt lgkmcnt(0)
	v_add_f32_e32 v13, v13, v25
	s_nop 1
	v_mov_b32_dpp v25, v13 row_half_mirror row_mask:0xf bank_mask:0xf
	s_waitcnt lgkmcnt(0)
	v_add_f32_e32 v13, v13, v25
	s_nop 1
	v_mov_b32_dpp v25, v13 row_mirror row_mask:0xf bank_mask:0xf
	s_waitcnt lgkmcnt(0)
	v_add_f32_e32 v13, v13, v25
	v_mov_b32_e32 v25, v13
	s_nop 1
	v_permlane16_swap_b32_e32 v13, v25
	s_nop 0
	s_waitcnt lgkmcnt(0)
	v_add_f32_e32 v13, v13, v25
	v_fmamk_f32 v13, v13, 0x3c800000, v196
	v_rsq_f32_e32 v116, v13
	s_nop 0
	v_pk_mul_f32 v[98:99], v[10:11], v[116:117] op_sel_hi:[1,0]
	s_nop 0
	v_pk_mul_f32 v[44:45], v[44:45], v[98:99]
	s_cbranch_vccz .LBB0_913
	v_lshl_or_b32 v98, v148, 10, v47
	v_ashrrev_i32_e32 v99, 31, v98
	v_lshl_add_u64 v[98:99], v[98:99], 2, s[26:27]
	global_store_dword v[98:99], v45, off sc1
	global_store_dword v[98:99], v44, off offset:128 sc1

.LBB0_923:
	v_pk_mul_f32 v[14:15], v[38:39], v[38:39]
	v_ashrrev_i32_e32 v29, 31, v28
	v_add_f32_e32 v14, v15, v14
	s_nop 1
	v_mov_b32_dpp v15, v14 quad_perm:[1,0,3,2] row_mask:0xf bank_mask:0xf
	v_cvt_pk_bf16_f32 v24, v13, s0
	v_cvt_pk_bf16_f32 v25, v12, s0
	v_lshl_add_u64 v[12:13], v[28:29], 0, v[134:135]
	v_lshl_add_u64 v[12:13], v[12:13], 1, s[4:5]
	s_waitcnt lgkmcnt(0)
	v_add_f32_e32 v14, v14, v15
	s_nop 1
	v_mov_b32_dpp v15, v14 quad_perm:[2,3,0,1] row_mask:0xf bank_mask:0xf
	global_store_short v[12:13], v24, off offset:128 sc1
	global_store_short v[12:13], v25, off offset:192 sc1
	s_and_b64 vcc, exec, s[70:71]
	s_waitcnt lgkmcnt(0)
	v_add_f32_e32 v14, v14, v15
	s_nop 1
	v_mov_b32_dpp v15, v14 row_half_mirror row_mask:0xf bank_mask:0xf
	s_waitcnt lgkmcnt(0)
	v_add_f32_e32 v14, v14, v15
	s_nop 1
	v_mov_b32_dpp v15, v14 row_mirror row_mask:0xf bank_mask:0xf
	s_waitcnt lgkmcnt(0)
	v_add_f32_e32 v14, v14, v15
	v_mov_b32_e32 v15, v14
	s_nop 1
	v_permlane16_swap_b32_e32 v14, v15
	s_nop 0
	s_waitcnt lgkmcnt(0)
	v_add_f32_e32 v14, v14, v15
	v_fmamk_f32 v14, v14, 0x3c800000, v196
	v_rsq_f32_e32 v14, v14
	s_nop 0
	v_pk_mul_f32 v[12:13], v[10:11], v[14:15] op_sel_hi:[1,0]
	s_nop 0
	v_pk_mul_f32 v[12:13], v[38:39], v[12:13]
	s_cbranch_vccz .LBB0_925
	v_lshl_or_b32 v14, v59, 10, v47
	v_ashrrev_i32_e32 v15, 31, v14
	v_lshl_add_u64 v[14:15], v[14:15], 2, s[26:27]
	global_store_dword v[14:15], v13, off sc1
	global_store_dword v[14:15], v12, off offset:128 sc1

.LBB0_927:
	v_pk_mul_f32 v[14:15], v[36:37], v[36:37]
	v_ashrrev_i32_e32 v59, 31, v58
	v_add_f32_e32 v14, v15, v14
	s_nop 1
	v_mov_b32_dpp v15, v14 quad_perm:[1,0,3,2] row_mask:0xf bank_mask:0xf
	v_cvt_pk_bf16_f32 v24, v13, s0
	v_cvt_pk_bf16_f32 v25, v12, s0
	v_lshl_add_u64 v[12:13], v[58:59], 0, v[134:135]
	v_lshl_add_u64 v[12:13], v[12:13], 1, s[4:5]
	s_waitcnt lgkmcnt(0)
	v_add_f32_e32 v14, v14, v15
	s_nop 1
	v_mov_b32_dpp v15, v14 quad_perm:[2,3,0,1] row_mask:0xf bank_mask:0xf
	global_store_short v[12:13], v24, off offset:128 sc1
	global_store_short v[12:13], v25, off offset:192 sc1
	s_and_b64 vcc, exec, s[70:71]
	s_waitcnt lgkmcnt(0)
	v_add_f32_e32 v14, v14, v15
	s_nop 1
	v_mov_b32_dpp v15, v14 row_half_mirror row_mask:0xf bank_mask:0xf
	s_waitcnt lgkmcnt(0)
	v_add_f32_e32 v14, v14, v15
	s_nop 1
	v_mov_b32_dpp v15, v14 row_mirror row_mask:0xf bank_mask:0xf
	s_waitcnt lgkmcnt(0)
	v_add_f32_e32 v14, v14, v15
	v_mov_b32_e32 v15, v14
	s_nop 1
	v_permlane16_swap_b32_e32 v14, v15
	s_nop 0
	s_waitcnt lgkmcnt(0)
	v_add_f32_e32 v14, v14, v15
	v_fmamk_f32 v14, v14, 0x3c800000, v196
	v_rsq_f32_e32 v14, v14
	s_nop 0
	v_pk_mul_f32 v[12:13], v[10:11], v[14:15] op_sel_hi:[1,0]
	s_nop 0
	v_pk_mul_f32 v[12:13], v[36:37], v[12:13]
	s_cbranch_vccz .LBB0_929
	v_lshl_or_b32 v14, v63, 10, v47
	v_ashrrev_i32_e32 v15, 31, v14
	v_lshl_add_u64 v[14:15], v[14:15], 2, s[26:27]
	global_store_dword v[14:15], v13, off sc1
	global_store_dword v[14:15], v12, off offset:128 sc1

.LBB0_931:
	v_pk_mul_f32 v[14:15], v[34:35], v[34:35]
	v_ashrrev_i32_e32 v63, 31, v62
	v_add_f32_e32 v14, v15, v14
	s_nop 1
	v_mov_b32_dpp v15, v14 quad_perm:[1,0,3,2] row_mask:0xf bank_mask:0xf
	v_cvt_pk_bf16_f32 v24, v13, s0
	v_cvt_pk_bf16_f32 v25, v12, s0
	v_lshl_add_u64 v[12:13], v[62:63], 0, v[134:135]
	v_lshl_add_u64 v[12:13], v[12:13], 1, s[4:5]
	s_waitcnt lgkmcnt(0)
	v_add_f32_e32 v14, v14, v15
	s_nop 1
	v_mov_b32_dpp v15, v14 quad_perm:[2,3,0,1] row_mask:0xf bank_mask:0xf
	global_store_short v[12:13], v24, off offset:128 sc1
	global_store_short v[12:13], v25, off offset:192 sc1
	s_and_b64 vcc, exec, s[70:71]
	s_waitcnt lgkmcnt(0)
	v_add_f32_e32 v14, v14, v15
	s_nop 1
	v_mov_b32_dpp v15, v14 row_half_mirror row_mask:0xf bank_mask:0xf
	s_waitcnt lgkmcnt(0)
	v_add_f32_e32 v14, v14, v15
	s_nop 1
	v_mov_b32_dpp v15, v14 row_mirror row_mask:0xf bank_mask:0xf
	s_waitcnt lgkmcnt(0)
	v_add_f32_e32 v14, v14, v15
	v_mov_b32_e32 v15, v14
	s_nop 1
	v_permlane16_swap_b32_e32 v14, v15
	s_nop 0
	s_waitcnt lgkmcnt(0)
	v_add_f32_e32 v14, v14, v15
	v_fmamk_f32 v14, v14, 0x3c800000, v196
	v_rsq_f32_e32 v14, v14
	s_nop 0
	v_pk_mul_f32 v[12:13], v[10:11], v[14:15] op_sel_hi:[1,0]
	s_nop 0
	v_pk_mul_f32 v[12:13], v[34:35], v[12:13]
	s_cbranch_vccz .LBB0_933
	v_lshl_or_b32 v14, v105, 10, v47
	v_ashrrev_i32_e32 v15, 31, v14
	v_lshl_add_u64 v[14:15], v[14:15], 2, s[26:27]
	global_store_dword v[14:15], v13, off sc1
	global_store_dword v[14:15], v12, off offset:128 sc1

.LBB0_935:
	v_pk_mul_f32 v[14:15], v[32:33], v[32:33]
	v_ashrrev_i32_e32 v73, 31, v72
	v_add_f32_e32 v14, v15, v14
	s_nop 1
	v_mov_b32_dpp v15, v14 quad_perm:[1,0,3,2] row_mask:0xf bank_mask:0xf
	v_cvt_pk_bf16_f32 v24, v13, s0
	v_cvt_pk_bf16_f32 v25, v12, s0
	v_lshl_add_u64 v[12:13], v[72:73], 0, v[134:135]
	v_lshl_add_u64 v[12:13], v[12:13], 1, s[4:5]
	s_waitcnt lgkmcnt(0)
	v_add_f32_e32 v14, v14, v15
	s_nop 1
	v_mov_b32_dpp v15, v14 quad_perm:[2,3,0,1] row_mask:0xf bank_mask:0xf
	global_store_short v[12:13], v24, off offset:128 sc1
	global_store_short v[12:13], v25, off offset:192 sc1
	s_and_b64 vcc, exec, s[70:71]
	s_waitcnt lgkmcnt(0)
	v_add_f32_e32 v14, v14, v15
	s_nop 1
	v_mov_b32_dpp v15, v14 row_half_mirror row_mask:0xf bank_mask:0xf
	s_waitcnt lgkmcnt(0)
	v_add_f32_e32 v14, v14, v15
	s_nop 1
	v_mov_b32_dpp v15, v14 row_mirror row_mask:0xf bank_mask:0xf
	s_waitcnt lgkmcnt(0)
	v_add_f32_e32 v14, v14, v15
	v_mov_b32_e32 v15, v14
	s_nop 1
	v_permlane16_swap_b32_e32 v14, v15
	s_nop 0
	s_waitcnt lgkmcnt(0)
	v_add_f32_e32 v14, v14, v15
	v_fmamk_f32 v14, v14, 0x3c800000, v196
	v_rsq_f32_e32 v14, v14
	s_nop 0
	v_pk_mul_f32 v[12:13], v[10:11], v[14:15] op_sel_hi:[1,0]
	s_nop 0
	v_pk_mul_f32 v[12:13], v[32:33], v[12:13]
	s_cbranch_vccz .LBB0_937
	v_lshl_or_b32 v14, v106, 10, v47
	v_ashrrev_i32_e32 v15, 31, v14
	v_lshl_add_u64 v[14:15], v[14:15], 2, s[26:27]
	global_store_dword v[14:15], v13, off sc1
	global_store_dword v[14:15], v12, off offset:128 sc1

.LBB0_939:
	v_pk_mul_f32 v[14:15], v[22:23], v[22:23]
	v_ashrrev_i32_e32 v77, 31, v76
	v_add_f32_e32 v14, v15, v14
	s_nop 1
	v_mov_b32_dpp v15, v14 quad_perm:[1,0,3,2] row_mask:0xf bank_mask:0xf
	v_cvt_pk_bf16_f32 v24, v13, s0
	v_cvt_pk_bf16_f32 v25, v12, s0
	v_lshl_add_u64 v[12:13], v[76:77], 0, v[134:135]
	v_lshl_add_u64 v[12:13], v[12:13], 1, s[4:5]
	s_waitcnt lgkmcnt(0)
	v_add_f32_e32 v14, v14, v15
	s_nop 1
	v_mov_b32_dpp v15, v14 quad_perm:[2,3,0,1] row_mask:0xf bank_mask:0xf
	global_store_short v[12:13], v24, off offset:128 sc1
	global_store_short v[12:13], v25, off offset:192 sc1
	s_and_b64 vcc, exec, s[70:71]
	s_waitcnt lgkmcnt(0)
	v_add_f32_e32 v14, v14, v15
	s_nop 1
	v_mov_b32_dpp v15, v14 row_half_mirror row_mask:0xf bank_mask:0xf
	s_waitcnt lgkmcnt(0)
	v_add_f32_e32 v14, v14, v15
	s_nop 1
	v_mov_b32_dpp v15, v14 row_mirror row_mask:0xf bank_mask:0xf
	s_waitcnt lgkmcnt(0)
	v_add_f32_e32 v14, v14, v15
	v_mov_b32_e32 v15, v14
	s_nop 1
	v_permlane16_swap_b32_e32 v14, v15
	s_nop 0
	s_waitcnt lgkmcnt(0)
	v_add_f32_e32 v14, v14, v15
	v_fmamk_f32 v14, v14, 0x3c800000, v196
	v_rsq_f32_e32 v14, v14
	s_nop 0
	v_pk_mul_f32 v[12:13], v[10:11], v[14:15] op_sel_hi:[1,0]
	s_nop 0
	v_pk_mul_f32 v[12:13], v[22:23], v[12:13]
	s_cbranch_vccz .LBB0_941
	v_lshl_or_b32 v14, v107, 10, v47
	v_ashrrev_i32_e32 v15, 31, v14
	v_lshl_add_u64 v[14:15], v[14:15], 2, s[26:27]
	global_store_dword v[14:15], v13, off sc1
	global_store_dword v[14:15], v12, off offset:128 sc1

.LBB0_943:
	v_pk_mul_f32 v[14:15], v[20:21], v[20:21]
	v_ashrrev_i32_e32 v69, 31, v68
	v_add_f32_e32 v14, v15, v14
	s_nop 1
	v_mov_b32_dpp v15, v14 quad_perm:[1,0,3,2] row_mask:0xf bank_mask:0xf
	v_cvt_pk_bf16_f32 v22, v13, s0
	v_cvt_pk_bf16_f32 v23, v12, s0
	v_lshl_add_u64 v[12:13], v[68:69], 0, v[134:135]
	v_lshl_add_u64 v[12:13], v[12:13], 1, s[4:5]
	s_waitcnt lgkmcnt(0)
	v_add_f32_e32 v14, v14, v15
	s_nop 1
	v_mov_b32_dpp v15, v14 quad_perm:[2,3,0,1] row_mask:0xf bank_mask:0xf
	global_store_short v[12:13], v22, off offset:128 sc1
	global_store_short v[12:13], v23, off offset:192 sc1
	s_and_b64 vcc, exec, s[70:71]
	s_waitcnt lgkmcnt(0)
	v_add_f32_e32 v14, v14, v15
	s_nop 1
	v_mov_b32_dpp v15, v14 row_half_mirror row_mask:0xf bank_mask:0xf
	s_waitcnt lgkmcnt(0)
	v_add_f32_e32 v14, v14, v15
	s_nop 1
	v_mov_b32_dpp v15, v14 row_mirror row_mask:0xf bank_mask:0xf
	s_waitcnt lgkmcnt(0)
	v_add_f32_e32 v14, v14, v15
	v_mov_b32_e32 v15, v14
	s_nop 1
	v_permlane16_swap_b32_e32 v14, v15
	s_nop 0
	s_waitcnt lgkmcnt(0)
	v_add_f32_e32 v14, v14, v15
	v_fmamk_f32 v14, v14, 0x3c800000, v196
	v_rsq_f32_e32 v14, v14
	s_nop 0
	v_pk_mul_f32 v[12:13], v[10:11], v[14:15] op_sel_hi:[1,0]
	s_nop 0
	v_pk_mul_f32 v[12:13], v[20:21], v[12:13]
	s_cbranch_vccz .LBB0_945
	v_lshl_or_b32 v14, v108, 10, v47
	v_ashrrev_i32_e32 v15, 31, v14
	v_lshl_add_u64 v[14:15], v[14:15], 2, s[26:27]
	global_store_dword v[14:15], v13, off sc1
	global_store_dword v[14:15], v12, off offset:128 sc1

.LBB0_947:
	v_pk_mul_f32 v[14:15], v[18:19], v[18:19]
	v_ashrrev_i32_e32 v67, 31, v66
	v_add_f32_e32 v14, v15, v14
	s_nop 1
	v_mov_b32_dpp v15, v14 quad_perm:[1,0,3,2] row_mask:0xf bank_mask:0xf
	v_cvt_pk_bf16_f32 v20, v13, s0
	v_cvt_pk_bf16_f32 v21, v12, s0
	v_lshl_add_u64 v[12:13], v[66:67], 0, v[134:135]
	v_lshl_add_u64 v[12:13], v[12:13], 1, s[4:5]
	s_waitcnt lgkmcnt(0)
	v_add_f32_e32 v14, v14, v15
	s_nop 1
	v_mov_b32_dpp v15, v14 quad_perm:[2,3,0,1] row_mask:0xf bank_mask:0xf
	global_store_short v[12:13], v20, off offset:128 sc1
	global_store_short v[12:13], v21, off offset:192 sc1
	s_and_b64 vcc, exec, s[70:71]
	s_waitcnt lgkmcnt(0)
	v_add_f32_e32 v14, v14, v15
	s_nop 1
	v_mov_b32_dpp v15, v14 row_half_mirror row_mask:0xf bank_mask:0xf
	s_waitcnt lgkmcnt(0)
	v_add_f32_e32 v14, v14, v15
	s_nop 1
	v_mov_b32_dpp v15, v14 row_mirror row_mask:0xf bank_mask:0xf
	s_waitcnt lgkmcnt(0)
	v_add_f32_e32 v14, v14, v15
	v_mov_b32_e32 v15, v14
	s_nop 1
	v_permlane16_swap_b32_e32 v14, v15
	s_nop 0
	s_waitcnt lgkmcnt(0)
	v_add_f32_e32 v14, v14, v15
	v_fmamk_f32 v14, v14, 0x3c800000, v196
	v_rsq_f32_e32 v14, v14
	s_nop 0
	v_pk_mul_f32 v[12:13], v[10:11], v[14:15] op_sel_hi:[1,0]
	s_nop 0
	v_pk_mul_f32 v[12:13], v[18:19], v[12:13]
	s_cbranch_vccz .LBB0_949
	v_lshl_or_b32 v14, v109, 10, v47
	v_ashrrev_i32_e32 v15, 31, v14
	v_lshl_add_u64 v[14:15], v[14:15], 2, s[26:27]
	global_store_dword v[14:15], v13, off sc1
	global_store_dword v[14:15], v12, off offset:128 sc1

.LBB0_951:
	v_pk_mul_f32 v[14:15], v[16:17], v[16:17]
	v_ashrrev_i32_e32 v65, 31, v64
	v_add_f32_e32 v14, v15, v14
	s_nop 1
	v_mov_b32_dpp v15, v14 quad_perm:[1,0,3,2] row_mask:0xf bank_mask:0xf
	v_cvt_pk_bf16_f32 v18, v13, s0
	v_cvt_pk_bf16_f32 v19, v12, s0
	v_lshl_add_u64 v[12:13], v[64:65], 0, v[134:135]
	v_lshl_add_u64 v[12:13], v[12:13], 1, s[4:5]
	s_waitcnt lgkmcnt(0)
	v_add_f32_e32 v14, v14, v15
	s_nop 1
	v_mov_b32_dpp v15, v14 quad_perm:[2,3,0,1] row_mask:0xf bank_mask:0xf
	global_store_short v[12:13], v18, off offset:128 sc1
	global_store_short v[12:13], v19, off offset:192 sc1
	s_and_b64 vcc, exec, s[70:71]
	s_waitcnt lgkmcnt(0)
	v_add_f32_e32 v14, v14, v15
	s_nop 1
	v_mov_b32_dpp v15, v14 row_half_mirror row_mask:0xf bank_mask:0xf
	s_waitcnt lgkmcnt(0)
	v_add_f32_e32 v14, v14, v15
	s_nop 1
	v_mov_b32_dpp v15, v14 row_mirror row_mask:0xf bank_mask:0xf
	s_waitcnt lgkmcnt(0)
	v_add_f32_e32 v14, v14, v15
	v_mov_b32_e32 v15, v14
	s_nop 1
	v_permlane16_swap_b32_e32 v14, v15
	s_nop 0
	s_waitcnt lgkmcnt(0)
	v_add_f32_e32 v14, v14, v15
	v_fmamk_f32 v14, v14, 0x3c800000, v196
	v_rsq_f32_e32 v14, v14
	s_nop 0
	v_pk_mul_f32 v[12:13], v[10:11], v[14:15] op_sel_hi:[1,0]
	s_nop 0
	v_pk_mul_f32 v[12:13], v[16:17], v[12:13]
	s_cbranch_vccz .LBB0_953
	v_lshl_or_b32 v14, v110, 10, v47
	v_ashrrev_i32_e32 v15, 31, v14
	v_lshl_add_u64 v[14:15], v[14:15], 2, s[26:27]
	global_store_dword v[14:15], v13, off sc1
	global_store_dword v[14:15], v12, off offset:128 sc1

.LBB0_955:
	v_pk_mul_f32 v[14:15], v[8:9], v[8:9]
	v_ashrrev_i32_e32 v57, 31, v56
	v_add_f32_e32 v14, v15, v14
	s_nop 1
	v_mov_b32_dpp v15, v14 quad_perm:[1,0,3,2] row_mask:0xf bank_mask:0xf
	v_cvt_pk_bf16_f32 v16, v13, s0
	v_cvt_pk_bf16_f32 v17, v12, s0
	v_lshl_add_u64 v[12:13], v[56:57], 0, v[134:135]
	v_lshl_add_u64 v[12:13], v[12:13], 1, s[4:5]
	s_waitcnt lgkmcnt(0)
	v_add_f32_e32 v14, v14, v15
	s_nop 1
	v_mov_b32_dpp v15, v14 quad_perm:[2,3,0,1] row_mask:0xf bank_mask:0xf
	global_store_short v[12:13], v16, off offset:128 sc1
	global_store_short v[12:13], v17, off offset:192 sc1
	s_and_b64 vcc, exec, s[70:71]
	s_waitcnt lgkmcnt(0)
	v_add_f32_e32 v14, v14, v15
	s_nop 1
	v_mov_b32_dpp v15, v14 row_half_mirror row_mask:0xf bank_mask:0xf
	s_waitcnt lgkmcnt(0)
	v_add_f32_e32 v14, v14, v15
	s_nop 1
	v_mov_b32_dpp v15, v14 row_mirror row_mask:0xf bank_mask:0xf
	s_waitcnt lgkmcnt(0)
	v_add_f32_e32 v14, v14, v15
	v_mov_b32_e32 v15, v14
	s_nop 1
	v_permlane16_swap_b32_e32 v14, v15
	s_nop 0
	s_waitcnt lgkmcnt(0)
	v_add_f32_e32 v14, v14, v15
	v_fmamk_f32 v14, v14, 0x3c800000, v196
	v_rsq_f32_e32 v14, v14
	s_nop 0
	v_pk_mul_f32 v[12:13], v[10:11], v[14:15] op_sel_hi:[1,0]
	s_nop 0
	v_pk_mul_f32 v[8:9], v[8:9], v[12:13]
	s_cbranch_vccz .LBB0_957
	v_lshl_or_b32 v12, v111, 10, v47
	v_ashrrev_i32_e32 v13, 31, v12
	v_lshl_add_u64 v[12:13], v[12:13], 2, s[26:27]
	global_store_dword v[12:13], v9, off sc1
	global_store_dword v[12:13], v8, off offset:128 sc1

.LBB0_959:
	v_pk_mul_f32 v[12:13], v[6:7], v[6:7]
	v_ashrrev_i32_e32 v55, 31, v54
	v_add_f32_e32 v12, v13, v12
	s_nop 1
	v_mov_b32_dpp v13, v12 quad_perm:[1,0,3,2] row_mask:0xf bank_mask:0xf
	v_cvt_pk_bf16_f32 v14, v9, s0
	v_cvt_pk_bf16_f32 v15, v8, s0
	v_lshl_add_u64 v[8:9], v[54:55], 0, v[134:135]
	v_lshl_add_u64 v[8:9], v[8:9], 1, s[4:5]
	s_waitcnt lgkmcnt(0)
	v_add_f32_e32 v12, v12, v13
	s_nop 1
	v_mov_b32_dpp v13, v12 quad_perm:[2,3,0,1] row_mask:0xf bank_mask:0xf
	global_store_short v[8:9], v14, off offset:128 sc1
	global_store_short v[8:9], v15, off offset:192 sc1
	s_and_b64 vcc, exec, s[70:71]
	s_waitcnt lgkmcnt(0)
	v_add_f32_e32 v12, v12, v13
	s_nop 1
	v_mov_b32_dpp v13, v12 row_half_mirror row_mask:0xf bank_mask:0xf
	s_waitcnt lgkmcnt(0)
	v_add_f32_e32 v12, v12, v13
	s_nop 1
	v_mov_b32_dpp v13, v12 row_mirror row_mask:0xf bank_mask:0xf
	s_waitcnt lgkmcnt(0)
	v_add_f32_e32 v12, v12, v13
	v_mov_b32_e32 v13, v12
	s_nop 1
	v_permlane16_swap_b32_e32 v12, v13
	s_nop 0
	s_waitcnt lgkmcnt(0)
	v_add_f32_e32 v12, v12, v13
	v_fmamk_f32 v12, v12, 0x3c800000, v196
	v_rsq_f32_e32 v12, v12
	s_nop 0
	v_pk_mul_f32 v[8:9], v[10:11], v[12:13] op_sel_hi:[1,0]
	s_nop 0
	v_pk_mul_f32 v[6:7], v[6:7], v[8:9]
	s_cbranch_vccz .LBB0_961
	v_lshl_or_b32 v8, v112, 10, v47
	v_ashrrev_i32_e32 v9, 31, v8
	v_lshl_add_u64 v[8:9], v[8:9], 2, s[26:27]
	global_store_dword v[8:9], v7, off sc1
	global_store_dword v[8:9], v6, off offset:128 sc1

.LBB0_963:
	v_pk_mul_f32 v[8:9], v[4:5], v[4:5]
	v_ashrrev_i32_e32 v53, 31, v52
	v_add_f32_e32 v8, v9, v8
	s_nop 1
	v_mov_b32_dpp v9, v8 quad_perm:[1,0,3,2] row_mask:0xf bank_mask:0xf
	v_cvt_pk_bf16_f32 v12, v7, s0
	v_cvt_pk_bf16_f32 v13, v6, s0
	v_lshl_add_u64 v[6:7], v[52:53], 0, v[134:135]
	v_lshl_add_u64 v[6:7], v[6:7], 1, s[4:5]
	s_waitcnt lgkmcnt(0)
	v_add_f32_e32 v8, v8, v9
	s_nop 1
	v_mov_b32_dpp v9, v8 quad_perm:[2,3,0,1] row_mask:0xf bank_mask:0xf
	global_store_short v[6:7], v12, off offset:128 sc1
	global_store_short v[6:7], v13, off offset:192 sc1
	s_and_b64 vcc, exec, s[70:71]
	s_waitcnt lgkmcnt(0)
	v_add_f32_e32 v8, v8, v9
	s_nop 1
	v_mov_b32_dpp v9, v8 row_half_mirror row_mask:0xf bank_mask:0xf
	s_waitcnt lgkmcnt(0)
	v_add_f32_e32 v8, v8, v9
	s_nop 1
	v_mov_b32_dpp v9, v8 row_mirror row_mask:0xf bank_mask:0xf
	s_waitcnt lgkmcnt(0)
	v_add_f32_e32 v8, v8, v9
	v_mov_b32_e32 v9, v8
	s_nop 1
	v_permlane16_swap_b32_e32 v8, v9
	s_nop 0
	s_waitcnt lgkmcnt(0)
	v_add_f32_e32 v8, v8, v9
	v_fmamk_f32 v8, v8, 0x3c800000, v196
	v_rsq_f32_e32 v8, v8
	s_nop 0
	v_pk_mul_f32 v[6:7], v[10:11], v[8:9] op_sel_hi:[1,0]
	s_nop 0
	v_pk_mul_f32 v[4:5], v[4:5], v[6:7]
	s_cbranch_vccz .LBB0_965
	v_lshl_or_b32 v6, v113, 10, v47
	v_ashrrev_i32_e32 v7, 31, v6
	v_lshl_add_u64 v[6:7], v[6:7], 2, s[26:27]
	global_store_dword v[6:7], v5, off sc1
	global_store_dword v[6:7], v4, off offset:128 sc1

.LBB0_967:
	v_pk_mul_f32 v[6:7], v[2:3], v[2:3]
	v_ashrrev_i32_e32 v51, 31, v50
	v_add_f32_e32 v6, v7, v6
	s_nop 1
	v_mov_b32_dpp v7, v6 quad_perm:[1,0,3,2] row_mask:0xf bank_mask:0xf
	v_cvt_pk_bf16_f32 v8, v5, s0
	v_cvt_pk_bf16_f32 v9, v4, s0
	v_lshl_add_u64 v[4:5], v[50:51], 0, v[134:135]
	v_lshl_add_u64 v[4:5], v[4:5], 1, s[4:5]
	s_waitcnt lgkmcnt(0)
	v_add_f32_e32 v6, v6, v7
	s_nop 1
	v_mov_b32_dpp v7, v6 quad_perm:[2,3,0,1] row_mask:0xf bank_mask:0xf
	global_store_short v[4:5], v8, off offset:128 sc1
	global_store_short v[4:5], v9, off offset:192 sc1
	s_and_b64 vcc, exec, s[70:71]
	s_waitcnt lgkmcnt(0)
	v_add_f32_e32 v6, v6, v7
	s_nop 1
	v_mov_b32_dpp v7, v6 row_half_mirror row_mask:0xf bank_mask:0xf
	s_waitcnt lgkmcnt(0)
	v_add_f32_e32 v6, v6, v7
	s_nop 1
	v_mov_b32_dpp v7, v6 row_mirror row_mask:0xf bank_mask:0xf
	s_waitcnt lgkmcnt(0)
	v_add_f32_e32 v6, v6, v7
	v_mov_b32_e32 v7, v6
	s_nop 1
	v_permlane16_swap_b32_e32 v6, v7
	s_nop 0
	s_waitcnt lgkmcnt(0)
	v_add_f32_e32 v6, v6, v7
	v_fmamk_f32 v6, v6, 0x3c800000, v196
	v_rsq_f32_e32 v6, v6
	s_nop 0
	v_pk_mul_f32 v[4:5], v[10:11], v[6:7] op_sel_hi:[1,0]
	s_nop 0
	v_pk_mul_f32 v[2:3], v[2:3], v[4:5]
	s_cbranch_vccz .LBB0_969
	v_lshl_or_b32 v4, v114, 10, v47
	v_ashrrev_i32_e32 v5, 31, v4
	v_lshl_add_u64 v[4:5], v[4:5], 2, s[26:27]
	global_store_dword v[4:5], v3, off sc1
	global_store_dword v[4:5], v2, off offset:128 sc1

.LBB0_971:
	v_pk_mul_f32 v[4:5], v[0:1], v[0:1]
	v_ashrrev_i32_e32 v49, 31, v48
	v_add_f32_e32 v4, v5, v4
	s_nop 1
	v_mov_b32_dpp v5, v4 quad_perm:[1,0,3,2] row_mask:0xf bank_mask:0xf
	v_cvt_pk_bf16_f32 v6, v3, s0
	v_cvt_pk_bf16_f32 v7, v2, s0
	v_lshl_add_u64 v[2:3], v[48:49], 0, v[134:135]
	v_lshl_add_u64 v[2:3], v[2:3], 1, s[4:5]
	s_waitcnt lgkmcnt(0)
	v_add_f32_e32 v4, v4, v5
	s_nop 1
	v_mov_b32_dpp v5, v4 quad_perm:[2,3,0,1] row_mask:0xf bank_mask:0xf
	global_store_short v[2:3], v6, off offset:128 sc1
	global_store_short v[2:3], v7, off offset:192 sc1
	s_and_b64 vcc, exec, s[70:71]
	s_waitcnt lgkmcnt(0)
	v_add_f32_e32 v4, v4, v5
	s_nop 1
	v_mov_b32_dpp v5, v4 row_half_mirror row_mask:0xf bank_mask:0xf
	s_waitcnt lgkmcnt(0)
	v_add_f32_e32 v4, v4, v5
	s_nop 1
	v_mov_b32_dpp v5, v4 row_mirror row_mask:0xf bank_mask:0xf
	s_waitcnt lgkmcnt(0)
	v_add_f32_e32 v4, v4, v5
	v_mov_b32_e32 v5, v4
	s_nop 1
	v_permlane16_swap_b32_e32 v4, v5
	s_nop 0
	s_waitcnt lgkmcnt(0)
	v_add_f32_e32 v4, v4, v5
	v_fmamk_f32 v4, v4, 0x3c800000, v196
	v_rsq_f32_e32 v4, v4
	s_nop 0
	v_pk_mul_f32 v[2:3], v[10:11], v[4:5] op_sel_hi:[1,0]
	s_nop 0
	v_pk_mul_f32 v[0:1], v[0:1], v[2:3]
	s_cbranch_vccz .LBB0_973
	v_lshl_or_b32 v2, v97, 10, v47
	v_ashrrev_i32_e32 v3, 31, v2
	v_lshl_add_u64 v[2:3], v[2:3], 2, s[26:27]
	global_store_dword v[2:3], v1, off sc1
	global_store_dword v[2:3], v0, off offset:128 sc1

.LBB0_1189:
	s_and_b64 vcc, exec, s[4:5]
	s_cbranch_vccz .LBB0_1170
	v_mov_b32_e32 v12, s82
	ds_read_b64 v[12:13], v12
	s_add_i32 s73, s84, -8
	s_cmp_lt_i32 s85, 64
	s_cselect_b64 s[68:69], -1, 0
	s_and_b64 s[4:5], s[68:69], exec
	s_waitcnt lgkmcnt(0)
	v_readfirstlane_b32 s8, v12
	s_cselect_b32 s4, 0, 0x200
	v_readfirstlane_b32 s70, v13
	s_add_u32 s4, s8, s4
	s_addc_u32 s5, s70, 0
	v_lshlrev_b32_e32 v14, 2, v108
	global_load_dword v13, v14, s[4:5]
	global_load_dword v12, v14, s[4:5] offset:128
	global_load_dword v15, v14, s[4:5] offset:256
	s_nop 0
	global_load_dword v14, v14, s[4:5] offset:384
	v_and_b32_e32 v31, 64, v170
	v_xor_b32_e32 v30, 1, v170
	v_pk_mul_f32 v[26:27], v[90:91], v[90:91]
	v_add_u32_e32 v31, 64, v31
	v_pk_mul_f32 v[28:29], v[92:93], v[92:93]
	v_add_f32_e32 v26, v27, v26
	v_cmp_lt_i32_e32 vcc, v30, v31
	v_add_f32_e32 v26, v26, v29
	v_add_f32_e32 v26, v26, v28
	v_cndmask_b32_e32 v27, v170, v30, vcc
	v_lshlrev_b32_e32 v42, 2, v27
	s_nop 1
	v_mov_b32_dpp v27, v26 quad_perm:[1,0,3,2] row_mask:0xf bank_mask:0xf
	v_xor_b32_e32 v28, 2, v170
	v_cmp_lt_i32_e32 vcc, v28, v31
	s_or_b64 s[70:71], s[68:69], s[0:1]
	s_lshl_b32 s8, s73, 7
	v_cndmask_b32_e32 v28, v170, v28, vcc
	v_lshlrev_b32_e32 v44, 2, v28
	s_waitcnt lgkmcnt(0)
	v_add_f32_e32 v26, v26, v27
	s_nop 1
	v_mov_b32_dpp v27, v26 quad_perm:[2,3,0,1] row_mask:0xf bank_mask:0xf
	v_xor_b32_e32 v28, 4, v170
	v_cmp_lt_i32_e32 vcc, v28, v31
	s_waitcnt lgkmcnt(0)
	v_add_f32_e32 v26, v26, v27
	v_cndmask_b32_e32 v28, v170, v28, vcc
	v_lshlrev_b32_e32 v45, 2, v28
	s_nop 1
	v_mov_b32_dpp v27, v26 row_half_mirror row_mask:0xf bank_mask:0xf
	v_xor_b32_e32 v28, 8, v170
	v_cmp_lt_i32_e32 vcc, v28, v31
	s_waitcnt lgkmcnt(0)
	v_add_f32_e32 v26, v26, v27
	v_cndmask_b32_e32 v28, v170, v28, vcc
	v_lshlrev_b32_e32 v46, 2, v28
	s_nop 1
	v_mov_b32_dpp v27, v26 row_mirror row_mask:0xf bank_mask:0xf
	v_xor_b32_e32 v28, 16, v170
	v_cmp_lt_i32_e32 vcc, v28, v31
	s_waitcnt lgkmcnt(0)
	v_add_f32_e32 v26, v26, v27
	v_cndmask_b32_e32 v28, v170, v28, vcc
	v_lshlrev_b32_e32 v43, 2, v28
	v_mov_b32_e32 v27, v26
	s_nop 1
	v_permlane16_swap_b32_e32 v26, v27
	s_nop 0
	s_and_b64 vcc, exec, s[70:71]
	s_waitcnt lgkmcnt(0)
	v_add_f32_e32 v26, v26, v27
	v_fmamk_f32 v26, v26, 0x3c000000, v166
	v_rsq_f32_e32 v28, v26
	v_lshl_add_u64 v[26:27], s[8:9], 2, v[116:117]
	s_waitcnt vmcnt(2)
	v_pk_mul_f32 v[30:31], v[12:13], v[28:29] op_sel_hi:[1,0]
	s_nop 0
	v_pk_mul_f32 v[40:41], v[90:91], v[30:31]
	s_waitcnt vmcnt(0)
	v_pk_mul_f32 v[28:29], v[14:15], v[28:29] op_sel_hi:[1,0]
	s_nop 0
	v_pk_mul_f32 v[30:31], v[92:93], v[28:29]
	s_cbranch_vccnz .LBB0_1192
	v_lshlrev_b32_e32 v28, 8, v118
	v_ashrrev_i32_e32 v29, 31, v28
	v_lshl_add_u64 v[28:29], v[28:29], 2, v[26:27]
	global_store_dword v[28:29], v41, off sc1
	global_store_dword v[28:29], v40, off offset:128 sc1
	global_store_dword v[28:29], v31, off offset:256 sc1
	global_store_dword v[28:29], v30, off offset:384 sc1

.LBB0_1194:
	v_pk_mul_f32 v[28:29], v[88:89], v[88:89]
	v_pk_mul_f32 v[54:55], v[86:87], v[86:87]
	v_add_f32_e32 v28, v29, v28
	v_add_f32_e32 v28, v28, v55
	v_add_f32_e32 v28, v28, v54
	s_nop 1
	v_mov_b32_dpp v29, v28 quad_perm:[1,0,3,2] row_mask:0xf bank_mask:0xf
	s_xor_b64 s[70:71], s[70:71], -1
	s_and_b64 s[0:1], s[68:69], exec
	s_cselect_b32 s0, s83, 0xdf9f000
	s_cselect_b32 s8, s66, s72
	s_waitcnt lgkmcnt(0)
	v_add_f32_e32 v28, v28, v29
	s_nop 1
	v_mov_b32_dpp v29, v28 quad_perm:[2,3,0,1] row_mask:0xf bank_mask:0xf
	s_cselect_b32 s72, s84, s73
	s_add_u32 s73, s14, s0
	s_addc_u32 s84, s15, 0
	s_and_b64 s[0:1], s[68:69], exec
	s_waitcnt lgkmcnt(0)
	v_add_f32_e32 v47, v28, v29
	s_nop 1
	v_mov_b32_dpp v54, v47 row_half_mirror row_mask:0xf bank_mask:0xf
	s_cselect_b32 s68, 10, 8
	s_lshl_b32 s0, s72, 7
	s_ashr_i32 s1, s0, 31
	s_lshl_b64 s[0:1], s[0:1], 1
	s_waitcnt lgkmcnt(0)
	v_add_f32_e32 v47, v47, v54
	s_nop 1
	v_mov_b32_dpp v56, v47 row_mirror row_mask:0xf bank_mask:0xf
	s_add_u32 s0, s73, s0
	v_add_u32_e32 v55, s8, v133
	s_addc_u32 s1, s84, s1
	v_lshlrev_b32_e32 v106, 1, v108
	s_waitcnt lgkmcnt(0)
	v_add_f32_e32 v47, v47, v56
	v_mov_b32_e32 v56, v47
	s_nop 1
	v_permlane16_swap_b32_e32 v47, v56
	s_nop 0
	v_lshlrev_b32_e32 v54, s68, v55
	v_lshl_add_u64 v[28:29], s[0:1], 0, v[106:107]
	v_ashrrev_i32_e32 v55, 31, v54
	v_lshl_add_u64 v[54:55], v[54:55], 1, v[28:29]
	v_cvt_pk_bf16_f32 v40, v40, s0
	global_store_short v[54:55], v40, off offset:64 sc1
	s_waitcnt lgkmcnt(0)
	v_add_f32_e32 v40, v47, v56
	v_fmamk_f32 v40, v40, 0x3c000000, v166
	v_rsq_f32_e32 v40, v40
	v_cvt_pk_bf16_f32 v41, v41, s0
	v_cvt_pk_bf16_f32 v31, v31, s0
	v_cvt_pk_bf16_f32 v30, v30, s0
	global_store_short v[54:55], v41, off sc1
	global_store_short v[54:55], v31, off offset:128 sc1
	global_store_short v[54:55], v30, off offset:192 sc1
	v_pk_mul_f32 v[30:31], v[12:13], v[40:41] op_sel_hi:[1,0]
	v_pk_mul_f32 v[40:41], v[14:15], v[40:41] op_sel_hi:[1,0]
	v_cndmask_b32_e64 v47, 0, 1, s[70:71]
	v_pk_mul_f32 v[30:31], v[88:89], v[30:31]
	v_cmp_ne_u32_e64 s[0:1], 1, v47
	s_andn2_b64 vcc, exec, s[70:71]
	v_pk_mul_f32 v[40:41], v[86:87], v[40:41]
	s_cbranch_vccnz .LBB0_1196
	v_add_lshl_u32 v54, s66, v141, 8
	v_ashrrev_i32_e32 v55, 31, v54
	v_lshl_add_u64 v[54:55], v[54:55], 2, v[26:27]
	global_store_dword v[54:55], v31, off sc1
	global_store_dword v[54:55], v30, off offset:128 sc1
	global_store_dword v[54:55], v41, off offset:256 sc1
	global_store_dword v[54:55], v40, off offset:384 sc1

.LBB0_1198:
	v_pk_mul_f32 v[54:55], v[80:81], v[80:81]
	v_pk_mul_f32 v[56:57], v[82:83], v[82:83]
	v_add_f32_e32 v47, v55, v54
	v_add_f32_e32 v47, v47, v57
	v_add_f32_e32 v47, v47, v56
	s_nop 1
	v_mov_b32_dpp v54, v47 quad_perm:[1,0,3,2] row_mask:0xf bank_mask:0xf
	v_cvt_pk_bf16_f32 v56, v31, s0
	v_cvt_pk_bf16_f32 v57, v40, s0
	v_add_u32_e32 v55, s8, v141
	v_cvt_pk_bf16_f32 v41, v41, s0
	s_waitcnt lgkmcnt(0)
	v_add_f32_e32 v47, v47, v54
	s_nop 1
	v_mov_b32_dpp v54, v47 quad_perm:[2,3,0,1] row_mask:0xf bank_mask:0xf
	s_and_b64 vcc, exec, s[0:1]
	s_waitcnt lgkmcnt(0)
	v_add_f32_e32 v47, v47, v54
	s_nop 1
	v_mov_b32_dpp v54, v47 row_half_mirror row_mask:0xf bank_mask:0xf
	s_waitcnt lgkmcnt(0)
	v_add_f32_e32 v31, v47, v54
	s_nop 1
	v_mov_b32_dpp v47, v31 row_mirror row_mask:0xf bank_mask:0xf
	v_cvt_pk_bf16_f32 v54, v30, s0
	v_lshlrev_b32_e32 v30, s68, v55
	s_waitcnt lgkmcnt(0)
	v_add_f32_e32 v40, v31, v47
	v_mov_b32_e32 v47, v40
	s_nop 1
	v_permlane16_swap_b32_e32 v40, v47
	s_nop 0
	v_ashrrev_i32_e32 v31, 31, v30
	v_lshl_add_u64 v[30:31], v[30:31], 1, v[28:29]
	global_store_short v[30:31], v56, off sc1
	global_store_short v[30:31], v54, off offset:64 sc1
	global_store_short v[30:31], v41, off offset:128 sc1
	global_store_short v[30:31], v57, off offset:192 sc1
	s_waitcnt lgkmcnt(0)
	v_add_f32_e32 v40, v40, v47
	v_fmamk_f32 v40, v40, 0x3c000000, v166
	v_rsq_f32_e32 v40, v40
	s_nop 0
	v_pk_mul_f32 v[30:31], v[12:13], v[40:41] op_sel_hi:[1,0]
	v_pk_mul_f32 v[54:55], v[14:15], v[40:41] op_sel_hi:[1,0]
	v_pk_mul_f32 v[40:41], v[80:81], v[30:31]
	v_pk_mul_f32 v[30:31], v[82:83], v[54:55]
	s_cbranch_vccnz .LBB0_1200
	v_add_lshl_u32 v54, s66, v142, 8
	v_ashrrev_i32_e32 v55, 31, v54
	v_lshl_add_u64 v[54:55], v[54:55], 2, v[26:27]
	global_store_dword v[54:55], v41, off sc1
	global_store_dword v[54:55], v40, off offset:128 sc1
	global_store_dword v[54:55], v31, off offset:256 sc1
	global_store_dword v[54:55], v30, off offset:384 sc1

.LBB0_1202:
	v_pk_mul_f32 v[54:55], v[76:77], v[76:77]
	v_pk_mul_f32 v[56:57], v[78:79], v[78:79]
	v_add_f32_e32 v47, v55, v54
	v_add_f32_e32 v47, v47, v57
	v_add_f32_e32 v47, v47, v56
	s_nop 1
	v_mov_b32_dpp v54, v47 quad_perm:[1,0,3,2] row_mask:0xf bank_mask:0xf
	v_cvt_pk_bf16_f32 v56, v40, s0
	v_add_u32_e32 v55, s8, v142
	v_cvt_pk_bf16_f32 v58, v30, s0
	v_lshlrev_b32_e32 v30, s68, v55
	s_waitcnt lgkmcnt(0)
	v_add_f32_e32 v47, v47, v54
	s_nop 1
	v_mov_b32_dpp v54, v47 quad_perm:[2,3,0,1] row_mask:0xf bank_mask:0xf
	v_cvt_pk_bf16_f32 v57, v31, s0
	v_ashrrev_i32_e32 v31, 31, v30
	v_cvt_pk_bf16_f32 v41, v41, s0
	v_lshl_add_u64 v[30:31], v[30:31], 1, v[28:29]
	s_waitcnt lgkmcnt(0)
	v_add_f32_e32 v47, v47, v54
	s_nop 1
	v_mov_b32_dpp v54, v47 row_half_mirror row_mask:0xf bank_mask:0xf
	global_store_short v[30:31], v41, off sc1
	global_store_short v[30:31], v56, off offset:64 sc1
	global_store_short v[30:31], v57, off offset:128 sc1
	global_store_short v[30:31], v58, off offset:192 sc1
	s_and_b64 vcc, exec, s[0:1]
	s_waitcnt lgkmcnt(0)
	v_add_f32_e32 v47, v47, v54
	s_nop 1
	v_mov_b32_dpp v54, v47 row_mirror row_mask:0xf bank_mask:0xf
	s_waitcnt lgkmcnt(0)
	v_add_f32_e32 v40, v47, v54
	v_mov_b32_e32 v47, v40
	s_nop 1
	v_permlane16_swap_b32_e32 v40, v47
	s_nop 0
	s_waitcnt lgkmcnt(0)
	v_add_f32_e32 v40, v40, v47
	v_fmamk_f32 v40, v40, 0x3c000000, v166
	v_rsq_f32_e32 v40, v40
	s_nop 0
	v_pk_mul_f32 v[30:31], v[12:13], v[40:41] op_sel_hi:[1,0]
	v_pk_mul_f32 v[54:55], v[14:15], v[40:41] op_sel_hi:[1,0]
	v_pk_mul_f32 v[40:41], v[76:77], v[30:31]
	v_pk_mul_f32 v[30:31], v[78:79], v[54:55]
	s_cbranch_vccnz .LBB0_1204
	v_add_lshl_u32 v54, s66, v143, 8
	v_ashrrev_i32_e32 v55, 31, v54
	v_lshl_add_u64 v[54:55], v[54:55], 2, v[26:27]
	global_store_dword v[54:55], v41, off sc1
	global_store_dword v[54:55], v40, off offset:128 sc1
	global_store_dword v[54:55], v31, off offset:256 sc1
	global_store_dword v[54:55], v30, off offset:384 sc1

.LBB0_1206:
	v_pk_mul_f32 v[54:55], v[72:73], v[72:73]
	v_pk_mul_f32 v[56:57], v[74:75], v[74:75]
	v_add_f32_e32 v47, v55, v54
	v_add_f32_e32 v47, v47, v57
	v_add_f32_e32 v47, v47, v56
	s_nop 1
	v_mov_b32_dpp v54, v47 quad_perm:[1,0,3,2] row_mask:0xf bank_mask:0xf
	v_cvt_pk_bf16_f32 v56, v40, s0
	v_add_u32_e32 v55, s8, v143
	v_cvt_pk_bf16_f32 v58, v30, s0
	v_lshlrev_b32_e32 v30, s68, v55
	s_waitcnt lgkmcnt(0)
	v_add_f32_e32 v47, v47, v54
	s_nop 1
	v_mov_b32_dpp v54, v47 quad_perm:[2,3,0,1] row_mask:0xf bank_mask:0xf
	v_cvt_pk_bf16_f32 v57, v31, s0
	v_ashrrev_i32_e32 v31, 31, v30
	v_cvt_pk_bf16_f32 v41, v41, s0
	v_lshl_add_u64 v[30:31], v[30:31], 1, v[28:29]
	s_waitcnt lgkmcnt(0)
	v_add_f32_e32 v47, v47, v54
	s_nop 1
	v_mov_b32_dpp v54, v47 row_half_mirror row_mask:0xf bank_mask:0xf
	global_store_short v[30:31], v41, off sc1
	global_store_short v[30:31], v56, off offset:64 sc1
	global_store_short v[30:31], v57, off offset:128 sc1
	global_store_short v[30:31], v58, off offset:192 sc1
	s_and_b64 vcc, exec, s[0:1]
	s_waitcnt lgkmcnt(0)
	v_add_f32_e32 v47, v47, v54
	s_nop 1
	v_mov_b32_dpp v54, v47 row_mirror row_mask:0xf bank_mask:0xf
	s_waitcnt lgkmcnt(0)
	v_add_f32_e32 v40, v47, v54
	v_mov_b32_e32 v47, v40
	s_nop 1
	v_permlane16_swap_b32_e32 v40, v47
	s_nop 0
	s_waitcnt lgkmcnt(0)
	v_add_f32_e32 v40, v40, v47
	v_fmamk_f32 v40, v40, 0x3c000000, v166
	v_rsq_f32_e32 v40, v40
	s_nop 0
	v_pk_mul_f32 v[30:31], v[12:13], v[40:41] op_sel_hi:[1,0]
	v_pk_mul_f32 v[54:55], v[14:15], v[40:41] op_sel_hi:[1,0]
	v_pk_mul_f32 v[40:41], v[72:73], v[30:31]
	v_pk_mul_f32 v[30:31], v[74:75], v[54:55]
	s_cbranch_vccnz .LBB0_1208
	v_add_lshl_u32 v54, s66, v144, 8
	v_ashrrev_i32_e32 v55, 31, v54
	v_lshl_add_u64 v[54:55], v[54:55], 2, v[26:27]
	global_store_dword v[54:55], v41, off sc1
	global_store_dword v[54:55], v40, off offset:128 sc1
	global_store_dword v[54:55], v31, off offset:256 sc1
	global_store_dword v[54:55], v30, off offset:384 sc1

.LBB0_1210:
	v_pk_mul_f32 v[54:55], v[68:69], v[68:69]
	v_pk_mul_f32 v[56:57], v[70:71], v[70:71]
	v_add_f32_e32 v47, v55, v54
	v_add_f32_e32 v47, v47, v57
	v_add_f32_e32 v47, v47, v56
	s_nop 1
	v_mov_b32_dpp v54, v47 quad_perm:[1,0,3,2] row_mask:0xf bank_mask:0xf
	v_cvt_pk_bf16_f32 v56, v40, s0
	v_add_u32_e32 v55, s8, v144
	v_cvt_pk_bf16_f32 v58, v30, s0
	v_lshlrev_b32_e32 v30, s68, v55
	s_waitcnt lgkmcnt(0)
	v_add_f32_e32 v47, v47, v54
	s_nop 1
	v_mov_b32_dpp v54, v47 quad_perm:[2,3,0,1] row_mask:0xf bank_mask:0xf
	v_cvt_pk_bf16_f32 v57, v31, s0
	v_ashrrev_i32_e32 v31, 31, v30
	v_cvt_pk_bf16_f32 v41, v41, s0
	v_lshl_add_u64 v[30:31], v[30:31], 1, v[28:29]
	s_waitcnt lgkmcnt(0)
	v_add_f32_e32 v47, v47, v54
	s_nop 1
	v_mov_b32_dpp v54, v47 row_half_mirror row_mask:0xf bank_mask:0xf
	global_store_short v[30:31], v41, off sc1
	global_store_short v[30:31], v56, off offset:64 sc1
	global_store_short v[30:31], v57, off offset:128 sc1
	global_store_short v[30:31], v58, off offset:192 sc1
	s_and_b64 vcc, exec, s[0:1]
	s_waitcnt lgkmcnt(0)
	v_add_f32_e32 v47, v47, v54
	s_nop 1
	v_mov_b32_dpp v54, v47 row_mirror row_mask:0xf bank_mask:0xf
	s_waitcnt lgkmcnt(0)
	v_add_f32_e32 v40, v47, v54
	v_mov_b32_e32 v47, v40
	s_nop 1
	v_permlane16_swap_b32_e32 v40, v47
	s_nop 0
	s_waitcnt lgkmcnt(0)
	v_add_f32_e32 v40, v40, v47
	v_fmamk_f32 v40, v40, 0x3c000000, v166
	v_rsq_f32_e32 v40, v40
	s_nop 0
	v_pk_mul_f32 v[30:31], v[12:13], v[40:41] op_sel_hi:[1,0]
	v_pk_mul_f32 v[54:55], v[14:15], v[40:41] op_sel_hi:[1,0]
	v_pk_mul_f32 v[40:41], v[68:69], v[30:31]
	v_pk_mul_f32 v[30:31], v[70:71], v[54:55]
	s_cbranch_vccnz .LBB0_1212
	v_add_lshl_u32 v54, s66, v145, 8
	v_ashrrev_i32_e32 v55, 31, v54
	v_lshl_add_u64 v[54:55], v[54:55], 2, v[26:27]
	global_store_dword v[54:55], v41, off sc1
	global_store_dword v[54:55], v40, off offset:128 sc1
	global_store_dword v[54:55], v31, off offset:256 sc1
	global_store_dword v[54:55], v30, off offset:384 sc1

.LBB0_1214:
	v_pk_mul_f32 v[54:55], v[64:65], v[64:65]
	v_pk_mul_f32 v[56:57], v[66:67], v[66:67]
	v_add_f32_e32 v47, v55, v54
	v_add_f32_e32 v47, v47, v57
	v_add_f32_e32 v47, v47, v56
	s_nop 1
	v_mov_b32_dpp v54, v47 quad_perm:[1,0,3,2] row_mask:0xf bank_mask:0xf
	v_cvt_pk_bf16_f32 v56, v40, s0
	v_add_u32_e32 v55, s8, v145
	v_cvt_pk_bf16_f32 v58, v30, s0
	v_lshlrev_b32_e32 v30, s68, v55
	s_waitcnt lgkmcnt(0)
	v_add_f32_e32 v47, v47, v54
	s_nop 1
	v_mov_b32_dpp v54, v47 quad_perm:[2,3,0,1] row_mask:0xf bank_mask:0xf
	v_cvt_pk_bf16_f32 v57, v31, s0
	v_ashrrev_i32_e32 v31, 31, v30
	v_cvt_pk_bf16_f32 v41, v41, s0
	v_lshl_add_u64 v[30:31], v[30:31], 1, v[28:29]
	s_waitcnt lgkmcnt(0)
	v_add_f32_e32 v47, v47, v54
	s_nop 1
	v_mov_b32_dpp v54, v47 row_half_mirror row_mask:0xf bank_mask:0xf
	global_store_short v[30:31], v41, off sc1
	global_store_short v[30:31], v56, off offset:64 sc1
	global_store_short v[30:31], v57, off offset:128 sc1
	global_store_short v[30:31], v58, off offset:192 sc1
	s_and_b64 vcc, exec, s[0:1]
	s_waitcnt lgkmcnt(0)
	v_add_f32_e32 v47, v47, v54
	s_nop 1
	v_mov_b32_dpp v54, v47 row_mirror row_mask:0xf bank_mask:0xf
	s_waitcnt lgkmcnt(0)
	v_add_f32_e32 v40, v47, v54
	v_mov_b32_e32 v47, v40
	s_nop 1
	v_permlane16_swap_b32_e32 v40, v47
	s_nop 0
	s_waitcnt lgkmcnt(0)
	v_add_f32_e32 v40, v40, v47
	v_fmamk_f32 v40, v40, 0x3c000000, v166
	v_rsq_f32_e32 v40, v40
	s_nop 0
	v_pk_mul_f32 v[30:31], v[12:13], v[40:41] op_sel_hi:[1,0]
	v_pk_mul_f32 v[54:55], v[14:15], v[40:41] op_sel_hi:[1,0]
	v_pk_mul_f32 v[40:41], v[64:65], v[30:31]
	v_pk_mul_f32 v[30:31], v[66:67], v[54:55]
	s_cbranch_vccnz .LBB0_1216
	v_add_lshl_u32 v54, s66, v146, 8
	v_ashrrev_i32_e32 v55, 31, v54
	v_lshl_add_u64 v[54:55], v[54:55], 2, v[26:27]
	global_store_dword v[54:55], v41, off sc1
	global_store_dword v[54:55], v40, off offset:128 sc1
	global_store_dword v[54:55], v31, off offset:256 sc1
	global_store_dword v[54:55], v30, off offset:384 sc1

.LBB0_1218:
	v_pk_mul_f32 v[54:55], v[50:51], v[50:51]
	v_pk_mul_f32 v[56:57], v[52:53], v[52:53]
	v_add_f32_e32 v47, v55, v54
	v_add_f32_e32 v47, v47, v57
	v_add_f32_e32 v47, v47, v56
	s_nop 1
	v_mov_b32_dpp v54, v47 quad_perm:[1,0,3,2] row_mask:0xf bank_mask:0xf
	v_cvt_pk_bf16_f32 v56, v40, s0
	v_add_u32_e32 v55, s8, v146
	v_cvt_pk_bf16_f32 v58, v30, s0
	v_lshlrev_b32_e32 v30, s68, v55
	s_waitcnt lgkmcnt(0)
	v_add_f32_e32 v47, v47, v54
	s_nop 1
	v_mov_b32_dpp v54, v47 quad_perm:[2,3,0,1] row_mask:0xf bank_mask:0xf
	v_cvt_pk_bf16_f32 v57, v31, s0
	v_ashrrev_i32_e32 v31, 31, v30
	v_cvt_pk_bf16_f32 v41, v41, s0
	v_lshl_add_u64 v[30:31], v[30:31], 1, v[28:29]
	s_waitcnt lgkmcnt(0)
	v_add_f32_e32 v47, v47, v54
	s_nop 1
	v_mov_b32_dpp v54, v47 row_half_mirror row_mask:0xf bank_mask:0xf
	global_store_short v[30:31], v41, off sc1
	global_store_short v[30:31], v56, off offset:64 sc1
	global_store_short v[30:31], v57, off offset:128 sc1
	global_store_short v[30:31], v58, off offset:192 sc1
	s_and_b64 vcc, exec, s[0:1]
	s_waitcnt lgkmcnt(0)
	v_add_f32_e32 v47, v47, v54
	s_nop 1
	v_mov_b32_dpp v54, v47 row_mirror row_mask:0xf bank_mask:0xf
	s_waitcnt lgkmcnt(0)
	v_add_f32_e32 v40, v47, v54
	v_mov_b32_e32 v47, v40
	s_nop 1
	v_permlane16_swap_b32_e32 v40, v47
	s_nop 0
	s_waitcnt lgkmcnt(0)
	v_add_f32_e32 v40, v40, v47
	v_fmamk_f32 v40, v40, 0x3c000000, v166
	v_rsq_f32_e32 v40, v40
	s_nop 0
	v_pk_mul_f32 v[30:31], v[12:13], v[40:41] op_sel_hi:[1,0]
	v_pk_mul_f32 v[54:55], v[14:15], v[40:41] op_sel_hi:[1,0]
	v_pk_mul_f32 v[40:41], v[50:51], v[30:31]
	v_pk_mul_f32 v[30:31], v[52:53], v[54:55]
	s_cbranch_vccnz .LBB0_1220
	v_add_lshl_u32 v50, s66, v147, 8
	v_ashrrev_i32_e32 v51, 31, v50
	v_lshl_add_u64 v[50:51], v[50:51], 2, v[26:27]
	global_store_dword v[50:51], v41, off sc1
	global_store_dword v[50:51], v40, off offset:128 sc1
	global_store_dword v[50:51], v31, off offset:256 sc1
	global_store_dword v[50:51], v30, off offset:384 sc1

.LBB0_1222:
	v_pk_mul_f32 v[50:51], v[38:39], v[38:39]
	v_pk_mul_f32 v[52:53], v[48:49], v[48:49]
	v_add_f32_e32 v47, v51, v50
	v_add_f32_e32 v47, v47, v53
	v_add_f32_e32 v47, v47, v52
	s_nop 1
	v_mov_b32_dpp v50, v47 quad_perm:[1,0,3,2] row_mask:0xf bank_mask:0xf
	v_cvt_pk_bf16_f32 v52, v40, s0
	v_add_u32_e32 v51, s8, v147
	v_cvt_pk_bf16_f32 v54, v30, s0
	v_lshlrev_b32_e32 v30, s68, v51
	s_waitcnt lgkmcnt(0)
	v_add_f32_e32 v47, v47, v50
	s_nop 1
	v_mov_b32_dpp v50, v47 quad_perm:[2,3,0,1] row_mask:0xf bank_mask:0xf
	v_cvt_pk_bf16_f32 v53, v31, s0
	v_ashrrev_i32_e32 v31, 31, v30
	v_cvt_pk_bf16_f32 v41, v41, s0
	v_lshl_add_u64 v[30:31], v[30:31], 1, v[28:29]
	s_waitcnt lgkmcnt(0)
	v_add_f32_e32 v47, v47, v50
	s_nop 1
	v_mov_b32_dpp v50, v47 row_half_mirror row_mask:0xf bank_mask:0xf
	global_store_short v[30:31], v41, off sc1
	global_store_short v[30:31], v52, off offset:64 sc1
	global_store_short v[30:31], v53, off offset:128 sc1
	global_store_short v[30:31], v54, off offset:192 sc1
	s_and_b64 vcc, exec, s[0:1]
	s_waitcnt lgkmcnt(0)
	v_add_f32_e32 v47, v47, v50
	s_nop 1
	v_mov_b32_dpp v50, v47 row_mirror row_mask:0xf bank_mask:0xf
	s_waitcnt lgkmcnt(0)
	v_add_f32_e32 v40, v47, v50
	v_mov_b32_e32 v47, v40
	s_nop 1
	v_permlane16_swap_b32_e32 v40, v47
	s_nop 0
	s_waitcnt lgkmcnt(0)
	v_add_f32_e32 v40, v40, v47
	v_fmamk_f32 v40, v40, 0x3c000000, v166
	v_rsq_f32_e32 v40, v40
	s_nop 0
	v_pk_mul_f32 v[30:31], v[12:13], v[40:41] op_sel_hi:[1,0]
	v_pk_mul_f32 v[40:41], v[14:15], v[40:41] op_sel_hi:[1,0]
	v_pk_mul_f32 v[38:39], v[38:39], v[30:31]
	v_pk_mul_f32 v[30:31], v[48:49], v[40:41]
	s_cbranch_vccnz .LBB0_1224
	v_add_lshl_u32 v40, s66, v148, 8
	v_ashrrev_i32_e32 v41, 31, v40
	v_lshl_add_u64 v[40:41], v[40:41], 2, v[26:27]
	global_store_dword v[40:41], v39, off sc1
	global_store_dword v[40:41], v38, off offset:128 sc1
	global_store_dword v[40:41], v31, off offset:256 sc1
	global_store_dword v[40:41], v30, off offset:384 sc1

.LBB0_1226:
	v_pk_mul_f32 v[40:41], v[34:35], v[34:35]
	v_pk_mul_f32 v[48:49], v[36:37], v[36:37]
	v_add_f32_e32 v40, v41, v40
	v_add_f32_e32 v40, v40, v49
	v_add_f32_e32 v40, v40, v48
	s_nop 1
	v_mov_b32_dpp v41, v40 quad_perm:[1,0,3,2] row_mask:0xf bank_mask:0xf
	v_cvt_pk_bf16_f32 v48, v38, s0
	v_add_u32_e32 v47, s8, v148
	v_cvt_pk_bf16_f32 v50, v30, s0
	v_lshlrev_b32_e32 v30, s68, v47
	s_waitcnt lgkmcnt(0)
	v_add_f32_e32 v40, v40, v41
	s_nop 1
	v_mov_b32_dpp v41, v40 quad_perm:[2,3,0,1] row_mask:0xf bank_mask:0xf
	v_cvt_pk_bf16_f32 v49, v31, s0
	v_ashrrev_i32_e32 v31, 31, v30
	v_cvt_pk_bf16_f32 v39, v39, s0
	v_lshl_add_u64 v[30:31], v[30:31], 1, v[28:29]
	s_waitcnt lgkmcnt(0)
	v_add_f32_e32 v40, v40, v41
	s_nop 1
	v_mov_b32_dpp v41, v40 row_half_mirror row_mask:0xf bank_mask:0xf
	global_store_short v[30:31], v39, off sc1
	global_store_short v[30:31], v48, off offset:64 sc1
	global_store_short v[30:31], v49, off offset:128 sc1
	global_store_short v[30:31], v50, off offset:192 sc1
	s_and_b64 vcc, exec, s[0:1]
	s_waitcnt lgkmcnt(0)
	v_add_f32_e32 v40, v40, v41
	s_nop 1
	v_mov_b32_dpp v41, v40 row_mirror row_mask:0xf bank_mask:0xf
	s_waitcnt lgkmcnt(0)
	v_add_f32_e32 v38, v40, v41
	v_mov_b32_e32 v40, v38
	s_nop 1
	v_permlane16_swap_b32_e32 v38, v40
	s_nop 0
	s_waitcnt lgkmcnt(0)
	v_add_f32_e32 v38, v38, v40
	v_fmamk_f32 v38, v38, 0x3c000000, v166
	v_rsq_f32_e32 v38, v38
	s_nop 0
	v_pk_mul_f32 v[30:31], v[12:13], v[38:39] op_sel_hi:[1,0]
	v_pk_mul_f32 v[38:39], v[14:15], v[38:39] op_sel_hi:[1,0]
	v_pk_mul_f32 v[34:35], v[34:35], v[30:31]
	v_pk_mul_f32 v[30:31], v[36:37], v[38:39]
	s_cbranch_vccnz .LBB0_1228
	v_add_lshl_u32 v36, s66, v149, 8
	v_ashrrev_i32_e32 v37, 31, v36
	v_lshl_add_u64 v[36:37], v[36:37], 2, v[26:27]
	global_store_dword v[36:37], v35, off sc1
	global_store_dword v[36:37], v34, off offset:128 sc1
	global_store_dword v[36:37], v31, off offset:256 sc1
	global_store_dword v[36:37], v30, off offset:384 sc1

.LBB0_1230:
	v_pk_mul_f32 v[36:37], v[24:25], v[24:25]
	v_pk_mul_f32 v[38:39], v[32:33], v[32:33]
	v_add_f32_e32 v36, v37, v36
	v_add_f32_e32 v36, v36, v39
	v_add_f32_e32 v36, v36, v38
	s_nop 1
	v_mov_b32_dpp v37, v36 quad_perm:[1,0,3,2] row_mask:0xf bank_mask:0xf
	v_cvt_pk_bf16_f32 v39, v34, s0
	v_add_u32_e32 v38, s8, v149
	v_cvt_pk_bf16_f32 v41, v30, s0
	v_lshlrev_b32_e32 v30, s68, v38
	s_waitcnt lgkmcnt(0)
	v_add_f32_e32 v36, v36, v37
	s_nop 1
	v_mov_b32_dpp v37, v36 quad_perm:[2,3,0,1] row_mask:0xf bank_mask:0xf
	v_cvt_pk_bf16_f32 v40, v31, s0
	v_ashrrev_i32_e32 v31, 31, v30
	v_cvt_pk_bf16_f32 v35, v35, s0
	v_lshl_add_u64 v[30:31], v[30:31], 1, v[28:29]
	s_waitcnt lgkmcnt(0)
	v_add_f32_e32 v36, v36, v37
	s_nop 1
	v_mov_b32_dpp v37, v36 row_half_mirror row_mask:0xf bank_mask:0xf
	global_store_short v[30:31], v35, off sc1
	global_store_short v[30:31], v39, off offset:64 sc1
	global_store_short v[30:31], v40, off offset:128 sc1
	global_store_short v[30:31], v41, off offset:192 sc1
	s_and_b64 vcc, exec, s[0:1]
	s_waitcnt lgkmcnt(0)
	v_add_f32_e32 v36, v36, v37
	s_nop 1
	v_mov_b32_dpp v37, v36 row_mirror row_mask:0xf bank_mask:0xf
	s_waitcnt lgkmcnt(0)
	v_add_f32_e32 v34, v36, v37
	v_mov_b32_e32 v36, v34
	s_nop 1
	v_permlane16_swap_b32_e32 v34, v36
	s_nop 0
	s_waitcnt lgkmcnt(0)
	v_add_f32_e32 v34, v34, v36
	v_fmamk_f32 v34, v34, 0x3c000000, v166
	v_rsq_f32_e32 v34, v34
	s_nop 0
	v_pk_mul_f32 v[30:31], v[12:13], v[34:35] op_sel_hi:[1,0]
	v_pk_mul_f32 v[34:35], v[14:15], v[34:35] op_sel_hi:[1,0]
	v_pk_mul_f32 v[30:31], v[24:25], v[30:31]
	v_pk_mul_f32 v[24:25], v[32:33], v[34:35]
	s_cbranch_vccnz .LBB0_1232
	v_add_lshl_u32 v32, s66, v150, 8
	v_ashrrev_i32_e32 v33, 31, v32
	v_lshl_add_u64 v[32:33], v[32:33], 2, v[26:27]
	global_store_dword v[32:33], v31, off sc1
	global_store_dword v[32:33], v30, off offset:128 sc1
	global_store_dword v[32:33], v25, off offset:256 sc1
	global_store_dword v[32:33], v24, off offset:384 sc1

.LBB0_1234:
	v_pk_mul_f32 v[32:33], v[20:21], v[20:21]
	v_pk_mul_f32 v[34:35], v[22:23], v[22:23]
	v_add_f32_e32 v32, v33, v32
	v_add_f32_e32 v32, v32, v35
	v_add_f32_e32 v32, v32, v34
	s_nop 1
	v_mov_b32_dpp v33, v32 quad_perm:[1,0,3,2] row_mask:0xf bank_mask:0xf
	v_cvt_pk_bf16_f32 v35, v30, s0
	v_add_u32_e32 v34, s8, v150
	v_cvt_pk_bf16_f32 v37, v24, s0
	v_lshlrev_b32_e32 v24, s68, v34
	s_waitcnt lgkmcnt(0)
	v_add_f32_e32 v32, v32, v33
	s_nop 1
	v_mov_b32_dpp v33, v32 quad_perm:[2,3,0,1] row_mask:0xf bank_mask:0xf
	v_cvt_pk_bf16_f32 v36, v25, s0
	v_ashrrev_i32_e32 v25, 31, v24
	v_cvt_pk_bf16_f32 v31, v31, s0
	v_lshl_add_u64 v[24:25], v[24:25], 1, v[28:29]
	s_waitcnt lgkmcnt(0)
	v_add_f32_e32 v32, v32, v33
	s_nop 1
	v_mov_b32_dpp v33, v32 row_half_mirror row_mask:0xf bank_mask:0xf
	global_store_short v[24:25], v31, off sc1
	global_store_short v[24:25], v35, off offset:64 sc1
	global_store_short v[24:25], v36, off offset:128 sc1
	global_store_short v[24:25], v37, off offset:192 sc1
	s_and_b64 vcc, exec, s[0:1]
	s_waitcnt lgkmcnt(0)
	v_add_f32_e32 v32, v32, v33
	s_nop 1
	v_mov_b32_dpp v33, v32 row_mirror row_mask:0xf bank_mask:0xf
	s_waitcnt lgkmcnt(0)
	v_add_f32_e32 v30, v32, v33
	v_mov_b32_e32 v32, v30
	s_nop 1
	v_permlane16_swap_b32_e32 v30, v32
	s_nop 0
	s_waitcnt lgkmcnt(0)
	v_add_f32_e32 v30, v30, v32
	v_fmamk_f32 v30, v30, 0x3c000000, v166
	v_rsq_f32_e32 v30, v30
	s_nop 0
	v_pk_mul_f32 v[24:25], v[12:13], v[30:31] op_sel_hi:[1,0]
	v_pk_mul_f32 v[30:31], v[14:15], v[30:31] op_sel_hi:[1,0]
	v_pk_mul_f32 v[24:25], v[20:21], v[24:25]
	v_pk_mul_f32 v[20:21], v[22:23], v[30:31]
	s_cbranch_vccnz .LBB0_1236
	v_add_lshl_u32 v22, s66, v151, 8
	v_ashrrev_i32_e32 v23, 31, v22
	v_lshl_add_u64 v[22:23], v[22:23], 2, v[26:27]
	global_store_dword v[22:23], v25, off sc1
	global_store_dword v[22:23], v24, off offset:128 sc1
	global_store_dword v[22:23], v21, off offset:256 sc1
	global_store_dword v[22:23], v20, off offset:384 sc1

.LBB0_1238:
	v_pk_mul_f32 v[22:23], v[16:17], v[16:17]
	v_pk_mul_f32 v[30:31], v[18:19], v[18:19]
	v_add_f32_e32 v22, v23, v22
	v_add_f32_e32 v22, v22, v31
	v_add_f32_e32 v22, v22, v30
	s_nop 1
	v_mov_b32_dpp v23, v22 quad_perm:[1,0,3,2] row_mask:0xf bank_mask:0xf
	v_add_u32_e32 v30, s8, v151
	v_cvt_pk_bf16_f32 v32, v20, s0
	v_lshlrev_b32_e32 v20, s68, v30
	v_cvt_pk_bf16_f32 v31, v21, s0
	s_waitcnt lgkmcnt(0)
	v_add_f32_e32 v22, v22, v23
	s_nop 1
	v_mov_b32_dpp v23, v22 quad_perm:[2,3,0,1] row_mask:0xf bank_mask:0xf
	v_ashrrev_i32_e32 v21, 31, v20
	v_cvt_pk_bf16_f32 v25, v25, s0
	v_cvt_pk_bf16_f32 v24, v24, s0
	v_lshl_add_u64 v[20:21], v[20:21], 1, v[28:29]
	s_waitcnt lgkmcnt(0)
	v_add_f32_e32 v22, v22, v23
	s_nop 1
	v_mov_b32_dpp v23, v22 row_half_mirror row_mask:0xf bank_mask:0xf
	global_store_short v[20:21], v25, off sc1
	global_store_short v[20:21], v24, off offset:64 sc1
	global_store_short v[20:21], v31, off offset:128 sc1
	global_store_short v[20:21], v32, off offset:192 sc1
	s_and_b64 vcc, exec, s[0:1]
	s_waitcnt lgkmcnt(0)
	v_add_f32_e32 v22, v22, v23
	s_nop 1
	v_mov_b32_dpp v23, v22 row_mirror row_mask:0xf bank_mask:0xf
	s_waitcnt lgkmcnt(0)
	v_add_f32_e32 v22, v22, v23
	v_mov_b32_e32 v23, v22
	s_nop 1
	v_permlane16_swap_b32_e32 v22, v23
	s_nop 0
	s_waitcnt lgkmcnt(0)
	v_add_f32_e32 v22, v22, v23
	v_fmamk_f32 v22, v22, 0x3c000000, v166
	v_rsq_f32_e32 v22, v22
	s_nop 0
	v_pk_mul_f32 v[20:21], v[12:13], v[22:23] op_sel_hi:[1,0]
	v_pk_mul_f32 v[22:23], v[14:15], v[22:23] op_sel_hi:[1,0]
	v_pk_mul_f32 v[20:21], v[16:17], v[20:21]
	v_pk_mul_f32 v[16:17], v[18:19], v[22:23]
	s_cbranch_vccnz .LBB0_1240
	v_add_lshl_u32 v18, s66, v152, 8
	v_ashrrev_i32_e32 v19, 31, v18
	v_lshl_add_u64 v[18:19], v[18:19], 2, v[26:27]
	global_store_dword v[18:19], v21, off sc1
	global_store_dword v[18:19], v20, off offset:128 sc1
	global_store_dword v[18:19], v17, off offset:256 sc1
	global_store_dword v[18:19], v16, off offset:384 sc1

.LBB0_1242:
	v_pk_mul_f32 v[18:19], v[8:9], v[8:9]
	v_pk_mul_f32 v[22:23], v[10:11], v[10:11]
	v_add_f32_e32 v18, v19, v18
	v_add_f32_e32 v18, v18, v23
	v_add_f32_e32 v18, v18, v22
	s_nop 1
	v_mov_b32_dpp v19, v18 quad_perm:[1,0,3,2] row_mask:0xf bank_mask:0xf
	v_add_u32_e32 v22, s8, v152
	v_cvt_pk_bf16_f32 v24, v16, s0
	v_lshlrev_b32_e32 v16, s68, v22
	v_cvt_pk_bf16_f32 v23, v17, s0
	s_waitcnt lgkmcnt(0)
	v_add_f32_e32 v18, v18, v19
	s_nop 1
	v_mov_b32_dpp v19, v18 quad_perm:[2,3,0,1] row_mask:0xf bank_mask:0xf
	v_ashrrev_i32_e32 v17, 31, v16
	v_cvt_pk_bf16_f32 v21, v21, s0
	v_cvt_pk_bf16_f32 v20, v20, s0
	v_lshl_add_u64 v[16:17], v[16:17], 1, v[28:29]
	s_waitcnt lgkmcnt(0)
	v_add_f32_e32 v18, v18, v19
	s_nop 1
	v_mov_b32_dpp v19, v18 row_half_mirror row_mask:0xf bank_mask:0xf
	global_store_short v[16:17], v21, off sc1
	global_store_short v[16:17], v20, off offset:64 sc1
	global_store_short v[16:17], v23, off offset:128 sc1
	global_store_short v[16:17], v24, off offset:192 sc1
	s_and_b64 vcc, exec, s[0:1]
	s_waitcnt lgkmcnt(0)
	v_add_f32_e32 v18, v18, v19
	s_nop 1
	v_mov_b32_dpp v19, v18 row_mirror row_mask:0xf bank_mask:0xf
	s_waitcnt lgkmcnt(0)
	v_add_f32_e32 v18, v18, v19
	v_mov_b32_e32 v19, v18
	s_nop 1
	v_permlane16_swap_b32_e32 v18, v19
	s_nop 0
	s_waitcnt lgkmcnt(0)
	v_add_f32_e32 v18, v18, v19
	v_fmamk_f32 v18, v18, 0x3c000000, v166
	v_rsq_f32_e32 v18, v18
	s_nop 0
	v_pk_mul_f32 v[16:17], v[12:13], v[18:19] op_sel_hi:[1,0]
	v_pk_mul_f32 v[18:19], v[14:15], v[18:19] op_sel_hi:[1,0]
	v_pk_mul_f32 v[16:17], v[8:9], v[16:17]
	v_pk_mul_f32 v[8:9], v[10:11], v[18:19]
	s_cbranch_vccnz .LBB0_1244
	v_add_lshl_u32 v10, s66, v153, 8
	v_ashrrev_i32_e32 v11, 31, v10
	v_lshl_add_u64 v[10:11], v[10:11], 2, v[26:27]
	global_store_dword v[10:11], v17, off sc1
	global_store_dword v[10:11], v16, off offset:128 sc1
	global_store_dword v[10:11], v9, off offset:256 sc1
	global_store_dword v[10:11], v8, off offset:384 sc1

.LBB0_1246:
	v_pk_mul_f32 v[10:11], v[4:5], v[4:5]
	v_pk_mul_f32 v[18:19], v[6:7], v[6:7]
	v_add_f32_e32 v10, v11, v10
	v_add_f32_e32 v10, v10, v19
	v_add_f32_e32 v10, v10, v18
	s_nop 1
	v_mov_b32_dpp v11, v10 quad_perm:[1,0,3,2] row_mask:0xf bank_mask:0xf
	v_add_u32_e32 v18, s8, v153
	v_cvt_pk_bf16_f32 v20, v8, s0
	v_lshlrev_b32_e32 v8, s68, v18
	v_cvt_pk_bf16_f32 v19, v9, s0
	s_waitcnt lgkmcnt(0)
	v_add_f32_e32 v10, v10, v11
	s_nop 1
	v_mov_b32_dpp v11, v10 quad_perm:[2,3,0,1] row_mask:0xf bank_mask:0xf
	v_ashrrev_i32_e32 v9, 31, v8
	v_cvt_pk_bf16_f32 v17, v17, s0
	v_cvt_pk_bf16_f32 v16, v16, s0
	v_lshl_add_u64 v[8:9], v[8:9], 1, v[28:29]
	s_waitcnt lgkmcnt(0)
	v_add_f32_e32 v10, v10, v11
	s_nop 1
	v_mov_b32_dpp v11, v10 row_half_mirror row_mask:0xf bank_mask:0xf
	global_store_short v[8:9], v17, off sc1
	global_store_short v[8:9], v16, off offset:64 sc1
	global_store_short v[8:9], v19, off offset:128 sc1
	global_store_short v[8:9], v20, off offset:192 sc1
	s_and_b64 vcc, exec, s[0:1]
	s_waitcnt lgkmcnt(0)
	v_add_f32_e32 v10, v10, v11
	s_nop 1
	v_mov_b32_dpp v11, v10 row_mirror row_mask:0xf bank_mask:0xf
	s_waitcnt lgkmcnt(0)
	v_add_f32_e32 v10, v10, v11
	v_mov_b32_e32 v11, v10
	s_nop 1
	v_permlane16_swap_b32_e32 v10, v11
	s_nop 0
	s_waitcnt lgkmcnt(0)
	v_add_f32_e32 v10, v10, v11
	v_fmamk_f32 v10, v10, 0x3c000000, v166
	v_rsq_f32_e32 v10, v10
	s_nop 0
	v_pk_mul_f32 v[8:9], v[12:13], v[10:11] op_sel_hi:[1,0]
	v_pk_mul_f32 v[10:11], v[14:15], v[10:11] op_sel_hi:[1,0]
	v_pk_mul_f32 v[8:9], v[4:5], v[8:9]
	v_pk_mul_f32 v[4:5], v[6:7], v[10:11]
	s_cbranch_vccnz .LBB0_1248
	v_add_lshl_u32 v6, s66, v154, 8
	v_ashrrev_i32_e32 v7, 31, v6
	v_lshl_add_u64 v[6:7], v[6:7], 2, v[26:27]
	global_store_dword v[6:7], v9, off sc1
	global_store_dword v[6:7], v8, off offset:128 sc1
	global_store_dword v[6:7], v5, off offset:256 sc1
	global_store_dword v[6:7], v4, off offset:384 sc1

.LBB0_1250:
	v_pk_mul_f32 v[6:7], v[0:1], v[0:1]
	v_pk_mul_f32 v[10:11], v[2:3], v[2:3]
	v_add_f32_e32 v6, v7, v6
	v_add_f32_e32 v6, v11, v6
	v_add_f32_e32 v6, v10, v6
	s_nop 1
	v_mov_b32_dpp v7, v6 quad_perm:[1,0,3,2] row_mask:0xf bank_mask:0xf
	v_add_u32_e32 v10, s8, v154
	v_cvt_pk_bf16_f32 v16, v4, s0
	v_lshlrev_b32_e32 v4, s68, v10
	v_cvt_pk_bf16_f32 v11, v5, s0
	s_waitcnt lgkmcnt(0)
	v_add_f32_e32 v6, v6, v7
	s_nop 1
	v_mov_b32_dpp v7, v6 quad_perm:[2,3,0,1] row_mask:0xf bank_mask:0xf
	v_ashrrev_i32_e32 v5, 31, v4
	v_cvt_pk_bf16_f32 v9, v9, s0
	v_cvt_pk_bf16_f32 v8, v8, s0
	v_lshl_add_u64 v[4:5], v[4:5], 1, v[28:29]
	s_waitcnt lgkmcnt(0)
	v_add_f32_e32 v6, v6, v7
	s_nop 1
	v_mov_b32_dpp v7, v6 row_half_mirror row_mask:0xf bank_mask:0xf
	global_store_short v[4:5], v9, off sc1
	global_store_short v[4:5], v8, off offset:64 sc1
	global_store_short v[4:5], v11, off offset:128 sc1
	global_store_short v[4:5], v16, off offset:192 sc1
	s_and_b64 vcc, exec, s[0:1]
	s_waitcnt lgkmcnt(0)
	v_add_f32_e32 v6, v6, v7
	s_nop 1
	v_mov_b32_dpp v7, v6 row_mirror row_mask:0xf bank_mask:0xf
	s_waitcnt lgkmcnt(0)
	v_add_f32_e32 v6, v6, v7
	v_mov_b32_e32 v7, v6
	s_nop 1
	v_permlane16_swap_b32_e32 v6, v7
	s_nop 0
	s_waitcnt lgkmcnt(0)
	v_add_f32_e32 v6, v6, v7
	v_fmamk_f32 v6, v6, 0x3c000000, v166
	v_rsq_f32_e32 v6, v6
	s_nop 0
	v_pk_mul_f32 v[4:5], v[12:13], v[6:7] op_sel_hi:[1,0]
	v_pk_mul_f32 v[6:7], v[14:15], v[6:7] op_sel_hi:[1,0]
	v_pk_mul_f32 v[4:5], v[0:1], v[4:5]
	v_pk_mul_f32 v[0:1], v[2:3], v[6:7]
	s_cbranch_vccnz .LBB0_1252
	v_add_lshl_u32 v2, s66, v155, 8
	v_ashrrev_i32_e32 v3, 31, v2
	v_lshl_add_u64 v[2:3], v[2:3], 2, v[26:27]
	global_store_dword v[2:3], v5, off sc1
	global_store_dword v[2:3], v4, off offset:128 sc1
	global_store_dword v[2:3], v1, off offset:256 sc1
	global_store_dword v[2:3], v0, off offset:384 sc1
